# v42 plus relaxed first two vmcnt waits of the peeled first K-iteration for units after the first (epilogue stores retire behind MFMAs of the next tile)
# baseline (speedup 1.0000x reference)
; #define PG8_STAGE(bufoff, gbase, voff) do { _Pragma("unroll") for (int _i = 0; _i < 2; ++_i) \
;         __builtin_amdgcn_global_load_lds((const unsigned*)((const char*)(gbase) + (voff)[_i]), (PG8_LAS unsigned*)(lds + (bufoff) + ldsw + _i * 8192), 16, 0, 0); } while (0)
; #define PG8_WAIT_V(n) asm volatile("s_waitcnt vmcnt(" #n ")" ::: "memory")
; #define PG8_BAR __builtin_amdgcn_s_barrier()
; template <class Epi, class Sched, bool ALIGN_EPI = false, bool SP2 = false, bool A_TILED = false>
; __device__ __forceinline__ void gemm_phase(PG8_LAS unsigned char* lds, const Gemm g, const Sched& S, const Epi& E, const int wave_s) {
;     ...
;     Unit cur, nxt; int ui = 0;
;     if (!S.next(0, cur)) return;
;     f32x4 acc[2][2][4][2];
;     bf16x8 At[4][2], B0[2][2], B1[2][2];
;     const char* cA = (const char*)g.A + (size_t)cur.pm * tstepA; const char* cB = (const char*)g.Bt + (size_t)cur.pn * tstep;
;     S.a_ready(cur);
;     if constexpr (SP2) {
;         PG8_STAGE(PG8_SB(0, 0), cB, voffB); PG8_STAGE(PG8_SB(0, 1), cB + hstep, voffB); PG8_STAGE(PG8_SA(0, 0), cA, voffA); PG8_STAGE(PG8_SA(0, 1), cA + hstepA, voffA);
;         if (wr == 1) PG8_BAR;
;         PG8_WAIT_V(2); PG8_BAR;
;         PG8_STAGE(PG8_SB(1, 0), cB + kstep, voffB); PG8_STAGE(PG8_SA(1, 0), cA + kstepA, voffA); PG8_STAGE(PG8_SB(1, 1), cB + hstep + kstep, voffB);
;         PG8_WAIT_V(6); PG8_BAR;
;     } else {
;         PG8_STAGE(PG8_SB(0, 0), cB, voffB); PG8_STAGE(PG8_SA(0, 0), cA, voffA); PG8_STAGE(PG8_SB(0, 1), cB + hstep, voffB); PG8_STAGE(PG8_SA(0, 1), cA + hstepA, voffA);
;         if (wr == 1) PG8_BAR;
;         PG8_WAIT_V(4); PG8_BAR;
;         PG8_STAGE(PG8_SB(1, 0), cB + kstep, voffB); PG8_STAGE(PG8_SA(1, 0), cA + kstepA, voffA); PG8_STAGE(PG8_SB(1, 1), cB + hstep + kstep, voffB);
;         PG8_WAIT_V(6); PG8_BAR;
;     }
.LBB0_771:
	s_ashr_i32 s40, s86, 31
	s_add_u32 s0, s0, s29
	s_addc_u32 s1, s1, 0
	s_add_u32 s60, s0, 0x22600000
	s_addc_u32 s61, s1, 0
	s_lshl_b32 s0, s42, 5
	s_mov_b64 s[62:63], 0x80
	s_and_b32 s42, s0, 0x60
	s_add_i32 m0, s23, 0x18000
	v_lshl_add_u64 v[6:7], v[6:7], 0, s[62:63]
	s_lshl_b32 s41, s43, 6
	s_lshl_b32 s46, s43, 13
	s_lshl_b32 s47, s42, 7
	s_waitcnt vmcnt(2)
	s_barrier
	global_load_lds_dwordx4 v[6:7], off
	v_lshl_add_u64 v[4:5], v[4:5], 0, s[62:63]
	s_add_i32 m0, s23, 0x1a000
	s_add_i32 s43, s23, 0x8000
	s_add_i32 s44, s23, 0xa000
	global_load_lds_dwordx4 v[4:5], off
	v_lshl_add_u64 v[0:1], v[0:1], 0, s[62:63]
	s_mov_b32 m0, s43
	s_add_u32 s0, s80, 0x80080
	global_load_lds_dwordx4 v[0:1], off
	v_lshl_add_u64 v[0:1], v[2:3], 0, s[62:63]
	s_mov_b32 m0, s44
	s_addc_u32 s1, s81, 0
	global_load_lds_dwordx4 v[0:1], off
	s_add_i32 m0, s23, 0x1c000
	v_lshl_add_u64 v[0:1], s[0:1], 0, v[128:129]
	global_load_lds_dwordx4 v128, s[0:1]
	v_lshl_add_u64 v[0:1], s[0:1], 0, v[130:131]
	s_add_i32 m0, s23, 0x1e000
	s_movk_i32 s0, 0x3c0
	global_load_lds_dwordx4 v[0:1], off
	v_and_b32_e32 v0, 48, v8
	v_lshlrev_b32_e32 v1, 6, v8
	v_and_or_b32 v0, v1, s0, v0
	v_lshlrev_b32_e32 v1, 2, v8
	v_and_b32_e32 v1, 32, v1
	v_bitop3_b32 v2, v0, s46, v1 bitop3:0xde
	v_bitop3_b32 v148, s47, v0, v1 bitop3:0xf6
	v_lshlrev_b32_e32 v0, 15, v9
	v_and_b32_e32 v0, 0xffff0000, v0
	v_lshl_add_u32 v0, v10, 12, v0
	v_and_b32_e32 v1, 1, v9
	v_lshl_or_b32 v0, v1, 6, v0
	v_lshl_add_u32 v136, v11, 1, v0
	v_lshlrev_b32_e32 v0, 15, v13
	v_and_b32_e32 v0, 0xffff0000, v0
	s_waitcnt vmcnt(6)
	s_mov_b32 s98, 0
	s_cmpk_lt_u32 s45, 0x100
	v_lshl_add_u32 v0, v12, 12, v0
	v_and_b32_e32 v1, 1, v13
	s_sext_i32_i16 s50, s64
	s_cselect_b64 s[64:65], -1, 0
	v_mov_b32_e32 v137, 0
	v_lshl_or_b32 v0, v1, 6, v0
	s_add_i32 s45, 0, 0x10000
	s_add_i32 s46, 0, 0x14000
	v_lshl_add_u32 v138, v14, 1, v0
	v_mov_b32_e32 v139, v137
	s_mov_b64 s[66:67], 0x180
	v_add_u32_e32 v149, s45, v148
	v_add_u32_e32 v150, s46, v148
	v_add_u32_e32 v151, 0, v2
	s_mov_b64 s[68:69], 0x100
	s_movk_i32 s47, 0x3000
	s_add_i32 s48, s23, 0xc000
	s_add_i32 s49, s23, 0xe000
	s_barrier
	s_branch .LBB0_774

; template <class Epi, class Sched, bool ALIGN_EPI = false, bool SP2 = false, bool A_TILED = false>
; __device__ __forceinline__ void gemm_phase(PG8_LAS unsigned char* lds, const Gemm g, const Sched& S, const Epi& E, const int wave_s) {
;     ...
;         constexpr bool PEEL = SP2 && !Epi::AFTER_DRAIN;
;         if constexpr (PEEL) {
;             const char* a1 = cA + kstepA; const char* a2 = cA + 2 * kstepA; const char* b2 = cB + 2 * kstep; const char* a3 = a2 + kstepA; const char* b3 = b2 + kstep;
;             PG8_ITER(PG8_MMAZ)
.LBB0_776:
	s_ashr_i32 s73, s72, 31
	ds_read_b128 v[0:3], v149
	ds_read_b128 v[4:7], v149 offset:1024
	ds_read_b128 v[8:11], v149 offset:2048
	ds_read_b128 v[12:15], v149 offset:3072
	ds_read_b128 v[16:19], v150
	ds_read_b128 v[20:23], v150 offset:1024
	ds_read_b128 v[24:27], v150 offset:2048
	ds_read_b128 v[28:31], v150 offset:3072
	s_lshl_b64 s[52:53], s[72:73], 20
	s_add_u32 s74, s7, s52
	s_addc_u32 s75, s8, s53
	s_and_b64 s[52:53], s[0:1], exec
	s_cselect_b32 s51, s75, s83
	s_cselect_b32 s52, s74, s82
	s_ashr_i32 s71, s70, 31
	s_lshl_b64 s[54:55], s[70:71], 20
	s_add_u32 s76, s9, s54
	s_addc_u32 s77, s14, s55
	s_and_b64 s[54:55], s[0:1], exec
	s_cselect_b32 s53, s77, s81
	s_cselect_b32 s54, s76, s80
	s_add_u32 s56, s82, 0x80080
	s_addc_u32 s57, s83, 0
	s_mov_b32 m0, s48
	v_lshl_add_u64 v[64:65], s[56:57], 0, v[134:135]
	ds_read_b128 v[32:35], v151
	ds_read_b128 v[36:39], v151 offset:1024
	ds_read_b128 v[40:43], v151 offset:2048
	ds_read_b128 v[44:47], v151 offset:3072
	ds_read_b128 v[48:51], v151 offset:4096
	ds_read_b128 v[52:55], v151 offset:5120
	ds_read_b128 v[56:59], v151 offset:6144
	ds_read_b128 v[60:63], v151 offset:7168
	global_load_lds_dwordx4 v134, s[56:57]
	v_lshl_add_u64 v[64:65], s[56:57], 0, v[132:133]
	s_mov_b32 m0, s49
	s_nop 0
	global_load_lds_dwordx4 v132, s[56:57]
	s_waitcnt vmcnt(24) lgkmcnt(0)
	s_cmp_lg_u32 s98, 0
	s_cbranch_scc1 .Lpw_1
	s_waitcnt vmcnt(8)
.Lpw_1:
	s_setprio 1
	s_barrier
	v_mfma_f32_16x16x32_bf16 v[88:91], v[0:3], v[56:59], 0
	v_mfma_f32_16x16x32_bf16 v[64:67], v[0:3], v[32:35], 0
	v_mfma_f32_16x16x32_bf16 v[68:71], v[8:11], v[32:35], 0
	v_mfma_f32_16x16x32_bf16 v[72:75], v[0:3], v[40:43], 0
	v_mfma_f32_16x16x32_bf16 v[76:79], v[8:11], v[40:43], 0
	v_mfma_f32_16x16x32_bf16 v[80:83], v[0:3], v[48:51], 0
	v_mfma_f32_16x16x32_bf16 v[84:87], v[8:11], v[48:51], 0
	v_mfma_f32_16x16x32_bf16 v[92:95], v[4:7], v[60:63], v[88:91]
	v_mfma_f32_16x16x32_bf16 v[88:91], v[8:11], v[56:59], 0
	v_mfma_f32_16x16x32_bf16 v[64:67], v[4:7], v[36:39], v[64:67]
	v_mfma_f32_16x16x32_bf16 v[68:71], v[12:15], v[36:39], v[68:71]
	v_mfma_f32_16x16x32_bf16 v[72:75], v[4:7], v[44:47], v[72:75]
	v_mfma_f32_16x16x32_bf16 v[76:79], v[12:15], v[44:47], v[76:79]
	v_mfma_f32_16x16x32_bf16 v[80:83], v[4:7], v[52:55], v[80:83]
	v_mfma_f32_16x16x32_bf16 v[84:87], v[12:15], v[52:55], v[84:87]
	v_mfma_f32_16x16x32_bf16 v[100:103], v[12:15], v[60:63], v[88:91]
	s_setprio 0
	s_setprio 1
	v_mfma_f32_16x16x32_bf16 v[88:91], v[16:19], v[32:35], 0
	v_mfma_f32_16x16x32_bf16 v[32:35], v[24:27], v[32:35], 0
	v_mfma_f32_16x16x32_bf16 v[108:111], v[20:23], v[36:39], v[88:91]
	v_mfma_f32_16x16x32_bf16 v[32:35], v[28:31], v[36:39], v[32:35]
	v_mfma_f32_16x16x32_bf16 v[36:39], v[16:19], v[40:43], 0
	v_mfma_f32_16x16x32_bf16 v[40:43], v[24:27], v[40:43], 0
	v_mfma_f32_16x16x32_bf16 v[36:39], v[20:23], v[44:47], v[36:39]
	v_mfma_f32_16x16x32_bf16 v[40:43], v[28:31], v[44:47], v[40:43]
	v_mfma_f32_16x16x32_bf16 v[44:47], v[16:19], v[48:51], 0
	v_mfma_f32_16x16x32_bf16 v[48:51], v[24:27], v[48:51], 0
	v_mfma_f32_16x16x32_bf16 v[44:47], v[20:23], v[52:55], v[44:47]
	v_mfma_f32_16x16x32_bf16 v[52:55], v[28:31], v[52:55], v[48:51]
	v_mfma_f32_16x16x32_bf16 v[48:51], v[16:19], v[56:59], 0
	v_mfma_f32_16x16x32_bf16 v[152:155], v[20:23], v[60:63], v[48:51]
	v_mfma_f32_16x16x32_bf16 v[48:51], v[24:27], v[56:59], 0
	v_mfma_f32_16x16x32_bf16 v[156:159], v[28:31], v[60:63], v[48:51]
	s_barrier
	s_setprio 0
	s_add_i32 s55, s45, s15
	v_lshl_add_u64 v[146:147], s[80:81], 0, v[128:129]
	s_add_i32 s56, s55, 0x2000
	v_lshl_add_u64 v[120:121], v[146:147], 0, s[68:69]
	s_mov_b32 m0, s55
	v_lshl_add_u64 v[252:253], s[80:81], 0, v[130:131]
	s_add_u32 s58, s80, 0x80100
	ds_read_b128 v[48:51], v151 offset:16384
	ds_read_b128 v[56:59], v151 offset:17408
	ds_read_b128 v[60:63], v151 offset:18432
	ds_read_b128 v[88:91], v151 offset:19456
	ds_read_b128 v[96:99], v151 offset:20480
	ds_read_b128 v[104:107], v151 offset:21504
	ds_read_b128 v[112:115], v151 offset:22528
	ds_read_b128 v[116:119], v151 offset:23552
	global_load_lds_dwordx4 v[120:121], off
	v_lshl_add_u64 v[120:121], v[252:253], 0, s[68:69]
	s_mov_b32 m0, s56
	s_addc_u32 s59, s81, 0
	s_add_i32 s57, s46, s15
	global_load_lds_dwordx4 v[120:121], off
	v_lshl_add_u64 v[120:121], s[58:59], 0, v[128:129]
	s_mov_b32 m0, s57
	v_lshl_add_u64 v[140:141], s[82:83], 0, v[134:135]
	global_load_lds_dwordx4 v128, s[58:59]
	v_lshl_add_u64 v[120:121], s[58:59], 0, v[130:131]
	s_add_i32 s58, s57, 0x2000
	s_mov_b32 m0, s58
	v_lshl_add_u64 v[142:143], s[82:83], 0, v[132:133]
	global_load_lds_dwordx4 v[120:121], off
	v_lshl_add_u64 v[120:121], v[140:141], 0, s[68:69]
	s_mov_b32 m0, s23
	s_nop 0
	global_load_lds_dwordx4 v[120:121], off
	v_lshl_add_u64 v[120:121], v[142:143], 0, s[68:69]
	s_mov_b32 m0, s36
	s_nop 0
	global_load_lds_dwordx4 v[120:121], off
	s_waitcnt vmcnt(24) lgkmcnt(0)
	s_cmp_lg_u32 s98, 0
	s_cbranch_scc1 .Lpw_2
	s_waitcnt vmcnt(8)
.Lpw_2:
	s_setprio 1
	s_barrier
	v_mfma_f32_16x16x32_bf16 v[120:123], v[0:3], v[48:51], 0
	v_mfma_f32_16x16x32_bf16 v[160:163], v[4:7], v[56:59], v[120:123]
	v_mfma_f32_16x16x32_bf16 v[120:123], v[8:11], v[48:51], 0
	v_mfma_f32_16x16x32_bf16 v[164:167], v[12:15], v[56:59], v[120:123]
	v_mfma_f32_16x16x32_bf16 v[120:123], v[0:3], v[60:63], 0
	v_mfma_f32_16x16x32_bf16 v[168:171], v[4:7], v[88:91], v[120:123]
	v_mfma_f32_16x16x32_bf16 v[120:123], v[8:11], v[60:63], 0
	v_mfma_f32_16x16x32_bf16 v[172:175], v[12:15], v[88:91], v[120:123]
	v_mfma_f32_16x16x32_bf16 v[120:123], v[0:3], v[96:99], 0
	v_mfma_f32_16x16x32_bf16 v[0:3], v[0:3], v[112:115], 0
	v_mfma_f32_16x16x32_bf16 v[176:179], v[4:7], v[104:107], v[120:123]
	v_mfma_f32_16x16x32_bf16 v[0:3], v[4:7], v[116:119], v[0:3]
	v_mfma_f32_16x16x32_bf16 v[4:7], v[8:11], v[112:115], 0
	v_mfma_f32_16x16x32_bf16 v[120:123], v[8:11], v[96:99], 0
	v_mfma_f32_16x16x32_bf16 v[4:7], v[12:15], v[116:119], v[4:7]
	v_mfma_f32_16x16x32_bf16 v[180:183], v[12:15], v[104:107], v[120:123]
	s_setprio 0
	s_setprio 1
	v_mfma_f32_16x16x32_bf16 v[8:11], v[16:19], v[48:51], 0
	v_mfma_f32_16x16x32_bf16 v[12:15], v[20:23], v[56:59], v[8:11]
	v_mfma_f32_16x16x32_bf16 v[8:11], v[24:27], v[48:51], 0
	v_mfma_f32_16x16x32_bf16 v[184:187], v[28:31], v[56:59], v[8:11]
	v_mfma_f32_16x16x32_bf16 v[8:11], v[16:19], v[60:63], 0
	v_mfma_f32_16x16x32_bf16 v[188:191], v[20:23], v[88:91], v[8:11]
	v_mfma_f32_16x16x32_bf16 v[8:11], v[24:27], v[60:63], 0
	v_mfma_f32_16x16x32_bf16 v[192:195], v[28:31], v[88:91], v[8:11]
	v_mfma_f32_16x16x32_bf16 v[8:11], v[16:19], v[96:99], 0
	v_mfma_f32_16x16x32_bf16 v[196:199], v[20:23], v[104:107], v[8:11]
	v_mfma_f32_16x16x32_bf16 v[8:11], v[24:27], v[96:99], 0
	v_mfma_f32_16x16x32_bf16 v[200:203], v[28:31], v[104:107], v[8:11]
	v_mfma_f32_16x16x32_bf16 v[8:11], v[16:19], v[112:115], 0
	v_mfma_f32_16x16x32_bf16 v[204:207], v[20:23], v[116:119], v[8:11]
	v_mfma_f32_16x16x32_bf16 v[8:11], v[24:27], v[112:115], 0
	v_mfma_f32_16x16x32_bf16 v[208:211], v[28:31], v[116:119], v[8:11]
	s_barrier
	s_setprio 0
	s_add_i32 s59, 0, 0x18000
	s_add_i32 s73, 0, 0x1c000
	v_add_u32_e32 v144, s59, v148
	v_add_u32_e32 v145, s73, v148
	s_nop 0
	ds_read_b128 v[8:11], v144
	ds_read_b128 v[20:23], v144 offset:1024
	ds_read_b128 v[28:31], v144 offset:2048
	ds_read_b128 v[212:215], v144 offset:3072
	ds_read_b128 v[216:219], v145
	ds_read_b128 v[220:223], v145 offset:1024
	ds_read_b128 v[224:227], v145 offset:2048
	ds_read_b128 v[228:231], v145 offset:3072
	s_add_u32 s84, s82, 0x80100
	s_addc_u32 s85, s83, 0
	s_mov_b32 m0, s37
	v_lshl_add_u64 v[48:49], s[84:85], 0, v[134:135]
	ds_read_b128 v[16:19], v151 offset:32768
	ds_read_b128 v[24:27], v151 offset:33792
	ds_read_b128 v[60:63], v151 offset:34816
	ds_read_b128 v[232:235], v151 offset:35840
	ds_read_b128 v[236:239], v151 offset:36864
	ds_read_b128 v[240:243], v151 offset:37888
	ds_read_b128 v[244:247], v151 offset:38912
	ds_read_b128 v[248:251], v151 offset:39936
	global_load_lds_dwordx4 v134, s[84:85]
	v_lshl_add_u64 v[48:49], s[84:85], 0, v[132:133]
	s_mov_b32 m0, s38
	s_nop 0
	global_load_lds_dwordx4 v132, s[84:85]
	s_waitcnt vmcnt(8) lgkmcnt(0)
	s_setprio 1
	s_barrier
	v_mfma_f32_16x16x32_bf16 v[48:51], v[8:11], v[16:19], v[64:67]
	v_mfma_f32_16x16x32_bf16 v[120:123], v[20:23], v[24:27], v[48:51]
	v_mfma_f32_16x16x32_bf16 v[48:51], v[28:31], v[16:19], v[68:71]
	v_mfma_f32_16x16x32_bf16 v[112:115], v[212:215], v[24:27], v[48:51]
	v_mfma_f32_16x16x32_bf16 v[48:51], v[8:11], v[60:63], v[72:75]
	v_mfma_f32_16x16x32_bf16 v[104:107], v[20:23], v[232:235], v[48:51]
	v_mfma_f32_16x16x32_bf16 v[48:51], v[28:31], v[60:63], v[76:79]
	v_mfma_f32_16x16x32_bf16 v[96:99], v[212:215], v[232:235], v[48:51]
	v_mfma_f32_16x16x32_bf16 v[48:51], v[8:11], v[236:239], v[80:83]
	v_mfma_f32_16x16x32_bf16 v[88:91], v[20:23], v[240:243], v[48:51]
	v_mfma_f32_16x16x32_bf16 v[48:51], v[28:31], v[236:239], v[84:87]
	v_mfma_f32_16x16x32_bf16 v[80:83], v[212:215], v[240:243], v[48:51]
	v_mfma_f32_16x16x32_bf16 v[48:51], v[8:11], v[244:247], v[92:95]
	v_mfma_f32_16x16x32_bf16 v[56:59], v[20:23], v[248:251], v[48:51]
	v_mfma_f32_16x16x32_bf16 v[48:51], v[28:31], v[244:247], v[100:103]
	v_mfma_f32_16x16x32_bf16 v[48:51], v[212:215], v[248:251], v[48:51]
	s_setprio 0
	s_setprio 1
	v_mfma_f32_16x16x32_bf16 v[64:67], v[216:219], v[16:19], v[108:111]
	v_mfma_f32_16x16x32_bf16 v[16:19], v[224:227], v[16:19], v[32:35]
	v_mfma_f32_16x16x32_bf16 v[116:119], v[228:231], v[24:27], v[16:19]
	v_mfma_f32_16x16x32_bf16 v[16:19], v[216:219], v[60:63], v[36:39]
	v_mfma_f32_16x16x32_bf16 v[108:111], v[220:223], v[232:235], v[16:19]
	v_mfma_f32_16x16x32_bf16 v[16:19], v[224:227], v[60:63], v[40:43]
	v_mfma_f32_16x16x32_bf16 v[100:103], v[228:231], v[232:235], v[16:19]
	v_mfma_f32_16x16x32_bf16 v[16:19], v[216:219], v[236:239], v[44:47]
	v_mfma_f32_16x16x32_bf16 v[92:95], v[220:223], v[240:243], v[16:19]
	v_mfma_f32_16x16x32_bf16 v[16:19], v[224:227], v[236:239], v[52:55]
	v_mfma_f32_16x16x32_bf16 v[84:87], v[228:231], v[240:243], v[16:19]
	v_mfma_f32_16x16x32_bf16 v[16:19], v[216:219], v[244:247], v[152:155]
	v_mfma_f32_16x16x32_bf16 v[60:63], v[220:223], v[248:251], v[16:19]
	v_mfma_f32_16x16x32_bf16 v[16:19], v[224:227], v[244:247], v[156:159]
	v_mfma_f32_16x16x32_bf16 v[124:127], v[220:223], v[24:27], v[64:67]
	v_mfma_f32_16x16x32_bf16 v[52:55], v[228:231], v[248:251], v[16:19]
	s_barrier
	s_setprio 0
	s_add_i32 s59, s59, s15
	s_add_i32 s71, s59, 0x2000
	s_nop 1
	v_lshl_add_u64 v[16:17], v[146:147], 0, s[66:67]
	s_mov_b32 m0, s59
	s_add_u32 s84, s80, 0x80180
	ds_read_b128 v[36:39], v151 offset:49152
	ds_read_b128 v[44:47], v151 offset:50176
	ds_read_b128 v[152:155], v151 offset:51200
	ds_read_b128 v[156:159], v151 offset:52224
	ds_read_b128 v[232:235], v151 offset:53248
	ds_read_b128 v[236:239], v151 offset:54272
	ds_read_b128 v[240:243], v151 offset:55296
	ds_read_b128 v[244:247], v151 offset:56320
	global_load_lds_dwordx4 v[16:17], off
	v_lshl_add_u64 v[16:17], v[252:253], 0, s[66:67]
	s_mov_b32 m0, s71
	s_addc_u32 s85, s81, 0
	s_add_i32 s73, s73, s15
	global_load_lds_dwordx4 v[16:17], off
	v_lshl_add_u64 v[16:17], s[84:85], 0, v[128:129]
	s_mov_b32 m0, s73
	s_add_i32 s79, s73, 0x2000
	global_load_lds_dwordx4 v128, s[84:85]
	v_lshl_add_u64 v[16:17], s[84:85], 0, v[130:131]
	s_mov_b32 m0, s79
	s_nop 0
	global_load_lds_dwordx4 v130, s[84:85]
	v_lshl_add_u64 v[16:17], v[140:141], 0, s[66:67]
	s_mov_b32 m0, s43
	s_nop 0
	global_load_lds_dwordx4 v[16:17], off
	v_lshl_add_u64 v[16:17], v[142:143], 0, s[66:67]
	s_mov_b32 m0, s44
	s_nop 0
	global_load_lds_dwordx4 v[16:17], off
	s_waitcnt vmcnt(8) lgkmcnt(0)
	s_setprio 1
	s_barrier
	v_mfma_f32_16x16x32_bf16 v[16:19], v[8:11], v[36:39], v[160:163]
	v_mfma_f32_16x16x32_bf16 v[72:75], v[20:23], v[44:47], v[16:19]
	v_mfma_f32_16x16x32_bf16 v[16:19], v[28:31], v[36:39], v[164:167]
	v_mfma_f32_16x16x32_bf16 v[64:67], v[212:215], v[44:47], v[16:19]
	v_mfma_f32_16x16x32_bf16 v[16:19], v[8:11], v[152:155], v[168:171]
	v_mfma_f32_16x16x32_bf16 v[40:43], v[20:23], v[156:159], v[16:19]
	v_mfma_f32_16x16x32_bf16 v[16:19], v[28:31], v[152:155], v[172:175]
	v_mfma_f32_16x16x32_bf16 v[32:35], v[212:215], v[156:159], v[16:19]
	v_mfma_f32_16x16x32_bf16 v[16:19], v[8:11], v[232:235], v[176:179]
	v_mfma_f32_16x16x32_bf16 v[0:3], v[8:11], v[240:243], v[0:3]
	v_mfma_f32_16x16x32_bf16 v[24:27], v[20:23], v[236:239], v[16:19]
	v_mfma_f32_16x16x32_bf16 v[16:19], v[28:31], v[232:235], v[180:183]
	v_mfma_f32_16x16x32_bf16 v[8:11], v[20:23], v[244:247], v[0:3]
	v_mfma_f32_16x16x32_bf16 v[0:3], v[28:31], v[240:243], v[4:7]
	v_mfma_f32_16x16x32_bf16 v[16:19], v[212:215], v[236:239], v[16:19]
	v_mfma_f32_16x16x32_bf16 v[0:3], v[212:215], v[244:247], v[0:3]
	s_setprio 0
	s_setprio 1
	v_mfma_f32_16x16x32_bf16 v[4:7], v[216:219], v[36:39], v[12:15]
	v_mfma_f32_16x16x32_bf16 v[76:79], v[220:223], v[44:47], v[4:7]
	v_mfma_f32_16x16x32_bf16 v[4:7], v[224:227], v[36:39], v[184:187]
	v_mfma_f32_16x16x32_bf16 v[68:71], v[228:231], v[44:47], v[4:7]
	v_mfma_f32_16x16x32_bf16 v[4:7], v[216:219], v[152:155], v[188:191]
	v_mfma_f32_16x16x32_bf16 v[44:47], v[220:223], v[156:159], v[4:7]
	v_mfma_f32_16x16x32_bf16 v[4:7], v[224:227], v[152:155], v[192:195]
	v_mfma_f32_16x16x32_bf16 v[36:39], v[228:231], v[156:159], v[4:7]
	v_mfma_f32_16x16x32_bf16 v[4:7], v[216:219], v[232:235], v[196:199]
	v_mfma_f32_16x16x32_bf16 v[28:31], v[220:223], v[236:239], v[4:7]
	v_mfma_f32_16x16x32_bf16 v[4:7], v[224:227], v[232:235], v[200:203]
	v_mfma_f32_16x16x32_bf16 v[20:23], v[228:231], v[236:239], v[4:7]
	v_mfma_f32_16x16x32_bf16 v[4:7], v[216:219], v[240:243], v[204:207]
	v_mfma_f32_16x16x32_bf16 v[12:15], v[220:223], v[244:247], v[4:7]
	v_mfma_f32_16x16x32_bf16 v[4:7], v[224:227], v[240:243], v[208:211]
	v_mfma_f32_16x16x32_bf16 v[4:7], v[228:231], v[244:247], v[4:7]
	s_barrier
	s_setprio 0
	s_add_u32 s88, s80, 0x200
	s_addc_u32 s89, s81, 0
	s_add_u32 s80, s82, 0x80180
	s_addc_u32 s81, s83, 0
	s_mov_b32 s90, 0

;     __device__ __forceinline__ void operator()(const f32x4 (&acc)[2][2][4][2], const Unit& u, int wr, int wc, int fr, int fq) const {
;     ...
; #pragma unroll
;         for (int ai = 0; ai < 2; ++ai)
; #pragma unroll
;             for (int m = 0; m < 4; ++m) { bf16_t* rowp = O + (size_t)(row0 + ai * HALF + m * 16) * ldc + col0;
;                 if (ACT == 1) {
;                     const int ob = fr * 64 + 16 * fq, sw = ob ^ (((ob >> 9) & 1) << 5);
;                     rowp = O + ((size_t)(u.pm * (ldc / 64) + u.pn * 4 + (wc >> 1)) * 2 + ai) * 8192 + (((wr * 4 + m) * 2 + (wc & 1)) * 1024 + sw) / 2; }
;                 float rc[2][2], rs[2][2];
;                 if (ACT == 2) { const float pos = (float)((row0 + ai * HALF + m * 16) & 2047);
; #pragma unroll
;                     for (int n = 0; n < 2; ++n)
; #pragma unroll
;                         for (int e = 0; e < 2; ++e) { float r = pos * rinv[n][e]; r -= floorf(r); rs[n][e] = do_rope ? __builtin_amdgcn_sinf(r) : 0.f; rc[n][e] = do_rope ? __builtin_amdgcn_cosf(r) : 1.f; } }
; #pragma unroll
;                 for (int bj = 0; bj < 2; ++bj) { f32x4 v0 = acc[ai][bj][m][0], v1 = acc[ai][bj][m][1];
;                     if (ACT == 3) { const float pos = (float)((row0 + ai * HALF + m * 16) & 2047); float c3[4], s3[4];
; #pragma unroll
;                         for (int p = 0; p < 4; ++p) { float r = pos * rinv3[bj][p]; r -= floorf(r); s3[p] = rope3[bj] ? __builtin_amdgcn_sinf(r) : 0.f; c3[p] = rope3[bj] ? __builtin_amdgcn_cosf(r) : 1.f; }
;                         const f32x4 a = v0, b = v1;
;                         v0[0] = a[0] * c3[0] - a[1] * s3[0]; v0[1] = a[1] * c3[0] + a[0] * s3[0]; v0[2] = a[2] * c3[1] - a[3] * s3[1]; v0[3] = a[3] * c3[1] + a[2] * s3[1];
;                         v1[0] = b[0] * c3[2] - b[1] * s3[2]; v1[1] = b[1] * c3[2] + b[0] * s3[2]; v1[2] = b[2] * c3[3] - b[3] * s3[3]; v1[3] = b[3] * c3[3] + b[2] * s3[3]; }
;                     if (ACT == 2) { const f32x4 a = v0, b = v1;
;                         v0[0] = a[0] * rc[0][0] - a[1] * rs[0][0]; v0[1] = a[1] * rc[0][0] + a[0] * rs[0][0]; v0[2] = a[2] * rc[0][1] - a[3] * rs[0][1]; v0[3] = a[3] * rc[0][1] + a[2] * rs[0][1];
;                         v1[0] = b[0] * rc[1][0] - b[1] * rs[1][0]; v1[1] = b[1] * rc[1][0] + b[0] * rs[1][0]; v1[2] = b[2] * rc[1][1] - b[3] * rs[1][1]; v1[3] = b[3] * rc[1][1] + b[2] * rs[1][1]; }
.LBB0_780:
	v_mov_b32_e32 v140, 0
	s_lshl_b32 s51, s78, 8
	v_mbcnt_lo_u32_b32 v140, -1, v140
	v_mbcnt_hi_u32_b32 v140, -1, v140
	v_or_b32_e32 v140, s33, v140
	s_add_i32 s51, s51, s41
	v_and_or_b32 v152, v140, 15, s51
	s_lshl_b32 s50, s50, 8
	v_lshrrev_b32_e32 v140, 1, v140
	v_and_or_b32 v140, v140, 24, s50
	v_or_b32_e32 v140, s42, v140
	v_ashrrev_i32_e32 v141, 31, v140
	v_mov_b64_e32 v[144:145], s[60:61]
	v_mad_i64_i32 v[142:143], s[50:51], v152, s47, v[144:145]
	v_lshlrev_b64 v[146:147], 1, v[140:141]
	v_lshl_add_u64 v[140:141], v[142:143], 0, v[146:147]
	v_cvt_pk_bf16_f32 v120, v120, v121
	v_cvt_pk_bf16_f32 v121, v122, v123
	v_cvt_pk_bf16_f32 v122, v112, v113
	v_cvt_pk_bf16_f32 v123, v114, v115
	global_store_dwordx4 v[140:141], v[120:123], off
	v_cvt_pk_bf16_f32 v112, v124, v125
	v_cvt_pk_bf16_f32 v113, v126, v127
	v_cvt_pk_bf16_f32 v114, v116, v117
	v_cvt_pk_bf16_f32 v115, v118, v119
	global_store_dwordx4 v[140:141], v[112:115], off offset:256
	v_cvt_pk_bf16_f32 v104, v104, v105
	v_cvt_pk_bf16_f32 v105, v106, v107
	v_cvt_pk_bf16_f32 v106, v96, v97
	v_cvt_pk_bf16_f32 v107, v98, v99
	s_andn2_b64 vcc, exec, s[0:1]
	s_nop 0
	v_or_b32_e32 v112, 16, v152
	v_mad_i64_i32 v[112:113], s[50:51], v112, s47, v[144:145]
	v_lshl_add_u64 v[112:113], v[112:113], 0, v[146:147]
	global_store_dwordx4 v[112:113], v[104:107], off
	v_cvt_pk_bf16_f32 v96, v108, v109
	v_cvt_pk_bf16_f32 v97, v110, v111
	v_cvt_pk_bf16_f32 v98, v100, v101
	v_cvt_pk_bf16_f32 v99, v102, v103
	global_store_dwordx4 v[112:113], v[96:99], off offset:256
	v_cvt_pk_bf16_f32 v88, v88, v89
	v_cvt_pk_bf16_f32 v89, v90, v91
	v_cvt_pk_bf16_f32 v90, v80, v81
	v_cvt_pk_bf16_f32 v91, v82, v83
	s_mov_b64 s[0:1], -1
	s_nop 0
	v_or_b32_e32 v96, 32, v152
	v_mad_i64_i32 v[96:97], s[50:51], v96, s47, v[144:145]
	v_lshl_add_u64 v[96:97], v[96:97], 0, v[146:147]
	global_store_dwordx4 v[96:97], v[88:91], off
	v_cvt_pk_bf16_f32 v80, v92, v93
	v_cvt_pk_bf16_f32 v81, v94, v95
	v_cvt_pk_bf16_f32 v82, v84, v85
	v_cvt_pk_bf16_f32 v83, v86, v87
	global_store_dwordx4 v[96:97], v[80:83], off offset:256
	v_cvt_pk_bf16_f32 v56, v56, v57
	v_cvt_pk_bf16_f32 v57, v58, v59
	v_cvt_pk_bf16_f32 v58, v48, v49
	v_cvt_pk_bf16_f32 v59, v50, v51
	s_nop 1
	v_or_b32_e32 v80, 48, v152
	v_mad_i64_i32 v[80:81], s[50:51], v80, s47, v[144:145]
	v_lshl_add_u64 v[80:81], v[80:81], 0, v[146:147]
	global_store_dwordx4 v[80:81], v[56:59], off
	v_cvt_pk_bf16_f32 v48, v60, v61
	v_cvt_pk_bf16_f32 v49, v62, v63
	v_cvt_pk_bf16_f32 v50, v52, v53
	v_cvt_pk_bf16_f32 v51, v54, v55
	global_store_dwordx4 v[80:81], v[48:51], off offset:256
	s_nop 1
	v_add_u32_e32 v48, 0x80, v152
	v_mad_i64_i32 v[48:49], s[50:51], v48, s47, v[144:145]
	v_lshl_add_u64 v[52:53], v[48:49], 0, v[146:147]
	v_cvt_pk_bf16_f32 v48, v72, v73
	v_cvt_pk_bf16_f32 v49, v74, v75
	v_cvt_pk_bf16_f32 v50, v64, v65
	v_cvt_pk_bf16_f32 v51, v66, v67
	global_store_dwordx4 v[52:53], v[48:51], off
	s_nop 1
	v_cvt_pk_bf16_f32 v48, v76, v77
	v_cvt_pk_bf16_f32 v49, v78, v79
	v_cvt_pk_bf16_f32 v50, v68, v69
	v_cvt_pk_bf16_f32 v51, v70, v71
	global_store_dwordx4 v[52:53], v[48:51], off offset:256
	v_cvt_pk_bf16_f32 v40, v40, v41
	v_cvt_pk_bf16_f32 v41, v42, v43
	v_cvt_pk_bf16_f32 v42, v32, v33
	v_cvt_pk_bf16_f32 v43, v34, v35
	s_nop 1
	v_add_u32_e32 v48, 0x90, v152
	v_mad_i64_i32 v[48:49], s[50:51], v48, s47, v[144:145]
	v_lshl_add_u64 v[48:49], v[48:49], 0, v[146:147]
	global_store_dwordx4 v[48:49], v[40:43], off
	v_cvt_pk_bf16_f32 v32, v44, v45
	v_cvt_pk_bf16_f32 v33, v46, v47
	v_cvt_pk_bf16_f32 v34, v36, v37
	v_cvt_pk_bf16_f32 v35, v38, v39
	global_store_dwordx4 v[48:49], v[32:35], off offset:256
	v_cvt_pk_bf16_f32 v24, v24, v25
	v_cvt_pk_bf16_f32 v25, v26, v27
	v_cvt_pk_bf16_f32 v26, v16, v17
	v_cvt_pk_bf16_f32 v27, v18, v19
	s_nop 1
	v_add_u32_e32 v32, 0xa0, v152
	v_mad_i64_i32 v[32:33], s[50:51], v32, s47, v[144:145]
	v_lshl_add_u64 v[32:33], v[32:33], 0, v[146:147]
	global_store_dwordx4 v[32:33], v[24:27], off
	v_cvt_pk_bf16_f32 v16, v28, v29
	v_cvt_pk_bf16_f32 v17, v30, v31
	v_cvt_pk_bf16_f32 v18, v20, v21
	v_cvt_pk_bf16_f32 v19, v22, v23
	global_store_dwordx4 v[32:33], v[16:19], off offset:256
	v_cvt_pk_bf16_f32 v8, v8, v9
	v_cvt_pk_bf16_f32 v9, v10, v11
	v_cvt_pk_bf16_f32 v10, v0, v1
	v_cvt_pk_bf16_f32 v11, v2, v3
	s_nop 1
	v_add_u32_e32 v16, 0xb0, v152
	v_mad_i64_i32 v[16:17], s[50:51], v16, s47, v[144:145]
	v_lshl_add_u64 v[16:17], v[16:17], 0, v[146:147]
	global_store_dwordx4 v[16:17], v[8:11], off
	v_cvt_pk_bf16_f32 v0, v12, v13
	v_cvt_pk_bf16_f32 v1, v14, v15
	v_cvt_pk_bf16_f32 v2, v4, v5
	v_cvt_pk_bf16_f32 v3, v6, v7
	global_store_dwordx4 v[16:17], v[0:3], off offset:256
	s_mov_b32 s98, 1
	s_cbranch_vccnz .LBB0_773
	s_andn2_b64 vcc, exec, s[4:5]
	s_cbranch_vccnz .LBB0_772
	s_barrier
	s_branch .LBB0_772

; #define PG8_STAGE(bufoff, gbase, voff) do { _Pragma("unroll") for (int _i = 0; _i < 2; ++_i) \
;         __builtin_amdgcn_global_load_lds((const unsigned*)((const char*)(gbase) + (voff)[_i]), (PG8_LAS unsigned*)(lds + (bufoff) + ldsw + _i * 8192), 16, 0, 0); } while (0)
; #define PG8_WAIT_V(n) asm volatile("s_waitcnt vmcnt(" #n ")" ::: "memory")
; #define PG8_BAR __builtin_amdgcn_s_barrier()
; template <class Epi, class Sched, bool ALIGN_EPI = false, bool SP2 = false, bool A_TILED = false>
; __device__ __forceinline__ void gemm_phase(PG8_LAS unsigned char* lds, const Gemm g, const Sched& S, const Epi& E, const int wave_s) {
;     ...
;     Unit cur, nxt; int ui = 0;
;     if (!S.next(0, cur)) return;
;     f32x4 acc[2][2][4][2];
;     bf16x8 At[4][2], B0[2][2], B1[2][2];
;     const char* cA = (const char*)g.A + (size_t)cur.pm * tstepA; const char* cB = (const char*)g.Bt + (size_t)cur.pn * tstep;
;     S.a_ready(cur);
;     if constexpr (SP2) {
;         PG8_STAGE(PG8_SB(0, 0), cB, voffB); PG8_STAGE(PG8_SB(0, 1), cB + hstep, voffB); PG8_STAGE(PG8_SA(0, 0), cA, voffA); PG8_STAGE(PG8_SA(0, 1), cA + hstepA, voffA);
;         if (wr == 1) PG8_BAR;
;         PG8_WAIT_V(2); PG8_BAR;
;         PG8_STAGE(PG8_SB(1, 0), cB + kstep, voffB); PG8_STAGE(PG8_SA(1, 0), cA + kstepA, voffA); PG8_STAGE(PG8_SB(1, 1), cB + hstep + kstep, voffB);
;         PG8_WAIT_V(6); PG8_BAR;
;     } else {
;         PG8_STAGE(PG8_SB(0, 0), cB, voffB); PG8_STAGE(PG8_SA(0, 0), cA, voffA); PG8_STAGE(PG8_SB(0, 1), cB + hstep, voffB); PG8_STAGE(PG8_SA(0, 1), cA + hstepA, voffA);
;         if (wr == 1) PG8_BAR;
;         PG8_WAIT_V(4); PG8_BAR;
;         PG8_STAGE(PG8_SB(1, 0), cB + kstep, voffB); PG8_STAGE(PG8_SA(1, 0), cA + kstepA, voffA); PG8_STAGE(PG8_SB(1, 1), cB + hstep + kstep, voffB);
;         PG8_WAIT_V(6); PG8_BAR;
;     }
.LBB0_1145:
	s_ashr_i32 s40, s86, 31
	s_add_u32 s41, s0, 0x34600000
	s_addc_u32 s42, s1, 0
	s_lshl_b32 s47, s12, 13
	s_mov_b64 s[12:13], 0x80
	s_and_b32 s0, s46, 3
	s_add_i32 m0, s22, 0x18000
	v_lshl_add_u64 v[6:7], v[6:7], 0, s[12:13]
	s_lshl_b32 s48, s0, 12
	s_waitcnt vmcnt(2)
	s_barrier
	global_load_lds_dwordx4 v[6:7], off
	v_lshl_add_u64 v[4:5], v[4:5], 0, s[12:13]
	s_add_i32 m0, s22, 0x1a000
	s_add_i32 s43, s22, 0x8000
	s_add_i32 s44, s22, 0xa000
	global_load_lds_dwordx4 v[4:5], off
	v_lshl_add_u64 v[0:1], v[0:1], 0, s[12:13]
	s_mov_b32 m0, s43
	s_add_u32 s0, s76, 0x80080
	global_load_lds_dwordx4 v[0:1], off
	v_lshl_add_u64 v[0:1], v[2:3], 0, s[12:13]
	s_mov_b32 m0, s44
	s_addc_u32 s1, s77, 0
	global_load_lds_dwordx4 v[0:1], off
	s_add_i32 m0, s22, 0x1c000
	v_lshl_add_u64 v[0:1], s[0:1], 0, v[128:129]
	global_load_lds_dwordx4 v128, s[0:1]
	v_lshl_add_u64 v[0:1], s[0:1], 0, v[130:131]
	s_add_i32 m0, s22, 0x1e000
	s_cmpk_lt_u32 s45, 0x100
	global_load_lds_dwordx4 v130, s[0:1]
	v_and_b32_e32 v0, 15, v8
	v_and_b32_e32 v1, 48, v8
	v_lshl_or_b32 v0, v0, 6, v1
	v_lshlrev_b32_e32 v1, 2, v8
	v_and_b32_e32 v1, 32, v1
	v_bitop3_b32 v2, v0, s47, v1 bitop3:0xde
	v_bitop3_b32 v144, v0, s48, v1 bitop3:0xde
	v_lshlrev_b32_e32 v0, 15, v9
	v_and_b32_e32 v0, 0xffff0000, v0
	v_lshl_add_u32 v0, v10, 12, v0
	v_and_b32_e32 v1, 1, v9
	v_lshl_or_b32 v0, v1, 6, v0
	v_lshl_add_u32 v136, v11, 1, v0
	v_lshlrev_b32_e32 v0, 15, v13
	v_and_b32_e32 v0, 0xffff0000, v0
	s_sext_i32_i16 s49, s60
	s_waitcnt vmcnt(6)
	s_mov_b32 s98, 0
	s_cselect_b64 s[60:61], -1, 0
	s_and_b32 s0, s15, 0x400
	v_lshl_add_u32 v0, v12, 12, v0
	v_and_b32_e32 v1, 1, v13
	s_bfe_u32 s45, s46, 0x10001
	s_or_b32 s46, s0, s47
	v_mov_b32_e32 v137, 0
	v_lshl_or_b32 v0, v1, 6, v0
	s_add_i32 s47, 0, 0x10000
	s_add_i32 s48, 0, 0x14000
	v_lshl_add_u32 v138, v14, 1, v0
	v_mov_b32_e32 v139, v137
	v_mov_b64_e32 v[140:141], 0x200
	v_mov_b64_e32 v[142:143], 0x1ff
	v_add_u32_e32 v145, s47, v144
	v_add_u32_e32 v146, s48, v144
	v_add_u32_e32 v147, 0, v2
	s_mov_b64 s[62:63], 0x100
	s_mov_b64 s[64:65], 0x180
	s_barrier
	s_branch .LBB0_1148

.LBB0_1154:
	s_ashr_i32 s69, s68, 31
	s_lshl_b64 s[50:51], s[68:69], 20
	s_add_u32 s70, s7, s50
	ds_read_b128 v[0:3], v145
	ds_read_b128 v[4:7], v145 offset:1024
	ds_read_b128 v[8:11], v145 offset:2048
	ds_read_b128 v[12:15], v145 offset:3072
	ds_read_b128 v[16:19], v146
	ds_read_b128 v[20:23], v146 offset:1024
	ds_read_b128 v[24:27], v146 offset:2048
	ds_read_b128 v[28:31], v146 offset:3072
	s_addc_u32 s71, s8, s51
	s_ashr_i32 s67, s66, 31
	s_lshl_b64 s[50:51], s[66:67], 20
	s_add_u32 s72, s9, s50
	s_addc_u32 s73, s14, s51
	s_and_b64 s[50:51], s[0:1], exec
	s_cselect_b32 s50, s71, s79
	s_cselect_b32 s51, s70, s78
	s_cselect_b32 s52, s73, s77
	s_cselect_b32 s53, s72, s76
	s_add_u32 s56, s78, 0x80080
	s_addc_u32 s57, s79, 0
	s_add_i32 s54, s22, 0xc000
	v_lshl_add_u64 v[64:65], s[56:57], 0, v[134:135]
	s_mov_b32 m0, s54
	s_add_i32 s55, s22, 0xe000
	ds_read_b128 v[32:35], v147
	ds_read_b128 v[36:39], v147 offset:1024
	ds_read_b128 v[40:43], v147 offset:2048
	ds_read_b128 v[44:47], v147 offset:3072
	ds_read_b128 v[48:51], v147 offset:4096
	ds_read_b128 v[52:55], v147 offset:5120
	ds_read_b128 v[56:59], v147 offset:6144
	ds_read_b128 v[60:63], v147 offset:7168
	global_load_lds_dwordx4 v134, s[56:57]
	v_lshl_add_u64 v[64:65], s[56:57], 0, v[132:133]
	s_mov_b32 m0, s55
	s_nop 0
	global_load_lds_dwordx4 v132, s[56:57]
	s_waitcnt vmcnt(24) lgkmcnt(0)
	s_cmp_lg_u32 s98, 0
	s_cbranch_scc1 .Lpw_3
	s_waitcnt vmcnt(8)
.Lpw_3:
	s_setprio 1
	s_barrier
	v_mfma_f32_16x16x32_bf16 v[88:91], v[0:3], v[56:59], 0
	v_mfma_f32_16x16x32_bf16 v[64:67], v[0:3], v[32:35], 0
	v_mfma_f32_16x16x32_bf16 v[68:71], v[8:11], v[32:35], 0
	v_mfma_f32_16x16x32_bf16 v[72:75], v[0:3], v[40:43], 0
	v_mfma_f32_16x16x32_bf16 v[76:79], v[8:11], v[40:43], 0
	v_mfma_f32_16x16x32_bf16 v[80:83], v[0:3], v[48:51], 0
	v_mfma_f32_16x16x32_bf16 v[84:87], v[8:11], v[48:51], 0
	v_mfma_f32_16x16x32_bf16 v[96:99], v[4:7], v[60:63], v[88:91]
	v_mfma_f32_16x16x32_bf16 v[88:91], v[8:11], v[56:59], 0
	v_mfma_f32_16x16x32_bf16 v[64:67], v[4:7], v[36:39], v[64:67]
	v_mfma_f32_16x16x32_bf16 v[68:71], v[12:15], v[36:39], v[68:71]
	v_mfma_f32_16x16x32_bf16 v[72:75], v[4:7], v[44:47], v[72:75]
	v_mfma_f32_16x16x32_bf16 v[76:79], v[12:15], v[44:47], v[76:79]
	v_mfma_f32_16x16x32_bf16 v[80:83], v[4:7], v[52:55], v[80:83]
	v_mfma_f32_16x16x32_bf16 v[84:87], v[12:15], v[52:55], v[84:87]
	v_mfma_f32_16x16x32_bf16 v[100:103], v[12:15], v[60:63], v[88:91]
	s_setprio 0
	s_setprio 1
	v_mfma_f32_16x16x32_bf16 v[88:91], v[16:19], v[32:35], 0
	v_mfma_f32_16x16x32_bf16 v[32:35], v[24:27], v[32:35], 0
	v_mfma_f32_16x16x32_bf16 v[112:115], v[20:23], v[36:39], v[88:91]
	v_mfma_f32_16x16x32_bf16 v[32:35], v[28:31], v[36:39], v[32:35]
	v_mfma_f32_16x16x32_bf16 v[36:39], v[16:19], v[40:43], 0
	v_mfma_f32_16x16x32_bf16 v[40:43], v[24:27], v[40:43], 0
	v_mfma_f32_16x16x32_bf16 v[36:39], v[20:23], v[44:47], v[36:39]
	v_mfma_f32_16x16x32_bf16 v[40:43], v[28:31], v[44:47], v[40:43]
	v_mfma_f32_16x16x32_bf16 v[44:47], v[16:19], v[48:51], 0
	v_mfma_f32_16x16x32_bf16 v[48:51], v[24:27], v[48:51], 0
	v_mfma_f32_16x16x32_bf16 v[44:47], v[20:23], v[52:55], v[44:47]
	v_mfma_f32_16x16x32_bf16 v[48:51], v[28:31], v[52:55], v[48:51]
	v_mfma_f32_16x16x32_bf16 v[52:55], v[16:19], v[56:59], 0
	v_mfma_f32_16x16x32_bf16 v[56:59], v[24:27], v[56:59], 0
	v_mfma_f32_16x16x32_bf16 v[52:55], v[20:23], v[60:63], v[52:55]
	v_mfma_f32_16x16x32_bf16 v[56:59], v[28:31], v[60:63], v[56:59]
	s_barrier
	s_setprio 0
	s_add_i32 s56, s47, s15
	v_lshl_add_u64 v[242:243], s[76:77], 0, v[128:129]
	s_add_i32 s57, s56, 0x2000
	v_lshl_add_u64 v[148:149], v[242:243], 0, s[62:63]
	s_mov_b32 m0, s56
	v_lshl_add_u64 v[244:245], s[76:77], 0, v[130:131]
	s_add_u32 s80, s76, 0x80100
	ds_read_b128 v[60:63], v147 offset:16384
	ds_read_b128 v[88:91], v147 offset:17408
	ds_read_b128 v[92:95], v147 offset:18432
	ds_read_b128 v[104:107], v147 offset:19456
	ds_read_b128 v[108:111], v147 offset:20480
	ds_read_b128 v[116:119], v147 offset:21504
	ds_read_b128 v[120:123], v147 offset:22528
	ds_read_b128 v[124:127], v147 offset:23552
	global_load_lds_dwordx4 v[148:149], off
	v_lshl_add_u64 v[148:149], v[244:245], 0, s[62:63]
	s_mov_b32 m0, s57
	s_addc_u32 s81, s77, 0
	s_add_i32 s58, s48, s15
	global_load_lds_dwordx4 v[148:149], off
	v_lshl_add_u64 v[148:149], s[80:81], 0, v[128:129]
	s_mov_b32 m0, s58
	s_add_i32 s59, s58, 0x2000
	global_load_lds_dwordx4 v128, s[80:81]
	v_lshl_add_u64 v[148:149], s[80:81], 0, v[130:131]
	s_mov_b32 m0, s59
	v_lshl_add_u64 v[246:247], s[78:79], 0, v[134:135]
	global_load_lds_dwordx4 v130, s[80:81]
	v_lshl_add_u64 v[148:149], v[246:247], 0, s[62:63]
	s_mov_b32 m0, s22
	v_lshl_add_u64 v[248:249], s[78:79], 0, v[132:133]
	global_load_lds_dwordx4 v[148:149], off
	v_lshl_add_u64 v[148:149], v[248:249], 0, s[62:63]
	s_mov_b32 m0, s23
	s_nop 0
	global_load_lds_dwordx4 v[148:149], off
	s_waitcnt vmcnt(24) lgkmcnt(0)
	s_cmp_lg_u32 s98, 0
	s_cbranch_scc1 .Lpw_4
	s_waitcnt vmcnt(8)
.Lpw_4:
	s_setprio 1
	s_barrier
	v_mfma_f32_16x16x32_bf16 v[148:151], v[0:3], v[60:63], 0
	v_mfma_f32_16x16x32_bf16 v[158:161], v[0:3], v[92:95], 0
	v_mfma_f32_16x16x32_bf16 v[166:169], v[0:3], v[108:111], 0
	v_mfma_f32_16x16x32_bf16 v[0:3], v[0:3], v[120:123], 0
	v_mfma_f32_16x16x32_bf16 v[150:153], v[4:7], v[88:91], v[148:151]
	v_mfma_f32_16x16x32_bf16 v[158:161], v[4:7], v[104:107], v[158:161]
	v_mfma_f32_16x16x32_bf16 v[166:169], v[4:7], v[116:119], v[166:169]
	v_mfma_f32_16x16x32_bf16 v[0:3], v[4:7], v[124:127], v[0:3]
	v_mfma_f32_16x16x32_bf16 v[4:7], v[8:11], v[120:123], 0
	v_mfma_f32_16x16x32_bf16 v[154:157], v[8:11], v[60:63], 0
	v_mfma_f32_16x16x32_bf16 v[162:165], v[8:11], v[92:95], 0
	v_mfma_f32_16x16x32_bf16 v[170:173], v[8:11], v[108:111], 0
	v_mfma_f32_16x16x32_bf16 v[4:7], v[12:15], v[124:127], v[4:7]
	v_mfma_f32_16x16x32_bf16 v[154:157], v[12:15], v[88:91], v[154:157]
	v_mfma_f32_16x16x32_bf16 v[162:165], v[12:15], v[104:107], v[162:165]
	v_mfma_f32_16x16x32_bf16 v[170:173], v[12:15], v[116:119], v[170:173]
	s_setprio 0
	s_setprio 1
	v_mfma_f32_16x16x32_bf16 v[8:11], v[16:19], v[60:63], 0
	v_mfma_f32_16x16x32_bf16 v[174:177], v[20:23], v[88:91], v[8:11]
	v_mfma_f32_16x16x32_bf16 v[8:11], v[24:27], v[60:63], 0
	v_mfma_f32_16x16x32_bf16 v[60:63], v[28:31], v[88:91], v[8:11]
	v_mfma_f32_16x16x32_bf16 v[8:11], v[16:19], v[92:95], 0
	v_mfma_f32_16x16x32_bf16 v[178:181], v[20:23], v[104:107], v[8:11]
	v_mfma_f32_16x16x32_bf16 v[8:11], v[24:27], v[92:95], 0
	v_mfma_f32_16x16x32_bf16 v[182:185], v[28:31], v[104:107], v[8:11]
	v_mfma_f32_16x16x32_bf16 v[8:11], v[16:19], v[108:111], 0
	v_mfma_f32_16x16x32_bf16 v[186:189], v[20:23], v[116:119], v[8:11]
	v_mfma_f32_16x16x32_bf16 v[8:11], v[24:27], v[108:111], 0
	v_mfma_f32_16x16x32_bf16 v[190:193], v[28:31], v[116:119], v[8:11]
	v_mfma_f32_16x16x32_bf16 v[8:11], v[16:19], v[120:123], 0
	v_mfma_f32_16x16x32_bf16 v[194:197], v[20:23], v[124:127], v[8:11]
	v_mfma_f32_16x16x32_bf16 v[8:11], v[24:27], v[120:123], 0
	v_mfma_f32_16x16x32_bf16 v[198:201], v[28:31], v[124:127], v[8:11]
	s_barrier
	s_setprio 0
	s_add_i32 s67, 0, 0x18000
	s_add_i32 s75, 0, 0x1c000
	v_add_u32_e32 v148, s67, v144
	v_add_u32_e32 v149, s75, v144
	s_nop 0
	ds_read_b128 v[8:11], v148
	ds_read_b128 v[12:15], v148 offset:1024
	ds_read_b128 v[16:19], v148 offset:2048
	ds_read_b128 v[20:23], v148 offset:3072
	ds_read_b128 v[202:205], v149
	ds_read_b128 v[206:209], v149 offset:1024
	ds_read_b128 v[210:213], v149 offset:2048
	ds_read_b128 v[214:217], v149 offset:3072
	s_add_u32 s80, s78, 0x80100
	s_addc_u32 s81, s79, 0
	s_mov_b32 m0, s36
	v_lshl_add_u64 v[88:89], s[80:81], 0, v[134:135]
	ds_read_b128 v[24:27], v147 offset:32768
	ds_read_b128 v[28:31], v147 offset:33792
	ds_read_b128 v[218:221], v147 offset:34816
	ds_read_b128 v[222:225], v147 offset:35840
	ds_read_b128 v[226:229], v147 offset:36864
	ds_read_b128 v[230:233], v147 offset:37888
	ds_read_b128 v[234:237], v147 offset:38912
	ds_read_b128 v[238:241], v147 offset:39936
	global_load_lds_dwordx4 v134, s[80:81]
	v_lshl_add_u64 v[88:89], s[80:81], 0, v[132:133]
	s_mov_b32 m0, s37
	s_nop 0
	global_load_lds_dwordx4 v132, s[80:81]
	s_waitcnt vmcnt(8) lgkmcnt(0)
	s_setprio 1
	s_barrier
	v_mfma_f32_16x16x32_bf16 v[64:67], v[8:11], v[24:27], v[64:67]
	v_mfma_f32_16x16x32_bf16 v[120:123], v[12:15], v[28:31], v[64:67]
	v_mfma_f32_16x16x32_bf16 v[64:67], v[16:19], v[24:27], v[68:71]
	v_mfma_f32_16x16x32_bf16 v[124:127], v[20:23], v[28:31], v[64:67]
	v_mfma_f32_16x16x32_bf16 v[64:67], v[8:11], v[218:221], v[72:75]
	v_mfma_f32_16x16x32_bf16 v[104:107], v[12:15], v[222:225], v[64:67]
	v_mfma_f32_16x16x32_bf16 v[64:67], v[16:19], v[218:221], v[76:79]
	v_mfma_f32_16x16x32_bf16 v[108:111], v[20:23], v[222:225], v[64:67]
	v_mfma_f32_16x16x32_bf16 v[64:67], v[8:11], v[226:229], v[80:83]
	v_mfma_f32_16x16x32_bf16 v[88:91], v[12:15], v[230:233], v[64:67]
	v_mfma_f32_16x16x32_bf16 v[64:67], v[16:19], v[226:229], v[84:87]
	v_mfma_f32_16x16x32_bf16 v[92:95], v[20:23], v[230:233], v[64:67]
	v_mfma_f32_16x16x32_bf16 v[64:67], v[8:11], v[234:237], v[96:99]
	v_mfma_f32_16x16x32_bf16 v[68:71], v[16:19], v[234:237], v[100:103]
	v_mfma_f32_16x16x32_bf16 v[64:67], v[12:15], v[238:241], v[64:67]
	v_mfma_f32_16x16x32_bf16 v[68:71], v[20:23], v[238:241], v[68:71]
	s_setprio 0
	s_setprio 1
	v_mfma_f32_16x16x32_bf16 v[72:75], v[202:205], v[24:27], v[112:115]
	v_mfma_f32_16x16x32_bf16 v[24:27], v[210:213], v[24:27], v[32:35]
	v_mfma_f32_16x16x32_bf16 v[116:119], v[214:217], v[28:31], v[24:27]
	v_mfma_f32_16x16x32_bf16 v[24:27], v[202:205], v[218:221], v[36:39]
	v_mfma_f32_16x16x32_bf16 v[96:99], v[206:209], v[222:225], v[24:27]
	v_mfma_f32_16x16x32_bf16 v[24:27], v[210:213], v[218:221], v[40:43]
	v_mfma_f32_16x16x32_bf16 v[100:103], v[214:217], v[222:225], v[24:27]
	v_mfma_f32_16x16x32_bf16 v[24:27], v[202:205], v[226:229], v[44:47]
	v_mfma_f32_16x16x32_bf16 v[80:83], v[206:209], v[230:233], v[24:27]
	v_mfma_f32_16x16x32_bf16 v[24:27], v[210:213], v[226:229], v[48:51]
	v_mfma_f32_16x16x32_bf16 v[84:87], v[214:217], v[230:233], v[24:27]
	v_mfma_f32_16x16x32_bf16 v[24:27], v[202:205], v[234:237], v[52:55]
	v_mfma_f32_16x16x32_bf16 v[48:51], v[206:209], v[238:241], v[24:27]
	v_mfma_f32_16x16x32_bf16 v[24:27], v[210:213], v[234:237], v[56:59]
	v_mfma_f32_16x16x32_bf16 v[112:115], v[206:209], v[28:31], v[72:75]
	v_mfma_f32_16x16x32_bf16 v[52:55], v[214:217], v[238:241], v[24:27]
	s_barrier
	s_setprio 0
	s_add_i32 s67, s67, s15
	s_add_i32 s69, s67, 0x2000
	s_nop 1
	v_lshl_add_u64 v[24:25], v[242:243], 0, s[64:65]
	s_mov_b32 m0, s67
	s_add_u32 s80, s76, 0x80180
	ds_read_b128 v[32:35], v147 offset:49152
	ds_read_b128 v[36:39], v147 offset:50176
	ds_read_b128 v[218:221], v147 offset:51200
	ds_read_b128 v[222:225], v147 offset:52224
	ds_read_b128 v[226:229], v147 offset:53248
	ds_read_b128 v[230:233], v147 offset:54272
	ds_read_b128 v[234:237], v147 offset:55296
	ds_read_b128 v[238:241], v147 offset:56320
	global_load_lds_dwordx4 v[24:25], off
	v_lshl_add_u64 v[24:25], v[244:245], 0, s[64:65]
	s_mov_b32 m0, s69
	s_addc_u32 s81, s77, 0
	s_add_i32 s75, s75, s15
	global_load_lds_dwordx4 v[24:25], off
	v_lshl_add_u64 v[24:25], s[80:81], 0, v[128:129]
	s_mov_b32 m0, s75
	s_add_i32 s82, s75, 0x2000
	global_load_lds_dwordx4 v128, s[80:81]
	v_lshl_add_u64 v[24:25], s[80:81], 0, v[130:131]
	s_mov_b32 m0, s82
	s_nop 0
	global_load_lds_dwordx4 v130, s[80:81]
	v_lshl_add_u64 v[24:25], v[246:247], 0, s[64:65]
	s_mov_b32 m0, s43
	s_nop 0
	global_load_lds_dwordx4 v[24:25], off
	v_lshl_add_u64 v[24:25], v[248:249], 0, s[64:65]
	s_mov_b32 m0, s44
	s_nop 0
	global_load_lds_dwordx4 v[24:25], off
	s_waitcnt vmcnt(8) lgkmcnt(0)
	s_setprio 1
	s_barrier
	v_mfma_f32_16x16x32_bf16 v[24:27], v[8:11], v[32:35], v[150:153]
	v_mfma_f32_16x16x32_bf16 v[72:75], v[12:15], v[36:39], v[24:27]
	v_mfma_f32_16x16x32_bf16 v[24:27], v[16:19], v[32:35], v[154:157]
	v_mfma_f32_16x16x32_bf16 v[76:79], v[20:23], v[36:39], v[24:27]
	v_mfma_f32_16x16x32_bf16 v[24:27], v[8:11], v[218:221], v[158:161]
	v_mfma_f32_16x16x32_bf16 v[40:43], v[12:15], v[222:225], v[24:27]
	v_mfma_f32_16x16x32_bf16 v[24:27], v[16:19], v[218:221], v[162:165]
	v_mfma_f32_16x16x32_bf16 v[0:3], v[8:11], v[234:237], v[0:3]
	v_mfma_f32_16x16x32_bf16 v[44:47], v[20:23], v[222:225], v[24:27]
	v_mfma_f32_16x16x32_bf16 v[24:27], v[8:11], v[226:229], v[166:169]
	v_mfma_f32_16x16x32_bf16 v[28:31], v[16:19], v[226:229], v[170:173]
	v_mfma_f32_16x16x32_bf16 v[8:11], v[12:15], v[238:241], v[0:3]
	v_mfma_f32_16x16x32_bf16 v[0:3], v[16:19], v[234:237], v[4:7]
	v_mfma_f32_16x16x32_bf16 v[24:27], v[12:15], v[230:233], v[24:27]
	v_mfma_f32_16x16x32_bf16 v[28:31], v[20:23], v[230:233], v[28:31]
	v_mfma_f32_16x16x32_bf16 v[12:15], v[20:23], v[238:241], v[0:3]
	s_setprio 0
	s_setprio 1
	v_mfma_f32_16x16x32_bf16 v[0:3], v[202:205], v[32:35], v[174:177]
	v_mfma_f32_16x16x32_bf16 v[56:59], v[206:209], v[36:39], v[0:3]
	v_mfma_f32_16x16x32_bf16 v[0:3], v[210:213], v[32:35], v[60:63]
	v_mfma_f32_16x16x32_bf16 v[60:63], v[214:217], v[36:39], v[0:3]
	v_mfma_f32_16x16x32_bf16 v[0:3], v[202:205], v[218:221], v[178:181]
	v_mfma_f32_16x16x32_bf16 v[32:35], v[206:209], v[222:225], v[0:3]
	v_mfma_f32_16x16x32_bf16 v[0:3], v[210:213], v[218:221], v[182:185]
	v_mfma_f32_16x16x32_bf16 v[36:39], v[214:217], v[222:225], v[0:3]
	v_mfma_f32_16x16x32_bf16 v[0:3], v[202:205], v[226:229], v[186:189]
	v_mfma_f32_16x16x32_bf16 v[16:19], v[206:209], v[230:233], v[0:3]
	v_mfma_f32_16x16x32_bf16 v[0:3], v[210:213], v[226:229], v[190:193]
	v_mfma_f32_16x16x32_bf16 v[20:23], v[214:217], v[230:233], v[0:3]
	v_mfma_f32_16x16x32_bf16 v[0:3], v[202:205], v[234:237], v[194:197]
	v_mfma_f32_16x16x32_bf16 v[4:7], v[210:213], v[234:237], v[198:201]
	v_mfma_f32_16x16x32_bf16 v[0:3], v[206:209], v[238:241], v[0:3]
	v_mfma_f32_16x16x32_bf16 v[4:7], v[214:217], v[238:241], v[4:7]
	s_barrier
	s_setprio 0
	s_add_u32 s83, s76, 0x200
	s_addc_u32 s84, s77, 0
	s_add_u32 s76, s78, 0x80180
	s_addc_u32 s77, s79, 0
	s_mov_b32 s85, 0

;     __device__ __forceinline__ void operator()(const f32x4 (&acc)[2][2][4][2], const Unit& u, int wr, int wc, int fr, int fq) const {
;     ...
;         for (int ai = 0; ai < 2; ++ai)
; #pragma unroll
;             for (int m = 0; m < 4; ++m) { bf16_t* rowp = O + (size_t)(row0 + ai * HALF + m * 16) * ldc + col0;
;                 if (ACT == 1) {
;                     const int ob = fr * 64 + 16 * fq, sw = ob ^ (((ob >> 9) & 1) << 5);
;                     rowp = O + ((size_t)(u.pm * (ldc / 64) + u.pn * 4 + (wc >> 1)) * 2 + ai) * 8192 + (((wr * 4 + m) * 2 + (wc & 1)) * 1024 + sw) / 2; }
;                 float rc[2][2], rs[2][2];
;                 if (ACT == 2) { const float pos = (float)((row0 + ai * HALF + m * 16) & 2047);
; #pragma unroll
;                     for (int n = 0; n < 2; ++n)
; #pragma unroll
;                         for (int e = 0; e < 2; ++e) { float r = pos * rinv[n][e]; r -= floorf(r); rs[n][e] = do_rope ? __builtin_amdgcn_sinf(r) : 0.f; rc[n][e] = do_rope ? __builtin_amdgcn_cosf(r) : 1.f; } }
; #pragma unroll
;                 for (int bj = 0; bj < 2; ++bj) { f32x4 v0 = acc[ai][bj][m][0], v1 = acc[ai][bj][m][1];
;                     if (ACT == 3) { const float pos = (float)((row0 + ai * HALF + m * 16) & 2047); float c3[4], s3[4];
; #pragma unroll
;                         for (int p = 0; p < 4; ++p) { float r = pos * rinv3[bj][p]; r -= floorf(r); s3[p] = rope3[bj] ? __builtin_amdgcn_sinf(r) : 0.f; c3[p] = rope3[bj] ? __builtin_amdgcn_cosf(r) : 1.f; }
;                         const f32x4 a = v0, b = v1;
;                         v0[0] = a[0] * c3[0] - a[1] * s3[0]; v0[1] = a[1] * c3[0] + a[0] * s3[0]; v0[2] = a[2] * c3[1] - a[3] * s3[1]; v0[3] = a[3] * c3[1] + a[2] * s3[1];
;                         v1[0] = b[0] * c3[2] - b[1] * s3[2]; v1[1] = b[1] * c3[2] + b[0] * s3[2]; v1[2] = b[2] * c3[3] - b[3] * s3[3]; v1[3] = b[3] * c3[3] + b[2] * s3[3]; }
;                     if (ACT == 2) { const f32x4 a = v0, b = v1;
;                         v0[0] = a[0] * rc[0][0] - a[1] * rs[0][0]; v0[1] = a[1] * rc[0][0] + a[0] * rs[0][0]; v0[2] = a[2] * rc[0][1] - a[3] * rs[0][1]; v0[3] = a[3] * rc[0][1] + a[2] * rs[0][1];
;                         v1[0] = b[0] * rc[1][0] - b[1] * rs[1][0]; v1[1] = b[1] * rc[1][0] + b[0] * rs[1][0]; v1[2] = b[2] * rc[1][1] - b[3] * rs[1][1]; v1[3] = b[3] * rc[1][1] + b[2] * rs[1][1]; }
;                     if (ACT == 1) {
.LBB0_1158:
	v_mov_b32_e32 v148, 0
	s_lshl_b32 s49, s49, 2
	v_mbcnt_lo_u32_b32 v148, -1, v148
	v_mbcnt_hi_u32_b32 v148, -1, v148
	v_or_b32_e32 v148, s33, v148
	s_or_b32 s49, s49, s45
	v_and_b32_e32 v149, 15, v148
	v_and_b32_e32 v150, 48, v148
	v_lshlrev_b32_e32 v148, 2, v148
	s_lshl_b32 s50, s74, 7
	v_lshl_or_b32 v149, v149, 6, v150
	v_and_b32_e32 v148, 32, v148
	s_add_i32 s50, s49, s50
	s_ashr_i32 s51, s50, 31
	v_bitop3_b32 v148, v149, s46, v148 bitop3:0xde
	s_lshl_b64 s[50:51], s[50:51], 15
	v_ashrrev_i32_e32 v148, 1, v148
	s_add_u32 s74, s41, s50
	v_ashrrev_i32_e32 v149, 31, v148
	s_addc_u32 s75, s42, s51
	v_lshlrev_b64 v[150:151], 1, v[148:149]
	v_max_i32_e32 v120, 0, v120
	v_max_i32_e32 v121, 0, v121
	v_max_i32_e32 v122, 0, v122
	v_max_i32_e32 v123, 0, v123
	v_max_i32_e32 v112, 0, v112
	v_max_i32_e32 v116, 0, v116
	v_max_i32_e32 v113, 0, v113
	v_max_i32_e32 v114, 0, v114
	v_lshl_add_u64 v[152:153], s[74:75], 0, v[150:151]
	v_max_i32_e32 v124, 0, v124
	v_mul_f32_e32 v120, v120, v120
	v_max_i32_e32 v125, 0, v125
	v_mul_f32_e32 v121, v121, v121
	v_max_i32_e32 v126, 0, v126
	v_mul_f32_e32 v122, v122, v122
	v_max_i32_e32 v127, 0, v127
	v_mul_f32_e32 v123, v123, v123
	v_mul_f32_e32 v112, v112, v112
	v_mul_f32_e32 v116, v116, v116
	v_max_i32_e32 v117, 0, v117
	v_mul_f32_e32 v113, v113, v113
	v_mul_f32_e32 v114, v114, v114
	v_max_i32_e32 v115, 0, v115
	v_mul_f32_e32 v124, v124, v124
	v_mul_f32_e32 v125, v125, v125
	v_mul_f32_e32 v126, v126, v126
	v_mul_f32_e32 v127, v127, v127
	v_cvt_pk_bf16_f32 v120, v120, v121
	v_cvt_pk_bf16_f32 v121, v122, v123
	v_cvt_pk_bf16_f32 v122, v124, v125
	v_cvt_pk_bf16_f32 v123, v126, v127
	global_store_dwordx4 v[152:153], v[120:123], off
	v_mul_f32_e32 v117, v117, v117
	v_mul_f32_e32 v115, v115, v115
	v_cvt_pk_bf16_f32 v112, v112, v113
	v_cvt_pk_bf16_f32 v113, v114, v115
	v_cvt_pk_bf16_f32 v114, v116, v117
	v_add_co_u32_e32 v116, vcc, s39, v152
	v_max_i32_e32 v104, 0, v104
	v_max_i32_e32 v105, 0, v105
	v_max_i32_e32 v106, 0, v106
	v_max_i32_e32 v107, 0, v107
	v_max_i32_e32 v96, 0, v96
	v_max_i32_e32 v118, 0, v118
	v_max_i32_e32 v119, 0, v119
	v_addc_co_u32_e32 v117, vcc, 0, v153, vcc
	v_max_i32_e32 v108, 0, v108
	v_mul_f32_e32 v104, v104, v104
	v_max_i32_e32 v109, 0, v109
	v_mul_f32_e32 v105, v105, v105
	v_max_i32_e32 v110, 0, v110
	v_mul_f32_e32 v106, v106, v106
	v_max_i32_e32 v111, 0, v111
	v_mul_f32_e32 v107, v107, v107
	v_mul_f32_e32 v96, v96, v96
	v_max_i32_e32 v97, 0, v97
	v_max_i32_e32 v98, 0, v98
	v_max_i32_e32 v99, 0, v99
	v_mul_f32_e32 v118, v118, v118
	v_mul_f32_e32 v119, v119, v119
	v_cvt_pk_bf16_f32 v115, v118, v119
	global_store_dwordx4 v[116:117], v[112:115], off
	v_mul_f32_e32 v108, v108, v108
	v_mul_f32_e32 v109, v109, v109
	v_mul_f32_e32 v110, v110, v110
	v_mul_f32_e32 v111, v111, v111
	v_cvt_pk_bf16_f32 v104, v104, v105
	v_cvt_pk_bf16_f32 v105, v106, v107
	v_cvt_pk_bf16_f32 v106, v108, v109
	v_cvt_pk_bf16_f32 v107, v110, v111
	global_store_dwordx4 v[152:153], v[104:107], off offset:2048
	v_max_i32_e32 v100, 0, v100
	v_max_i32_e32 v101, 0, v101
	v_mul_f32_e32 v97, v97, v97
	v_max_i32_e32 v102, 0, v102
	v_mul_f32_e32 v98, v98, v98
	v_max_i32_e32 v103, 0, v103
	v_mul_f32_e32 v99, v99, v99
	v_cvt_pk_bf16_f32 v96, v96, v97
	v_mul_f32_e32 v100, v100, v100
	v_mul_f32_e32 v101, v101, v101
	v_mul_f32_e32 v102, v102, v102
	v_mul_f32_e32 v103, v103, v103
	v_cvt_pk_bf16_f32 v97, v98, v99
	v_cvt_pk_bf16_f32 v98, v100, v101
	v_cvt_pk_bf16_f32 v99, v102, v103
	global_store_dwordx4 v[116:117], v[96:99], off offset:2048
	v_max_i32_e32 v88, 0, v88
	v_max_i32_e32 v89, 0, v89
	v_or_b32_e32 v96, 0x800, v148
	v_ashrrev_i32_e32 v97, 31, v96
	v_lshlrev_b64 v[96:97], 1, v[96:97]
	v_max_i32_e32 v90, 0, v90
	v_max_i32_e32 v91, 0, v91
	v_max_i32_e32 v80, 0, v80
	v_max_i32_e32 v84, 0, v84
	v_max_i32_e32 v81, 0, v81
	v_max_i32_e32 v82, 0, v82
	v_lshl_add_u64 v[98:99], s[74:75], 0, v[96:97]
	v_max_i32_e32 v92, 0, v92
	v_mul_f32_e32 v88, v88, v88
	v_max_i32_e32 v93, 0, v93
	v_mul_f32_e32 v89, v89, v89
	v_max_i32_e32 v94, 0, v94
	v_mul_f32_e32 v90, v90, v90
	v_max_i32_e32 v95, 0, v95
	v_mul_f32_e32 v91, v91, v91
	v_mul_f32_e32 v80, v80, v80
	v_mul_f32_e32 v84, v84, v84
	v_max_i32_e32 v85, 0, v85
	v_mul_f32_e32 v81, v81, v81
	v_mul_f32_e32 v82, v82, v82
	v_max_i32_e32 v83, 0, v83
	v_mul_f32_e32 v92, v92, v92
	v_mul_f32_e32 v93, v93, v93
	v_mul_f32_e32 v94, v94, v94
	v_mul_f32_e32 v95, v95, v95
	v_cvt_pk_bf16_f32 v88, v88, v89
	v_cvt_pk_bf16_f32 v89, v90, v91
	v_cvt_pk_bf16_f32 v90, v92, v93
	v_cvt_pk_bf16_f32 v91, v94, v95
	global_store_dwordx4 v[98:99], v[88:91], off
	v_mul_f32_e32 v85, v85, v85
	v_mul_f32_e32 v83, v83, v83
	v_cvt_pk_bf16_f32 v80, v80, v81
	v_cvt_pk_bf16_f32 v81, v82, v83
	v_cvt_pk_bf16_f32 v82, v84, v85
	v_add_co_u32_e32 v84, vcc, s39, v98
	v_max_i32_e32 v86, 0, v86
	v_max_i32_e32 v87, 0, v87
	v_addc_co_u32_e32 v85, vcc, 0, v99, vcc
	v_mul_f32_e32 v86, v86, v86
	v_mul_f32_e32 v87, v87, v87
	v_cvt_pk_bf16_f32 v83, v86, v87
	global_store_dwordx4 v[84:85], v[80:83], off
	v_max_i32_e32 v64, 0, v64
	v_max_i32_e32 v65, 0, v65
	v_or_b32_e32 v80, 0xc00, v148
	v_ashrrev_i32_e32 v81, 31, v80
	v_lshlrev_b64 v[80:81], 1, v[80:81]
	v_max_i32_e32 v66, 0, v66
	v_max_i32_e32 v67, 0, v67
	v_max_i32_e32 v48, 0, v48
	v_max_i32_e32 v52, 0, v52
	v_max_i32_e32 v49, 0, v49
	v_max_i32_e32 v50, 0, v50
	v_lshl_add_u64 v[82:83], s[74:75], 0, v[80:81]
	v_max_i32_e32 v68, 0, v68
	v_mul_f32_e32 v64, v64, v64
	v_max_i32_e32 v69, 0, v69
	v_mul_f32_e32 v65, v65, v65
	v_max_i32_e32 v70, 0, v70
	v_mul_f32_e32 v66, v66, v66
	v_max_i32_e32 v71, 0, v71
	v_mul_f32_e32 v67, v67, v67
	v_mul_f32_e32 v48, v48, v48
	v_mul_f32_e32 v52, v52, v52
; #define PG8_BAR __builtin_amdgcn_s_barrier()
;     __device__ __forceinline__ void operator()(const f32x4 (&acc)[2][2][4][2], const Unit& u, int wr, int wc, int fr, int fq) const {
;     ...
;                 for (int bj = 0; bj < 2; ++bj) { f32x4 v0 = acc[ai][bj][m][0], v1 = acc[ai][bj][m][1];
;                     if (ACT == 3) { const float pos = (float)((row0 + ai * HALF + m * 16) & 2047); float c3[4], s3[4];
; #pragma unroll
;                         for (int p = 0; p < 4; ++p) { float r = pos * rinv3[bj][p]; r -= floorf(r); s3[p] = rope3[bj] ? __builtin_amdgcn_sinf(r) : 0.f; c3[p] = rope3[bj] ? __builtin_amdgcn_cosf(r) : 1.f; }
;                         const f32x4 a = v0, b = v1;
;                         v0[0] = a[0] * c3[0] - a[1] * s3[0]; v0[1] = a[1] * c3[0] + a[0] * s3[0]; v0[2] = a[2] * c3[1] - a[3] * s3[1]; v0[3] = a[3] * c3[1] + a[2] * s3[1];
;                         v1[0] = b[0] * c3[2] - b[1] * s3[2]; v1[1] = b[1] * c3[2] + b[0] * s3[2]; v1[2] = b[2] * c3[3] - b[3] * s3[3]; v1[3] = b[3] * c3[3] + b[2] * s3[3]; }
;                     if (ACT == 2) { const f32x4 a = v0, b = v1;
;                         v0[0] = a[0] * rc[0][0] - a[1] * rs[0][0]; v0[1] = a[1] * rc[0][0] + a[0] * rs[0][0]; v0[2] = a[2] * rc[0][1] - a[3] * rs[0][1]; v0[3] = a[3] * rc[0][1] + a[2] * rs[0][1];
;                         v1[0] = b[0] * rc[1][0] - b[1] * rs[1][0]; v1[1] = b[1] * rc[1][0] + b[0] * rs[1][0]; v1[2] = b[2] * rc[1][1] - b[3] * rs[1][1]; v1[3] = b[3] * rc[1][1] + b[2] * rs[1][1]; }
;                     if (ACT == 1) {
; #pragma unroll
;                         for (int j = 0; j < 4; ++j) { const float a = __int_as_float(max(__float_as_int(v0[j]), 0)), b = __int_as_float(max(__float_as_int(v1[j]), 0)); v0[j] = a * a; v1[j] = b * b; } }
;                     u32x4 w; w.x = cvt_pk_bf16(v0[0], v0[1]); w.y = cvt_pk_bf16(v0[2], v0[3]); w.z = cvt_pk_bf16(v1[0], v1[1]); w.w = cvt_pk_bf16(v1[2], v1[3]);
;                     *(u32x4*)(rowp + (ACT == 1 ? bj * 2 * 2 * 8192 : bj * HALF)) = w; } }
; template <class Epi, class Sched, bool ALIGN_EPI = false, bool SP2 = false, bool A_TILED = false>
; __device__ __forceinline__ void gemm_phase(PG8_LAS unsigned char* lds, const Gemm g, const Sched& S, const Epi& E, const int wave_s) {
;     ...
;         if (!has_next) break;
;         cur = nxt; cA = nA; cB = nB; ++ui;
;         if constexpr (ALIGN_EPI) { if (wr == 1) PG8_BAR; }
	v_max_i32_e32 v53, 0, v53
	v_mul_f32_e32 v49, v49, v49
	v_mul_f32_e32 v50, v50, v50
	v_max_i32_e32 v51, 0, v51
	v_mul_f32_e32 v68, v68, v68
	v_mul_f32_e32 v69, v69, v69
	v_mul_f32_e32 v70, v70, v70
	v_mul_f32_e32 v71, v71, v71
	v_cvt_pk_bf16_f32 v64, v64, v65
	v_cvt_pk_bf16_f32 v65, v66, v67
	v_cvt_pk_bf16_f32 v66, v68, v69
	v_cvt_pk_bf16_f32 v67, v70, v71
	global_store_dwordx4 v[82:83], v[64:67], off
	v_mul_f32_e32 v53, v53, v53
	v_mul_f32_e32 v51, v51, v51
	v_cvt_pk_bf16_f32 v48, v48, v49
	v_cvt_pk_bf16_f32 v49, v50, v51
	v_cvt_pk_bf16_f32 v50, v52, v53
	v_add_co_u32_e32 v52, vcc, s39, v82
	v_max_i32_e32 v54, 0, v54
	v_max_i32_e32 v55, 0, v55
	v_addc_co_u32_e32 v53, vcc, 0, v83, vcc
	v_mul_f32_e32 v54, v54, v54
	v_mul_f32_e32 v55, v55, v55
	v_cvt_pk_bf16_f32 v51, v54, v55
	global_store_dwordx4 v[52:53], v[48:51], off
	s_add_u32 s74, s74, 0x4000
	s_addc_u32 s75, s75, 0
	v_max_i32_e32 v49, 0, v76
	v_max_i32_e32 v48, 0, v72
	v_mul_f32_e32 v50, v49, v49
	v_max_i32_e32 v49, 0, v73
	v_mul_f32_e32 v48, v48, v48
	v_max_i32_e32 v51, 0, v77
	v_mul_f32_e32 v49, v49, v49
	v_max_i32_e32 v54, 0, v74
	v_max_i32_e32 v64, 0, v75
	v_lshl_add_u64 v[52:53], s[74:75], 0, v[150:151]
	v_mul_f32_e32 v51, v51, v51
	v_max_i32_e32 v55, 0, v78
	v_mul_f32_e32 v54, v54, v54
	v_max_i32_e32 v65, 0, v79
	v_mul_f32_e32 v64, v64, v64
	v_cvt_pk_bf16_f32 v48, v48, v49
	v_cvt_pk_bf16_f32 v49, v54, v64
	v_mul_f32_e32 v55, v55, v55
	v_mul_f32_e32 v65, v65, v65
	v_cvt_pk_bf16_f32 v50, v50, v51
	v_cvt_pk_bf16_f32 v51, v55, v65
	global_store_dwordx4 v[52:53], v[48:51], off
	v_or_b32_e32 v112, 0x400, v148
	v_max_i32_e32 v54, 0, v58
	v_max_i32_e32 v49, 0, v60
	v_max_i32_e32 v48, 0, v56
	v_mul_f32_e32 v50, v49, v49
	v_max_i32_e32 v49, 0, v57
	v_mul_f32_e32 v48, v48, v48
	v_max_i32_e32 v51, 0, v61
	v_mul_f32_e32 v49, v49, v49
	v_max_i32_e32 v56, 0, v59
	v_add_co_u32_e32 v52, vcc, s39, v52
	v_ashrrev_i32_e32 v113, 31, v112
	v_mul_f32_e32 v51, v51, v51
	v_max_i32_e32 v55, 0, v62
	v_mul_f32_e32 v54, v54, v54
	v_max_i32_e32 v57, 0, v63
	v_mul_f32_e32 v56, v56, v56
	v_cvt_pk_bf16_f32 v48, v48, v49
	v_cvt_pk_bf16_f32 v49, v54, v56
	v_addc_co_u32_e32 v53, vcc, 0, v53, vcc
	v_max_i32_e32 v40, 0, v40
	v_max_i32_e32 v41, 0, v41
	v_max_i32_e32 v42, 0, v42
	v_max_i32_e32 v43, 0, v43
	v_max_i32_e32 v32, 0, v32
	v_max_i32_e32 v36, 0, v36
	v_max_i32_e32 v33, 0, v33
	v_max_i32_e32 v34, 0, v34
	v_mul_f32_e32 v55, v55, v55
	v_mul_f32_e32 v57, v57, v57
	v_cvt_pk_bf16_f32 v50, v50, v51
	v_cvt_pk_bf16_f32 v51, v55, v57
	global_store_dwordx4 v[52:53], v[48:51], off
	v_max_i32_e32 v44, 0, v44
	v_mul_f32_e32 v40, v40, v40
	v_lshl_add_u64 v[48:49], v[112:113], 1, s[74:75]
	v_max_i32_e32 v45, 0, v45
	v_mul_f32_e32 v41, v41, v41
	v_max_i32_e32 v46, 0, v46
	v_mul_f32_e32 v42, v42, v42
	v_max_i32_e32 v47, 0, v47
	v_mul_f32_e32 v43, v43, v43
	v_mul_f32_e32 v32, v32, v32
	v_mul_f32_e32 v36, v36, v36
	v_max_i32_e32 v37, 0, v37
	v_mul_f32_e32 v33, v33, v33
	v_mul_f32_e32 v34, v34, v34
	v_max_i32_e32 v35, 0, v35
	v_mul_f32_e32 v44, v44, v44
	v_mul_f32_e32 v45, v45, v45
	v_mul_f32_e32 v46, v46, v46
	v_mul_f32_e32 v47, v47, v47
	v_cvt_pk_bf16_f32 v40, v40, v41
	v_cvt_pk_bf16_f32 v41, v42, v43
	v_cvt_pk_bf16_f32 v42, v44, v45
	v_cvt_pk_bf16_f32 v43, v46, v47
	global_store_dwordx4 v[48:49], v[40:43], off
	v_mul_f32_e32 v37, v37, v37
	v_mul_f32_e32 v35, v35, v35
	v_cvt_pk_bf16_f32 v32, v32, v33
	v_cvt_pk_bf16_f32 v33, v34, v35
	v_cvt_pk_bf16_f32 v34, v36, v37
	v_add_co_u32_e32 v36, vcc, s39, v48
	v_max_i32_e32 v38, 0, v38
	v_max_i32_e32 v39, 0, v39
	v_addc_co_u32_e32 v37, vcc, 0, v49, vcc
	v_max_i32_e32 v24, 0, v24
	v_max_i32_e32 v25, 0, v25
	v_max_i32_e32 v26, 0, v26
	v_max_i32_e32 v27, 0, v27
	v_max_i32_e32 v16, 0, v16
	v_max_i32_e32 v20, 0, v20
	v_max_i32_e32 v17, 0, v17
	v_max_i32_e32 v18, 0, v18
	v_mul_f32_e32 v38, v38, v38
	v_mul_f32_e32 v39, v39, v39
	v_cvt_pk_bf16_f32 v35, v38, v39
	global_store_dwordx4 v[36:37], v[32:35], off
	v_max_i32_e32 v28, 0, v28
	v_mul_f32_e32 v24, v24, v24
	v_lshl_add_u64 v[32:33], s[74:75], 0, v[96:97]
	v_max_i32_e32 v29, 0, v29
	v_mul_f32_e32 v25, v25, v25
	v_max_i32_e32 v30, 0, v30
	v_mul_f32_e32 v26, v26, v26
	v_max_i32_e32 v31, 0, v31
	v_mul_f32_e32 v27, v27, v27
	v_mul_f32_e32 v16, v16, v16
	v_mul_f32_e32 v20, v20, v20
	v_max_i32_e32 v21, 0, v21
	v_mul_f32_e32 v17, v17, v17
	v_mul_f32_e32 v18, v18, v18
	v_max_i32_e32 v19, 0, v19
	v_mul_f32_e32 v28, v28, v28
	v_mul_f32_e32 v29, v29, v29
	v_mul_f32_e32 v30, v30, v30
	v_mul_f32_e32 v31, v31, v31
	v_cvt_pk_bf16_f32 v24, v24, v25
	v_cvt_pk_bf16_f32 v25, v26, v27
	v_cvt_pk_bf16_f32 v26, v28, v29
	v_cvt_pk_bf16_f32 v27, v30, v31
	global_store_dwordx4 v[32:33], v[24:27], off
	v_mul_f32_e32 v21, v21, v21
	v_mul_f32_e32 v19, v19, v19
	v_cvt_pk_bf16_f32 v16, v16, v17
	v_cvt_pk_bf16_f32 v17, v18, v19
	v_cvt_pk_bf16_f32 v18, v20, v21
	v_add_co_u32_e32 v20, vcc, s39, v32
	v_max_i32_e32 v22, 0, v22
	v_max_i32_e32 v23, 0, v23
	v_addc_co_u32_e32 v21, vcc, 0, v33, vcc
	v_max_i32_e32 v8, 0, v8
	v_max_i32_e32 v9, 0, v9
	v_max_i32_e32 v10, 0, v10
	v_max_i32_e32 v11, 0, v11
	v_max_i32_e32 v0, 0, v0
	v_max_i32_e32 v4, 0, v4
	v_max_i32_e32 v1, 0, v1
	v_max_i32_e32 v2, 0, v2
	v_mul_f32_e32 v22, v22, v22
	v_mul_f32_e32 v23, v23, v23
	v_cvt_pk_bf16_f32 v19, v22, v23
	global_store_dwordx4 v[20:21], v[16:19], off
	v_max_i32_e32 v12, 0, v12
	v_mul_f32_e32 v8, v8, v8
	v_lshl_add_u64 v[16:17], s[74:75], 0, v[80:81]
	v_max_i32_e32 v13, 0, v13
	v_mul_f32_e32 v9, v9, v9
	v_max_i32_e32 v14, 0, v14
	v_mul_f32_e32 v10, v10, v10
	v_max_i32_e32 v15, 0, v15
	v_mul_f32_e32 v11, v11, v11
	v_mul_f32_e32 v0, v0, v0
	v_mul_f32_e32 v4, v4, v4
	v_max_i32_e32 v5, 0, v5
	v_mul_f32_e32 v1, v1, v1
	v_mul_f32_e32 v2, v2, v2
	v_max_i32_e32 v3, 0, v3
	v_mul_f32_e32 v12, v12, v12
	v_mul_f32_e32 v13, v13, v13
	v_mul_f32_e32 v14, v14, v14
	v_mul_f32_e32 v15, v15, v15
	v_cvt_pk_bf16_f32 v8, v8, v9
	v_cvt_pk_bf16_f32 v9, v10, v11
	v_cvt_pk_bf16_f32 v10, v12, v13
	v_cvt_pk_bf16_f32 v11, v14, v15
	global_store_dwordx4 v[16:17], v[8:11], off
	v_mul_f32_e32 v5, v5, v5
	v_mul_f32_e32 v3, v3, v3
	v_cvt_pk_bf16_f32 v0, v0, v1
	v_cvt_pk_bf16_f32 v1, v2, v3
	v_cvt_pk_bf16_f32 v2, v4, v5
	v_add_co_u32_e32 v4, vcc, 0x10000, v16
	v_max_i32_e32 v6, 0, v6
	s_nop 0
	v_addc_co_u32_e32 v5, vcc, 0, v17, vcc
	v_max_i32_e32 v7, 0, v7
	s_andn2_b64 vcc, exec, s[0:1]
	s_mov_b64 s[0:1], -1
	v_mul_f32_e32 v6, v6, v6
	v_mul_f32_e32 v7, v7, v7
	v_cvt_pk_bf16_f32 v3, v6, v7
	global_store_dwordx4 v[4:5], v[0:3], off
	s_mov_b32 s98, 1
	s_cbranch_vccnz .LBB0_1147
	s_andn2_b64 vcc, exec, s[4:5]
	s_cbranch_vccnz .LBB0_1146
	s_barrier
	s_branch .LBB0_1146

; #define PG8_STAGE(bufoff, gbase, voff) do { _Pragma("unroll") for (int _i = 0; _i < 2; ++_i) \
;         __builtin_amdgcn_global_load_lds((const unsigned*)((const char*)(gbase) + (voff)[_i]), (PG8_LAS unsigned*)(lds + (bufoff) + ldsw + _i * 8192), 16, 0, 0); } while (0)
; #define PG8_WAIT_V(n) asm volatile("s_waitcnt vmcnt(" #n ")" ::: "memory")
; #define PG8_BAR __builtin_amdgcn_s_barrier()
; template <class Epi, class Sched, bool ALIGN_EPI = false, bool SP2 = false, bool A_TILED = false>
; __device__ __forceinline__ void gemm_phase(PG8_LAS unsigned char* lds, const Gemm g, const Sched& S, const Epi& E, const int wave_s) {
;     ...
;     if constexpr (SP2) {
;         PG8_STAGE(PG8_SB(0, 0), cB, voffB); PG8_STAGE(PG8_SB(0, 1), cB + hstep, voffB); PG8_STAGE(PG8_SA(0, 0), cA, voffA); PG8_STAGE(PG8_SA(0, 1), cA + hstepA, voffA);
;         if (wr == 1) PG8_BAR;
;         PG8_WAIT_V(2); PG8_BAR;
;         PG8_STAGE(PG8_SB(1, 0), cB + kstep, voffB); PG8_STAGE(PG8_SA(1, 0), cA + kstepA, voffA); PG8_STAGE(PG8_SB(1, 1), cB + hstep + kstep, voffB);
;         PG8_WAIT_V(6); PG8_BAR;
;     } else {
;         PG8_STAGE(PG8_SB(0, 0), cB, voffB); PG8_STAGE(PG8_SA(0, 0), cA, voffA); PG8_STAGE(PG8_SB(0, 1), cB + hstep, voffB); PG8_STAGE(PG8_SA(0, 1), cA + hstepA, voffA);
;         if (wr == 1) PG8_BAR;
;         PG8_WAIT_V(4); PG8_BAR;
;         PG8_STAGE(PG8_SB(1, 0), cB + kstep, voffB); PG8_STAGE(PG8_SA(1, 0), cA + kstepA, voffA); PG8_STAGE(PG8_SB(1, 1), cB + hstep + kstep, voffB);
;         PG8_WAIT_V(6); PG8_BAR;
.LBB0_1613:
	s_ashr_i32 s40, s86, 31
	s_sext_i32_i16 s50, s12
	s_add_u32 s12, s2, 0x22600000
	s_addc_u32 s13, s3, 0
	v_and_b32_e32 v15, 48, v14
	v_lshlrev_b32_e32 v16, 6, v14
	s_movk_i32 s3, 0x3c0
	v_lshlrev_b32_e32 v14, 2, v14
	s_mov_b64 s[60:61], 0x80
	s_and_b32 s46, s41, 3
	s_lshl_b32 s2, s42, 13
	v_and_or_b32 v15, v16, s3, v15
	v_and_b32_e32 v14, 32, v14
	s_add_i32 m0, s23, 0x18000
	v_lshl_add_u64 v[6:7], v[6:7], 0, s[60:61]
	s_lshl_b32 s41, s42, 6
	v_bitop3_b32 v16, v15, s2, v14 bitop3:0xde
	s_lshl_b32 s42, s46, 5
	s_lshl_b32 s2, s46, 12
	s_waitcnt vmcnt(2)
	s_barrier
	global_load_lds_dwordx4 v[6:7], off
	v_lshl_add_u64 v[4:5], v[4:5], 0, s[60:61]
	s_add_i32 m0, s23, 0x1a000
	s_add_i32 s43, s23, 0x8000
	s_add_i32 s44, s23, 0xa000
	v_bitop3_b32 v148, v15, s2, v14 bitop3:0xde
	global_load_lds_dwordx4 v[4:5], off
	v_lshl_add_u64 v[0:1], v[0:1], 0, s[60:61]
	s_mov_b32 m0, s43
	s_add_u32 s2, s78, 0x80080
	global_load_lds_dwordx4 v[0:1], off
	v_lshl_add_u64 v[0:1], v[2:3], 0, s[60:61]
	s_mov_b32 m0, s44
	s_addc_u32 s3, s79, 0
	global_load_lds_dwordx4 v[0:1], off
	s_add_i32 m0, s23, 0x1c000
	v_lshl_add_u64 v[0:1], s[2:3], 0, v[128:129]
	global_load_lds_dwordx4 v128, s[2:3]
	v_lshl_add_u64 v[0:1], s[2:3], 0, v[130:131]
	s_add_i32 m0, s23, 0x1e000
	s_cmpk_lt_u32 s45, 0x100
	global_load_lds_dwordx4 v130, s[2:3]
	v_lshlrev_b32_e32 v0, 15, v8
	v_and_b32_e32 v0, 0xffff0000, v0
	v_lshl_add_u32 v0, v9, 12, v0
	v_and_b32_e32 v1, 1, v8
	v_lshl_or_b32 v0, v1, 6, v0
	v_lshl_add_u32 v136, v10, 1, v0
	v_lshlrev_b32_e32 v0, 15, v12
	v_and_b32_e32 v0, 0xffff0000, v0
	s_waitcnt vmcnt(6)
	s_mov_b32 s98, 0
	v_lshl_add_u32 v0, v11, 12, v0
	v_and_b32_e32 v1, 1, v12
	s_cselect_b64 s[62:63], -1, 0
	s_lshl_b32 s45, s46, 4
	v_mov_b32_e32 v137, 0
	v_lshl_or_b32 v0, v1, 6, v0
	s_add_i32 s46, 0, 0x10000
	s_add_i32 s47, 0, 0x14000
	v_lshl_add_u32 v138, v13, 1, v0
	v_mov_b32_e32 v139, v137
	v_add_u32_e32 v149, s46, v148
	v_add_u32_e32 v150, s47, v148
	v_add_u32_e32 v151, 0, v16
	s_mov_b64 s[64:65], 0x100
	s_mov_b64 s[66:67], 0x180
	s_mov_b32 s48, 0xc2fc0000
	s_mov_b32 s49, 0x9000
	v_mov_b32_e32 v152, 0x42800000
	v_not_b32_e32 v153, 63
	s_barrier
	s_branch .LBB0_1616

; template <class Epi, class Sched, bool ALIGN_EPI = false, bool SP2 = false, bool A_TILED = false>
; __device__ __forceinline__ void gemm_phase(PG8_LAS unsigned char* lds, const Gemm g, const Sched& S, const Epi& E, const int wave_s) {
;     ...
;         const bool has_next = Epi::AFTER_DRAIN ? false : S.next(ui + 1, nxt);
;         const char* nA = has_next ? (const char*)g.A + (size_t)nxt.pm * tstepA : cA; const char* nB = has_next ? (const char*)g.Bt + (size_t)nxt.pn * tstep : cB;
;         constexpr bool PEEL = SP2 && !Epi::AFTER_DRAIN;
;         if constexpr (PEEL) {
;             const char* a1 = cA + kstepA; const char* a2 = cA + 2 * kstepA; const char* b2 = cB + 2 * kstep; const char* a3 = a2 + kstepA; const char* b3 = b2 + kstep;
;             PG8_ITER(PG8_MMAZ)
.LBB0_1618:
	s_ashr_i32 s71, s70, 31
	s_lshl_b64 s[52:53], s[70:71], 20
	s_add_u32 s72, s1, s52
	ds_read_b128 v[0:3], v149
	ds_read_b128 v[4:7], v149 offset:1024
	ds_read_b128 v[8:11], v149 offset:2048
	ds_read_b128 v[12:15], v149 offset:3072
	ds_read_b128 v[16:19], v150
	ds_read_b128 v[20:23], v150 offset:1024
	ds_read_b128 v[24:27], v150 offset:2048
	ds_read_b128 v[28:31], v150 offset:3072
	s_addc_u32 s73, s8, s53
	s_ashr_i32 s69, s68, 31
	s_lshl_b64 s[52:53], s[68:69], 20
	s_add_u32 s74, s9, s52
	s_addc_u32 s75, s14, s53
	s_and_b64 s[52:53], s[2:3], exec
	s_cselect_b32 s51, s73, s81
	s_cselect_b32 s52, s72, s80
	s_cselect_b32 s53, s75, s79
	s_cselect_b32 s54, s74, s78
	s_add_u32 s56, s80, 0x80080
	s_addc_u32 s57, s81, 0
	s_add_i32 s55, s23, 0xc000
	v_lshl_add_u64 v[64:65], s[56:57], 0, v[134:135]
	s_mov_b32 m0, s55
	ds_read_b128 v[32:35], v151
	ds_read_b128 v[36:39], v151 offset:1024
	ds_read_b128 v[40:43], v151 offset:2048
	ds_read_b128 v[44:47], v151 offset:3072
	ds_read_b128 v[48:51], v151 offset:4096
	ds_read_b128 v[52:55], v151 offset:5120
	ds_read_b128 v[56:59], v151 offset:6144
	ds_read_b128 v[60:63], v151 offset:7168
	global_load_lds_dwordx4 v134, s[56:57]
	v_lshl_add_u64 v[64:65], s[56:57], 0, v[132:133]
	s_add_i32 s56, s23, 0xe000
	s_mov_b32 m0, s56
	s_nop 0
	global_load_lds_dwordx4 v[64:65], off
	s_waitcnt vmcnt(24) lgkmcnt(0)
	s_cmp_lg_u32 s98, 0
	s_cbranch_scc1 .Lpw_5
	s_waitcnt vmcnt(8)
.Lpw_5:
	s_setprio 1
	s_barrier
	v_mfma_f32_16x16x32_bf16 v[88:91], v[0:3], v[56:59], 0
	v_mfma_f32_16x16x32_bf16 v[64:67], v[0:3], v[32:35], 0
	v_mfma_f32_16x16x32_bf16 v[68:71], v[8:11], v[32:35], 0
	v_mfma_f32_16x16x32_bf16 v[72:75], v[0:3], v[40:43], 0
	v_mfma_f32_16x16x32_bf16 v[76:79], v[8:11], v[40:43], 0
	v_mfma_f32_16x16x32_bf16 v[80:83], v[0:3], v[48:51], 0
	v_mfma_f32_16x16x32_bf16 v[84:87], v[8:11], v[48:51], 0
	v_mfma_f32_16x16x32_bf16 v[96:99], v[4:7], v[60:63], v[88:91]
	v_mfma_f32_16x16x32_bf16 v[88:91], v[8:11], v[56:59], 0
	v_mfma_f32_16x16x32_bf16 v[64:67], v[4:7], v[36:39], v[64:67]
	v_mfma_f32_16x16x32_bf16 v[68:71], v[12:15], v[36:39], v[68:71]
	v_mfma_f32_16x16x32_bf16 v[72:75], v[4:7], v[44:47], v[72:75]
	v_mfma_f32_16x16x32_bf16 v[76:79], v[12:15], v[44:47], v[76:79]
	v_mfma_f32_16x16x32_bf16 v[80:83], v[4:7], v[52:55], v[80:83]
	v_mfma_f32_16x16x32_bf16 v[84:87], v[12:15], v[52:55], v[84:87]
	v_mfma_f32_16x16x32_bf16 v[100:103], v[12:15], v[60:63], v[88:91]
	s_setprio 0
	s_setprio 1
	v_mfma_f32_16x16x32_bf16 v[88:91], v[16:19], v[32:35], 0
	v_mfma_f32_16x16x32_bf16 v[32:35], v[24:27], v[32:35], 0
	v_mfma_f32_16x16x32_bf16 v[112:115], v[20:23], v[36:39], v[88:91]
	v_mfma_f32_16x16x32_bf16 v[32:35], v[28:31], v[36:39], v[32:35]
	v_mfma_f32_16x16x32_bf16 v[36:39], v[16:19], v[40:43], 0
	v_mfma_f32_16x16x32_bf16 v[40:43], v[24:27], v[40:43], 0
	v_mfma_f32_16x16x32_bf16 v[36:39], v[20:23], v[44:47], v[36:39]
	v_mfma_f32_16x16x32_bf16 v[40:43], v[28:31], v[44:47], v[40:43]
	v_mfma_f32_16x16x32_bf16 v[44:47], v[16:19], v[48:51], 0
	v_mfma_f32_16x16x32_bf16 v[48:51], v[24:27], v[48:51], 0
	v_mfma_f32_16x16x32_bf16 v[44:47], v[20:23], v[52:55], v[44:47]
	v_mfma_f32_16x16x32_bf16 v[48:51], v[28:31], v[52:55], v[48:51]
	v_mfma_f32_16x16x32_bf16 v[52:55], v[16:19], v[56:59], 0
	v_mfma_f32_16x16x32_bf16 v[56:59], v[24:27], v[56:59], 0
	v_mfma_f32_16x16x32_bf16 v[52:55], v[20:23], v[60:63], v[52:55]
	v_mfma_f32_16x16x32_bf16 v[56:59], v[28:31], v[60:63], v[56:59]
	s_barrier
	s_setprio 0
	s_add_i32 s57, s46, s15
	v_lshl_add_u64 v[250:251], s[78:79], 0, v[128:129]
	s_add_i32 s58, s57, 0x2000
	v_lshl_add_u64 v[144:145], v[250:251], 0, s[64:65]
	s_mov_b32 m0, s57
	v_lshl_add_u64 v[252:253], s[78:79], 0, v[130:131]
	s_add_u32 s82, s78, 0x80100
	ds_read_b128 v[60:63], v151 offset:16384
	ds_read_b128 v[88:91], v151 offset:17408
	ds_read_b128 v[92:95], v151 offset:18432
	ds_read_b128 v[104:107], v151 offset:19456
	ds_read_b128 v[108:111], v151 offset:20480
	ds_read_b128 v[116:119], v151 offset:21504
	ds_read_b128 v[120:123], v151 offset:22528
	ds_read_b128 v[124:127], v151 offset:23552
	global_load_lds_dwordx4 v[144:145], off
	v_lshl_add_u64 v[144:145], v[252:253], 0, s[64:65]
	s_mov_b32 m0, s58
	s_addc_u32 s83, s79, 0
	s_add_i32 s59, s47, s15
	global_load_lds_dwordx4 v[144:145], off
	v_lshl_add_u64 v[144:145], s[82:83], 0, v[128:129]
	s_mov_b32 m0, s59
	s_add_i32 s69, s59, 0x2000
	global_load_lds_dwordx4 v128, s[82:83]
	v_lshl_add_u64 v[144:145], s[82:83], 0, v[130:131]
	s_mov_b32 m0, s69
	v_lshl_add_u64 v[140:141], s[80:81], 0, v[134:135]
	global_load_lds_dwordx4 v130, s[82:83]
	v_lshl_add_u64 v[144:145], v[140:141], 0, s[64:65]
	s_mov_b32 m0, s23
	v_lshl_add_u64 v[142:143], s[80:81], 0, v[132:133]
	global_load_lds_dwordx4 v[144:145], off
	v_lshl_add_u64 v[144:145], v[142:143], 0, s[64:65]
	s_mov_b32 m0, s36
	s_nop 0
	global_load_lds_dwordx4 v[144:145], off
	s_waitcnt vmcnt(24) lgkmcnt(0)
	s_cmp_lg_u32 s98, 0
	s_cbranch_scc1 .Lpw_6
	s_waitcnt vmcnt(8)
.Lpw_6:
	s_setprio 1
	s_barrier
	v_mfma_f32_16x16x32_bf16 v[144:147], v[0:3], v[60:63], 0
	v_mfma_f32_16x16x32_bf16 v[154:157], v[4:7], v[88:91], v[144:147]
	v_mfma_f32_16x16x32_bf16 v[144:147], v[8:11], v[60:63], 0
	v_mfma_f32_16x16x32_bf16 v[158:161], v[12:15], v[88:91], v[144:147]
	v_mfma_f32_16x16x32_bf16 v[144:147], v[0:3], v[92:95], 0
	v_mfma_f32_16x16x32_bf16 v[162:165], v[4:7], v[104:107], v[144:147]
	v_mfma_f32_16x16x32_bf16 v[144:147], v[8:11], v[92:95], 0
	v_mfma_f32_16x16x32_bf16 v[166:169], v[12:15], v[104:107], v[144:147]
	v_mfma_f32_16x16x32_bf16 v[144:147], v[0:3], v[108:111], 0
	v_mfma_f32_16x16x32_bf16 v[0:3], v[0:3], v[120:123], 0
	v_mfma_f32_16x16x32_bf16 v[170:173], v[4:7], v[116:119], v[144:147]
	v_mfma_f32_16x16x32_bf16 v[0:3], v[4:7], v[124:127], v[0:3]
	v_mfma_f32_16x16x32_bf16 v[4:7], v[8:11], v[120:123], 0
	v_mfma_f32_16x16x32_bf16 v[144:147], v[8:11], v[108:111], 0
	v_mfma_f32_16x16x32_bf16 v[4:7], v[12:15], v[124:127], v[4:7]
	v_mfma_f32_16x16x32_bf16 v[174:177], v[12:15], v[116:119], v[144:147]
	s_setprio 0
	s_setprio 1
	v_mfma_f32_16x16x32_bf16 v[8:11], v[16:19], v[60:63], 0
	v_mfma_f32_16x16x32_bf16 v[178:181], v[20:23], v[88:91], v[8:11]
	v_mfma_f32_16x16x32_bf16 v[8:11], v[24:27], v[60:63], 0
	v_mfma_f32_16x16x32_bf16 v[182:185], v[28:31], v[88:91], v[8:11]
	v_mfma_f32_16x16x32_bf16 v[8:11], v[16:19], v[92:95], 0
	v_mfma_f32_16x16x32_bf16 v[186:189], v[20:23], v[104:107], v[8:11]
	v_mfma_f32_16x16x32_bf16 v[8:11], v[24:27], v[92:95], 0
	v_mfma_f32_16x16x32_bf16 v[190:193], v[28:31], v[104:107], v[8:11]
	v_mfma_f32_16x16x32_bf16 v[8:11], v[16:19], v[108:111], 0
	v_mfma_f32_16x16x32_bf16 v[194:197], v[20:23], v[116:119], v[8:11]
	v_mfma_f32_16x16x32_bf16 v[8:11], v[24:27], v[108:111], 0
	v_mfma_f32_16x16x32_bf16 v[198:201], v[28:31], v[116:119], v[8:11]
	v_mfma_f32_16x16x32_bf16 v[8:11], v[16:19], v[120:123], 0
	v_mfma_f32_16x16x32_bf16 v[202:205], v[20:23], v[124:127], v[8:11]
	v_mfma_f32_16x16x32_bf16 v[8:11], v[24:27], v[120:123], 0
	v_mfma_f32_16x16x32_bf16 v[206:209], v[28:31], v[124:127], v[8:11]
	s_barrier
	s_setprio 0
	s_add_i32 s71, 0, 0x18000
	s_add_i32 s88, 0, 0x1c000
	v_add_u32_e32 v144, s71, v148
	v_add_u32_e32 v145, s88, v148
	s_nop 0
	ds_read_b128 v[8:11], v144
	ds_read_b128 v[12:15], v144 offset:1024
	ds_read_b128 v[16:19], v144 offset:2048
	ds_read_b128 v[20:23], v144 offset:3072
	ds_read_b128 v[210:213], v145
	ds_read_b128 v[214:217], v145 offset:1024
	ds_read_b128 v[218:221], v145 offset:2048
	ds_read_b128 v[222:225], v145 offset:3072
	s_add_u32 s82, s80, 0x80100
	s_addc_u32 s83, s81, 0
	s_mov_b32 m0, s37
	v_lshl_add_u64 v[88:89], s[82:83], 0, v[134:135]
	ds_read_b128 v[24:27], v151 offset:32768
	ds_read_b128 v[28:31], v151 offset:33792
	ds_read_b128 v[60:63], v151 offset:34816
	ds_read_b128 v[226:229], v151 offset:35840
	ds_read_b128 v[230:233], v151 offset:36864
	ds_read_b128 v[234:237], v151 offset:37888
	ds_read_b128 v[238:241], v151 offset:38912
	ds_read_b128 v[242:245], v151 offset:39936
	global_load_lds_dwordx4 v134, s[82:83]
	v_lshl_add_u64 v[88:89], s[82:83], 0, v[132:133]
	s_mov_b32 m0, s38
	s_nop 0
	global_load_lds_dwordx4 v132, s[82:83]
	s_waitcnt vmcnt(8) lgkmcnt(0)
	s_setprio 1
	s_barrier
	v_mfma_f32_16x16x32_bf16 v[64:67], v[8:11], v[24:27], v[64:67]
	v_mfma_f32_16x16x32_bf16 v[124:127], v[12:15], v[28:31], v[64:67]
	v_mfma_f32_16x16x32_bf16 v[64:67], v[16:19], v[24:27], v[68:71]
	v_mfma_f32_16x16x32_bf16 v[120:123], v[20:23], v[28:31], v[64:67]
	v_mfma_f32_16x16x32_bf16 v[64:67], v[8:11], v[60:63], v[72:75]
	v_mfma_f32_16x16x32_bf16 v[108:111], v[12:15], v[226:229], v[64:67]
	v_mfma_f32_16x16x32_bf16 v[64:67], v[16:19], v[60:63], v[76:79]
	v_mfma_f32_16x16x32_bf16 v[104:107], v[20:23], v[226:229], v[64:67]
	v_mfma_f32_16x16x32_bf16 v[64:67], v[8:11], v[230:233], v[80:83]
	v_mfma_f32_16x16x32_bf16 v[92:95], v[12:15], v[234:237], v[64:67]
	v_mfma_f32_16x16x32_bf16 v[64:67], v[16:19], v[230:233], v[84:87]
	v_mfma_f32_16x16x32_bf16 v[88:91], v[20:23], v[234:237], v[64:67]
	v_mfma_f32_16x16x32_bf16 v[64:67], v[8:11], v[238:241], v[96:99]
	v_mfma_f32_16x16x32_bf16 v[76:79], v[12:15], v[242:245], v[64:67]
	v_mfma_f32_16x16x32_bf16 v[64:67], v[16:19], v[238:241], v[100:103]
	v_mfma_f32_16x16x32_bf16 v[72:75], v[20:23], v[242:245], v[64:67]
	s_setprio 0
	s_setprio 1
	v_mfma_f32_16x16x32_bf16 v[64:67], v[210:213], v[24:27], v[112:115]
	v_mfma_f32_16x16x32_bf16 v[24:27], v[218:221], v[24:27], v[32:35]
	v_mfma_f32_16x16x32_bf16 v[112:115], v[222:225], v[28:31], v[24:27]
	v_mfma_f32_16x16x32_bf16 v[24:27], v[210:213], v[60:63], v[36:39]
	v_mfma_f32_16x16x32_bf16 v[100:103], v[214:217], v[226:229], v[24:27]
	v_mfma_f32_16x16x32_bf16 v[24:27], v[218:221], v[60:63], v[40:43]
	v_mfma_f32_16x16x32_bf16 v[96:99], v[222:225], v[226:229], v[24:27]
	v_mfma_f32_16x16x32_bf16 v[24:27], v[210:213], v[230:233], v[44:47]
	v_mfma_f32_16x16x32_bf16 v[84:87], v[214:217], v[234:237], v[24:27]
	v_mfma_f32_16x16x32_bf16 v[24:27], v[218:221], v[230:233], v[48:51]
	v_mfma_f32_16x16x32_bf16 v[80:83], v[222:225], v[234:237], v[24:27]
	v_mfma_f32_16x16x32_bf16 v[24:27], v[210:213], v[238:241], v[52:55]
	v_mfma_f32_16x16x32_bf16 v[68:71], v[214:217], v[242:245], v[24:27]
	v_mfma_f32_16x16x32_bf16 v[24:27], v[218:221], v[238:241], v[56:59]
	v_mfma_f32_16x16x32_bf16 v[116:119], v[214:217], v[28:31], v[64:67]
	v_mfma_f32_16x16x32_bf16 v[64:67], v[222:225], v[242:245], v[24:27]
	s_barrier
; template <class Epi, class Sched, bool ALIGN_EPI = false, bool SP2 = false, bool A_TILED = false>
; __device__ __forceinline__ void gemm_phase(PG8_LAS unsigned char* lds, const Gemm g, const Sched& S, const Epi& E, const int wave_s) {
;     ...
;         for (int t = PEEL ? 2 : 0; t < nt; t += 2) {
;             const bool last = (t == nt - 2);
;             const char* a1 = cA + (size_t)(t + 1) * kstepA;
;             const char* a2 = last ? nA : cA + (size_t)(t + 2) * kstepA; const char* b2 = last ? nB : cB + (size_t)(t + 2) * kstep;
;             const char* a3 = a2 + kstepA; const char* b3 = b2 + kstep;
	s_setprio 0
	s_add_i32 s71, s71, s15
	s_add_i32 s77, s71, 0x2000
	s_nop 1
	v_lshl_add_u64 v[24:25], v[250:251], 0, s[66:67]
	s_mov_b32 m0, s71
	s_add_u32 s82, s78, 0x80180
	ds_read_b128 v[32:35], v151 offset:49152
	ds_read_b128 v[36:39], v151 offset:50176
	ds_read_b128 v[226:229], v151 offset:51200
	ds_read_b128 v[230:233], v151 offset:52224
	ds_read_b128 v[234:237], v151 offset:53248
	ds_read_b128 v[238:241], v151 offset:54272
	ds_read_b128 v[242:245], v151 offset:55296
	ds_read_b128 v[246:249], v151 offset:56320
	global_load_lds_dwordx4 v[24:25], off
	v_lshl_add_u64 v[24:25], v[252:253], 0, s[66:67]
	s_mov_b32 m0, s77
	s_addc_u32 s83, s79, 0
	s_add_i32 s88, s88, s15
	global_load_lds_dwordx4 v[24:25], off
	v_lshl_add_u64 v[24:25], s[82:83], 0, v[128:129]
	s_mov_b32 m0, s88
	s_add_i32 s89, s88, 0x2000
	global_load_lds_dwordx4 v128, s[82:83]
	v_lshl_add_u64 v[24:25], s[82:83], 0, v[130:131]
	s_mov_b32 m0, s89
	s_nop 0
	global_load_lds_dwordx4 v130, s[82:83]
	v_lshl_add_u64 v[24:25], v[140:141], 0, s[66:67]
	s_mov_b32 m0, s43
	s_nop 0
	global_load_lds_dwordx4 v[24:25], off
	v_lshl_add_u64 v[24:25], v[142:143], 0, s[66:67]
	s_mov_b32 m0, s44
	s_nop 0
	global_load_lds_dwordx4 v[24:25], off
	s_waitcnt vmcnt(8) lgkmcnt(0)
	s_setprio 1
	s_barrier
	v_mfma_f32_16x16x32_bf16 v[24:27], v[8:11], v[32:35], v[154:157]
	v_mfma_f32_16x16x32_bf16 v[60:63], v[12:15], v[36:39], v[24:27]
	v_mfma_f32_16x16x32_bf16 v[24:27], v[16:19], v[32:35], v[158:161]
	v_mfma_f32_16x16x32_bf16 v[56:59], v[20:23], v[36:39], v[24:27]
	v_mfma_f32_16x16x32_bf16 v[24:27], v[8:11], v[226:229], v[162:165]
	v_mfma_f32_16x16x32_bf16 v[44:47], v[12:15], v[230:233], v[24:27]
	v_mfma_f32_16x16x32_bf16 v[24:27], v[16:19], v[226:229], v[166:169]
	v_mfma_f32_16x16x32_bf16 v[40:43], v[20:23], v[230:233], v[24:27]
	v_mfma_f32_16x16x32_bf16 v[24:27], v[8:11], v[234:237], v[170:173]
	v_mfma_f32_16x16x32_bf16 v[0:3], v[8:11], v[242:245], v[0:3]
	v_mfma_f32_16x16x32_bf16 v[28:31], v[12:15], v[238:241], v[24:27]
	v_mfma_f32_16x16x32_bf16 v[24:27], v[16:19], v[234:237], v[174:177]
	v_mfma_f32_16x16x32_bf16 v[12:15], v[12:15], v[246:249], v[0:3]
	v_mfma_f32_16x16x32_bf16 v[0:3], v[16:19], v[242:245], v[4:7]
	v_mfma_f32_16x16x32_bf16 v[24:27], v[20:23], v[238:241], v[24:27]
	v_mfma_f32_16x16x32_bf16 v[8:11], v[20:23], v[246:249], v[0:3]
	s_setprio 0
	s_setprio 1
	v_mfma_f32_16x16x32_bf16 v[0:3], v[210:213], v[32:35], v[178:181]
	v_mfma_f32_16x16x32_bf16 v[52:55], v[214:217], v[36:39], v[0:3]
	v_mfma_f32_16x16x32_bf16 v[0:3], v[218:221], v[32:35], v[182:185]
	v_mfma_f32_16x16x32_bf16 v[48:51], v[222:225], v[36:39], v[0:3]
	v_mfma_f32_16x16x32_bf16 v[0:3], v[210:213], v[226:229], v[186:189]
	v_mfma_f32_16x16x32_bf16 v[36:39], v[214:217], v[230:233], v[0:3]
	v_mfma_f32_16x16x32_bf16 v[0:3], v[218:221], v[226:229], v[190:193]
	v_mfma_f32_16x16x32_bf16 v[32:35], v[222:225], v[230:233], v[0:3]
	v_mfma_f32_16x16x32_bf16 v[0:3], v[210:213], v[234:237], v[194:197]
	v_mfma_f32_16x16x32_bf16 v[20:23], v[214:217], v[238:241], v[0:3]
	v_mfma_f32_16x16x32_bf16 v[0:3], v[218:221], v[234:237], v[198:201]
	v_mfma_f32_16x16x32_bf16 v[16:19], v[222:225], v[238:241], v[0:3]
	v_mfma_f32_16x16x32_bf16 v[0:3], v[210:213], v[242:245], v[202:205]
	v_mfma_f32_16x16x32_bf16 v[4:7], v[214:217], v[246:249], v[0:3]
	v_mfma_f32_16x16x32_bf16 v[0:3], v[218:221], v[242:245], v[206:209]
	v_mfma_f32_16x16x32_bf16 v[0:3], v[222:225], v[246:249], v[0:3]
	s_barrier
	s_setprio 0
	s_add_u32 s90, s78, 0x200
	s_addc_u32 s85, s79, 0
	s_add_u32 s78, s80, 0x80180
	s_addc_u32 s79, s81, 0
	s_mov_b32 s91, 0

;     __device__ __forceinline__ void operator()(const f32x4 (&acc)[2][2][4][2], const Unit& u, int wr, int wc, int fr, int fq) const {
;         const int row0 = u.pm * BM + wr * 64 + fr; const int col0 = u.pn * BM + wc * 32 + 8 * fq;
;         const bool do_rope = (ACT == 2) && (((u.pn * BM) % 6144) < 4096);
;         float rinv[2][2];
;         if (ACT == 2) {
; #pragma unroll
;             for (int n = 0; n < 2; ++n)
; #pragma unroll
;                 for (int e = 0; e < 2; ++e) rinv[n][e] = exp2f(-(float)(16 * wc + 4 * fq + 2 * n + e) * (13.287712379549449f / 64.0f)) * 0.15915494309189535f;
;         }
;         float rinv3[2][4]; bool rope3[2];
;         if (ACT == 3) {
; #pragma unroll
;             for (int bj = 0; bj < 2; ++bj) { const int jj = (col0 + bj * HALF) % 192; rope3[bj] = jj >= 128; const int i0 = (jj - 128) >> 1;
; #pragma unroll
;                 for (int p = 0; p < 4; ++p) rinv3[bj][p] = exp2f(-(float)(i0 + p) * (13.287712379549449f / 32.0f)) * 0.15915494309189535f; }
;         }
; #pragma unroll
;         for (int ai = 0; ai < 2; ++ai)
; #pragma unroll
;             for (int m = 0; m < 4; ++m) { bf16_t* rowp = O + (size_t)(row0 + ai * HALF + m * 16) * ldc + col0;
;                 if (ACT == 1) {
;                     const int ob = fr * 64 + 16 * fq, sw = ob ^ (((ob >> 9) & 1) << 5);
;                     rowp = O + ((size_t)(u.pm * (ldc / 64) + u.pn * 4 + (wc >> 1)) * 2 + ai) * 8192 + (((wr * 4 + m) * 2 + (wc & 1)) * 1024 + sw) / 2; }
;                 float rc[2][2], rs[2][2];
;                 if (ACT == 2) { const float pos = (float)((row0 + ai * HALF + m * 16) & 2047);
; #pragma unroll
;                     for (int n = 0; n < 2; ++n)
; #pragma unroll
;                         for (int e = 0; e < 2; ++e) { float r = pos * rinv[n][e]; r -= floorf(r); rs[n][e] = do_rope ? __builtin_amdgcn_sinf(r) : 0.f; rc[n][e] = do_rope ? __builtin_amdgcn_cosf(r) : 1.f; } }
; #pragma unroll
;                 for (int bj = 0; bj < 2; ++bj) { f32x4 v0 = acc[ai][bj][m][0], v1 = acc[ai][bj][m][1];
;                     if (ACT == 3) { const float pos = (float)((row0 + ai * HALF + m * 16) & 2047); float c3[4], s3[4];
; #pragma unroll
;                         for (int p = 0; p < 4; ++p) { float r = pos * rinv3[bj][p]; r -= floorf(r); s3[p] = rope3[bj] ? __builtin_amdgcn_sinf(r) : 0.f; c3[p] = rope3[bj] ? __builtin_amdgcn_cosf(r) : 1.f; }
.LBB0_1622:
	v_mov_b32_e32 v140, 0
	s_lshl_b32 s50, s50, 8
	v_mbcnt_lo_u32_b32 v140, -1, v140
	v_mbcnt_hi_u32_b32 v140, -1, v140
	v_or_b32_e32 v140, s33, v140
	s_mul_hi_i32 s52, s50, 0x2aaaaaab
	v_and_b32_e32 v142, 15, v140
	v_bfe_u32 v140, v140, 4, 2
	v_lshl_or_b32 v141, v140, 3, s42
	v_lshl_or_b32 v140, v140, 2, s45
	v_cvt_f32_ubyte0_e32 v143, v140
	v_mul_f32_e32 v144, 0xbe549a78, v143
	v_cmp_gt_f32_e32 vcc, s48, v144
	v_or_b32_e32 v145, 1, v140
	v_cvt_f32_ubyte0_e32 v145, v145
	v_cndmask_b32_e32 v144, 0, v152, vcc
	v_fmac_f32_e32 v144, 0xbe549a78, v143
	v_mul_f32_e32 v146, 0xbe549a78, v145
	v_exp_f32_e32 v143, v144
	v_cndmask_b32_e32 v144, 0, v153, vcc
	v_cmp_gt_f32_e32 vcc, s48, v146
	s_lshr_b32 s53, s52, 31
	v_ldexp_f32 v143, v143, v144
	v_cndmask_b32_e32 v146, 0, v152, vcc
	v_fmac_f32_e32 v146, 0xbe549a78, v145
	v_exp_f32_e32 v145, v146
	v_mul_f32_e32 v155, 0.15915494, v143
	v_cndmask_b32_e32 v143, 0, v153, vcc
	s_lshr_b32 s52, s52, 10
	v_ldexp_f32 v143, v145, v143
	v_mul_f32_e32 v154, 0.15915494, v143
	v_or_b32_e32 v143, 2, v140
	v_cvt_f32_ubyte0_e32 v143, v143
	v_mul_f32_e32 v144, 0xbe549a78, v143
	v_cmp_gt_f32_e32 vcc, s48, v144
	v_or_b32_e32 v140, 3, v140
	v_cvt_f32_ubyte0_e32 v140, v140
	v_cndmask_b32_e32 v144, 0, v152, vcc
	v_fmac_f32_e32 v144, 0xbe549a78, v143
	v_mul_f32_e32 v145, 0xbe549a78, v140
	v_exp_f32_e32 v143, v144
	v_cndmask_b32_e32 v144, 0, v153, vcc
	v_cmp_gt_f32_e32 vcc, s48, v145
	s_lshl_b32 s51, s76, 8
	v_ldexp_f32 v143, v143, v144
	v_cndmask_b32_e32 v145, 0, v152, vcc
	v_fmac_f32_e32 v145, 0xbe549a78, v140
	v_exp_f32_e32 v140, v145
	s_add_i32 s52, s52, s53
	v_mul_f32_e32 v157, 0.15915494, v143
	v_cndmask_b32_e32 v143, 0, v153, vcc
	s_add_i32 s51, s51, s41
	s_mulk_i32 s52, 0x1800
	v_ldexp_f32 v140, v140, v143
	s_sub_i32 s52, s50, s52
	v_mul_f32_e32 v156, 0.15915494, v140
	v_or_b32_e32 v140, s50, v141
	v_mov_b32_e32 v143, s51
	s_movk_i32 s50, 0x7cf
	v_or_b32_e32 v158, s51, v142
	v_bitop3_b32 v142, v142, s50, v143 bitop3:0xc8
	v_cvt_f32_u32_e32 v146, v142
	s_cmpk_lt_i32 s52, 0x1000
	s_cselect_b64 vcc, -1, 0
	v_ashrrev_i32_e32 v141, 31, v140
	v_mul_f32_e32 v147, v155, v146
	v_floor_f32_e32 v147, v147
	v_fma_f32 v147, v155, v146, -v147
	v_sin_f32_e32 v159, v147
	v_cos_f32_e32 v147, v147
	v_mul_f32_e32 v160, v154, v146
	v_mul_f32_e32 v164, v156, v146
	v_floor_f32_e32 v160, v160
	v_cndmask_b32_e32 v162, 1.0, v147, vcc
	v_mul_f32_e32 v147, v157, v146
	v_floor_f32_e32 v147, v147
	v_floor_f32_e32 v164, v164
	v_fma_f32 v160, v154, v146, -v160
	v_fma_f32 v147, v157, v146, -v147
	v_fma_f32 v146, v156, v146, -v164
	v_sin_f32_e32 v163, v147
	v_cos_f32_e32 v147, v147
	v_sin_f32_e32 v164, v146
	v_cos_f32_e32 v146, v146
	v_sin_f32_e32 v161, v160
	v_mov_b64_e32 v[144:145], s[12:13]
	v_cos_f32_e32 v160, v160
	v_mad_i64_i32 v[142:143], s[50:51], v158, s49, v[144:145]
	v_cndmask_b32_e32 v159, 0, v159, vcc
	v_cndmask_b32_e32 v165, 1.0, v147, vcc
	v_cndmask_b32_e32 v166, 1.0, v146, vcc
	v_lshlrev_b64 v[146:147], 1, v[140:141]
	v_lshl_add_u64 v[140:141], v[142:143], 0, v[146:147]
	v_mul_f32_e32 v142, v125, v159
	v_cndmask_b32_e32 v161, 0, v161, vcc
	v_fma_f32 v142, v124, v162, -v142
	v_mul_f32_e32 v124, v124, v159
	v_cndmask_b32_e32 v160, 1.0, v160, vcc
	v_fmac_f32_e32 v124, v125, v162
	v_mul_f32_e32 v125, v127, v161
	v_cndmask_b32_e32 v163, 0, v163, vcc
	v_fma_f32 v125, v126, v160, -v125
	v_mul_f32_e32 v126, v126, v161
	v_cndmask_b32_e32 v164, 0, v164, vcc
	v_fmac_f32_e32 v126, v127, v160
	v_mul_f32_e32 v127, v121, v163
	v_fma_f32 v127, v120, v165, -v127
	v_mul_f32_e32 v143, v120, v163
	v_mul_f32_e32 v120, v123, v164
	v_fma_f32 v167, v122, v166, -v120
	v_mul_f32_e32 v168, v122, v164
	v_cvt_pk_bf16_f32 v120, v142, v124
	v_fmac_f32_e32 v143, v121, v165
	v_fmac_f32_e32 v168, v123, v166
	v_cvt_pk_bf16_f32 v121, v125, v126
	v_cvt_pk_bf16_f32 v122, v127, v143
	v_cvt_pk_bf16_f32 v123, v167, v168
	global_store_dwordx4 v[140:141], v[120:123], off
	s_movk_i32 s50, 0x7df
	s_nop 0
	v_mul_f32_e32 v120, v117, v159
	v_fma_f32 v120, v116, v162, -v120
	v_mul_f32_e32 v116, v116, v159
	v_fmac_f32_e32 v116, v117, v162
	v_mul_f32_e32 v117, v119, v161
	v_fma_f32 v117, v118, v160, -v117
	v_mul_f32_e32 v118, v118, v161
	v_fmac_f32_e32 v118, v119, v160
	v_mul_f32_e32 v119, v113, v163
	v_fma_f32 v119, v112, v165, -v119
	v_mul_f32_e32 v121, v112, v163
	v_mul_f32_e32 v112, v115, v164
	v_fma_f32 v122, v114, v166, -v112
	v_mul_f32_e32 v123, v114, v164
	v_cvt_pk_bf16_f32 v112, v120, v116
	v_fmac_f32_e32 v121, v113, v165
	v_fmac_f32_e32 v123, v115, v166
	v_cvt_pk_bf16_f32 v113, v117, v118
	v_cvt_pk_bf16_f32 v114, v119, v121
	v_cvt_pk_bf16_f32 v115, v122, v123
	global_store_dwordx4 v[140:141], v[112:115], off offset:256
	s_nop 1
	v_bitop3_b32 v112, v158, s50, 16 bitop3:0xc8
	v_cvt_f32_u32_e32 v114, v112
	v_or_b32_e32 v112, 16, v158
	v_mad_i64_i32 v[112:113], s[50:51], v112, s49, v[144:145]
	v_mul_f32_e32 v115, v155, v114
	v_floor_f32_e32 v115, v115
	v_fma_f32 v115, v155, v114, -v115
	v_mul_f32_e32 v117, v154, v114
	v_sin_f32_e32 v116, v115
	v_floor_f32_e32 v117, v117
	v_cos_f32_e32 v115, v115
	v_fma_f32 v117, v154, v114, -v117
	v_mul_f32_e32 v119, v157, v114
	v_sin_f32_e32 v118, v117
	v_floor_f32_e32 v119, v119
	v_mul_f32_e32 v121, v156, v114
	v_cos_f32_e32 v117, v117
	v_fma_f32 v119, v157, v114, -v119
	v_floor_f32_e32 v121, v121
	v_cndmask_b32_e32 v116, 0, v116, vcc
	v_sin_f32_e32 v120, v119
	v_fma_f32 v114, v156, v114, -v121
	v_cndmask_b32_e32 v115, 1.0, v115, vcc
	v_cos_f32_e32 v119, v119
	v_sin_f32_e32 v121, v114
	v_mul_f32_e32 v122, v109, v116
	v_cndmask_b32_e32 v118, 0, v118, vcc
	v_cos_f32_e32 v114, v114
	v_fma_f32 v122, v108, v115, -v122
	v_mul_f32_e32 v108, v108, v116
;     __device__ __forceinline__ void operator()(const f32x4 (&acc)[2][2][4][2], const Unit& u, int wr, int wc, int fr, int fq) const {
;     ...
;                 if (ACT == 2) { const float pos = (float)((row0 + ai * HALF + m * 16) & 2047);
; #pragma unroll
;                     for (int n = 0; n < 2; ++n)
; #pragma unroll
;                         for (int e = 0; e < 2; ++e) { float r = pos * rinv[n][e]; r -= floorf(r); rs[n][e] = do_rope ? __builtin_amdgcn_sinf(r) : 0.f; rc[n][e] = do_rope ? __builtin_amdgcn_cosf(r) : 1.f; } }
; #pragma unroll
;                 for (int bj = 0; bj < 2; ++bj) { f32x4 v0 = acc[ai][bj][m][0], v1 = acc[ai][bj][m][1];
;                     if (ACT == 3) { const float pos = (float)((row0 + ai * HALF + m * 16) & 2047); float c3[4], s3[4];
; #pragma unroll
;                         for (int p = 0; p < 4; ++p) { float r = pos * rinv3[bj][p]; r -= floorf(r); s3[p] = rope3[bj] ? __builtin_amdgcn_sinf(r) : 0.f; c3[p] = rope3[bj] ? __builtin_amdgcn_cosf(r) : 1.f; }
;                         const f32x4 a = v0, b = v1;
;                         v0[0] = a[0] * c3[0] - a[1] * s3[0]; v0[1] = a[1] * c3[0] + a[0] * s3[0]; v0[2] = a[2] * c3[1] - a[3] * s3[1]; v0[3] = a[3] * c3[1] + a[2] * s3[1];
;                         v1[0] = b[0] * c3[2] - b[1] * s3[2]; v1[1] = b[1] * c3[2] + b[0] * s3[2]; v1[2] = b[2] * c3[3] - b[3] * s3[3]; v1[3] = b[3] * c3[3] + b[2] * s3[3]; }
;                     if (ACT == 2) { const f32x4 a = v0, b = v1;
;                         v0[0] = a[0] * rc[0][0] - a[1] * rs[0][0]; v0[1] = a[1] * rc[0][0] + a[0] * rs[0][0]; v0[2] = a[2] * rc[0][1] - a[3] * rs[0][1]; v0[3] = a[3] * rc[0][1] + a[2] * rs[0][1];
;                         v1[0] = b[0] * rc[1][0] - b[1] * rs[1][0]; v1[1] = b[1] * rc[1][0] + b[0] * rs[1][0]; v1[2] = b[2] * rc[1][1] - b[3] * rs[1][1]; v1[3] = b[3] * rc[1][1] + b[2] * rs[1][1]; }
;                     if (ACT == 1) {
; #pragma unroll
;                         for (int j = 0; j < 4; ++j) { const float a = __int_as_float(max(__float_as_int(v0[j]), 0)), b = __int_as_float(max(__float_as_int(v1[j]), 0)); v0[j] = a * a; v1[j] = b * b; } }
;                     u32x4 w; w.x = cvt_pk_bf16(v0[0], v0[1]); w.y = cvt_pk_bf16(v0[2], v0[3]); w.z = cvt_pk_bf16(v1[0], v1[1]); w.w = cvt_pk_bf16(v1[2], v1[3]);
;                     *(u32x4*)(rowp + (ACT == 1 ? bj * 2 * 2 * 8192 : bj * HALF)) = w; } }
	v_cndmask_b32_e32 v117, 1.0, v117, vcc
	v_fmac_f32_e32 v108, v109, v115
	v_mul_f32_e32 v109, v111, v118
	v_cndmask_b32_e32 v120, 0, v120, vcc
	v_fma_f32 v109, v110, v117, -v109
	v_mul_f32_e32 v110, v110, v118
	v_cndmask_b32_e32 v119, 1.0, v119, vcc
	v_cndmask_b32_e32 v121, 0, v121, vcc
	v_fmac_f32_e32 v110, v111, v117
	v_mul_f32_e32 v111, v105, v120
	v_cndmask_b32_e32 v114, 1.0, v114, vcc
	v_fma_f32 v111, v104, v119, -v111
	v_mul_f32_e32 v123, v104, v120
	v_mul_f32_e32 v104, v107, v121
	v_lshl_add_u64 v[112:113], v[112:113], 0, v[146:147]
	v_fma_f32 v124, v106, v114, -v104
	v_mul_f32_e32 v125, v106, v121
	v_cvt_pk_bf16_f32 v104, v122, v108
	v_fmac_f32_e32 v123, v105, v119
	v_fmac_f32_e32 v125, v107, v114
	v_cvt_pk_bf16_f32 v105, v109, v110
	v_cvt_pk_bf16_f32 v106, v111, v123
	v_cvt_pk_bf16_f32 v107, v124, v125
	global_store_dwordx4 v[112:113], v[104:107], off
	s_movk_i32 s50, 0x7ef
	s_nop 0
	v_mul_f32_e32 v104, v101, v116
	v_fma_f32 v104, v100, v115, -v104
	v_mul_f32_e32 v100, v100, v116
	v_fmac_f32_e32 v100, v101, v115
	v_mul_f32_e32 v101, v103, v118
	v_fma_f32 v101, v102, v117, -v101
	v_mul_f32_e32 v102, v102, v118
	v_fmac_f32_e32 v102, v103, v117
	v_mul_f32_e32 v103, v97, v120
	v_fma_f32 v103, v96, v119, -v103
	v_mul_f32_e32 v105, v96, v120
	v_mul_f32_e32 v96, v99, v121
	v_fma_f32 v106, v98, v114, -v96
	v_mul_f32_e32 v107, v98, v121
	v_cvt_pk_bf16_f32 v96, v104, v100
	v_fmac_f32_e32 v105, v97, v119
	v_fmac_f32_e32 v107, v99, v114
	v_cvt_pk_bf16_f32 v97, v101, v102
	v_cvt_pk_bf16_f32 v98, v103, v105
	v_cvt_pk_bf16_f32 v99, v106, v107
	global_store_dwordx4 v[112:113], v[96:99], off offset:256
	s_nop 1
	v_bitop3_b32 v96, v158, s50, 32 bitop3:0xc8
	v_cvt_f32_u32_e32 v98, v96
	v_or_b32_e32 v96, 32, v158
	v_mad_i64_i32 v[96:97], s[50:51], v96, s49, v[144:145]
	v_mul_f32_e32 v99, v155, v98
	v_floor_f32_e32 v99, v99
	v_fma_f32 v99, v155, v98, -v99
	v_mul_f32_e32 v101, v154, v98
	v_sin_f32_e32 v100, v99
	v_floor_f32_e32 v101, v101
	v_cos_f32_e32 v99, v99
	v_fma_f32 v101, v154, v98, -v101
	v_mul_f32_e32 v103, v157, v98
	v_sin_f32_e32 v102, v101
	v_floor_f32_e32 v103, v103
	v_mul_f32_e32 v105, v156, v98
	v_cos_f32_e32 v101, v101
	v_fma_f32 v103, v157, v98, -v103
	v_floor_f32_e32 v105, v105
	v_cndmask_b32_e32 v100, 0, v100, vcc
	v_sin_f32_e32 v104, v103
	v_fma_f32 v98, v156, v98, -v105
	v_cndmask_b32_e32 v99, 1.0, v99, vcc
	v_cos_f32_e32 v103, v103
	v_sin_f32_e32 v105, v98
	v_mul_f32_e32 v106, v93, v100
	v_cndmask_b32_e32 v102, 0, v102, vcc
	v_cos_f32_e32 v98, v98
	v_fma_f32 v106, v92, v99, -v106
	v_mul_f32_e32 v92, v92, v100
	v_cndmask_b32_e32 v101, 1.0, v101, vcc
	v_fmac_f32_e32 v92, v93, v99
	v_mul_f32_e32 v93, v95, v102
	v_cndmask_b32_e32 v104, 0, v104, vcc
	v_fma_f32 v93, v94, v101, -v93
	v_mul_f32_e32 v94, v94, v102
	v_cndmask_b32_e32 v103, 1.0, v103, vcc
	v_cndmask_b32_e32 v105, 0, v105, vcc
	v_fmac_f32_e32 v94, v95, v101
	v_mul_f32_e32 v95, v89, v104
	v_cndmask_b32_e32 v98, 1.0, v98, vcc
	v_fma_f32 v95, v88, v103, -v95
	v_mul_f32_e32 v107, v88, v104
	v_mul_f32_e32 v88, v91, v105
	v_lshl_add_u64 v[96:97], v[96:97], 0, v[146:147]
	v_fma_f32 v108, v90, v98, -v88
	v_mul_f32_e32 v109, v90, v105
	v_cvt_pk_bf16_f32 v88, v106, v92
	v_fmac_f32_e32 v107, v89, v103
	v_fmac_f32_e32 v109, v91, v98
	v_cvt_pk_bf16_f32 v89, v93, v94
	v_cvt_pk_bf16_f32 v90, v95, v107
	v_cvt_pk_bf16_f32 v91, v108, v109
	global_store_dwordx4 v[96:97], v[88:91], off
	s_movk_i32 s50, 0x7ff
	s_nop 0
	v_mul_f32_e32 v88, v85, v100
	v_fma_f32 v88, v84, v99, -v88
	v_mul_f32_e32 v84, v84, v100
	v_fmac_f32_e32 v84, v85, v99
	v_mul_f32_e32 v85, v87, v102
	v_fma_f32 v85, v86, v101, -v85
	v_mul_f32_e32 v86, v86, v102
	v_fmac_f32_e32 v86, v87, v101
	v_mul_f32_e32 v87, v81, v104
	v_fma_f32 v87, v80, v103, -v87
	v_mul_f32_e32 v89, v80, v104
	v_mul_f32_e32 v80, v83, v105
	v_fma_f32 v90, v82, v98, -v80
	v_mul_f32_e32 v91, v82, v105
	v_cvt_pk_bf16_f32 v80, v88, v84
	v_fmac_f32_e32 v89, v81, v103
	v_fmac_f32_e32 v91, v83, v98
	v_cvt_pk_bf16_f32 v81, v85, v86
	v_cvt_pk_bf16_f32 v82, v87, v89
	v_cvt_pk_bf16_f32 v83, v90, v91
	global_store_dwordx4 v[96:97], v[80:83], off offset:256
	s_nop 1
	v_bitop3_b32 v80, v158, s50, 48 bitop3:0xc8
	v_cvt_f32_u32_e32 v82, v80
	v_or_b32_e32 v80, 48, v158
	v_mad_i64_i32 v[80:81], s[50:51], v80, s49, v[144:145]
	v_mul_f32_e32 v83, v155, v82
	v_floor_f32_e32 v83, v83
	v_fma_f32 v83, v155, v82, -v83
	v_mul_f32_e32 v85, v154, v82
	v_sin_f32_e32 v84, v83
	v_floor_f32_e32 v85, v85
	v_cos_f32_e32 v83, v83
	v_fma_f32 v85, v154, v82, -v85
	v_mul_f32_e32 v87, v157, v82
	v_sin_f32_e32 v86, v85
	v_floor_f32_e32 v87, v87
	v_mul_f32_e32 v89, v156, v82
	v_cos_f32_e32 v85, v85
	v_fma_f32 v87, v157, v82, -v87
	v_floor_f32_e32 v89, v89
	v_cndmask_b32_e32 v84, 0, v84, vcc
	v_sin_f32_e32 v88, v87
	v_fma_f32 v82, v156, v82, -v89
	v_cndmask_b32_e32 v83, 1.0, v83, vcc
	v_cos_f32_e32 v87, v87
	v_sin_f32_e32 v89, v82
	v_mul_f32_e32 v90, v77, v84
	v_cndmask_b32_e32 v86, 0, v86, vcc
	v_cos_f32_e32 v82, v82
	v_fma_f32 v90, v76, v83, -v90
	v_mul_f32_e32 v76, v76, v84
	v_cndmask_b32_e32 v85, 1.0, v85, vcc
	v_fmac_f32_e32 v76, v77, v83
	v_mul_f32_e32 v77, v79, v86
	v_cndmask_b32_e32 v88, 0, v88, vcc
	v_fma_f32 v77, v78, v85, -v77
	v_mul_f32_e32 v78, v78, v86
	v_cndmask_b32_e32 v87, 1.0, v87, vcc
	v_cndmask_b32_e32 v89, 0, v89, vcc
	v_fmac_f32_e32 v78, v79, v85
	v_mul_f32_e32 v79, v73, v88
	v_cndmask_b32_e32 v82, 1.0, v82, vcc
	v_fma_f32 v79, v72, v87, -v79
	v_mul_f32_e32 v91, v72, v88
	v_mul_f32_e32 v72, v75, v89
	v_lshl_add_u64 v[80:81], v[80:81], 0, v[146:147]
	v_fma_f32 v92, v74, v82, -v72
	v_mul_f32_e32 v93, v74, v89
	v_cvt_pk_bf16_f32 v72, v90, v76
	v_fmac_f32_e32 v91, v73, v87
;     __device__ __forceinline__ void operator()(const f32x4 (&acc)[2][2][4][2], const Unit& u, int wr, int wc, int fr, int fq) const {
;     ...
;                 if (ACT == 2) { const float pos = (float)((row0 + ai * HALF + m * 16) & 2047);
; #pragma unroll
;                     for (int n = 0; n < 2; ++n)
; #pragma unroll
;                         for (int e = 0; e < 2; ++e) { float r = pos * rinv[n][e]; r -= floorf(r); rs[n][e] = do_rope ? __builtin_amdgcn_sinf(r) : 0.f; rc[n][e] = do_rope ? __builtin_amdgcn_cosf(r) : 1.f; } }
; #pragma unroll
;                 for (int bj = 0; bj < 2; ++bj) { f32x4 v0 = acc[ai][bj][m][0], v1 = acc[ai][bj][m][1];
;                     if (ACT == 3) { const float pos = (float)((row0 + ai * HALF + m * 16) & 2047); float c3[4], s3[4];
; #pragma unroll
;                         for (int p = 0; p < 4; ++p) { float r = pos * rinv3[bj][p]; r -= floorf(r); s3[p] = rope3[bj] ? __builtin_amdgcn_sinf(r) : 0.f; c3[p] = rope3[bj] ? __builtin_amdgcn_cosf(r) : 1.f; }
;                         const f32x4 a = v0, b = v1;
;                         v0[0] = a[0] * c3[0] - a[1] * s3[0]; v0[1] = a[1] * c3[0] + a[0] * s3[0]; v0[2] = a[2] * c3[1] - a[3] * s3[1]; v0[3] = a[3] * c3[1] + a[2] * s3[1];
;                         v1[0] = b[0] * c3[2] - b[1] * s3[2]; v1[1] = b[1] * c3[2] + b[0] * s3[2]; v1[2] = b[2] * c3[3] - b[3] * s3[3]; v1[3] = b[3] * c3[3] + b[2] * s3[3]; }
;                     if (ACT == 2) { const f32x4 a = v0, b = v1;
;                         v0[0] = a[0] * rc[0][0] - a[1] * rs[0][0]; v0[1] = a[1] * rc[0][0] + a[0] * rs[0][0]; v0[2] = a[2] * rc[0][1] - a[3] * rs[0][1]; v0[3] = a[3] * rc[0][1] + a[2] * rs[0][1];
;                         v1[0] = b[0] * rc[1][0] - b[1] * rs[1][0]; v1[1] = b[1] * rc[1][0] + b[0] * rs[1][0]; v1[2] = b[2] * rc[1][1] - b[3] * rs[1][1]; v1[3] = b[3] * rc[1][1] + b[2] * rs[1][1]; }
;                     if (ACT == 1) {
; #pragma unroll
;                         for (int j = 0; j < 4; ++j) { const float a = __int_as_float(max(__float_as_int(v0[j]), 0)), b = __int_as_float(max(__float_as_int(v1[j]), 0)); v0[j] = a * a; v1[j] = b * b; } }
;                     u32x4 w; w.x = cvt_pk_bf16(v0[0], v0[1]); w.y = cvt_pk_bf16(v0[2], v0[3]); w.z = cvt_pk_bf16(v1[0], v1[1]); w.w = cvt_pk_bf16(v1[2], v1[3]);
;                     *(u32x4*)(rowp + (ACT == 1 ? bj * 2 * 2 * 8192 : bj * HALF)) = w; } }
	v_fmac_f32_e32 v93, v75, v82
	v_cvt_pk_bf16_f32 v73, v77, v78
	v_cvt_pk_bf16_f32 v74, v79, v91
	v_cvt_pk_bf16_f32 v75, v92, v93
	global_store_dwordx4 v[80:81], v[72:75], off
	s_nop 1
	v_mul_f32_e32 v72, v69, v84
	v_fma_f32 v72, v68, v83, -v72
	v_mul_f32_e32 v68, v68, v84
	v_fmac_f32_e32 v68, v69, v83
	v_mul_f32_e32 v69, v71, v86
	v_fma_f32 v69, v70, v85, -v69
	v_mul_f32_e32 v70, v70, v86
	v_fmac_f32_e32 v70, v71, v85
	v_mul_f32_e32 v71, v65, v88
	v_fma_f32 v71, v64, v87, -v71
	v_mul_f32_e32 v73, v64, v88
	v_mul_f32_e32 v64, v67, v89
	v_fma_f32 v74, v66, v82, -v64
	v_cvt_pk_bf16_f32 v64, v72, v68
	v_add_u32_e32 v68, 0x80, v158
	v_fmac_f32_e32 v73, v65, v87
	v_cvt_pk_bf16_f32 v65, v69, v70
	v_and_b32_e32 v69, 0x7cf, v68
	v_cvt_f32_u32_e32 v69, v69
	v_mul_f32_e32 v75, v66, v89
	v_cvt_pk_bf16_f32 v66, v71, v73
	v_fmac_f32_e32 v75, v67, v82
	v_cvt_pk_bf16_f32 v67, v74, v75
	global_store_dwordx4 v[80:81], v[64:67], off offset:256
	v_mul_f32_e32 v71, v157, v69
	v_floor_f32_e32 v71, v71
	v_mul_f32_e32 v66, v155, v69
	v_floor_f32_e32 v66, v66
	v_mad_i64_i32 v[64:65], s[50:51], v68, s49, v[144:145]
	v_fma_f32 v66, v155, v69, -v66
	v_mul_f32_e32 v68, v154, v69
	v_sin_f32_e32 v67, v66
	v_floor_f32_e32 v68, v68
	v_cos_f32_e32 v66, v66
	v_fma_f32 v68, v154, v69, -v68
	v_sin_f32_e32 v70, v68
	v_mul_f32_e32 v73, v156, v69
	v_cos_f32_e32 v68, v68
	v_fma_f32 v71, v157, v69, -v71
	v_floor_f32_e32 v73, v73
	v_cndmask_b32_e32 v67, 0, v67, vcc
	v_sin_f32_e32 v72, v71
	v_fma_f32 v69, v156, v69, -v73
	v_cndmask_b32_e32 v66, 1.0, v66, vcc
	v_cos_f32_e32 v71, v71
	v_sin_f32_e32 v73, v69
	v_mul_f32_e32 v74, v61, v67
	v_cndmask_b32_e32 v70, 0, v70, vcc
	v_cos_f32_e32 v69, v69
	v_fma_f32 v74, v60, v66, -v74
	v_mul_f32_e32 v60, v60, v67
	v_cndmask_b32_e32 v68, 1.0, v68, vcc
	v_fmac_f32_e32 v60, v61, v66
	v_mul_f32_e32 v61, v63, v70
	v_cndmask_b32_e32 v72, 0, v72, vcc
	v_fma_f32 v61, v62, v68, -v61
	v_mul_f32_e32 v62, v62, v70
	v_cndmask_b32_e32 v71, 1.0, v71, vcc
	v_cndmask_b32_e32 v73, 0, v73, vcc
	v_fmac_f32_e32 v62, v63, v68
	v_mul_f32_e32 v63, v57, v72
	v_cndmask_b32_e32 v69, 1.0, v69, vcc
	v_fma_f32 v63, v56, v71, -v63
	v_mul_f32_e32 v75, v56, v72
	v_mul_f32_e32 v56, v59, v73
	v_lshl_add_u64 v[64:65], v[64:65], 0, v[146:147]
	v_fma_f32 v76, v58, v69, -v56
	v_mul_f32_e32 v77, v58, v73
	v_cvt_pk_bf16_f32 v56, v74, v60
	v_fmac_f32_e32 v75, v57, v71
	v_fmac_f32_e32 v77, v59, v69
	v_cvt_pk_bf16_f32 v57, v61, v62
	v_cvt_pk_bf16_f32 v58, v63, v75
	v_cvt_pk_bf16_f32 v59, v76, v77
	global_store_dwordx4 v[64:65], v[56:59], off
	s_nop 1
	v_mul_f32_e32 v56, v53, v67
	v_fma_f32 v56, v52, v66, -v56
	v_mul_f32_e32 v52, v52, v67
	v_fmac_f32_e32 v52, v53, v66
	v_mul_f32_e32 v53, v55, v70
	v_fma_f32 v53, v54, v68, -v53
	v_mul_f32_e32 v54, v54, v70
	v_fmac_f32_e32 v54, v55, v68
	v_mul_f32_e32 v55, v49, v72
	v_fma_f32 v55, v48, v71, -v55
	v_mul_f32_e32 v57, v48, v72
	v_mul_f32_e32 v48, v51, v73
	v_fma_f32 v58, v50, v69, -v48
	v_cvt_pk_bf16_f32 v48, v56, v52
	v_add_u32_e32 v52, 0x90, v158
	v_fmac_f32_e32 v57, v49, v71
	v_cvt_pk_bf16_f32 v49, v53, v54
	v_and_b32_e32 v53, 0x7df, v52
	v_cvt_f32_u32_e32 v53, v53
	v_mul_f32_e32 v59, v50, v73
	v_cvt_pk_bf16_f32 v50, v55, v57
	v_fmac_f32_e32 v59, v51, v69
	v_cvt_pk_bf16_f32 v51, v58, v59
	global_store_dwordx4 v[64:65], v[48:51], off offset:256
	v_mul_f32_e32 v55, v157, v53
	v_floor_f32_e32 v55, v55
	v_mul_f32_e32 v50, v155, v53
	v_floor_f32_e32 v50, v50
	v_mad_i64_i32 v[48:49], s[50:51], v52, s49, v[144:145]
	v_fma_f32 v50, v155, v53, -v50
	v_mul_f32_e32 v52, v154, v53
	v_sin_f32_e32 v51, v50
	v_floor_f32_e32 v52, v52
	v_cos_f32_e32 v50, v50
	v_fma_f32 v52, v154, v53, -v52
	v_sin_f32_e32 v54, v52
	v_mul_f32_e32 v57, v156, v53
	v_cos_f32_e32 v52, v52
	v_fma_f32 v55, v157, v53, -v55
	v_floor_f32_e32 v57, v57
	v_cndmask_b32_e32 v51, 0, v51, vcc
	v_sin_f32_e32 v56, v55
	v_fma_f32 v53, v156, v53, -v57
	v_cndmask_b32_e32 v50, 1.0, v50, vcc
	v_cos_f32_e32 v55, v55
	v_sin_f32_e32 v57, v53
	v_mul_f32_e32 v58, v45, v51
	v_cndmask_b32_e32 v54, 0, v54, vcc
	v_cos_f32_e32 v53, v53
	v_fma_f32 v58, v44, v50, -v58
	v_mul_f32_e32 v44, v44, v51
	v_cndmask_b32_e32 v52, 1.0, v52, vcc
	v_fmac_f32_e32 v44, v45, v50
	v_mul_f32_e32 v45, v47, v54
	v_cndmask_b32_e32 v56, 0, v56, vcc
	v_fma_f32 v45, v46, v52, -v45
	v_mul_f32_e32 v46, v46, v54
	v_cndmask_b32_e32 v55, 1.0, v55, vcc
	v_cndmask_b32_e32 v57, 0, v57, vcc
	v_fmac_f32_e32 v46, v47, v52
	v_mul_f32_e32 v47, v41, v56
	v_cndmask_b32_e32 v53, 1.0, v53, vcc
	v_fma_f32 v47, v40, v55, -v47
	v_mul_f32_e32 v59, v40, v56
	v_mul_f32_e32 v40, v43, v57
	v_lshl_add_u64 v[48:49], v[48:49], 0, v[146:147]
	v_fma_f32 v60, v42, v53, -v40
	v_mul_f32_e32 v61, v42, v57
	v_cvt_pk_bf16_f32 v40, v58, v44
	v_fmac_f32_e32 v59, v41, v55
	v_fmac_f32_e32 v61, v43, v53
	v_cvt_pk_bf16_f32 v41, v45, v46
	v_cvt_pk_bf16_f32 v42, v47, v59
	v_cvt_pk_bf16_f32 v43, v60, v61
	global_store_dwordx4 v[48:49], v[40:43], off
	s_nop 1
	v_mul_f32_e32 v40, v37, v51
	v_fma_f32 v40, v36, v50, -v40
	v_mul_f32_e32 v36, v36, v51
	v_fmac_f32_e32 v36, v37, v50
	v_mul_f32_e32 v37, v39, v54
	v_fma_f32 v37, v38, v52, -v37
	v_mul_f32_e32 v38, v38, v54
	v_fmac_f32_e32 v38, v39, v52
	v_mul_f32_e32 v39, v33, v56
	v_fma_f32 v39, v32, v55, -v39
;     __device__ __forceinline__ void operator()(const f32x4 (&acc)[2][2][4][2], const Unit& u, int wr, int wc, int fr, int fq) const {
;     ...
;                 if (ACT == 2) { const float pos = (float)((row0 + ai * HALF + m * 16) & 2047);
; #pragma unroll
;                     for (int n = 0; n < 2; ++n)
; #pragma unroll
;                         for (int e = 0; e < 2; ++e) { float r = pos * rinv[n][e]; r -= floorf(r); rs[n][e] = do_rope ? __builtin_amdgcn_sinf(r) : 0.f; rc[n][e] = do_rope ? __builtin_amdgcn_cosf(r) : 1.f; } }
; #pragma unroll
;                 for (int bj = 0; bj < 2; ++bj) { f32x4 v0 = acc[ai][bj][m][0], v1 = acc[ai][bj][m][1];
;                     if (ACT == 3) { const float pos = (float)((row0 + ai * HALF + m * 16) & 2047); float c3[4], s3[4];
; #pragma unroll
;                         for (int p = 0; p < 4; ++p) { float r = pos * rinv3[bj][p]; r -= floorf(r); s3[p] = rope3[bj] ? __builtin_amdgcn_sinf(r) : 0.f; c3[p] = rope3[bj] ? __builtin_amdgcn_cosf(r) : 1.f; }
;                         const f32x4 a = v0, b = v1;
;                         v0[0] = a[0] * c3[0] - a[1] * s3[0]; v0[1] = a[1] * c3[0] + a[0] * s3[0]; v0[2] = a[2] * c3[1] - a[3] * s3[1]; v0[3] = a[3] * c3[1] + a[2] * s3[1];
;                         v1[0] = b[0] * c3[2] - b[1] * s3[2]; v1[1] = b[1] * c3[2] + b[0] * s3[2]; v1[2] = b[2] * c3[3] - b[3] * s3[3]; v1[3] = b[3] * c3[3] + b[2] * s3[3]; }
;                     if (ACT == 2) { const f32x4 a = v0, b = v1;
;                         v0[0] = a[0] * rc[0][0] - a[1] * rs[0][0]; v0[1] = a[1] * rc[0][0] + a[0] * rs[0][0]; v0[2] = a[2] * rc[0][1] - a[3] * rs[0][1]; v0[3] = a[3] * rc[0][1] + a[2] * rs[0][1];
;                         v1[0] = b[0] * rc[1][0] - b[1] * rs[1][0]; v1[1] = b[1] * rc[1][0] + b[0] * rs[1][0]; v1[2] = b[2] * rc[1][1] - b[3] * rs[1][1]; v1[3] = b[3] * rc[1][1] + b[2] * rs[1][1]; }
;                     if (ACT == 1) {
; #pragma unroll
;                         for (int j = 0; j < 4; ++j) { const float a = __int_as_float(max(__float_as_int(v0[j]), 0)), b = __int_as_float(max(__float_as_int(v1[j]), 0)); v0[j] = a * a; v1[j] = b * b; } }
;                     u32x4 w; w.x = cvt_pk_bf16(v0[0], v0[1]); w.y = cvt_pk_bf16(v0[2], v0[3]); w.z = cvt_pk_bf16(v1[0], v1[1]); w.w = cvt_pk_bf16(v1[2], v1[3]);
;                     *(u32x4*)(rowp + (ACT == 1 ? bj * 2 * 2 * 8192 : bj * HALF)) = w; } }
	v_mul_f32_e32 v41, v32, v56
	v_mul_f32_e32 v32, v35, v57
	v_fma_f32 v42, v34, v53, -v32
	v_cvt_pk_bf16_f32 v32, v40, v36
	v_add_u32_e32 v36, 0xa0, v158
	v_fmac_f32_e32 v41, v33, v55
	v_cvt_pk_bf16_f32 v33, v37, v38
	v_and_b32_e32 v37, 0x7ef, v36
	v_cvt_f32_u32_e32 v37, v37
	v_mul_f32_e32 v43, v34, v57
	v_cvt_pk_bf16_f32 v34, v39, v41
	v_fmac_f32_e32 v43, v35, v53
	v_cvt_pk_bf16_f32 v35, v42, v43
	global_store_dwordx4 v[48:49], v[32:35], off offset:256
	v_mul_f32_e32 v39, v157, v37
	v_floor_f32_e32 v39, v39
	v_mul_f32_e32 v34, v155, v37
	v_floor_f32_e32 v34, v34
	v_mad_i64_i32 v[32:33], s[50:51], v36, s49, v[144:145]
	v_fma_f32 v34, v155, v37, -v34
	v_mul_f32_e32 v36, v154, v37
	v_sin_f32_e32 v35, v34
	v_floor_f32_e32 v36, v36
	v_cos_f32_e32 v34, v34
	v_fma_f32 v36, v154, v37, -v36
	v_sin_f32_e32 v38, v36
	v_mul_f32_e32 v41, v156, v37
	v_cos_f32_e32 v36, v36
	v_fma_f32 v39, v157, v37, -v39
	v_floor_f32_e32 v41, v41
	v_cndmask_b32_e32 v35, 0, v35, vcc
	v_sin_f32_e32 v40, v39
	v_fma_f32 v37, v156, v37, -v41
	v_cndmask_b32_e32 v34, 1.0, v34, vcc
	v_cos_f32_e32 v39, v39
	v_sin_f32_e32 v41, v37
	v_mul_f32_e32 v42, v29, v35
	v_cndmask_b32_e32 v38, 0, v38, vcc
	v_cos_f32_e32 v37, v37
	v_fma_f32 v42, v28, v34, -v42
	v_mul_f32_e32 v28, v28, v35
	v_cndmask_b32_e32 v36, 1.0, v36, vcc
	v_fmac_f32_e32 v28, v29, v34
	v_mul_f32_e32 v29, v31, v38
	v_cndmask_b32_e32 v40, 0, v40, vcc
	v_fma_f32 v29, v30, v36, -v29
	v_mul_f32_e32 v30, v30, v38
	v_cndmask_b32_e32 v39, 1.0, v39, vcc
	v_cndmask_b32_e32 v41, 0, v41, vcc
	v_fmac_f32_e32 v30, v31, v36
	v_mul_f32_e32 v31, v25, v40
	v_cndmask_b32_e32 v37, 1.0, v37, vcc
	v_fma_f32 v31, v24, v39, -v31
	v_mul_f32_e32 v43, v24, v40
	v_mul_f32_e32 v24, v27, v41
	v_lshl_add_u64 v[32:33], v[32:33], 0, v[146:147]
	v_fma_f32 v44, v26, v37, -v24
	v_mul_f32_e32 v45, v26, v41
	v_cvt_pk_bf16_f32 v24, v42, v28
	v_fmac_f32_e32 v43, v25, v39
	v_fmac_f32_e32 v45, v27, v37
	v_cvt_pk_bf16_f32 v25, v29, v30
	v_cvt_pk_bf16_f32 v26, v31, v43
	v_cvt_pk_bf16_f32 v27, v44, v45
	global_store_dwordx4 v[32:33], v[24:27], off
	s_nop 1
	v_mul_f32_e32 v24, v21, v35
	v_fma_f32 v24, v20, v34, -v24
	v_mul_f32_e32 v20, v20, v35
	v_fmac_f32_e32 v20, v21, v34
	v_mul_f32_e32 v21, v23, v38
	v_fma_f32 v21, v22, v36, -v21
	v_mul_f32_e32 v22, v22, v38
	v_fmac_f32_e32 v22, v23, v36
	v_mul_f32_e32 v23, v17, v40
	v_fma_f32 v23, v16, v39, -v23
	v_mul_f32_e32 v25, v16, v40
	v_mul_f32_e32 v16, v19, v41
	v_fma_f32 v26, v18, v37, -v16
	v_cvt_pk_bf16_f32 v16, v24, v20
	v_add_u32_e32 v20, 0xb0, v158
	v_fmac_f32_e32 v25, v17, v39
	v_cvt_pk_bf16_f32 v17, v21, v22
	v_and_b32_e32 v21, 0x7ff, v20
	v_cvt_f32_u32_e32 v21, v21
	v_mul_f32_e32 v27, v18, v41
	v_cvt_pk_bf16_f32 v18, v23, v25
	v_fmac_f32_e32 v27, v19, v37
	v_cvt_pk_bf16_f32 v19, v26, v27
	global_store_dwordx4 v[32:33], v[16:19], off offset:256
	v_mul_f32_e32 v23, v157, v21
	v_floor_f32_e32 v23, v23
	v_mul_f32_e32 v18, v155, v21
	v_floor_f32_e32 v18, v18
	v_mad_i64_i32 v[16:17], s[50:51], v20, s49, v[144:145]
	v_fma_f32 v18, v155, v21, -v18
	v_mul_f32_e32 v20, v154, v21
	v_sin_f32_e32 v19, v18
	v_floor_f32_e32 v20, v20
	v_cos_f32_e32 v18, v18
	v_fma_f32 v20, v154, v21, -v20
	v_sin_f32_e32 v22, v20
	v_mul_f32_e32 v25, v156, v21
	v_cos_f32_e32 v20, v20
	v_fma_f32 v23, v157, v21, -v23
	v_floor_f32_e32 v25, v25
	v_cndmask_b32_e32 v19, 0, v19, vcc
	v_sin_f32_e32 v24, v23
	v_fma_f32 v21, v156, v21, -v25
	v_cndmask_b32_e32 v18, 1.0, v18, vcc
	v_cos_f32_e32 v23, v23
	v_sin_f32_e32 v25, v21
	v_mul_f32_e32 v26, v13, v19
	v_cndmask_b32_e32 v22, 0, v22, vcc
	v_cos_f32_e32 v21, v21
	v_fma_f32 v26, v12, v18, -v26
	v_mul_f32_e32 v12, v12, v19
	v_cndmask_b32_e32 v20, 1.0, v20, vcc
	v_fmac_f32_e32 v12, v13, v18
	v_mul_f32_e32 v13, v15, v22
	v_cndmask_b32_e32 v24, 0, v24, vcc
	v_fma_f32 v13, v14, v20, -v13
	v_mul_f32_e32 v14, v14, v22
	v_cndmask_b32_e32 v23, 1.0, v23, vcc
	v_cndmask_b32_e32 v25, 0, v25, vcc
	v_fmac_f32_e32 v14, v15, v20
	v_mul_f32_e32 v15, v9, v24
	v_cndmask_b32_e32 v21, 1.0, v21, vcc
	v_fma_f32 v15, v8, v23, -v15
	v_mul_f32_e32 v27, v8, v24
	v_mul_f32_e32 v8, v11, v25
	v_lshl_add_u64 v[16:17], v[16:17], 0, v[146:147]
	v_fma_f32 v28, v10, v21, -v8
	v_mul_f32_e32 v29, v10, v25
	v_cvt_pk_bf16_f32 v8, v26, v12
	v_fmac_f32_e32 v27, v9, v23
	v_fmac_f32_e32 v29, v11, v21
	v_cvt_pk_bf16_f32 v9, v13, v14
	v_cvt_pk_bf16_f32 v10, v15, v27
	v_cvt_pk_bf16_f32 v11, v28, v29
	global_store_dwordx4 v[16:17], v[8:11], off
	s_andn2_b64 vcc, exec, s[2:3]
	s_mov_b64 s[2:3], -1
	v_mul_f32_e32 v8, v5, v19
	v_fma_f32 v8, v4, v18, -v8
	v_mul_f32_e32 v4, v4, v19
	v_fmac_f32_e32 v4, v5, v18
	v_mul_f32_e32 v5, v7, v22
	v_fma_f32 v5, v6, v20, -v5
	v_mul_f32_e32 v6, v6, v22
	v_fmac_f32_e32 v6, v7, v20
	v_mul_f32_e32 v7, v1, v24
	v_fma_f32 v7, v0, v23, -v7
	v_mul_f32_e32 v9, v0, v24
	v_mul_f32_e32 v0, v3, v25
	v_mul_f32_e32 v11, v2, v25
	v_fmac_f32_e32 v9, v1, v23
	v_fma_f32 v10, v2, v21, -v0
	v_fmac_f32_e32 v11, v3, v21
	v_cvt_pk_bf16_f32 v0, v8, v4
	v_cvt_pk_bf16_f32 v1, v5, v6
	v_cvt_pk_bf16_f32 v2, v7, v9
	v_cvt_pk_bf16_f32 v3, v10, v11
	global_store_dwordx4 v[16:17], v[0:3], off offset:256
	s_mov_b32 s98, 1
	s_cbranch_vccnz .LBB0_1615
	s_andn2_b64 vcc, exec, s[6:7]
	s_cbranch_vccnz .LBB0_1614
	s_barrier
	s_branch .LBB0_1614

; #define PG8_STAGE(bufoff, gbase, voff) do { _Pragma("unroll") for (int _i = 0; _i < 2; ++_i) \
;         __builtin_amdgcn_global_load_lds((const unsigned*)((const char*)(gbase) + (voff)[_i]), (PG8_LAS unsigned*)(lds + (bufoff) + ldsw + _i * 8192), 16, 0, 0); } while (0)
; #define PG8_WAIT_V(n) asm volatile("s_waitcnt vmcnt(" #n ")" ::: "memory")
; #define PG8_BAR __builtin_amdgcn_s_barrier()
; template <class Epi, class Sched, bool ALIGN_EPI = false, bool SP2 = false, bool A_TILED = false>
; __device__ __forceinline__ void gemm_phase(PG8_LAS unsigned char* lds, const Gemm g, const Sched& S, const Epi& E, const int wave_s) {
;     ...
;     if constexpr (SP2) {
;         PG8_STAGE(PG8_SB(0, 0), cB, voffB); PG8_STAGE(PG8_SB(0, 1), cB + hstep, voffB); PG8_STAGE(PG8_SA(0, 0), cA, voffA); PG8_STAGE(PG8_SA(0, 1), cA + hstepA, voffA);
;         if (wr == 1) PG8_BAR;
;         PG8_WAIT_V(2); PG8_BAR;
;         PG8_STAGE(PG8_SB(1, 0), cB + kstep, voffB); PG8_STAGE(PG8_SA(1, 0), cA + kstepA, voffA); PG8_STAGE(PG8_SB(1, 1), cB + hstep + kstep, voffB);
;         PG8_WAIT_V(6); PG8_BAR;
;     } else {
;         PG8_STAGE(PG8_SB(0, 0), cB, voffB); PG8_STAGE(PG8_SA(0, 0), cA, voffA); PG8_STAGE(PG8_SB(0, 1), cB + hstep, voffB); PG8_STAGE(PG8_SA(0, 1), cA + hstepA, voffA);
;         if (wr == 1) PG8_BAR;
;         PG8_WAIT_V(4); PG8_BAR;
;         PG8_STAGE(PG8_SB(1, 0), cB + kstep, voffB); PG8_STAGE(PG8_SA(1, 0), cA + kstepA, voffA); PG8_STAGE(PG8_SB(1, 1), cB + hstep + kstep, voffB);
;         PG8_WAIT_V(6); PG8_BAR;
.LBB0_1943:
	s_ashr_i32 s40, s86, 31
	s_add_u32 s41, s2, 0x34600000
	s_sext_i32_i16 s49, s12
	s_addc_u32 s42, s3, 0
	s_lshl_b32 s47, s13, 13
	s_mov_b64 s[12:13], 0x80
	s_and_b32 s2, s46, 3
	v_and_b32_e32 v15, 15, v14
	v_and_b32_e32 v16, 48, v14
	v_lshlrev_b32_e32 v14, 2, v14
	s_add_i32 m0, s22, 0x18000
	v_lshl_add_u64 v[6:7], v[6:7], 0, s[12:13]
	v_lshl_or_b32 v15, v15, 6, v16
	v_and_b32_e32 v14, 32, v14
	s_lshl_b32 s2, s2, 12
	s_waitcnt vmcnt(2)
	s_barrier
	global_load_lds_dwordx4 v[6:7], off
	v_lshl_add_u64 v[4:5], v[4:5], 0, s[12:13]
	s_add_i32 m0, s22, 0x1a000
	s_add_i32 s43, s22, 0x8000
	s_add_i32 s44, s22, 0xa000
	v_bitop3_b32 v144, v15, s2, v14 bitop3:0xde
	global_load_lds_dwordx4 v[4:5], off
	v_lshl_add_u64 v[0:1], v[0:1], 0, s[12:13]
	s_mov_b32 m0, s43
	s_add_u32 s2, s76, 0x80080
	global_load_lds_dwordx4 v[0:1], off
	v_lshl_add_u64 v[0:1], v[2:3], 0, s[12:13]
	s_mov_b32 m0, s44
	s_addc_u32 s3, s77, 0
	global_load_lds_dwordx4 v[0:1], off
	s_add_i32 m0, s22, 0x1c000
	v_lshl_add_u64 v[0:1], s[2:3], 0, v[128:129]
	global_load_lds_dwordx4 v128, s[2:3]
	v_lshl_add_u64 v[0:1], s[2:3], 0, v[130:131]
	s_add_i32 m0, s22, 0x1e000
	s_cmpk_lt_u32 s45, 0x100
	global_load_lds_dwordx4 v130, s[2:3]
	v_lshlrev_b32_e32 v0, 15, v8
	v_and_b32_e32 v0, 0xffff0000, v0
	v_lshl_add_u32 v0, v9, 12, v0
	v_and_b32_e32 v1, 1, v8
	v_lshl_or_b32 v0, v1, 6, v0
	v_lshl_add_u32 v136, v10, 1, v0
	v_lshlrev_b32_e32 v0, 15, v12
	v_and_b32_e32 v0, 0xffff0000, v0
	s_waitcnt vmcnt(6)
	s_mov_b32 s98, 0
	s_cselect_b64 s[60:61], -1, 0
	s_and_b32 s2, s15, 0x400
	v_lshl_add_u32 v0, v11, 12, v0
	v_and_b32_e32 v1, 1, v12
	v_bitop3_b32 v16, v15, s47, v14 bitop3:0xde
	s_bfe_u32 s45, s46, 0x10001
	s_or_b32 s46, s2, s47
	v_mov_b32_e32 v137, 0
	v_lshl_or_b32 v0, v1, 6, v0
	s_add_i32 s47, 0, 0x10000
	s_add_i32 s48, 0, 0x14000
	v_lshl_add_u32 v138, v13, 1, v0
	v_mov_b32_e32 v139, v137
	v_mov_b64_e32 v[140:141], 0x200
	v_mov_b64_e32 v[142:143], 0x1ff
	v_add_u32_e32 v145, s47, v144
	v_add_u32_e32 v146, s48, v144
	v_add_u32_e32 v147, 0, v16
	s_mov_b64 s[62:63], 0x100
	s_mov_b64 s[64:65], 0x180
	s_barrier
	s_branch .LBB0_1946

; template <class Epi, class Sched, bool ALIGN_EPI = false, bool SP2 = false, bool A_TILED = false>
; __device__ __forceinline__ void gemm_phase(PG8_LAS unsigned char* lds, const Gemm g, const Sched& S, const Epi& E, const int wave_s) {
;     ...
;         const bool has_next = Epi::AFTER_DRAIN ? false : S.next(ui + 1, nxt);
;         const char* nA = has_next ? (const char*)g.A + (size_t)nxt.pm * tstepA : cA; const char* nB = has_next ? (const char*)g.Bt + (size_t)nxt.pn * tstep : cB;
;         constexpr bool PEEL = SP2 && !Epi::AFTER_DRAIN;
;         if constexpr (PEEL) {
;             const char* a1 = cA + kstepA; const char* a2 = cA + 2 * kstepA; const char* b2 = cB + 2 * kstep; const char* a3 = a2 + kstepA; const char* b3 = b2 + kstep;
;             PG8_ITER(PG8_MMAZ)
.LBB0_1952:
	s_ashr_i32 s69, s68, 31
	s_lshl_b64 s[50:51], s[68:69], 20
	s_add_u32 s70, s1, s50
	ds_read_b128 v[0:3], v145
	ds_read_b128 v[4:7], v145 offset:1024
	ds_read_b128 v[8:11], v145 offset:2048
	ds_read_b128 v[12:15], v145 offset:3072
	ds_read_b128 v[16:19], v146
	ds_read_b128 v[20:23], v146 offset:1024
	ds_read_b128 v[24:27], v146 offset:2048
	ds_read_b128 v[28:31], v146 offset:3072
	s_addc_u32 s71, s8, s51
	s_ashr_i32 s67, s66, 31
	s_lshl_b64 s[50:51], s[66:67], 20
	s_add_u32 s72, s9, s50
	s_addc_u32 s73, s14, s51
	s_and_b64 s[50:51], s[2:3], exec
	s_cselect_b32 s50, s71, s79
	s_cselect_b32 s51, s70, s78
	s_cselect_b32 s52, s73, s77
	s_cselect_b32 s53, s72, s76
	s_add_u32 s56, s78, 0x80080
	s_addc_u32 s57, s79, 0
	s_add_i32 s54, s22, 0xc000
	v_lshl_add_u64 v[64:65], s[56:57], 0, v[134:135]
	s_mov_b32 m0, s54
	s_add_i32 s55, s22, 0xe000
	ds_read_b128 v[32:35], v147
	ds_read_b128 v[36:39], v147 offset:1024
	ds_read_b128 v[40:43], v147 offset:2048
	ds_read_b128 v[44:47], v147 offset:3072
	ds_read_b128 v[48:51], v147 offset:4096
	ds_read_b128 v[52:55], v147 offset:5120
	ds_read_b128 v[56:59], v147 offset:6144
	ds_read_b128 v[60:63], v147 offset:7168
	global_load_lds_dwordx4 v134, s[56:57]
	v_lshl_add_u64 v[64:65], s[56:57], 0, v[132:133]
	s_mov_b32 m0, s55
	s_nop 0
	global_load_lds_dwordx4 v132, s[56:57]
	s_waitcnt vmcnt(24) lgkmcnt(0)
	s_cmp_lg_u32 s98, 0
	s_cbranch_scc1 .Lpw_7
	s_waitcnt vmcnt(8)

.Lpw_8:
	s_setprio 1
	s_barrier
	v_mfma_f32_16x16x32_bf16 v[148:151], v[0:3], v[60:63], 0
	v_mfma_f32_16x16x32_bf16 v[158:161], v[0:3], v[92:95], 0
	v_mfma_f32_16x16x32_bf16 v[166:169], v[0:3], v[108:111], 0
	v_mfma_f32_16x16x32_bf16 v[0:3], v[0:3], v[120:123], 0
	v_mfma_f32_16x16x32_bf16 v[150:153], v[4:7], v[88:91], v[148:151]
	v_mfma_f32_16x16x32_bf16 v[158:161], v[4:7], v[104:107], v[158:161]
	v_mfma_f32_16x16x32_bf16 v[166:169], v[4:7], v[116:119], v[166:169]
	v_mfma_f32_16x16x32_bf16 v[0:3], v[4:7], v[124:127], v[0:3]
	v_mfma_f32_16x16x32_bf16 v[4:7], v[8:11], v[120:123], 0
	v_mfma_f32_16x16x32_bf16 v[154:157], v[8:11], v[60:63], 0
	v_mfma_f32_16x16x32_bf16 v[162:165], v[8:11], v[92:95], 0
	v_mfma_f32_16x16x32_bf16 v[170:173], v[8:11], v[108:111], 0
	v_mfma_f32_16x16x32_bf16 v[4:7], v[12:15], v[124:127], v[4:7]
	v_mfma_f32_16x16x32_bf16 v[154:157], v[12:15], v[88:91], v[154:157]
	v_mfma_f32_16x16x32_bf16 v[162:165], v[12:15], v[104:107], v[162:165]
	v_mfma_f32_16x16x32_bf16 v[170:173], v[12:15], v[116:119], v[170:173]
	s_setprio 0
	s_setprio 1
	v_mfma_f32_16x16x32_bf16 v[8:11], v[16:19], v[60:63], 0
	v_mfma_f32_16x16x32_bf16 v[174:177], v[20:23], v[88:91], v[8:11]
	v_mfma_f32_16x16x32_bf16 v[8:11], v[24:27], v[60:63], 0
	v_mfma_f32_16x16x32_bf16 v[60:63], v[28:31], v[88:91], v[8:11]
	v_mfma_f32_16x16x32_bf16 v[8:11], v[16:19], v[92:95], 0
	v_mfma_f32_16x16x32_bf16 v[178:181], v[20:23], v[104:107], v[8:11]
	v_mfma_f32_16x16x32_bf16 v[8:11], v[24:27], v[92:95], 0
	v_mfma_f32_16x16x32_bf16 v[182:185], v[28:31], v[104:107], v[8:11]
	v_mfma_f32_16x16x32_bf16 v[8:11], v[16:19], v[108:111], 0
	v_mfma_f32_16x16x32_bf16 v[186:189], v[20:23], v[116:119], v[8:11]
	v_mfma_f32_16x16x32_bf16 v[8:11], v[24:27], v[108:111], 0
	v_mfma_f32_16x16x32_bf16 v[190:193], v[28:31], v[116:119], v[8:11]
	v_mfma_f32_16x16x32_bf16 v[8:11], v[16:19], v[120:123], 0
	v_mfma_f32_16x16x32_bf16 v[194:197], v[20:23], v[124:127], v[8:11]
	v_mfma_f32_16x16x32_bf16 v[8:11], v[24:27], v[120:123], 0
	v_mfma_f32_16x16x32_bf16 v[198:201], v[28:31], v[124:127], v[8:11]
	s_barrier
	s_setprio 0
	s_add_i32 s67, 0, 0x18000
	s_add_i32 s75, 0, 0x1c000
	v_add_u32_e32 v148, s67, v144
	v_add_u32_e32 v149, s75, v144
	s_nop 0
	ds_read_b128 v[8:11], v148
	ds_read_b128 v[12:15], v148 offset:1024
	ds_read_b128 v[16:19], v148 offset:2048
	ds_read_b128 v[20:23], v148 offset:3072
	ds_read_b128 v[202:205], v149
	ds_read_b128 v[206:209], v149 offset:1024
	ds_read_b128 v[210:213], v149 offset:2048
	ds_read_b128 v[214:217], v149 offset:3072
	s_add_u32 s80, s78, 0x80100
	s_addc_u32 s81, s79, 0
	s_mov_b32 m0, s36
	v_lshl_add_u64 v[88:89], s[80:81], 0, v[134:135]
	ds_read_b128 v[24:27], v147 offset:32768
	ds_read_b128 v[28:31], v147 offset:33792
	ds_read_b128 v[218:221], v147 offset:34816
	ds_read_b128 v[222:225], v147 offset:35840
	ds_read_b128 v[226:229], v147 offset:36864
	ds_read_b128 v[230:233], v147 offset:37888
	ds_read_b128 v[234:237], v147 offset:38912
	ds_read_b128 v[238:241], v147 offset:39936
	global_load_lds_dwordx4 v134, s[80:81]
	v_lshl_add_u64 v[88:89], s[80:81], 0, v[132:133]
	s_mov_b32 m0, s37
	s_nop 0
	global_load_lds_dwordx4 v132, s[80:81]
	s_waitcnt vmcnt(8) lgkmcnt(0)
	s_setprio 1
	s_barrier
	v_mfma_f32_16x16x32_bf16 v[64:67], v[8:11], v[24:27], v[64:67]
	v_mfma_f32_16x16x32_bf16 v[120:123], v[12:15], v[28:31], v[64:67]
	v_mfma_f32_16x16x32_bf16 v[64:67], v[16:19], v[24:27], v[68:71]
	v_mfma_f32_16x16x32_bf16 v[124:127], v[20:23], v[28:31], v[64:67]
	v_mfma_f32_16x16x32_bf16 v[64:67], v[8:11], v[218:221], v[72:75]
	v_mfma_f32_16x16x32_bf16 v[104:107], v[12:15], v[222:225], v[64:67]
	v_mfma_f32_16x16x32_bf16 v[64:67], v[16:19], v[218:221], v[76:79]
	v_mfma_f32_16x16x32_bf16 v[108:111], v[20:23], v[222:225], v[64:67]
	v_mfma_f32_16x16x32_bf16 v[64:67], v[8:11], v[226:229], v[80:83]
	v_mfma_f32_16x16x32_bf16 v[88:91], v[12:15], v[230:233], v[64:67]
	v_mfma_f32_16x16x32_bf16 v[64:67], v[16:19], v[226:229], v[84:87]
	v_mfma_f32_16x16x32_bf16 v[92:95], v[20:23], v[230:233], v[64:67]
	v_mfma_f32_16x16x32_bf16 v[64:67], v[8:11], v[234:237], v[96:99]
	v_mfma_f32_16x16x32_bf16 v[68:71], v[16:19], v[234:237], v[100:103]
	v_mfma_f32_16x16x32_bf16 v[64:67], v[12:15], v[238:241], v[64:67]
	v_mfma_f32_16x16x32_bf16 v[68:71], v[20:23], v[238:241], v[68:71]
	s_setprio 0
	s_setprio 1
	v_mfma_f32_16x16x32_bf16 v[72:75], v[202:205], v[24:27], v[112:115]
	v_mfma_f32_16x16x32_bf16 v[24:27], v[210:213], v[24:27], v[32:35]
	v_mfma_f32_16x16x32_bf16 v[116:119], v[214:217], v[28:31], v[24:27]
	v_mfma_f32_16x16x32_bf16 v[24:27], v[202:205], v[218:221], v[36:39]
	v_mfma_f32_16x16x32_bf16 v[96:99], v[206:209], v[222:225], v[24:27]
	v_mfma_f32_16x16x32_bf16 v[24:27], v[210:213], v[218:221], v[40:43]
	v_mfma_f32_16x16x32_bf16 v[100:103], v[214:217], v[222:225], v[24:27]
	v_mfma_f32_16x16x32_bf16 v[24:27], v[202:205], v[226:229], v[44:47]
	v_mfma_f32_16x16x32_bf16 v[80:83], v[206:209], v[230:233], v[24:27]
	v_mfma_f32_16x16x32_bf16 v[24:27], v[210:213], v[226:229], v[48:51]
	v_mfma_f32_16x16x32_bf16 v[84:87], v[214:217], v[230:233], v[24:27]
	v_mfma_f32_16x16x32_bf16 v[24:27], v[202:205], v[234:237], v[52:55]
	v_mfma_f32_16x16x32_bf16 v[48:51], v[206:209], v[238:241], v[24:27]
	v_mfma_f32_16x16x32_bf16 v[24:27], v[210:213], v[234:237], v[56:59]
	v_mfma_f32_16x16x32_bf16 v[112:115], v[206:209], v[28:31], v[72:75]
	v_mfma_f32_16x16x32_bf16 v[52:55], v[214:217], v[238:241], v[24:27]
	s_barrier
; template <class Epi, class Sched, bool ALIGN_EPI = false, bool SP2 = false, bool A_TILED = false>
; __device__ __forceinline__ void gemm_phase(PG8_LAS unsigned char* lds, const Gemm g, const Sched& S, const Epi& E, const int wave_s) {
;     ...
;         for (int t = PEEL ? 2 : 0; t < nt; t += 2) {
;             const bool last = (t == nt - 2);
;             const char* a1 = cA + (size_t)(t + 1) * kstepA;
;             const char* a2 = last ? nA : cA + (size_t)(t + 2) * kstepA; const char* b2 = last ? nB : cB + (size_t)(t + 2) * kstep;
;             const char* a3 = a2 + kstepA; const char* b3 = b2 + kstep;
	s_setprio 0
	s_add_i32 s67, s67, s15
	s_add_i32 s69, s67, 0x2000
	s_nop 1
	v_lshl_add_u64 v[24:25], v[242:243], 0, s[64:65]
	s_mov_b32 m0, s67
	s_add_u32 s80, s76, 0x80180
	ds_read_b128 v[32:35], v147 offset:49152
	ds_read_b128 v[36:39], v147 offset:50176
	ds_read_b128 v[218:221], v147 offset:51200
	ds_read_b128 v[222:225], v147 offset:52224
	ds_read_b128 v[226:229], v147 offset:53248
	ds_read_b128 v[230:233], v147 offset:54272
	ds_read_b128 v[234:237], v147 offset:55296
	ds_read_b128 v[238:241], v147 offset:56320
	global_load_lds_dwordx4 v[24:25], off
	v_lshl_add_u64 v[24:25], v[244:245], 0, s[64:65]
	s_mov_b32 m0, s69
	s_addc_u32 s81, s77, 0
	s_add_i32 s75, s75, s15
	global_load_lds_dwordx4 v[24:25], off
	v_lshl_add_u64 v[24:25], s[80:81], 0, v[128:129]
	s_mov_b32 m0, s75
	s_add_i32 s82, s75, 0x2000
	global_load_lds_dwordx4 v128, s[80:81]
	v_lshl_add_u64 v[24:25], s[80:81], 0, v[130:131]
	s_mov_b32 m0, s82
	s_nop 0
	global_load_lds_dwordx4 v130, s[80:81]
	v_lshl_add_u64 v[24:25], v[246:247], 0, s[64:65]
	s_mov_b32 m0, s43
	s_nop 0
	global_load_lds_dwordx4 v[24:25], off
	v_lshl_add_u64 v[24:25], v[248:249], 0, s[64:65]
	s_mov_b32 m0, s44
	s_nop 0
	global_load_lds_dwordx4 v[24:25], off
	s_waitcnt vmcnt(8) lgkmcnt(0)
	s_setprio 1
	s_barrier
	v_mfma_f32_16x16x32_bf16 v[24:27], v[8:11], v[32:35], v[150:153]
	v_mfma_f32_16x16x32_bf16 v[72:75], v[12:15], v[36:39], v[24:27]
	v_mfma_f32_16x16x32_bf16 v[24:27], v[16:19], v[32:35], v[154:157]
	v_mfma_f32_16x16x32_bf16 v[76:79], v[20:23], v[36:39], v[24:27]
	v_mfma_f32_16x16x32_bf16 v[24:27], v[8:11], v[218:221], v[158:161]
	v_mfma_f32_16x16x32_bf16 v[40:43], v[12:15], v[222:225], v[24:27]
	v_mfma_f32_16x16x32_bf16 v[24:27], v[16:19], v[218:221], v[162:165]
	v_mfma_f32_16x16x32_bf16 v[0:3], v[8:11], v[234:237], v[0:3]
	v_mfma_f32_16x16x32_bf16 v[44:47], v[20:23], v[222:225], v[24:27]
	v_mfma_f32_16x16x32_bf16 v[24:27], v[8:11], v[226:229], v[166:169]
	v_mfma_f32_16x16x32_bf16 v[28:31], v[16:19], v[226:229], v[170:173]
	v_mfma_f32_16x16x32_bf16 v[8:11], v[12:15], v[238:241], v[0:3]
	v_mfma_f32_16x16x32_bf16 v[0:3], v[16:19], v[234:237], v[4:7]
	v_mfma_f32_16x16x32_bf16 v[24:27], v[12:15], v[230:233], v[24:27]
	v_mfma_f32_16x16x32_bf16 v[28:31], v[20:23], v[230:233], v[28:31]
	v_mfma_f32_16x16x32_bf16 v[12:15], v[20:23], v[238:241], v[0:3]
	s_setprio 0
	s_setprio 1
	v_mfma_f32_16x16x32_bf16 v[0:3], v[202:205], v[32:35], v[174:177]
	v_mfma_f32_16x16x32_bf16 v[56:59], v[206:209], v[36:39], v[0:3]
	v_mfma_f32_16x16x32_bf16 v[0:3], v[210:213], v[32:35], v[60:63]
	v_mfma_f32_16x16x32_bf16 v[60:63], v[214:217], v[36:39], v[0:3]
	v_mfma_f32_16x16x32_bf16 v[0:3], v[202:205], v[218:221], v[178:181]
	v_mfma_f32_16x16x32_bf16 v[32:35], v[206:209], v[222:225], v[0:3]
	v_mfma_f32_16x16x32_bf16 v[0:3], v[210:213], v[218:221], v[182:185]
	v_mfma_f32_16x16x32_bf16 v[36:39], v[214:217], v[222:225], v[0:3]
	v_mfma_f32_16x16x32_bf16 v[0:3], v[202:205], v[226:229], v[186:189]
	v_mfma_f32_16x16x32_bf16 v[16:19], v[206:209], v[230:233], v[0:3]
	v_mfma_f32_16x16x32_bf16 v[0:3], v[210:213], v[226:229], v[190:193]
	v_mfma_f32_16x16x32_bf16 v[20:23], v[214:217], v[230:233], v[0:3]
	v_mfma_f32_16x16x32_bf16 v[0:3], v[202:205], v[234:237], v[194:197]
	v_mfma_f32_16x16x32_bf16 v[4:7], v[210:213], v[234:237], v[198:201]
	v_mfma_f32_16x16x32_bf16 v[0:3], v[206:209], v[238:241], v[0:3]
	v_mfma_f32_16x16x32_bf16 v[4:7], v[214:217], v[238:241], v[4:7]
	s_barrier
	s_setprio 0
	s_add_u32 s83, s76, 0x200
	s_addc_u32 s85, s77, 0
	s_add_u32 s76, s78, 0x80180
	s_addc_u32 s77, s79, 0
	s_mov_b32 s88, 0

;     __device__ __forceinline__ void operator()(const f32x4 (&acc)[2][2][4][2], const Unit& u, int wr, int wc, int fr, int fq) const {
;     ...
;         for (int ai = 0; ai < 2; ++ai)
; #pragma unroll
;             for (int m = 0; m < 4; ++m) { bf16_t* rowp = O + (size_t)(row0 + ai * HALF + m * 16) * ldc + col0;
;                 if (ACT == 1) {
;                     const int ob = fr * 64 + 16 * fq, sw = ob ^ (((ob >> 9) & 1) << 5);
;                     rowp = O + ((size_t)(u.pm * (ldc / 64) + u.pn * 4 + (wc >> 1)) * 2 + ai) * 8192 + (((wr * 4 + m) * 2 + (wc & 1)) * 1024 + sw) / 2; }
;                 float rc[2][2], rs[2][2];
;                 if (ACT == 2) { const float pos = (float)((row0 + ai * HALF + m * 16) & 2047);
; #pragma unroll
;                     for (int n = 0; n < 2; ++n)
; #pragma unroll
;                         for (int e = 0; e < 2; ++e) { float r = pos * rinv[n][e]; r -= floorf(r); rs[n][e] = do_rope ? __builtin_amdgcn_sinf(r) : 0.f; rc[n][e] = do_rope ? __builtin_amdgcn_cosf(r) : 1.f; } }
; #pragma unroll
;                 for (int bj = 0; bj < 2; ++bj) { f32x4 v0 = acc[ai][bj][m][0], v1 = acc[ai][bj][m][1];
;                     if (ACT == 3) { const float pos = (float)((row0 + ai * HALF + m * 16) & 2047); float c3[4], s3[4];
; #pragma unroll
;                         for (int p = 0; p < 4; ++p) { float r = pos * rinv3[bj][p]; r -= floorf(r); s3[p] = rope3[bj] ? __builtin_amdgcn_sinf(r) : 0.f; c3[p] = rope3[bj] ? __builtin_amdgcn_cosf(r) : 1.f; }
;                         const f32x4 a = v0, b = v1;
;                         v0[0] = a[0] * c3[0] - a[1] * s3[0]; v0[1] = a[1] * c3[0] + a[0] * s3[0]; v0[2] = a[2] * c3[1] - a[3] * s3[1]; v0[3] = a[3] * c3[1] + a[2] * s3[1];
;                         v1[0] = b[0] * c3[2] - b[1] * s3[2]; v1[1] = b[1] * c3[2] + b[0] * s3[2]; v1[2] = b[2] * c3[3] - b[3] * s3[3]; v1[3] = b[3] * c3[3] + b[2] * s3[3]; }
;                     if (ACT == 2) { const f32x4 a = v0, b = v1;
;                         v0[0] = a[0] * rc[0][0] - a[1] * rs[0][0]; v0[1] = a[1] * rc[0][0] + a[0] * rs[0][0]; v0[2] = a[2] * rc[0][1] - a[3] * rs[0][1]; v0[3] = a[3] * rc[0][1] + a[2] * rs[0][1];
;                         v1[0] = b[0] * rc[1][0] - b[1] * rs[1][0]; v1[1] = b[1] * rc[1][0] + b[0] * rs[1][0]; v1[2] = b[2] * rc[1][1] - b[3] * rs[1][1]; v1[3] = b[3] * rc[1][1] + b[2] * rs[1][1]; }
;                     if (ACT == 1) {
.LBB0_1956:
	v_mov_b32_e32 v148, 0
	s_lshl_b32 s49, s49, 2
	v_mbcnt_lo_u32_b32 v148, -1, v148
	v_mbcnt_hi_u32_b32 v148, -1, v148
	v_or_b32_e32 v148, s33, v148
	s_or_b32 s49, s49, s45
	v_and_b32_e32 v149, 15, v148
	v_and_b32_e32 v150, 48, v148
	v_lshlrev_b32_e32 v148, 2, v148
	s_lshl_b32 s50, s74, 7
	v_lshl_or_b32 v149, v149, 6, v150
	v_and_b32_e32 v148, 32, v148
	s_add_i32 s50, s49, s50
	s_ashr_i32 s51, s50, 31
	v_bitop3_b32 v148, v149, s46, v148 bitop3:0xde
	s_lshl_b64 s[50:51], s[50:51], 15
	v_ashrrev_i32_e32 v148, 1, v148
	s_add_u32 s74, s41, s50
	v_ashrrev_i32_e32 v149, 31, v148
	s_addc_u32 s75, s42, s51
	v_lshlrev_b64 v[150:151], 1, v[148:149]
	v_max_i32_e32 v120, 0, v120
	v_max_i32_e32 v121, 0, v121
	v_max_i32_e32 v122, 0, v122
	v_max_i32_e32 v123, 0, v123
	v_max_i32_e32 v112, 0, v112
	v_max_i32_e32 v116, 0, v116
	v_max_i32_e32 v113, 0, v113
	v_max_i32_e32 v114, 0, v114
	v_lshl_add_u64 v[152:153], s[74:75], 0, v[150:151]
	v_max_i32_e32 v124, 0, v124
	v_mul_f32_e32 v120, v120, v120
	v_max_i32_e32 v125, 0, v125
	v_mul_f32_e32 v121, v121, v121
	v_max_i32_e32 v126, 0, v126
	v_mul_f32_e32 v122, v122, v122
	v_max_i32_e32 v127, 0, v127
	v_mul_f32_e32 v123, v123, v123
	v_mul_f32_e32 v112, v112, v112
	v_mul_f32_e32 v116, v116, v116
	v_max_i32_e32 v117, 0, v117
	v_mul_f32_e32 v113, v113, v113
	v_mul_f32_e32 v114, v114, v114
	v_max_i32_e32 v115, 0, v115
	v_mul_f32_e32 v124, v124, v124
	v_mul_f32_e32 v125, v125, v125
	v_mul_f32_e32 v126, v126, v126
	v_mul_f32_e32 v127, v127, v127
	v_cvt_pk_bf16_f32 v120, v120, v121
	v_cvt_pk_bf16_f32 v121, v122, v123
	v_cvt_pk_bf16_f32 v122, v124, v125
	v_cvt_pk_bf16_f32 v123, v126, v127
	global_store_dwordx4 v[152:153], v[120:123], off
	v_mul_f32_e32 v117, v117, v117
	v_mul_f32_e32 v115, v115, v115
	v_cvt_pk_bf16_f32 v112, v112, v113
	v_cvt_pk_bf16_f32 v113, v114, v115
	v_cvt_pk_bf16_f32 v114, v116, v117
	v_add_co_u32_e32 v116, vcc, s39, v152
	v_max_i32_e32 v104, 0, v104
	v_max_i32_e32 v105, 0, v105
	v_max_i32_e32 v106, 0, v106
	v_max_i32_e32 v107, 0, v107
	v_max_i32_e32 v96, 0, v96
	v_max_i32_e32 v118, 0, v118
	v_max_i32_e32 v119, 0, v119
	v_addc_co_u32_e32 v117, vcc, 0, v153, vcc
	v_max_i32_e32 v108, 0, v108
	v_mul_f32_e32 v104, v104, v104
	v_max_i32_e32 v109, 0, v109
	v_mul_f32_e32 v105, v105, v105
	v_max_i32_e32 v110, 0, v110
	v_mul_f32_e32 v106, v106, v106
	v_max_i32_e32 v111, 0, v111
	v_mul_f32_e32 v107, v107, v107
	v_mul_f32_e32 v96, v96, v96
	v_max_i32_e32 v97, 0, v97
	v_max_i32_e32 v98, 0, v98
	v_max_i32_e32 v99, 0, v99
	v_mul_f32_e32 v118, v118, v118
	v_mul_f32_e32 v119, v119, v119
	v_cvt_pk_bf16_f32 v115, v118, v119
	global_store_dwordx4 v[116:117], v[112:115], off
	v_mul_f32_e32 v108, v108, v108
	v_mul_f32_e32 v109, v109, v109
	v_mul_f32_e32 v110, v110, v110
	v_mul_f32_e32 v111, v111, v111
	v_cvt_pk_bf16_f32 v104, v104, v105
	v_cvt_pk_bf16_f32 v105, v106, v107
	v_cvt_pk_bf16_f32 v106, v108, v109
	v_cvt_pk_bf16_f32 v107, v110, v111
	global_store_dwordx4 v[152:153], v[104:107], off offset:2048
	v_max_i32_e32 v100, 0, v100
	v_max_i32_e32 v101, 0, v101
	v_mul_f32_e32 v97, v97, v97
	v_max_i32_e32 v102, 0, v102
	v_mul_f32_e32 v98, v98, v98
	v_max_i32_e32 v103, 0, v103
	v_mul_f32_e32 v99, v99, v99
	v_cvt_pk_bf16_f32 v96, v96, v97
	v_mul_f32_e32 v100, v100, v100
	v_mul_f32_e32 v101, v101, v101
	v_mul_f32_e32 v102, v102, v102
	v_mul_f32_e32 v103, v103, v103
	v_cvt_pk_bf16_f32 v97, v98, v99
	v_cvt_pk_bf16_f32 v98, v100, v101
	v_cvt_pk_bf16_f32 v99, v102, v103
	global_store_dwordx4 v[116:117], v[96:99], off offset:2048
	v_max_i32_e32 v88, 0, v88
	v_max_i32_e32 v89, 0, v89
	v_or_b32_e32 v96, 0x800, v148
	v_ashrrev_i32_e32 v97, 31, v96
	v_lshlrev_b64 v[96:97], 1, v[96:97]
	v_max_i32_e32 v90, 0, v90
	v_max_i32_e32 v91, 0, v91
	v_max_i32_e32 v80, 0, v80
	v_max_i32_e32 v84, 0, v84
	v_max_i32_e32 v81, 0, v81
	v_max_i32_e32 v82, 0, v82
	v_lshl_add_u64 v[98:99], s[74:75], 0, v[96:97]
	v_max_i32_e32 v92, 0, v92
	v_mul_f32_e32 v88, v88, v88
	v_max_i32_e32 v93, 0, v93
	v_mul_f32_e32 v89, v89, v89
	v_max_i32_e32 v94, 0, v94
	v_mul_f32_e32 v90, v90, v90
	v_max_i32_e32 v95, 0, v95
	v_mul_f32_e32 v91, v91, v91
	v_mul_f32_e32 v80, v80, v80
	v_mul_f32_e32 v84, v84, v84
	v_max_i32_e32 v85, 0, v85
	v_mul_f32_e32 v81, v81, v81
	v_mul_f32_e32 v82, v82, v82
	v_max_i32_e32 v83, 0, v83
	v_mul_f32_e32 v92, v92, v92
	v_mul_f32_e32 v93, v93, v93
	v_mul_f32_e32 v94, v94, v94
	v_mul_f32_e32 v95, v95, v95
	v_cvt_pk_bf16_f32 v88, v88, v89
	v_cvt_pk_bf16_f32 v89, v90, v91
	v_cvt_pk_bf16_f32 v90, v92, v93
	v_cvt_pk_bf16_f32 v91, v94, v95
	global_store_dwordx4 v[98:99], v[88:91], off
	v_mul_f32_e32 v85, v85, v85
	v_mul_f32_e32 v83, v83, v83
	v_cvt_pk_bf16_f32 v80, v80, v81
	v_cvt_pk_bf16_f32 v81, v82, v83
	v_cvt_pk_bf16_f32 v82, v84, v85
	v_add_co_u32_e32 v84, vcc, s39, v98
	v_max_i32_e32 v86, 0, v86
	v_max_i32_e32 v87, 0, v87
	v_addc_co_u32_e32 v85, vcc, 0, v99, vcc
	v_mul_f32_e32 v86, v86, v86
	v_mul_f32_e32 v87, v87, v87
	v_cvt_pk_bf16_f32 v83, v86, v87
	global_store_dwordx4 v[84:85], v[80:83], off
	v_max_i32_e32 v64, 0, v64
	v_max_i32_e32 v65, 0, v65
	v_or_b32_e32 v80, 0xc00, v148
	v_ashrrev_i32_e32 v81, 31, v80
	v_lshlrev_b64 v[80:81], 1, v[80:81]
	v_max_i32_e32 v66, 0, v66
	v_max_i32_e32 v67, 0, v67
	v_max_i32_e32 v48, 0, v48
	v_max_i32_e32 v52, 0, v52
	v_max_i32_e32 v49, 0, v49
	v_max_i32_e32 v50, 0, v50
	v_lshl_add_u64 v[82:83], s[74:75], 0, v[80:81]
	v_max_i32_e32 v68, 0, v68
	v_mul_f32_e32 v64, v64, v64
	v_max_i32_e32 v69, 0, v69
	v_mul_f32_e32 v65, v65, v65
	v_max_i32_e32 v70, 0, v70
	v_mul_f32_e32 v66, v66, v66
	v_max_i32_e32 v71, 0, v71
	v_mul_f32_e32 v67, v67, v67
	v_mul_f32_e32 v48, v48, v48
	v_mul_f32_e32 v52, v52, v52
; #define PG8_BAR __builtin_amdgcn_s_barrier()
;     __device__ __forceinline__ void operator()(const f32x4 (&acc)[2][2][4][2], const Unit& u, int wr, int wc, int fr, int fq) const {
;     ...
;                 for (int bj = 0; bj < 2; ++bj) { f32x4 v0 = acc[ai][bj][m][0], v1 = acc[ai][bj][m][1];
;                     if (ACT == 3) { const float pos = (float)((row0 + ai * HALF + m * 16) & 2047); float c3[4], s3[4];
; #pragma unroll
;                         for (int p = 0; p < 4; ++p) { float r = pos * rinv3[bj][p]; r -= floorf(r); s3[p] = rope3[bj] ? __builtin_amdgcn_sinf(r) : 0.f; c3[p] = rope3[bj] ? __builtin_amdgcn_cosf(r) : 1.f; }
;                         const f32x4 a = v0, b = v1;
;                         v0[0] = a[0] * c3[0] - a[1] * s3[0]; v0[1] = a[1] * c3[0] + a[0] * s3[0]; v0[2] = a[2] * c3[1] - a[3] * s3[1]; v0[3] = a[3] * c3[1] + a[2] * s3[1];
;                         v1[0] = b[0] * c3[2] - b[1] * s3[2]; v1[1] = b[1] * c3[2] + b[0] * s3[2]; v1[2] = b[2] * c3[3] - b[3] * s3[3]; v1[3] = b[3] * c3[3] + b[2] * s3[3]; }
;                     if (ACT == 2) { const f32x4 a = v0, b = v1;
;                         v0[0] = a[0] * rc[0][0] - a[1] * rs[0][0]; v0[1] = a[1] * rc[0][0] + a[0] * rs[0][0]; v0[2] = a[2] * rc[0][1] - a[3] * rs[0][1]; v0[3] = a[3] * rc[0][1] + a[2] * rs[0][1];
;                         v1[0] = b[0] * rc[1][0] - b[1] * rs[1][0]; v1[1] = b[1] * rc[1][0] + b[0] * rs[1][0]; v1[2] = b[2] * rc[1][1] - b[3] * rs[1][1]; v1[3] = b[3] * rc[1][1] + b[2] * rs[1][1]; }
;                     if (ACT == 1) {
; #pragma unroll
;                         for (int j = 0; j < 4; ++j) { const float a = __int_as_float(max(__float_as_int(v0[j]), 0)), b = __int_as_float(max(__float_as_int(v1[j]), 0)); v0[j] = a * a; v1[j] = b * b; } }
;                     u32x4 w; w.x = cvt_pk_bf16(v0[0], v0[1]); w.y = cvt_pk_bf16(v0[2], v0[3]); w.z = cvt_pk_bf16(v1[0], v1[1]); w.w = cvt_pk_bf16(v1[2], v1[3]);
;                     *(u32x4*)(rowp + (ACT == 1 ? bj * 2 * 2 * 8192 : bj * HALF)) = w; } }
; template <class Epi, class Sched, bool ALIGN_EPI = false, bool SP2 = false, bool A_TILED = false>
; __device__ __forceinline__ void gemm_phase(PG8_LAS unsigned char* lds, const Gemm g, const Sched& S, const Epi& E, const int wave_s) {
;     ...
;         if (!has_next) break;
;         cur = nxt; cA = nA; cB = nB; ++ui;
;         if constexpr (ALIGN_EPI) { if (wr == 1) PG8_BAR; }
	v_max_i32_e32 v53, 0, v53
	v_mul_f32_e32 v49, v49, v49
	v_mul_f32_e32 v50, v50, v50
	v_max_i32_e32 v51, 0, v51
	v_mul_f32_e32 v68, v68, v68
	v_mul_f32_e32 v69, v69, v69
	v_mul_f32_e32 v70, v70, v70
	v_mul_f32_e32 v71, v71, v71
	v_cvt_pk_bf16_f32 v64, v64, v65
	v_cvt_pk_bf16_f32 v65, v66, v67
	v_cvt_pk_bf16_f32 v66, v68, v69
	v_cvt_pk_bf16_f32 v67, v70, v71
	global_store_dwordx4 v[82:83], v[64:67], off
	v_mul_f32_e32 v53, v53, v53
	v_mul_f32_e32 v51, v51, v51
	v_cvt_pk_bf16_f32 v48, v48, v49
	v_cvt_pk_bf16_f32 v49, v50, v51
	v_cvt_pk_bf16_f32 v50, v52, v53
	v_add_co_u32_e32 v52, vcc, s39, v82
	v_max_i32_e32 v54, 0, v54
	v_max_i32_e32 v55, 0, v55
	v_addc_co_u32_e32 v53, vcc, 0, v83, vcc
	v_mul_f32_e32 v54, v54, v54
	v_mul_f32_e32 v55, v55, v55
	v_cvt_pk_bf16_f32 v51, v54, v55
	global_store_dwordx4 v[52:53], v[48:51], off
	s_add_u32 s74, s74, 0x4000
	s_addc_u32 s75, s75, 0
	v_max_i32_e32 v49, 0, v76
	v_max_i32_e32 v48, 0, v72
	v_mul_f32_e32 v50, v49, v49
	v_max_i32_e32 v49, 0, v73
	v_mul_f32_e32 v48, v48, v48
	v_max_i32_e32 v51, 0, v77
	v_mul_f32_e32 v49, v49, v49
	v_max_i32_e32 v54, 0, v74
	v_max_i32_e32 v64, 0, v75
	v_lshl_add_u64 v[52:53], s[74:75], 0, v[150:151]
	v_mul_f32_e32 v51, v51, v51
	v_max_i32_e32 v55, 0, v78
	v_mul_f32_e32 v54, v54, v54
	v_max_i32_e32 v65, 0, v79
	v_mul_f32_e32 v64, v64, v64
	v_cvt_pk_bf16_f32 v48, v48, v49
	v_cvt_pk_bf16_f32 v49, v54, v64
	v_mul_f32_e32 v55, v55, v55
	v_mul_f32_e32 v65, v65, v65
	v_cvt_pk_bf16_f32 v50, v50, v51
	v_cvt_pk_bf16_f32 v51, v55, v65
	global_store_dwordx4 v[52:53], v[48:51], off
	v_or_b32_e32 v112, 0x400, v148
	v_max_i32_e32 v54, 0, v58
	v_max_i32_e32 v49, 0, v60
	v_max_i32_e32 v48, 0, v56
	v_mul_f32_e32 v50, v49, v49
	v_max_i32_e32 v49, 0, v57
	v_mul_f32_e32 v48, v48, v48
	v_max_i32_e32 v51, 0, v61
	v_mul_f32_e32 v49, v49, v49
	v_max_i32_e32 v56, 0, v59
	v_add_co_u32_e32 v52, vcc, s39, v52
	v_ashrrev_i32_e32 v113, 31, v112
	v_mul_f32_e32 v51, v51, v51
	v_max_i32_e32 v55, 0, v62
	v_mul_f32_e32 v54, v54, v54
	v_max_i32_e32 v57, 0, v63
	v_mul_f32_e32 v56, v56, v56
	v_cvt_pk_bf16_f32 v48, v48, v49
	v_cvt_pk_bf16_f32 v49, v54, v56
	v_addc_co_u32_e32 v53, vcc, 0, v53, vcc
	v_max_i32_e32 v40, 0, v40
	v_max_i32_e32 v41, 0, v41
	v_max_i32_e32 v42, 0, v42
	v_max_i32_e32 v43, 0, v43
	v_max_i32_e32 v32, 0, v32
	v_max_i32_e32 v36, 0, v36
	v_max_i32_e32 v33, 0, v33
	v_max_i32_e32 v34, 0, v34
	v_mul_f32_e32 v55, v55, v55
	v_mul_f32_e32 v57, v57, v57
	v_cvt_pk_bf16_f32 v50, v50, v51
	v_cvt_pk_bf16_f32 v51, v55, v57
	global_store_dwordx4 v[52:53], v[48:51], off
	v_max_i32_e32 v44, 0, v44
	v_mul_f32_e32 v40, v40, v40
	v_lshl_add_u64 v[48:49], v[112:113], 1, s[74:75]
	v_max_i32_e32 v45, 0, v45
	v_mul_f32_e32 v41, v41, v41
	v_max_i32_e32 v46, 0, v46
	v_mul_f32_e32 v42, v42, v42
	v_max_i32_e32 v47, 0, v47
	v_mul_f32_e32 v43, v43, v43
	v_mul_f32_e32 v32, v32, v32
	v_mul_f32_e32 v36, v36, v36
	v_max_i32_e32 v37, 0, v37
	v_mul_f32_e32 v33, v33, v33
	v_mul_f32_e32 v34, v34, v34
	v_max_i32_e32 v35, 0, v35
	v_mul_f32_e32 v44, v44, v44
	v_mul_f32_e32 v45, v45, v45
	v_mul_f32_e32 v46, v46, v46
	v_mul_f32_e32 v47, v47, v47
	v_cvt_pk_bf16_f32 v40, v40, v41
	v_cvt_pk_bf16_f32 v41, v42, v43
	v_cvt_pk_bf16_f32 v42, v44, v45
	v_cvt_pk_bf16_f32 v43, v46, v47
	global_store_dwordx4 v[48:49], v[40:43], off
	v_mul_f32_e32 v37, v37, v37
	v_mul_f32_e32 v35, v35, v35
	v_cvt_pk_bf16_f32 v32, v32, v33
	v_cvt_pk_bf16_f32 v33, v34, v35
	v_cvt_pk_bf16_f32 v34, v36, v37
	v_add_co_u32_e32 v36, vcc, s39, v48
	v_max_i32_e32 v38, 0, v38
	v_max_i32_e32 v39, 0, v39
	v_addc_co_u32_e32 v37, vcc, 0, v49, vcc
	v_max_i32_e32 v24, 0, v24
	v_max_i32_e32 v25, 0, v25
	v_max_i32_e32 v26, 0, v26
	v_max_i32_e32 v27, 0, v27
	v_max_i32_e32 v16, 0, v16
	v_max_i32_e32 v20, 0, v20
	v_max_i32_e32 v17, 0, v17
	v_max_i32_e32 v18, 0, v18
	v_mul_f32_e32 v38, v38, v38
	v_mul_f32_e32 v39, v39, v39
	v_cvt_pk_bf16_f32 v35, v38, v39
	global_store_dwordx4 v[36:37], v[32:35], off
	v_max_i32_e32 v28, 0, v28
	v_mul_f32_e32 v24, v24, v24
	v_lshl_add_u64 v[32:33], s[74:75], 0, v[96:97]
	v_max_i32_e32 v29, 0, v29
	v_mul_f32_e32 v25, v25, v25
	v_max_i32_e32 v30, 0, v30
	v_mul_f32_e32 v26, v26, v26
	v_max_i32_e32 v31, 0, v31
	v_mul_f32_e32 v27, v27, v27
	v_mul_f32_e32 v16, v16, v16
	v_mul_f32_e32 v20, v20, v20
	v_max_i32_e32 v21, 0, v21
	v_mul_f32_e32 v17, v17, v17
	v_mul_f32_e32 v18, v18, v18
	v_max_i32_e32 v19, 0, v19
	v_mul_f32_e32 v28, v28, v28
	v_mul_f32_e32 v29, v29, v29
	v_mul_f32_e32 v30, v30, v30
	v_mul_f32_e32 v31, v31, v31
	v_cvt_pk_bf16_f32 v24, v24, v25
	v_cvt_pk_bf16_f32 v25, v26, v27
	v_cvt_pk_bf16_f32 v26, v28, v29
	v_cvt_pk_bf16_f32 v27, v30, v31
	global_store_dwordx4 v[32:33], v[24:27], off
	v_mul_f32_e32 v21, v21, v21
	v_mul_f32_e32 v19, v19, v19
	v_cvt_pk_bf16_f32 v16, v16, v17
	v_cvt_pk_bf16_f32 v17, v18, v19
	v_cvt_pk_bf16_f32 v18, v20, v21
	v_add_co_u32_e32 v20, vcc, s39, v32
	v_max_i32_e32 v22, 0, v22
	v_max_i32_e32 v23, 0, v23
	v_addc_co_u32_e32 v21, vcc, 0, v33, vcc
	v_max_i32_e32 v8, 0, v8
	v_max_i32_e32 v9, 0, v9
	v_max_i32_e32 v10, 0, v10
	v_max_i32_e32 v11, 0, v11
	v_max_i32_e32 v0, 0, v0
	v_max_i32_e32 v4, 0, v4
	v_max_i32_e32 v1, 0, v1
	v_max_i32_e32 v2, 0, v2
	v_mul_f32_e32 v22, v22, v22
	v_mul_f32_e32 v23, v23, v23
	v_cvt_pk_bf16_f32 v19, v22, v23
	global_store_dwordx4 v[20:21], v[16:19], off
	v_max_i32_e32 v12, 0, v12
	v_mul_f32_e32 v8, v8, v8
	v_lshl_add_u64 v[16:17], s[74:75], 0, v[80:81]
	v_max_i32_e32 v13, 0, v13
	v_mul_f32_e32 v9, v9, v9
	v_max_i32_e32 v14, 0, v14
	v_mul_f32_e32 v10, v10, v10
	v_max_i32_e32 v15, 0, v15
	v_mul_f32_e32 v11, v11, v11
	v_mul_f32_e32 v0, v0, v0
	v_mul_f32_e32 v4, v4, v4
	v_max_i32_e32 v5, 0, v5
	v_mul_f32_e32 v1, v1, v1
	v_mul_f32_e32 v2, v2, v2
	v_max_i32_e32 v3, 0, v3
	v_mul_f32_e32 v12, v12, v12
	v_mul_f32_e32 v13, v13, v13
	v_mul_f32_e32 v14, v14, v14
	v_mul_f32_e32 v15, v15, v15
	v_cvt_pk_bf16_f32 v8, v8, v9
	v_cvt_pk_bf16_f32 v9, v10, v11
	v_cvt_pk_bf16_f32 v10, v12, v13
	v_cvt_pk_bf16_f32 v11, v14, v15
	global_store_dwordx4 v[16:17], v[8:11], off
	v_mul_f32_e32 v5, v5, v5
	v_mul_f32_e32 v3, v3, v3
	v_cvt_pk_bf16_f32 v0, v0, v1
	v_cvt_pk_bf16_f32 v1, v2, v3
	v_cvt_pk_bf16_f32 v2, v4, v5
	v_add_co_u32_e32 v4, vcc, 0x10000, v16
	v_max_i32_e32 v6, 0, v6
	s_nop 0
	v_addc_co_u32_e32 v5, vcc, 0, v17, vcc
	v_max_i32_e32 v7, 0, v7
	s_andn2_b64 vcc, exec, s[2:3]
	s_mov_b64 s[2:3], -1
	v_mul_f32_e32 v6, v6, v6
	v_mul_f32_e32 v7, v7, v7
	v_cvt_pk_bf16_f32 v3, v6, v7
	global_store_dwordx4 v[4:5], v[0:3], off
	s_mov_b32 s98, 1
	s_cbranch_vccnz .LBB0_1945
	s_andn2_b64 vcc, exec, s[6:7]
	s_cbranch_vccnz .LBB0_1944
	s_barrier
	s_branch .LBB0_1944

; #define PG8_STAGE(bufoff, gbase, voff) do { _Pragma("unroll") for (int _i = 0; _i < 2; ++_i) \
;         __builtin_amdgcn_global_load_lds((const unsigned*)((const char*)(gbase) + (voff)[_i]), (PG8_LAS unsigned*)(lds + (bufoff) + ldsw + _i * 8192), 16, 0, 0); } while (0)
; #define PG8_WAIT_V(n) asm volatile("s_waitcnt vmcnt(" #n ")" ::: "memory")
; #define PG8_BAR __builtin_amdgcn_s_barrier()
; template <class Epi, class Sched, bool ALIGN_EPI = false, bool SP2 = false, bool A_TILED = false>
; __device__ __forceinline__ void gemm_phase(PG8_LAS unsigned char* lds, const Gemm g, const Sched& S, const Epi& E, const int wave_s) {
;     ...
;     if constexpr (SP2) {
;         PG8_STAGE(PG8_SB(0, 0), cB, voffB); PG8_STAGE(PG8_SB(0, 1), cB + hstep, voffB); PG8_STAGE(PG8_SA(0, 0), cA, voffA); PG8_STAGE(PG8_SA(0, 1), cA + hstepA, voffA);
;         if (wr == 1) PG8_BAR;
;         PG8_WAIT_V(2); PG8_BAR;
;         PG8_STAGE(PG8_SB(1, 0), cB + kstep, voffB); PG8_STAGE(PG8_SA(1, 0), cA + kstepA, voffA); PG8_STAGE(PG8_SB(1, 1), cB + hstep + kstep, voffB);
;         PG8_WAIT_V(6); PG8_BAR;
;     } else {
;         PG8_STAGE(PG8_SB(0, 0), cB, voffB); PG8_STAGE(PG8_SA(0, 0), cA, voffA); PG8_STAGE(PG8_SB(0, 1), cB + hstep, voffB); PG8_STAGE(PG8_SA(0, 1), cA + hstepA, voffA);
;         if (wr == 1) PG8_BAR;
;         PG8_WAIT_V(4); PG8_BAR;
;         PG8_STAGE(PG8_SB(1, 0), cB + kstep, voffB); PG8_STAGE(PG8_SA(1, 0), cA + kstepA, voffA); PG8_STAGE(PG8_SB(1, 1), cB + hstep + kstep, voffB);
;         PG8_WAIT_V(6); PG8_BAR;
.LBB0_2411:
	s_sext_i32_i8 s44, s12
	s_mul_i32 s12, s96, 0x7c00000
	s_ashr_i32 s39, s86, 31
	s_add_u32 s2, s2, s12
	s_addc_u32 s3, s3, 0
	s_add_u32 s12, s2, 0x22600000
	s_addc_u32 s13, s3, 0
	v_and_b32_e32 v15, 48, v14
	v_lshlrev_b32_e32 v16, 6, v14
	s_movk_i32 s3, 0x3c0
	v_lshlrev_b32_e32 v14, 2, v14
	s_lshl_b32 s2, s42, 13
	v_and_or_b32 v15, v16, s3, v15
	v_and_b32_e32 v14, 32, v14
	v_bitop3_b32 v16, v15, s2, v14 bitop3:0xde
	s_lshl_b32 s2, s41, 5
	s_mov_b64 s[62:63], 0x80
	s_and_b32 s41, s2, 0x60
	s_add_i32 m0, s22, 0x18000
	v_lshl_add_u64 v[6:7], v[6:7], 0, s[62:63]
	s_lshl_b32 s40, s42, 6
	s_lshl_b32 s2, s41, 7
	s_waitcnt vmcnt(2)
	s_barrier
	global_load_lds_dwordx4 v[6:7], off
	v_lshl_add_u64 v[4:5], v[4:5], 0, s[62:63]
	s_add_i32 m0, s22, 0x1a000
	s_add_i32 s42, s22, 0x8000
	s_add_i32 s43, s22, 0xa000
	v_bitop3_b32 v140, s2, v15, v14 bitop3:0xf6
	global_load_lds_dwordx4 v[4:5], off
	v_lshl_add_u64 v[0:1], v[0:1], 0, s[62:63]
	s_mov_b32 m0, s42
	s_add_u32 s2, s78, 0x80080
	global_load_lds_dwordx4 v[0:1], off
	v_lshl_add_u64 v[0:1], v[2:3], 0, s[62:63]
	s_mov_b32 m0, s43
	s_addc_u32 s3, s79, 0
	global_load_lds_dwordx4 v[0:1], off
	s_add_i32 m0, s22, 0x1c000
	v_lshl_add_u64 v[0:1], s[2:3], 0, v[128:129]
	global_load_lds_dwordx4 v128, s[2:3]
	v_lshl_add_u64 v[0:1], s[2:3], 0, v[130:131]
	s_add_i32 m0, s22, 0x1e000
	s_cmpk_lt_u32 s45, 0x100
	global_load_lds_dwordx4 v130, s[2:3]
	v_lshlrev_b32_e32 v0, 15, v8
	v_and_b32_e32 v0, 0xffff0000, v0
	v_lshl_add_u32 v0, v9, 12, v0
	v_and_b32_e32 v1, 1, v8
	v_lshl_or_b32 v0, v1, 6, v0
	v_lshl_add_u32 v132, v10, 1, v0
	v_lshlrev_b32_e32 v0, 15, v11
	v_and_b32_e32 v0, 0xffff0000, v0
	s_waitcnt vmcnt(6)
	s_mov_b32 s98, 0
	v_lshl_add_u32 v0, v12, 12, v0
	v_and_b32_e32 v1, 1, v11
	s_cselect_b64 s[64:65], -1, 0
	v_mov_b32_e32 v133, 0
	v_lshl_or_b32 v0, v1, 6, v0
	s_add_i32 s45, 0, 0x10000
	s_add_i32 s46, 0, 0x14000
	v_lshl_add_u32 v134, v13, 1, v0
	v_mov_b32_e32 v135, v133
	v_add_u32_e32 v141, s45, v140
	v_add_u32_e32 v142, s46, v140
	v_add_u32_e32 v143, 0, v16
	s_mov_b64 s[66:67], 0x100
	s_mov_b64 s[68:69], 0x180
	s_movk_i32 s47, 0x1400
	s_add_i32 s48, s22, 0xc000
	s_add_i32 s49, s22, 0xe000
	s_barrier
	s_branch .LBB0_2414

; template <class Epi, class Sched, bool ALIGN_EPI = false, bool SP2 = false, bool A_TILED = false>
; __device__ __forceinline__ void gemm_phase(PG8_LAS unsigned char* lds, const Gemm g, const Sched& S, const Epi& E, const int wave_s) {
;     ...
;         const bool has_next = Epi::AFTER_DRAIN ? false : S.next(ui + 1, nxt);
;         const char* nA = has_next ? (const char*)g.A + (size_t)nxt.pm * tstepA : cA; const char* nB = has_next ? (const char*)g.Bt + (size_t)nxt.pn * tstep : cB;
;         constexpr bool PEEL = SP2 && !Epi::AFTER_DRAIN;
;         if constexpr (PEEL) {
;             const char* a1 = cA + kstepA; const char* a2 = cA + 2 * kstepA; const char* b2 = cB + 2 * kstep; const char* a3 = a2 + kstepA; const char* b3 = b2 + kstep;
;             PG8_ITER(PG8_MMAZ)
.LBB0_2416:
	s_ashr_i32 s73, s72, 31
	s_lshl_b64 s[50:51], s[72:73], 20
	s_add_u32 s74, s1, s50
	ds_read_b128 v[0:3], v141
	ds_read_b128 v[4:7], v141 offset:1024
	ds_read_b128 v[8:11], v141 offset:2048
	ds_read_b128 v[12:15], v141 offset:3072
	ds_read_b128 v[16:19], v142
	ds_read_b128 v[20:23], v142 offset:1024
	ds_read_b128 v[24:27], v142 offset:2048
	ds_read_b128 v[28:31], v142 offset:3072
	s_addc_u32 s75, s8, s51
	s_ashr_i32 s71, s70, 31
	s_lshl_b64 s[50:51], s[70:71], 20
	s_add_u32 s76, s9, s50
	s_addc_u32 s77, s14, s51
	s_and_b64 s[50:51], s[2:3], exec
	s_cselect_b32 s50, s75, s81
	s_cselect_b32 s51, s74, s80
	s_cselect_b32 s52, s77, s79
	s_cselect_b32 s53, s76, s78
	s_add_u32 s54, s80, 0x80080
	s_addc_u32 s55, s81, 0
	s_mov_b32 m0, s48
	v_lshl_add_u64 v[64:65], s[54:55], 0, v[128:129]
	ds_read_b128 v[32:35], v143
	ds_read_b128 v[36:39], v143 offset:1024
	ds_read_b128 v[40:43], v143 offset:2048
	ds_read_b128 v[44:47], v143 offset:3072
	ds_read_b128 v[48:51], v143 offset:4096
	ds_read_b128 v[52:55], v143 offset:5120
	ds_read_b128 v[56:59], v143 offset:6144
	ds_read_b128 v[60:63], v143 offset:7168
	global_load_lds_dwordx4 v128, s[54:55]
	v_lshl_add_u64 v[64:65], s[54:55], 0, v[130:131]
	s_mov_b32 m0, s49
	s_nop 0
	global_load_lds_dwordx4 v130, s[54:55]
	s_waitcnt vmcnt(40) lgkmcnt(0)
	s_cmp_lg_u32 s98, 0
	s_cbranch_scc1 .Lpw_9
	s_waitcnt vmcnt(8)
.Lpw_9:
	s_setprio 1
	s_barrier
	v_mfma_f32_16x16x32_bf16 v[64:67], v[0:3], v[32:35], 0
	v_mfma_f32_16x16x32_bf16 v[68:71], v[8:11], v[32:35], 0
	v_mfma_f32_16x16x32_bf16 v[72:75], v[0:3], v[40:43], 0
	v_mfma_f32_16x16x32_bf16 v[76:79], v[8:11], v[40:43], 0
	v_mfma_f32_16x16x32_bf16 v[80:83], v[0:3], v[48:51], 0
	v_mfma_f32_16x16x32_bf16 v[84:87], v[8:11], v[48:51], 0
	v_mfma_f32_16x16x32_bf16 v[88:91], v[0:3], v[56:59], 0
	v_mfma_f32_16x16x32_bf16 v[92:95], v[8:11], v[56:59], 0
	v_mfma_f32_16x16x32_bf16 v[64:67], v[4:7], v[36:39], v[64:67]
	v_mfma_f32_16x16x32_bf16 v[68:71], v[12:15], v[36:39], v[68:71]
	v_mfma_f32_16x16x32_bf16 v[72:75], v[4:7], v[44:47], v[72:75]
	v_mfma_f32_16x16x32_bf16 v[76:79], v[12:15], v[44:47], v[76:79]
	v_mfma_f32_16x16x32_bf16 v[80:83], v[4:7], v[52:55], v[80:83]
	v_mfma_f32_16x16x32_bf16 v[84:87], v[12:15], v[52:55], v[84:87]
	v_mfma_f32_16x16x32_bf16 v[88:91], v[4:7], v[60:63], v[88:91]
	v_mfma_f32_16x16x32_bf16 v[92:95], v[12:15], v[60:63], v[92:95]
	s_setprio 0
	s_setprio 1
	v_mfma_f32_16x16x32_bf16 v[96:99], v[16:19], v[32:35], 0
	v_mfma_f32_16x16x32_bf16 v[32:35], v[24:27], v[32:35], 0
	v_mfma_f32_16x16x32_bf16 v[96:99], v[20:23], v[36:39], v[96:99]
	v_mfma_f32_16x16x32_bf16 v[32:35], v[28:31], v[36:39], v[32:35]
	v_mfma_f32_16x16x32_bf16 v[36:39], v[16:19], v[40:43], 0
	v_mfma_f32_16x16x32_bf16 v[40:43], v[24:27], v[40:43], 0
	v_mfma_f32_16x16x32_bf16 v[36:39], v[20:23], v[44:47], v[36:39]
	v_mfma_f32_16x16x32_bf16 v[40:43], v[28:31], v[44:47], v[40:43]
	v_mfma_f32_16x16x32_bf16 v[44:47], v[16:19], v[48:51], 0
	v_mfma_f32_16x16x32_bf16 v[48:51], v[24:27], v[48:51], 0
	v_mfma_f32_16x16x32_bf16 v[100:103], v[28:31], v[52:55], v[48:51]
	v_mfma_f32_16x16x32_bf16 v[48:51], v[16:19], v[56:59], 0
	v_mfma_f32_16x16x32_bf16 v[104:107], v[20:23], v[60:63], v[48:51]
	v_mfma_f32_16x16x32_bf16 v[48:51], v[24:27], v[56:59], 0
	v_mfma_f32_16x16x32_bf16 v[44:47], v[20:23], v[52:55], v[44:47]
	v_mfma_f32_16x16x32_bf16 v[108:111], v[28:31], v[60:63], v[48:51]
	s_barrier
	s_setprio 0
	s_add_i32 s54, s45, s15
	v_lshl_add_u64 v[250:251], s[78:79], 0, v[128:129]
	s_add_i32 s55, s54, 0x2000
	v_lshl_add_u64 v[144:145], v[250:251], 0, s[66:67]
	s_mov_b32 m0, s54
	v_lshl_add_u64 v[252:253], s[78:79], 0, v[130:131]
	s_add_u32 s58, s78, 0x80100
	ds_read_b128 v[48:51], v143 offset:16384
	ds_read_b128 v[52:55], v143 offset:17408
	ds_read_b128 v[56:59], v143 offset:18432
	ds_read_b128 v[60:63], v143 offset:19456
	ds_read_b128 v[112:115], v143 offset:20480
	ds_read_b128 v[116:119], v143 offset:21504
	ds_read_b128 v[120:123], v143 offset:22528
	ds_read_b128 v[124:127], v143 offset:23552
	global_load_lds_dwordx4 v[144:145], off
	v_lshl_add_u64 v[144:145], v[252:253], 0, s[66:67]
	s_mov_b32 m0, s55
	s_addc_u32 s59, s79, 0
	s_add_i32 s56, s46, s15
	global_load_lds_dwordx4 v[144:145], off
	v_lshl_add_u64 v[144:145], s[58:59], 0, v[128:129]
	s_mov_b32 m0, s56
	s_add_i32 s57, s56, 0x2000
	global_load_lds_dwordx4 v128, s[58:59]
	v_lshl_add_u64 v[144:145], s[58:59], 0, v[130:131]
	s_mov_b32 m0, s57
	v_lshl_add_u64 v[136:137], s[80:81], 0, v[128:129]
	global_load_lds_dwordx4 v130, s[58:59]
	v_lshl_add_u64 v[144:145], v[136:137], 0, s[66:67]
	s_mov_b32 m0, s22
	v_lshl_add_u64 v[138:139], s[80:81], 0, v[130:131]
	global_load_lds_dwordx4 v[144:145], off
	v_lshl_add_u64 v[144:145], v[138:139], 0, s[66:67]
	s_mov_b32 m0, s23
	s_nop 0
	global_load_lds_dwordx4 v[144:145], off
	s_waitcnt vmcnt(40) lgkmcnt(0)
	s_cmp_lg_u32 s98, 0
	s_cbranch_scc1 .Lpw_10
	s_waitcnt vmcnt(8)
.Lpw_10:
	s_setprio 1
	s_barrier
	v_mfma_f32_16x16x32_bf16 v[144:147], v[0:3], v[48:51], 0
	v_mfma_f32_16x16x32_bf16 v[154:157], v[0:3], v[56:59], 0
	v_mfma_f32_16x16x32_bf16 v[162:165], v[0:3], v[112:115], 0
	v_mfma_f32_16x16x32_bf16 v[0:3], v[0:3], v[120:123], 0
	v_mfma_f32_16x16x32_bf16 v[150:153], v[8:11], v[48:51], 0
	v_mfma_f32_16x16x32_bf16 v[158:161], v[8:11], v[56:59], 0
	v_mfma_f32_16x16x32_bf16 v[166:169], v[8:11], v[112:115], 0
	v_mfma_f32_16x16x32_bf16 v[170:173], v[4:7], v[124:127], v[0:3]
	v_mfma_f32_16x16x32_bf16 v[0:3], v[8:11], v[120:123], 0
	v_mfma_f32_16x16x32_bf16 v[146:149], v[4:7], v[52:55], v[144:147]
	v_mfma_f32_16x16x32_bf16 v[150:153], v[12:15], v[52:55], v[150:153]
	v_mfma_f32_16x16x32_bf16 v[154:157], v[4:7], v[60:63], v[154:157]
	v_mfma_f32_16x16x32_bf16 v[158:161], v[12:15], v[60:63], v[158:161]
	v_mfma_f32_16x16x32_bf16 v[162:165], v[4:7], v[116:119], v[162:165]
	v_mfma_f32_16x16x32_bf16 v[166:169], v[12:15], v[116:119], v[166:169]
	v_mfma_f32_16x16x32_bf16 v[174:177], v[12:15], v[124:127], v[0:3]
	s_setprio 0
	s_setprio 1
	v_mfma_f32_16x16x32_bf16 v[0:3], v[16:19], v[48:51], 0
	v_mfma_f32_16x16x32_bf16 v[178:181], v[20:23], v[52:55], v[0:3]
	v_mfma_f32_16x16x32_bf16 v[0:3], v[24:27], v[48:51], 0
	v_mfma_f32_16x16x32_bf16 v[182:185], v[28:31], v[52:55], v[0:3]
	v_mfma_f32_16x16x32_bf16 v[0:3], v[16:19], v[56:59], 0
	v_mfma_f32_16x16x32_bf16 v[186:189], v[20:23], v[60:63], v[0:3]
	v_mfma_f32_16x16x32_bf16 v[0:3], v[24:27], v[56:59], 0
	v_mfma_f32_16x16x32_bf16 v[190:193], v[28:31], v[60:63], v[0:3]
	v_mfma_f32_16x16x32_bf16 v[0:3], v[16:19], v[112:115], 0
	v_mfma_f32_16x16x32_bf16 v[194:197], v[20:23], v[116:119], v[0:3]
	v_mfma_f32_16x16x32_bf16 v[0:3], v[24:27], v[112:115], 0
	v_mfma_f32_16x16x32_bf16 v[198:201], v[28:31], v[116:119], v[0:3]
	v_mfma_f32_16x16x32_bf16 v[0:3], v[16:19], v[120:123], 0
	v_mfma_f32_16x16x32_bf16 v[202:205], v[20:23], v[124:127], v[0:3]
	v_mfma_f32_16x16x32_bf16 v[0:3], v[24:27], v[120:123], 0
	v_mfma_f32_16x16x32_bf16 v[206:209], v[28:31], v[124:127], v[0:3]
	s_barrier
	s_setprio 0
	s_add_i32 s61, 0, 0x18000
	s_add_i32 s71, 0, 0x1c000
	v_add_u32_e32 v144, s61, v140
	v_add_u32_e32 v145, s71, v140
	ds_read_b128 v[112:115], v144
	ds_read_b128 v[116:119], v144 offset:1024
	ds_read_b128 v[120:123], v144 offset:2048
	ds_read_b128 v[124:127], v144 offset:3072
	ds_read_b128 v[210:213], v145
	ds_read_b128 v[214:217], v145 offset:1024
	ds_read_b128 v[218:221], v145 offset:2048
	ds_read_b128 v[222:225], v145 offset:3072
	s_add_u32 s58, s80, 0x80100
	s_addc_u32 s59, s81, 0
	s_mov_b32 m0, s36
	v_lshl_add_u64 v[0:1], s[58:59], 0, v[128:129]
	ds_read_b128 v[48:51], v143 offset:32768
	ds_read_b128 v[52:55], v143 offset:33792
	ds_read_b128 v[226:229], v143 offset:34816
	ds_read_b128 v[230:233], v143 offset:35840
	ds_read_b128 v[234:237], v143 offset:36864
	ds_read_b128 v[238:241], v143 offset:37888
	ds_read_b128 v[242:245], v143 offset:38912
	ds_read_b128 v[246:249], v143 offset:39936
	global_load_lds_dwordx4 v128, s[58:59]
	v_lshl_add_u64 v[0:1], s[58:59], 0, v[130:131]
	s_mov_b32 m0, s37
	s_nop 0
	global_load_lds_dwordx4 v130, s[58:59]
	s_waitcnt vmcnt(8) lgkmcnt(0)
	s_setprio 1
	s_barrier
	v_mfma_f32_16x16x32_bf16 v[0:3], v[112:115], v[48:51], v[64:67]
	v_mfma_f32_16x16x32_bf16 v[24:27], v[116:119], v[52:55], v[0:3]
	v_mfma_f32_16x16x32_bf16 v[0:3], v[120:123], v[48:51], v[68:71]
	v_mfma_f32_16x16x32_bf16 v[28:31], v[124:127], v[52:55], v[0:3]
	v_mfma_f32_16x16x32_bf16 v[0:3], v[112:115], v[226:229], v[72:75]
	v_mfma_f32_16x16x32_bf16 v[16:19], v[116:119], v[230:233], v[0:3]
	v_mfma_f32_16x16x32_bf16 v[0:3], v[120:123], v[226:229], v[76:79]
	v_mfma_f32_16x16x32_bf16 v[20:23], v[124:127], v[230:233], v[0:3]
	v_mfma_f32_16x16x32_bf16 v[0:3], v[112:115], v[234:237], v[80:83]
	v_mfma_f32_16x16x32_bf16 v[8:11], v[116:119], v[238:241], v[0:3]
	v_mfma_f32_16x16x32_bf16 v[0:3], v[120:123], v[234:237], v[84:87]
	v_mfma_f32_16x16x32_bf16 v[12:15], v[124:127], v[238:241], v[0:3]
	v_mfma_f32_16x16x32_bf16 v[0:3], v[112:115], v[242:245], v[88:91]
	v_mfma_f32_16x16x32_bf16 v[4:7], v[120:123], v[242:245], v[92:95]
	v_mfma_f32_16x16x32_bf16 v[0:3], v[116:119], v[246:249], v[0:3]
	v_mfma_f32_16x16x32_bf16 v[4:7], v[124:127], v[246:249], v[4:7]
	s_setprio 0
	s_setprio 1
	v_mfma_f32_16x16x32_bf16 v[32:35], v[218:221], v[48:51], v[32:35]
	v_mfma_f32_16x16x32_bf16 v[60:63], v[222:225], v[52:55], v[32:35]
	v_mfma_f32_16x16x32_bf16 v[32:35], v[210:213], v[226:229], v[36:39]
	v_mfma_f32_16x16x32_bf16 v[56:59], v[210:213], v[48:51], v[96:99]
	v_mfma_f32_16x16x32_bf16 v[48:51], v[214:217], v[230:233], v[32:35]
	v_mfma_f32_16x16x32_bf16 v[32:35], v[218:221], v[226:229], v[40:43]
	v_mfma_f32_16x16x32_bf16 v[56:59], v[214:217], v[52:55], v[56:59]
	v_mfma_f32_16x16x32_bf16 v[52:55], v[222:225], v[230:233], v[32:35]
	v_mfma_f32_16x16x32_bf16 v[32:35], v[210:213], v[234:237], v[44:47]
	v_mfma_f32_16x16x32_bf16 v[40:43], v[214:217], v[238:241], v[32:35]
	v_mfma_f32_16x16x32_bf16 v[32:35], v[218:221], v[234:237], v[100:103]
	v_mfma_f32_16x16x32_bf16 v[44:47], v[222:225], v[238:241], v[32:35]
	v_mfma_f32_16x16x32_bf16 v[32:35], v[210:213], v[242:245], v[104:107]
	v_mfma_f32_16x16x32_bf16 v[36:39], v[218:221], v[242:245], v[108:111]
	v_mfma_f32_16x16x32_bf16 v[32:35], v[214:217], v[246:249], v[32:35]
	v_mfma_f32_16x16x32_bf16 v[36:39], v[222:225], v[246:249], v[36:39]
	s_barrier
; template <class Epi, class Sched, bool ALIGN_EPI = false, bool SP2 = false, bool A_TILED = false>
; __device__ __forceinline__ void gemm_phase(PG8_LAS unsigned char* lds, const Gemm g, const Sched& S, const Epi& E, const int wave_s) {
;     ...
;         for (int t = PEEL ? 2 : 0; t < nt; t += 2) {
;             const bool last = (t == nt - 2);
;             const char* a1 = cA + (size_t)(t + 1) * kstepA;
;             const char* a2 = last ? nA : cA + (size_t)(t + 2) * kstepA; const char* b2 = last ? nB : cB + (size_t)(t + 2) * kstep;
;             const char* a3 = a2 + kstepA; const char* b3 = b2 + kstep;
	s_setprio 0
	s_add_i32 s58, s61, s15
	s_add_i32 s59, s58, 0x2000
	v_lshl_add_u64 v[64:65], v[250:251], 0, s[68:69]
	s_mov_b32 m0, s58
	s_add_u32 s82, s78, 0x80180
	ds_read_b128 v[96:99], v143 offset:49152
	ds_read_b128 v[100:103], v143 offset:50176
	ds_read_b128 v[104:107], v143 offset:51200
	ds_read_b128 v[108:111], v143 offset:52224
	ds_read_b128 v[226:229], v143 offset:53248
	ds_read_b128 v[230:233], v143 offset:54272
	ds_read_b128 v[234:237], v143 offset:55296
	ds_read_b128 v[238:241], v143 offset:56320
	global_load_lds_dwordx4 v[64:65], off
	v_lshl_add_u64 v[64:65], v[252:253], 0, s[68:69]
	s_mov_b32 m0, s59
	s_addc_u32 s83, s79, 0
	s_add_i32 s61, s71, s15
	global_load_lds_dwordx4 v[64:65], off
	v_lshl_add_u64 v[64:65], s[82:83], 0, v[128:129]
	s_mov_b32 m0, s61
	s_add_i32 s71, s61, 0x2000
	global_load_lds_dwordx4 v128, s[82:83]
	v_lshl_add_u64 v[64:65], s[82:83], 0, v[130:131]
	s_mov_b32 m0, s71
	s_nop 0
	global_load_lds_dwordx4 v130, s[82:83]
	v_lshl_add_u64 v[64:65], v[136:137], 0, s[68:69]
	s_mov_b32 m0, s42
	s_nop 0
	global_load_lds_dwordx4 v[64:65], off
	v_lshl_add_u64 v[64:65], v[138:139], 0, s[68:69]
	s_mov_b32 m0, s43
	s_nop 0
	global_load_lds_dwordx4 v[64:65], off
	s_waitcnt vmcnt(8) lgkmcnt(0)
	s_setprio 1
	s_barrier
	v_mfma_f32_16x16x32_bf16 v[64:67], v[112:115], v[96:99], v[146:149]
	v_mfma_f32_16x16x32_bf16 v[88:91], v[116:119], v[100:103], v[64:67]
	v_mfma_f32_16x16x32_bf16 v[64:67], v[120:123], v[96:99], v[150:153]
	v_mfma_f32_16x16x32_bf16 v[92:95], v[124:127], v[100:103], v[64:67]
	v_mfma_f32_16x16x32_bf16 v[64:67], v[112:115], v[104:107], v[154:157]
	v_mfma_f32_16x16x32_bf16 v[80:83], v[116:119], v[108:111], v[64:67]
	v_mfma_f32_16x16x32_bf16 v[64:67], v[120:123], v[104:107], v[158:161]
	v_mfma_f32_16x16x32_bf16 v[84:87], v[124:127], v[108:111], v[64:67]
	v_mfma_f32_16x16x32_bf16 v[64:67], v[112:115], v[226:229], v[162:165]
	v_mfma_f32_16x16x32_bf16 v[72:75], v[116:119], v[230:233], v[64:67]
	v_mfma_f32_16x16x32_bf16 v[64:67], v[120:123], v[226:229], v[166:169]
	v_mfma_f32_16x16x32_bf16 v[76:79], v[124:127], v[230:233], v[64:67]
	v_mfma_f32_16x16x32_bf16 v[64:67], v[112:115], v[234:237], v[170:173]
	v_mfma_f32_16x16x32_bf16 v[68:71], v[120:123], v[234:237], v[174:177]
	v_mfma_f32_16x16x32_bf16 v[64:67], v[116:119], v[238:241], v[64:67]
	v_mfma_f32_16x16x32_bf16 v[68:71], v[124:127], v[238:241], v[68:71]
	s_setprio 0
	s_setprio 1
	v_mfma_f32_16x16x32_bf16 v[112:115], v[210:213], v[96:99], v[178:181]
	v_mfma_f32_16x16x32_bf16 v[96:99], v[218:221], v[96:99], v[182:185]
	v_mfma_f32_16x16x32_bf16 v[124:127], v[222:225], v[100:103], v[96:99]
	v_mfma_f32_16x16x32_bf16 v[96:99], v[210:213], v[104:107], v[186:189]
	v_mfma_f32_16x16x32_bf16 v[120:123], v[214:217], v[100:103], v[112:115]
	v_mfma_f32_16x16x32_bf16 v[112:115], v[214:217], v[108:111], v[96:99]
	v_mfma_f32_16x16x32_bf16 v[96:99], v[218:221], v[104:107], v[190:193]
	v_mfma_f32_16x16x32_bf16 v[116:119], v[222:225], v[108:111], v[96:99]
	v_mfma_f32_16x16x32_bf16 v[96:99], v[210:213], v[226:229], v[194:197]
	v_mfma_f32_16x16x32_bf16 v[104:107], v[214:217], v[230:233], v[96:99]
	v_mfma_f32_16x16x32_bf16 v[96:99], v[218:221], v[226:229], v[198:201]
	v_mfma_f32_16x16x32_bf16 v[108:111], v[222:225], v[230:233], v[96:99]
	v_mfma_f32_16x16x32_bf16 v[96:99], v[210:213], v[234:237], v[202:205]
	v_mfma_f32_16x16x32_bf16 v[100:103], v[218:221], v[234:237], v[206:209]
	v_mfma_f32_16x16x32_bf16 v[96:99], v[214:217], v[238:241], v[96:99]
	v_mfma_f32_16x16x32_bf16 v[100:103], v[222:225], v[238:241], v[100:103]
	s_barrier
	s_setprio 0
	s_add_u32 s73, s78, 0x200
	s_addc_u32 s85, s79, 0
	s_add_u32 s78, s80, 0x80180
	s_addc_u32 s79, s81, 0
	s_mov_b32 s88, 0

; #define PG8_BAR __builtin_amdgcn_s_barrier()
;     __device__ __forceinline__ void operator()(const f32x4 (&acc)[2][2][4][2], const Unit& u, int wr, int wc, int fr, int fq) const {
;         const int row0 = u.pm * BM + wr * 64 + fr, col0 = u.pn * BM + wc * 32 + 4 * fq;
; #pragma unroll
;         for (int ai = 0; ai < 2; ++ai)
; #pragma unroll
;             for (int m = 0; m < 4; ++m) { float* rowp = C + (size_t)(row0 + ai * HALF + m * 16) * ldc + col0;
; #pragma unroll
;                 for (int bj = 0; bj < 2; ++bj)
; #pragma unroll
;                     for (int n = 0; n < 2; ++n) *(f32x4*)(rowp + bj * HALF + n * 16) = acc[ai][bj][m][n]; }
; template <class Epi, class Sched, bool ALIGN_EPI = false, bool SP2 = false, bool A_TILED = false>
; __device__ __forceinline__ void gemm_phase(PG8_LAS unsigned char* lds, const Gemm g, const Sched& S, const Epi& E, const int wave_s) {
;     ...
;         if (!has_next) break;
;         cur = nxt; cA = nA; cB = nB; ++ui;
;         if constexpr (ALIGN_EPI) { if (wr == 1) PG8_BAR; }
.LBB0_2420:
	v_mov_b32_e32 v136, 0
	s_lshl_b32 s50, s60, 8
	v_mbcnt_lo_u32_b32 v136, -1, v136
	v_mbcnt_hi_u32_b32 v136, -1, v136
	v_or_b32_e32 v136, s33, v136
	s_add_i32 s50, s50, s40
	v_and_or_b32 v146, v136, 15, s50
	s_lshl_b32 s44, s44, 8
	v_lshrrev_b32_e32 v136, 2, v136
	v_and_or_b32 v136, v136, 12, s44
	v_or_b32_e32 v136, s41, v136
	v_ashrrev_i32_e32 v137, 31, v136
	v_mov_b64_e32 v[138:139], s[12:13]
	v_mad_i64_i32 v[144:145], s[50:51], v146, s47, v[138:139]
	v_lshlrev_b64 v[136:137], 2, v[136:137]
	v_lshl_add_u64 v[144:145], v[144:145], 0, v[136:137]
	global_store_dwordx4 v[144:145], v[24:27], off
	global_store_dwordx4 v[144:145], v[28:31], off offset:64
	global_store_dwordx4 v[144:145], v[56:59], off offset:512
	global_store_dwordx4 v[144:145], v[60:63], off offset:576
	v_or_b32_e32 v24, 16, v146
	v_mad_i64_i32 v[24:25], s[50:51], v24, s47, v[138:139]
	v_lshl_add_u64 v[24:25], v[24:25], 0, v[136:137]
	global_store_dwordx4 v[24:25], v[16:19], off
	global_store_dwordx4 v[24:25], v[20:23], off offset:64
	global_store_dwordx4 v[24:25], v[48:51], off offset:512
	global_store_dwordx4 v[24:25], v[52:55], off offset:576
	v_or_b32_e32 v16, 32, v146
	v_mad_i64_i32 v[16:17], s[50:51], v16, s47, v[138:139]
	v_lshl_add_u64 v[16:17], v[16:17], 0, v[136:137]
	global_store_dwordx4 v[16:17], v[8:11], off
	global_store_dwordx4 v[16:17], v[12:15], off offset:64
	global_store_dwordx4 v[16:17], v[40:43], off offset:512
	global_store_dwordx4 v[16:17], v[44:47], off offset:576
	v_or_b32_e32 v8, 48, v146
	v_mad_i64_i32 v[8:9], s[50:51], v8, s47, v[138:139]
	v_lshl_add_u64 v[8:9], v[8:9], 0, v[136:137]
	global_store_dwordx4 v[8:9], v[0:3], off
	global_store_dwordx4 v[8:9], v[4:7], off offset:64
	global_store_dwordx4 v[8:9], v[32:35], off offset:512
	global_store_dwordx4 v[8:9], v[36:39], off offset:576
	v_add_u32_e32 v0, 0x80, v146
	v_mad_i64_i32 v[0:1], s[50:51], v0, s47, v[138:139]
	v_lshl_add_u64 v[0:1], v[0:1], 0, v[136:137]
	global_store_dwordx4 v[0:1], v[88:91], off
	global_store_dwordx4 v[0:1], v[92:95], off offset:64
	global_store_dwordx4 v[0:1], v[120:123], off offset:512
	global_store_dwordx4 v[0:1], v[124:127], off offset:576
	v_add_u32_e32 v0, 0x90, v146
	v_mad_i64_i32 v[0:1], s[50:51], v0, s47, v[138:139]
	v_lshl_add_u64 v[0:1], v[0:1], 0, v[136:137]
	global_store_dwordx4 v[0:1], v[80:83], off
	global_store_dwordx4 v[0:1], v[84:87], off offset:64
	global_store_dwordx4 v[0:1], v[112:115], off offset:512
	global_store_dwordx4 v[0:1], v[116:119], off offset:576
	v_add_u32_e32 v0, 0xa0, v146
	v_mad_i64_i32 v[0:1], s[50:51], v0, s47, v[138:139]
	v_lshl_add_u64 v[0:1], v[0:1], 0, v[136:137]
	global_store_dwordx4 v[0:1], v[72:75], off
	global_store_dwordx4 v[0:1], v[76:79], off offset:64
	global_store_dwordx4 v[0:1], v[104:107], off offset:512
	global_store_dwordx4 v[0:1], v[108:111], off offset:576
	v_add_u32_e32 v0, 0xb0, v146
	v_mad_i64_i32 v[0:1], s[50:51], v0, s47, v[138:139]
	v_lshl_add_u64 v[0:1], v[0:1], 0, v[136:137]
	s_andn2_b64 vcc, exec, s[2:3]
	s_mov_b64 s[2:3], -1
	global_store_dwordx4 v[0:1], v[64:67], off
	global_store_dwordx4 v[0:1], v[68:71], off offset:64
	global_store_dwordx4 v[0:1], v[96:99], off offset:512
	global_store_dwordx4 v[0:1], v[100:103], off offset:576
	s_mov_b32 s98, 1
	s_cbranch_vccnz .LBB0_2413
	s_andn2_b64 vcc, exec, s[6:7]
	s_cbranch_vccnz .LBB0_2412
	s_barrier
	s_branch .LBB0_2412

; #define PG8_STAGE(bufoff, gbase, voff) do { _Pragma("unroll") for (int _i = 0; _i < 2; ++_i) \
;         __builtin_amdgcn_global_load_lds((const unsigned*)((const char*)(gbase) + (voff)[_i]), (PG8_LAS unsigned*)(lds + (bufoff) + ldsw + _i * 8192), 16, 0, 0); } while (0)
; #define PG8_WAIT_V(n) asm volatile("s_waitcnt vmcnt(" #n ")" ::: "memory")
; #define PG8_BAR __builtin_amdgcn_s_barrier()
; template <class Epi, class Sched, bool ALIGN_EPI = false, bool SP2 = false, bool A_TILED = false>
; __device__ __forceinline__ void gemm_phase(PG8_LAS unsigned char* lds, const Gemm g, const Sched& S, const Epi& E, const int wave_s) {
;     ...
;     if constexpr (SP2) {
;         PG8_STAGE(PG8_SB(0, 0), cB, voffB); PG8_STAGE(PG8_SB(0, 1), cB + hstep, voffB); PG8_STAGE(PG8_SA(0, 0), cA, voffA); PG8_STAGE(PG8_SA(0, 1), cA + hstepA, voffA);
;         if (wr == 1) PG8_BAR;
;         PG8_WAIT_V(2); PG8_BAR;
;         PG8_STAGE(PG8_SB(1, 0), cB + kstep, voffB); PG8_STAGE(PG8_SA(1, 0), cA + kstepA, voffA); PG8_STAGE(PG8_SB(1, 1), cB + hstep + kstep, voffB);
;         PG8_WAIT_V(6); PG8_BAR;
;     } else {
;         PG8_STAGE(PG8_SB(0, 0), cB, voffB); PG8_STAGE(PG8_SA(0, 0), cA, voffA); PG8_STAGE(PG8_SB(0, 1), cB + hstep, voffB); PG8_STAGE(PG8_SA(0, 1), cA + hstepA, voffA);
;         if (wr == 1) PG8_BAR;
;         PG8_WAIT_V(4); PG8_BAR;
;         PG8_STAGE(PG8_SB(1, 0), cB + kstep, voffB); PG8_STAGE(PG8_SA(1, 0), cA + kstepA, voffA); PG8_STAGE(PG8_SB(1, 1), cB + hstep + kstep, voffB);
;         PG8_WAIT_V(6); PG8_BAR;
.LBB0_2540:
	s_sext_i32_i8 s5, s2
	s_mul_i32 s2, s96, 0x7800000
	s_add_u32 s2, s12, s2
	s_addc_u32 s44, s13, 0
	s_add_u32 s60, s2, 0x24600000
	s_addc_u32 s61, s44, 0
	v_and_b32_e32 v15, 48, v14
	v_lshlrev_b32_e32 v16, 6, v14
	s_movk_i32 s44, 0x3c0
	v_lshlrev_b32_e32 v14, 2, v14
	s_lshl_b32 s2, s50, 13
	v_and_or_b32 v15, v16, s44, v15
	v_and_b32_e32 v14, 32, v14
	v_bitop3_b32 v16, v15, s2, v14 bitop3:0xde
	s_lshl_b32 s2, s8, 5
	s_mov_b64 s[62:63], 0x80
	s_lshl_b32 s49, s50, 6
	s_and_b32 s50, s2, 0x60
	s_add_i32 m0, s38, 0x18000
	v_lshl_add_u64 v[6:7], v[6:7], 0, s[62:63]
	s_lshl_b32 s2, s50, 7
	s_waitcnt vmcnt(2)
	s_barrier
	global_load_lds_dwordx4 v[6:7], off
	v_lshl_add_u64 v[4:5], v[4:5], 0, s[62:63]
	s_add_i32 m0, s38, 0x1a000
	s_add_i32 s51, s38, 0x8000
	s_add_i32 s52, s38, 0xa000
	global_load_lds_dwordx4 v[4:5], off
	v_lshl_add_u64 v[0:1], v[0:1], 0, s[62:63]
	s_mov_b32 m0, s51
	s_add_u32 s54, s78, 0x20080
	global_load_lds_dwordx4 v[0:1], off
	v_lshl_add_u64 v[0:1], v[2:3], 0, s[62:63]
	s_mov_b32 m0, s52
	s_addc_u32 s55, s79, 0
	global_load_lds_dwordx4 v[0:1], off
	s_add_i32 m0, s38, 0x1c000
	v_lshl_add_u64 v[0:1], s[54:55], 0, v[128:129]
	global_load_lds_dwordx4 v128, s[54:55]
	v_lshl_add_u64 v[0:1], s[54:55], 0, v[130:131]
	s_add_i32 m0, s38, 0x1e000
	s_cmpk_lt_u32 s3, 0x100
	global_load_lds_dwordx4 v130, s[54:55]
	v_lshlrev_b32_e32 v0, 13, v8
	v_and_b32_e32 v0, 0xffffc000, v0
	v_lshl_add_u32 v0, v9, 10, v0
	v_and_b32_e32 v1, 1, v8
	v_lshl_or_b32 v0, v1, 6, v0
	v_lshl_add_u32 v136, v10, 1, v0
	v_lshlrev_b32_e32 v0, 13, v12
	v_and_b32_e32 v0, 0xffffc000, v0
	s_waitcnt vmcnt(6)
	s_mov_b32 s98, 0
	v_lshl_add_u32 v0, v11, 10, v0
	v_and_b32_e32 v1, 1, v12
	v_bitop3_b32 v148, s2, v15, v14 bitop3:0xf6
	s_cselect_b64 s[64:65], -1, 0
	v_lshl_or_b32 v0, v1, 6, v0
	s_add_i32 s53, 0, 0x10000
	s_add_i32 s54, 0, 0x14000
	s_mov_b32 s48, 0
	v_mov_b32_e32 v137, v129
	v_lshl_add_u32 v138, v13, 1, v0
	v_mov_b32_e32 v139, v129
	v_add_u32_e32 v149, s53, v148
	v_add_u32_e32 v150, s54, v148
	v_add_u32_e32 v151, 0, v16
	s_mov_b64 s[66:67], 0x100
	s_mov_b64 s[68:69], 0x180
	s_mov_b32 s55, 0xc2fc0000
	s_movk_i32 s56, 0x7f
	s_movk_i32 s57, 0x1800
	v_mov_b32_e32 v152, 0x42800000
	v_not_b32_e32 v153, 63
	s_barrier
	s_branch .LBB0_2543

; template <class Epi, class Sched, bool ALIGN_EPI = false, bool SP2 = false, bool A_TILED = false>
; __device__ __forceinline__ void gemm_phase(PG8_LAS unsigned char* lds, const Gemm g, const Sched& S, const Epi& E, const int wave_s) {
;     ...
;         const bool has_next = Epi::AFTER_DRAIN ? false : S.next(ui + 1, nxt);
;         const char* nA = has_next ? (const char*)g.A + (size_t)nxt.pm * tstepA : cA; const char* nB = has_next ? (const char*)g.Bt + (size_t)nxt.pn * tstep : cB;
;         constexpr bool PEEL = SP2 && !Epi::AFTER_DRAIN;
;         if constexpr (PEEL) {
;             const char* a1 = cA + kstepA; const char* a2 = cA + 2 * kstepA; const char* b2 = cB + 2 * kstep; const char* a3 = a2 + kstepA; const char* b3 = b2 + kstep;
;             PG8_ITER(PG8_MMAZ)
.LBB0_2545:
	s_ashr_i32 s73, s72, 31
	s_lshl_b64 s[58:59], s[72:73], 18
	s_add_u32 s74, s14, s58
	ds_read_b128 v[0:3], v149
	ds_read_b128 v[4:7], v149 offset:1024
	ds_read_b128 v[8:11], v149 offset:2048
	ds_read_b128 v[12:15], v149 offset:3072
	ds_read_b128 v[16:19], v150
	ds_read_b128 v[20:23], v150 offset:1024
	ds_read_b128 v[24:27], v150 offset:2048
	ds_read_b128 v[28:31], v150 offset:3072
	s_addc_u32 s75, s15, s59
	s_ashr_i32 s71, s70, 31
	s_lshl_b64 s[58:59], s[70:71], 18
	s_add_u32 s76, s23, s58
	s_addc_u32 s77, s36, s59
	s_and_b64 s[58:59], s[2:3], exec
	s_cselect_b32 s58, s75, s81
	s_cselect_b32 s59, s74, s80
	s_cselect_b32 s71, s77, s79
	s_cselect_b32 s73, s76, s78
	s_add_u32 s82, s80, 0x20080
	s_addc_u32 s83, s81, 0
	s_add_i32 s88, s38, 0xc000
	v_lshl_add_u64 v[64:65], s[82:83], 0, v[134:135]
	s_mov_b32 m0, s88
	s_add_i32 s89, s38, 0xe000
	ds_read_b128 v[32:35], v151
	ds_read_b128 v[36:39], v151 offset:1024
	ds_read_b128 v[40:43], v151 offset:2048
	ds_read_b128 v[44:47], v151 offset:3072
	ds_read_b128 v[48:51], v151 offset:4096
	ds_read_b128 v[52:55], v151 offset:5120
	ds_read_b128 v[56:59], v151 offset:6144
	ds_read_b128 v[60:63], v151 offset:7168
	global_load_lds_dwordx4 v134, s[82:83]
	v_lshl_add_u64 v[64:65], s[82:83], 0, v[132:133]
	s_mov_b32 m0, s89
	s_nop 0
	global_load_lds_dwordx4 v132, s[82:83]
	s_waitcnt vmcnt(24) lgkmcnt(0)
	s_cmp_lg_u32 s98, 0
	s_cbranch_scc1 .Lpw_11
	s_waitcnt vmcnt(8)
.Lpw_11:
	s_setprio 1
	s_barrier
	v_mfma_f32_16x16x32_bf16 v[88:91], v[0:3], v[56:59], 0
	v_mfma_f32_16x16x32_bf16 v[64:67], v[0:3], v[32:35], 0
	v_mfma_f32_16x16x32_bf16 v[68:71], v[8:11], v[32:35], 0
	v_mfma_f32_16x16x32_bf16 v[72:75], v[0:3], v[40:43], 0
	v_mfma_f32_16x16x32_bf16 v[76:79], v[8:11], v[40:43], 0
	v_mfma_f32_16x16x32_bf16 v[80:83], v[0:3], v[48:51], 0
	v_mfma_f32_16x16x32_bf16 v[84:87], v[8:11], v[48:51], 0
	v_mfma_f32_16x16x32_bf16 v[96:99], v[4:7], v[60:63], v[88:91]
	v_mfma_f32_16x16x32_bf16 v[88:91], v[8:11], v[56:59], 0
	v_mfma_f32_16x16x32_bf16 v[64:67], v[4:7], v[36:39], v[64:67]
	v_mfma_f32_16x16x32_bf16 v[68:71], v[12:15], v[36:39], v[68:71]
	v_mfma_f32_16x16x32_bf16 v[72:75], v[4:7], v[44:47], v[72:75]
	v_mfma_f32_16x16x32_bf16 v[76:79], v[12:15], v[44:47], v[76:79]
	v_mfma_f32_16x16x32_bf16 v[80:83], v[4:7], v[52:55], v[80:83]
	v_mfma_f32_16x16x32_bf16 v[84:87], v[12:15], v[52:55], v[84:87]
	v_mfma_f32_16x16x32_bf16 v[100:103], v[12:15], v[60:63], v[88:91]
	s_setprio 0
	s_setprio 1
	v_mfma_f32_16x16x32_bf16 v[88:91], v[16:19], v[32:35], 0
	v_mfma_f32_16x16x32_bf16 v[32:35], v[24:27], v[32:35], 0
	v_mfma_f32_16x16x32_bf16 v[112:115], v[20:23], v[36:39], v[88:91]
	v_mfma_f32_16x16x32_bf16 v[32:35], v[28:31], v[36:39], v[32:35]
	v_mfma_f32_16x16x32_bf16 v[36:39], v[16:19], v[40:43], 0
	v_mfma_f32_16x16x32_bf16 v[40:43], v[24:27], v[40:43], 0
	v_mfma_f32_16x16x32_bf16 v[36:39], v[20:23], v[44:47], v[36:39]
	v_mfma_f32_16x16x32_bf16 v[40:43], v[28:31], v[44:47], v[40:43]
	v_mfma_f32_16x16x32_bf16 v[44:47], v[16:19], v[48:51], 0
	v_mfma_f32_16x16x32_bf16 v[48:51], v[24:27], v[48:51], 0
	v_mfma_f32_16x16x32_bf16 v[44:47], v[20:23], v[52:55], v[44:47]
	v_mfma_f32_16x16x32_bf16 v[48:51], v[28:31], v[52:55], v[48:51]
	v_mfma_f32_16x16x32_bf16 v[52:55], v[16:19], v[56:59], 0
	v_mfma_f32_16x16x32_bf16 v[56:59], v[24:27], v[56:59], 0
	v_mfma_f32_16x16x32_bf16 v[52:55], v[20:23], v[60:63], v[52:55]
	v_mfma_f32_16x16x32_bf16 v[56:59], v[28:31], v[60:63], v[56:59]
	s_barrier
	s_setprio 0
	s_add_i32 s90, s53, s37
	v_lshl_add_u64 v[250:251], s[78:79], 0, v[128:129]
	s_add_i32 s91, s90, 0x2000
	v_lshl_add_u64 v[144:145], v[250:251], 0, s[66:67]
	s_mov_b32 m0, s90
	v_lshl_add_u64 v[252:253], s[78:79], 0, v[130:131]
	s_add_u32 s82, s78, 0x20100
	ds_read_b128 v[60:63], v151 offset:16384
	ds_read_b128 v[88:91], v151 offset:17408
	ds_read_b128 v[92:95], v151 offset:18432
	ds_read_b128 v[104:107], v151 offset:19456
	ds_read_b128 v[108:111], v151 offset:20480
	ds_read_b128 v[116:119], v151 offset:21504
	ds_read_b128 v[120:123], v151 offset:22528
	ds_read_b128 v[124:127], v151 offset:23552
	global_load_lds_dwordx4 v[144:145], off
	v_lshl_add_u64 v[144:145], v[252:253], 0, s[66:67]
	s_mov_b32 m0, s91
	s_addc_u32 s83, s79, 0
	s_add_i32 s93, s54, s37
	global_load_lds_dwordx4 v[144:145], off
	v_lshl_add_u64 v[144:145], s[82:83], 0, v[128:129]
	s_mov_b32 m0, s93
	s_add_i32 s95, s93, 0x2000
	global_load_lds_dwordx4 v128, s[82:83]
	v_lshl_add_u64 v[144:145], s[82:83], 0, v[130:131]
	s_mov_b32 m0, s95
	v_lshl_add_u64 v[140:141], s[80:81], 0, v[134:135]
	global_load_lds_dwordx4 v130, s[82:83]
	v_lshl_add_u64 v[144:145], v[140:141], 0, s[66:67]
	s_mov_b32 m0, s38
	v_lshl_add_u64 v[142:143], s[80:81], 0, v[132:133]
	global_load_lds_dwordx4 v[144:145], off
	v_lshl_add_u64 v[144:145], v[142:143], 0, s[66:67]
	s_mov_b32 m0, s39
	s_nop 0
	global_load_lds_dwordx4 v[144:145], off
	s_waitcnt vmcnt(24) lgkmcnt(0)
	s_cmp_lg_u32 s98, 0
	s_cbranch_scc1 .Lpw_12
	s_waitcnt vmcnt(8)
.Lpw_12:
	s_setprio 1
	s_barrier
	v_mfma_f32_16x16x32_bf16 v[144:147], v[0:3], v[60:63], 0
	v_mfma_f32_16x16x32_bf16 v[154:157], v[4:7], v[88:91], v[144:147]
	v_mfma_f32_16x16x32_bf16 v[144:147], v[8:11], v[60:63], 0
	v_mfma_f32_16x16x32_bf16 v[158:161], v[12:15], v[88:91], v[144:147]
	v_mfma_f32_16x16x32_bf16 v[144:147], v[0:3], v[92:95], 0
	v_mfma_f32_16x16x32_bf16 v[162:165], v[4:7], v[104:107], v[144:147]
	v_mfma_f32_16x16x32_bf16 v[144:147], v[8:11], v[92:95], 0
	v_mfma_f32_16x16x32_bf16 v[166:169], v[12:15], v[104:107], v[144:147]
	v_mfma_f32_16x16x32_bf16 v[144:147], v[0:3], v[108:111], 0
	v_mfma_f32_16x16x32_bf16 v[0:3], v[0:3], v[120:123], 0
	v_mfma_f32_16x16x32_bf16 v[170:173], v[4:7], v[116:119], v[144:147]
	v_mfma_f32_16x16x32_bf16 v[0:3], v[4:7], v[124:127], v[0:3]
	v_mfma_f32_16x16x32_bf16 v[4:7], v[8:11], v[120:123], 0
	v_mfma_f32_16x16x32_bf16 v[144:147], v[8:11], v[108:111], 0
	v_mfma_f32_16x16x32_bf16 v[4:7], v[12:15], v[124:127], v[4:7]
	v_mfma_f32_16x16x32_bf16 v[174:177], v[12:15], v[116:119], v[144:147]
	s_setprio 0
	s_setprio 1
	v_mfma_f32_16x16x32_bf16 v[8:11], v[16:19], v[60:63], 0
	v_mfma_f32_16x16x32_bf16 v[178:181], v[20:23], v[88:91], v[8:11]
	v_mfma_f32_16x16x32_bf16 v[8:11], v[24:27], v[60:63], 0
	v_mfma_f32_16x16x32_bf16 v[182:185], v[28:31], v[88:91], v[8:11]
	v_mfma_f32_16x16x32_bf16 v[8:11], v[16:19], v[92:95], 0
	v_mfma_f32_16x16x32_bf16 v[186:189], v[20:23], v[104:107], v[8:11]
	v_mfma_f32_16x16x32_bf16 v[8:11], v[24:27], v[92:95], 0
	v_mfma_f32_16x16x32_bf16 v[190:193], v[28:31], v[104:107], v[8:11]
	v_mfma_f32_16x16x32_bf16 v[8:11], v[16:19], v[108:111], 0
	v_mfma_f32_16x16x32_bf16 v[194:197], v[20:23], v[116:119], v[8:11]
	v_mfma_f32_16x16x32_bf16 v[8:11], v[24:27], v[108:111], 0
	v_mfma_f32_16x16x32_bf16 v[198:201], v[28:31], v[116:119], v[8:11]
	v_mfma_f32_16x16x32_bf16 v[8:11], v[16:19], v[120:123], 0
	v_mfma_f32_16x16x32_bf16 v[202:205], v[20:23], v[124:127], v[8:11]
	v_mfma_f32_16x16x32_bf16 v[8:11], v[24:27], v[120:123], 0
	v_mfma_f32_16x16x32_bf16 v[206:209], v[28:31], v[124:127], v[8:11]
	s_barrier
	s_setprio 0
	s_add_i32 s96, 0, 0x18000
	s_add_i32 vcc_lo, 0, 0x1c000
	v_add_u32_e32 v144, s96, v148
	v_add_u32_e32 v145, vcc_lo, v148
	s_nop 0
	ds_read_b128 v[8:11], v144
	ds_read_b128 v[12:15], v144 offset:1024
	ds_read_b128 v[16:19], v144 offset:2048
	ds_read_b128 v[20:23], v144 offset:3072
	ds_read_b128 v[210:213], v145
	ds_read_b128 v[214:217], v145 offset:1024
	ds_read_b128 v[218:221], v145 offset:2048
	ds_read_b128 v[222:225], v145 offset:3072
	s_add_u32 s82, s80, 0x20100
	s_addc_u32 s83, s81, 0
	s_mov_b32 m0, s40
	v_lshl_add_u64 v[88:89], s[82:83], 0, v[134:135]
	ds_read_b128 v[24:27], v151 offset:32768
	ds_read_b128 v[28:31], v151 offset:33792
	ds_read_b128 v[60:63], v151 offset:34816
	ds_read_b128 v[226:229], v151 offset:35840
	ds_read_b128 v[230:233], v151 offset:36864
	ds_read_b128 v[234:237], v151 offset:37888
	ds_read_b128 v[238:241], v151 offset:38912
	ds_read_b128 v[242:245], v151 offset:39936
	global_load_lds_dwordx4 v134, s[82:83]
	v_lshl_add_u64 v[88:89], s[82:83], 0, v[132:133]
	s_mov_b32 m0, s41
	s_nop 0
	global_load_lds_dwordx4 v132, s[82:83]
	s_waitcnt vmcnt(8) lgkmcnt(0)
	s_setprio 1
	s_barrier
	v_mfma_f32_16x16x32_bf16 v[64:67], v[8:11], v[24:27], v[64:67]
	v_mfma_f32_16x16x32_bf16 v[124:127], v[12:15], v[28:31], v[64:67]
	v_mfma_f32_16x16x32_bf16 v[64:67], v[16:19], v[24:27], v[68:71]
	v_mfma_f32_16x16x32_bf16 v[120:123], v[20:23], v[28:31], v[64:67]
	v_mfma_f32_16x16x32_bf16 v[64:67], v[8:11], v[60:63], v[72:75]
	v_mfma_f32_16x16x32_bf16 v[108:111], v[12:15], v[226:229], v[64:67]
	v_mfma_f32_16x16x32_bf16 v[64:67], v[16:19], v[60:63], v[76:79]
	v_mfma_f32_16x16x32_bf16 v[104:107], v[20:23], v[226:229], v[64:67]
	v_mfma_f32_16x16x32_bf16 v[64:67], v[8:11], v[230:233], v[80:83]
	v_mfma_f32_16x16x32_bf16 v[92:95], v[12:15], v[234:237], v[64:67]
	v_mfma_f32_16x16x32_bf16 v[64:67], v[16:19], v[230:233], v[84:87]
	v_mfma_f32_16x16x32_bf16 v[88:91], v[20:23], v[234:237], v[64:67]
	v_mfma_f32_16x16x32_bf16 v[64:67], v[8:11], v[238:241], v[96:99]
	v_mfma_f32_16x16x32_bf16 v[76:79], v[12:15], v[242:245], v[64:67]
	v_mfma_f32_16x16x32_bf16 v[64:67], v[16:19], v[238:241], v[100:103]
	v_mfma_f32_16x16x32_bf16 v[72:75], v[20:23], v[242:245], v[64:67]
	s_setprio 0
	s_setprio 1
	v_mfma_f32_16x16x32_bf16 v[64:67], v[210:213], v[24:27], v[112:115]
	v_mfma_f32_16x16x32_bf16 v[24:27], v[218:221], v[24:27], v[32:35]
	v_mfma_f32_16x16x32_bf16 v[112:115], v[222:225], v[28:31], v[24:27]
	v_mfma_f32_16x16x32_bf16 v[24:27], v[210:213], v[60:63], v[36:39]
	v_mfma_f32_16x16x32_bf16 v[100:103], v[214:217], v[226:229], v[24:27]
	v_mfma_f32_16x16x32_bf16 v[24:27], v[218:221], v[60:63], v[40:43]
	v_mfma_f32_16x16x32_bf16 v[96:99], v[222:225], v[226:229], v[24:27]
	v_mfma_f32_16x16x32_bf16 v[24:27], v[210:213], v[230:233], v[44:47]
	v_mfma_f32_16x16x32_bf16 v[84:87], v[214:217], v[234:237], v[24:27]
	v_mfma_f32_16x16x32_bf16 v[24:27], v[218:221], v[230:233], v[48:51]
	v_mfma_f32_16x16x32_bf16 v[80:83], v[222:225], v[234:237], v[24:27]
	v_mfma_f32_16x16x32_bf16 v[24:27], v[210:213], v[238:241], v[52:55]
	v_mfma_f32_16x16x32_bf16 v[68:71], v[214:217], v[242:245], v[24:27]
	v_mfma_f32_16x16x32_bf16 v[24:27], v[218:221], v[238:241], v[56:59]
	v_mfma_f32_16x16x32_bf16 v[116:119], v[214:217], v[28:31], v[64:67]
	v_mfma_f32_16x16x32_bf16 v[64:67], v[222:225], v[242:245], v[24:27]
	s_barrier
; template <class Epi, class Sched, bool ALIGN_EPI = false, bool SP2 = false, bool A_TILED = false>
; __device__ __forceinline__ void gemm_phase(PG8_LAS unsigned char* lds, const Gemm g, const Sched& S, const Epi& E, const int wave_s) {
;     ...
;         for (int t = PEEL ? 2 : 0; t < nt; t += 2) {
;             const bool last = (t == nt - 2);
;             const char* a1 = cA + (size_t)(t + 1) * kstepA;
;             const char* a2 = last ? nA : cA + (size_t)(t + 2) * kstepA; const char* b2 = last ? nB : cB + (size_t)(t + 2) * kstep;
;             const char* a3 = a2 + kstepA; const char* b3 = b2 + kstep;
	s_setprio 0
	s_add_i32 s96, s96, s37
	s_add_i32 s97, s96, 0x2000
	s_nop 1
	v_lshl_add_u64 v[24:25], v[250:251], 0, s[68:69]
	s_mov_b32 m0, s96
	s_add_u32 s82, s78, 0x20180
	ds_read_b128 v[32:35], v151 offset:49152
	ds_read_b128 v[36:39], v151 offset:50176
	ds_read_b128 v[226:229], v151 offset:51200
	ds_read_b128 v[230:233], v151 offset:52224
	ds_read_b128 v[234:237], v151 offset:53248
	ds_read_b128 v[238:241], v151 offset:54272
	ds_read_b128 v[242:245], v151 offset:55296
	ds_read_b128 v[246:249], v151 offset:56320
	global_load_lds_dwordx4 v[24:25], off
	v_lshl_add_u64 v[24:25], v[252:253], 0, s[68:69]
	s_mov_b32 m0, s97
	s_addc_u32 s83, s79, 0
	s_add_i32 vcc_lo, vcc_lo, s37
	global_load_lds_dwordx4 v[24:25], off
	v_lshl_add_u64 v[24:25], s[82:83], 0, v[128:129]
	s_mov_b32 m0, vcc_lo
	s_add_i32 vcc_hi, vcc_lo, 0x2000
	global_load_lds_dwordx4 v128, s[82:83]
	v_lshl_add_u64 v[24:25], s[82:83], 0, v[130:131]
	s_mov_b32 m0, vcc_hi
	s_nop 0
	global_load_lds_dwordx4 v130, s[82:83]
	v_lshl_add_u64 v[24:25], v[140:141], 0, s[68:69]
	s_mov_b32 m0, s51
	s_nop 0
	global_load_lds_dwordx4 v[24:25], off
	v_lshl_add_u64 v[24:25], v[142:143], 0, s[68:69]
	s_mov_b32 m0, s52
	s_nop 0
	global_load_lds_dwordx4 v[24:25], off
	s_waitcnt vmcnt(8) lgkmcnt(0)
	s_setprio 1
	s_barrier
	v_mfma_f32_16x16x32_bf16 v[24:27], v[8:11], v[32:35], v[154:157]
	v_mfma_f32_16x16x32_bf16 v[60:63], v[12:15], v[36:39], v[24:27]
	v_mfma_f32_16x16x32_bf16 v[24:27], v[16:19], v[32:35], v[158:161]
	v_mfma_f32_16x16x32_bf16 v[56:59], v[20:23], v[36:39], v[24:27]
	v_mfma_f32_16x16x32_bf16 v[24:27], v[8:11], v[226:229], v[162:165]
	v_mfma_f32_16x16x32_bf16 v[44:47], v[12:15], v[230:233], v[24:27]
	v_mfma_f32_16x16x32_bf16 v[24:27], v[16:19], v[226:229], v[166:169]
	v_mfma_f32_16x16x32_bf16 v[40:43], v[20:23], v[230:233], v[24:27]
	v_mfma_f32_16x16x32_bf16 v[24:27], v[8:11], v[234:237], v[170:173]
	v_mfma_f32_16x16x32_bf16 v[0:3], v[8:11], v[242:245], v[0:3]
	v_mfma_f32_16x16x32_bf16 v[28:31], v[12:15], v[238:241], v[24:27]
	v_mfma_f32_16x16x32_bf16 v[24:27], v[16:19], v[234:237], v[174:177]
	v_mfma_f32_16x16x32_bf16 v[12:15], v[12:15], v[246:249], v[0:3]
	v_mfma_f32_16x16x32_bf16 v[0:3], v[16:19], v[242:245], v[4:7]
	v_mfma_f32_16x16x32_bf16 v[24:27], v[20:23], v[238:241], v[24:27]
	v_mfma_f32_16x16x32_bf16 v[8:11], v[20:23], v[246:249], v[0:3]
	s_setprio 0
	s_setprio 1
	v_mfma_f32_16x16x32_bf16 v[0:3], v[210:213], v[32:35], v[178:181]
	v_mfma_f32_16x16x32_bf16 v[52:55], v[214:217], v[36:39], v[0:3]
	v_mfma_f32_16x16x32_bf16 v[0:3], v[218:221], v[32:35], v[182:185]
	v_mfma_f32_16x16x32_bf16 v[48:51], v[222:225], v[36:39], v[0:3]
	v_mfma_f32_16x16x32_bf16 v[0:3], v[210:213], v[226:229], v[186:189]
	v_mfma_f32_16x16x32_bf16 v[36:39], v[214:217], v[230:233], v[0:3]
	v_mfma_f32_16x16x32_bf16 v[0:3], v[218:221], v[226:229], v[190:193]
	v_mfma_f32_16x16x32_bf16 v[32:35], v[222:225], v[230:233], v[0:3]
	v_mfma_f32_16x16x32_bf16 v[0:3], v[210:213], v[234:237], v[194:197]
	v_mfma_f32_16x16x32_bf16 v[20:23], v[214:217], v[238:241], v[0:3]
	v_mfma_f32_16x16x32_bf16 v[0:3], v[218:221], v[234:237], v[198:201]
	v_mfma_f32_16x16x32_bf16 v[16:19], v[222:225], v[238:241], v[0:3]
	v_mfma_f32_16x16x32_bf16 v[0:3], v[210:213], v[242:245], v[202:205]
	v_mfma_f32_16x16x32_bf16 v[4:7], v[214:217], v[246:249], v[0:3]
	v_mfma_f32_16x16x32_bf16 v[0:3], v[218:221], v[242:245], v[206:209]
	v_mfma_f32_16x16x32_bf16 v[0:3], v[222:225], v[246:249], v[0:3]
	s_barrier
	s_setprio 0
	s_add_u32 s85, s78, 0x200
	s_addc_u32 s8, s79, 0
	s_add_u32 s78, s80, 0x20180
	s_addc_u32 s79, s81, 0
	s_mov_b32 s94, 0

;     __device__ __forceinline__ void operator()(const f32x4 (&acc)[2][2][4][2], const Unit& u, int wr, int wc, int fr, int fq) const {
;     ...
;         float rinv3[2][4]; bool rope3[2];
;         if (ACT == 3) {
; #pragma unroll
;             for (int bj = 0; bj < 2; ++bj) { const int jj = (col0 + bj * HALF) % 192; rope3[bj] = jj >= 128; const int i0 = (jj - 128) >> 1;
; #pragma unroll
;                 for (int p = 0; p < 4; ++p) rinv3[bj][p] = exp2f(-(float)(i0 + p) * (13.287712379549449f / 32.0f)) * 0.15915494309189535f; }
;         }
; #pragma unroll
;         for (int ai = 0; ai < 2; ++ai)
; #pragma unroll
;             for (int m = 0; m < 4; ++m) { bf16_t* rowp = O + (size_t)(row0 + ai * HALF + m * 16) * ldc + col0;
;                 if (ACT == 1) {
;                     const int ob = fr * 64 + 16 * fq, sw = ob ^ (((ob >> 9) & 1) << 5);
;                     rowp = O + ((size_t)(u.pm * (ldc / 64) + u.pn * 4 + (wc >> 1)) * 2 + ai) * 8192 + (((wr * 4 + m) * 2 + (wc & 1)) * 1024 + sw) / 2; }
;                 float rc[2][2], rs[2][2];
;                 if (ACT == 2) { const float pos = (float)((row0 + ai * HALF + m * 16) & 2047);
; #pragma unroll
;                     for (int n = 0; n < 2; ++n)
; #pragma unroll
;                         for (int e = 0; e < 2; ++e) { float r = pos * rinv[n][e]; r -= floorf(r); rs[n][e] = do_rope ? __builtin_amdgcn_sinf(r) : 0.f; rc[n][e] = do_rope ? __builtin_amdgcn_cosf(r) : 1.f; } }
; #pragma unroll
;                 for (int bj = 0; bj < 2; ++bj) { f32x4 v0 = acc[ai][bj][m][0], v1 = acc[ai][bj][m][1];
;                     if (ACT == 3) { const float pos = (float)((row0 + ai * HALF + m * 16) & 2047); float c3[4], s3[4];
; #pragma unroll
;                         for (int p = 0; p < 4; ++p) { float r = pos * rinv3[bj][p]; r -= floorf(r); s3[p] = rope3[bj] ? __builtin_amdgcn_sinf(r) : 0.f; c3[p] = rope3[bj] ? __builtin_amdgcn_cosf(r) : 1.f; }
;                         const f32x4 a = v0, b = v1;
;                         v0[0] = a[0] * c3[0] - a[1] * s3[0]; v0[1] = a[1] * c3[0] + a[0] * s3[0]; v0[2] = a[2] * c3[1] - a[3] * s3[1]; v0[3] = a[3] * c3[1] + a[2] * s3[1];
;                         v1[0] = b[0] * c3[2] - b[1] * s3[2]; v1[1] = b[1] * c3[2] + b[0] * s3[2]; v1[2] = b[2] * c3[3] - b[3] * s3[3]; v1[3] = b[3] * c3[3] + b[2] * s3[3]; }
.LBB0_2549:
	v_mov_b32_e32 v140, 0
	s_lshl_b32 s5, s5, 8
	v_mbcnt_lo_u32_b32 v140, -1, v140
	v_mbcnt_hi_u32_b32 v140, -1, v140
	v_or_b32_e32 v141, s33, v140
	s_lshl_b32 s4, s4, 8
	v_lshrrev_b32_e32 v140, 1, v141
	v_and_or_b32 v140, v140, 24, s5
	v_or_b32_e32 v140, s50, v140
	v_mul_hi_i32 v142, v140, s43
	v_lshrrev_b32_e32 v143, 31, v142
	v_lshrrev_b32_e32 v142, 5, v142
	v_add_u32_e32 v142, v142, v143
	v_mul_lo_u32 v142, v142, s42
	v_sub_u32_e32 v163, v140, v142
	v_add_u32_e32 v142, 0xffffff80, v163
	v_ashrrev_i32_e32 v142, 1, v142
	v_cvt_f32_i32_e32 v143, v142
	v_and_b32_e32 v146, 15, v141
	s_add_i32 s4, s4, s49
	v_or_b32_e32 v162, s4, v146
	v_mul_f32_e32 v141, 0xbed49a78, v143
	v_cmp_gt_f32_e32 vcc, s55, v141
	s_movk_i32 s8, 0x7df
	s_nop 0
	v_cndmask_b32_e32 v141, 0, v152, vcc
	v_fmac_f32_e32 v141, 0xbed49a78, v143
	v_exp_f32_e32 v141, v141
	v_or_b32_e32 v143, 1, v142
	v_cvt_f32_i32_e32 v143, v143
	v_cndmask_b32_e32 v144, 0, v153, vcc
	v_ldexp_f32 v141, v141, v144
	v_mul_f32_e32 v154, 0.15915494, v141
	v_mul_f32_e32 v141, 0xbed49a78, v143
	v_cmp_gt_f32_e32 vcc, s55, v141
	s_nop 1
	v_cndmask_b32_e32 v141, 0, v152, vcc
	v_fmac_f32_e32 v141, 0xbed49a78, v143
	v_exp_f32_e32 v141, v141
	v_or_b32_e32 v143, 2, v142
	v_cvt_f32_i32_e32 v143, v143
	v_cndmask_b32_e32 v144, 0, v153, vcc
	v_ldexp_f32 v141, v141, v144
	v_mul_f32_e32 v156, 0.15915494, v141
	v_mul_f32_e32 v141, 0xbed49a78, v143
	v_cmp_gt_f32_e32 vcc, s55, v141
	v_or_b32_e32 v142, 3, v142
	v_cvt_f32_i32_e32 v142, v142
	v_cndmask_b32_e32 v141, 0, v152, vcc
	v_fmac_f32_e32 v141, 0xbed49a78, v143
	v_exp_f32_e32 v141, v141
	v_cndmask_b32_e32 v143, 0, v153, vcc
	v_ldexp_f32 v141, v141, v143
	v_mul_f32_e32 v158, 0.15915494, v141
	v_mul_f32_e32 v141, 0xbed49a78, v142
	v_cmp_gt_f32_e32 vcc, s55, v141
	s_nop 1
	v_cndmask_b32_e32 v141, 0, v152, vcc
	v_fmac_f32_e32 v141, 0xbed49a78, v142
	v_or_b32_e32 v142, 0x80, v140
	v_mul_hi_i32 v143, v142, s43
	v_lshrrev_b32_e32 v144, 31, v143
	v_lshrrev_b32_e32 v143, 5, v143
	v_add_u32_e32 v143, v143, v144
	v_mul_lo_u32 v143, v143, s42
	v_sub_u32_e32 v164, v142, v143
	v_add_u32_e32 v142, 0xffffff80, v164
	v_exp_f32_e32 v141, v141
	v_ashrrev_i32_e32 v142, 1, v142
	v_cvt_f32_i32_e32 v143, v142
	v_cndmask_b32_e32 v144, 0, v153, vcc
	v_ldexp_f32 v141, v141, v144
	v_mul_f32_e32 v161, 0.15915494, v141
	v_mul_f32_e32 v141, 0xbed49a78, v143
	v_cmp_gt_f32_e32 vcc, s55, v141
	s_nop 1
	v_cndmask_b32_e32 v141, 0, v152, vcc
	v_fmac_f32_e32 v141, 0xbed49a78, v143
	v_exp_f32_e32 v141, v141
	v_add_u32_e32 v143, 1, v142
	v_cvt_f32_i32_e32 v143, v143
	v_cndmask_b32_e32 v144, 0, v153, vcc
	v_ldexp_f32 v141, v141, v144
	v_mul_f32_e32 v155, 0.15915494, v141
	v_mul_f32_e32 v141, 0xbed49a78, v143
	v_cmp_gt_f32_e32 vcc, s55, v141
	s_nop 1
	v_cndmask_b32_e32 v141, 0, v152, vcc
	v_fmac_f32_e32 v141, 0xbed49a78, v143
	v_exp_f32_e32 v141, v141
	v_add_u32_e32 v143, 2, v142
	v_cvt_f32_i32_e32 v143, v143
	v_add_u32_e32 v142, 3, v142
	v_cndmask_b32_e32 v144, 0, v153, vcc
	v_cvt_f32_i32_e32 v142, v142
	v_ldexp_f32 v141, v141, v144
	v_mul_f32_e32 v157, 0.15915494, v141
	v_mul_f32_e32 v141, 0xbed49a78, v143
	v_cmp_gt_f32_e32 vcc, s55, v141
	v_mul_f32_e32 v144, 0xbed49a78, v142
	s_nop 0
	v_cndmask_b32_e32 v141, 0, v152, vcc
	v_fmac_f32_e32 v141, 0xbed49a78, v143
	v_cndmask_b32_e32 v143, 0, v153, vcc
	v_cmp_gt_f32_e32 vcc, s55, v144
	v_exp_f32_e32 v141, v141
	s_nop 0
	v_cndmask_b32_e32 v144, 0, v152, vcc
	v_fmac_f32_e32 v144, 0xbed49a78, v142
	v_exp_f32_e32 v142, v144
	v_ldexp_f32 v141, v141, v143
	v_mul_f32_e32 v160, 0.15915494, v141
	v_cndmask_b32_e32 v141, 0, v153, vcc
	v_ldexp_f32 v141, v142, v141
	v_mov_b32_e32 v142, s4
	s_movk_i32 s4, 0x7cf
	v_bitop3_b32 v142, v146, s4, v142 bitop3:0xc8
	v_cvt_f32_u32_e32 v165, v142
	v_mul_f32_e32 v159, 0.15915494, v141
	v_ashrrev_i32_e32 v141, 31, v140
	v_mov_b64_e32 v[144:145], s[60:61]
	v_mul_f32_e32 v166, v156, v165
	v_floor_f32_e32 v166, v166
	v_fma_f32 v166, v156, v165, -v166
	v_sin_f32_e32 v167, v166
	v_mad_i64_i32 v[142:143], s[4:5], v162, s57, v[144:145]
	v_lshlrev_b64 v[146:147], 1, v[140:141]
	v_lshl_add_u64 v[140:141], v[142:143], 0, v[146:147]
	v_mul_f32_e32 v142, v154, v165
	v_floor_f32_e32 v142, v142
	v_cmp_lt_i32_e32 vcc, s56, v163
	v_fma_f32 v142, v154, v165, -v142
	v_sin_f32_e32 v143, v142
	v_cndmask_b32_e32 v163, 0, v167, vcc
	v_mul_f32_e32 v167, v158, v165
	v_cos_f32_e32 v142, v142
	v_floor_f32_e32 v167, v167
	v_mul_f32_e32 v169, v161, v165
	v_cos_f32_e32 v166, v166
	v_fma_f32 v167, v158, v165, -v167
	v_floor_f32_e32 v169, v169
	v_sin_f32_e32 v168, v167
	v_cos_f32_e32 v167, v167
	v_fma_f32 v169, v161, v165, -v169
	v_sin_f32_e32 v170, v169
	v_cos_f32_e32 v169, v169
	v_cndmask_b32_e32 v143, 0, v143, vcc
	v_cndmask_b32_e32 v142, 1.0, v142, vcc
	v_cndmask_b32_e32 v166, 1.0, v166, vcc
	v_mul_f32_e32 v171, v125, v143
	v_mul_f32_e32 v125, v125, v142
	v_cndmask_b32_e32 v168, 0, v168, vcc
	v_cndmask_b32_e32 v167, 1.0, v167, vcc
	v_fma_f32 v171, v124, v142, -v171
	v_fmac_f32_e32 v125, v124, v143
	v_mul_f32_e32 v124, v127, v163
	v_mul_f32_e32 v127, v127, v166
	v_cndmask_b32_e32 v170, 0, v170, vcc
	v_cndmask_b32_e32 v169, 1.0, v169, vcc
	v_fma_f32 v124, v126, v166, -v124
	v_fmac_f32_e32 v127, v126, v163
	v_mul_f32_e32 v126, v121, v168
	v_mul_f32_e32 v142, v121, v167
	v_fma_f32 v126, v120, v167, -v126
	v_fmac_f32_e32 v142, v120, v168
	v_mul_f32_e32 v120, v123, v170
	v_mul_f32_e32 v123, v123, v169
	v_fma_f32 v143, v122, v169, -v120
	v_fmac_f32_e32 v123, v122, v170
	v_cvt_pk_bf16_f32 v120, v171, v125
	v_cvt_pk_bf16_f32 v121, v124, v127
	v_cvt_pk_bf16_f32 v122, v126, v142
	v_cvt_pk_bf16_f32 v123, v143, v123
	global_store_dwordx4 v[140:141], v[120:123], off
; __device__ __forceinline__ unsigned cvt_pk_bf16(float lo, float hi) { unsigned r; asm volatile("v_cvt_pk_bf16_f32 %0, %1, %2" : "=v"(r) : "v"(lo), "v"(hi)); return r; }
;     __device__ __forceinline__ void operator()(const f32x4 (&acc)[2][2][4][2], const Unit& u, int wr, int wc, int fr, int fq) const {
;     ...
;                 for (int bj = 0; bj < 2; ++bj) { f32x4 v0 = acc[ai][bj][m][0], v1 = acc[ai][bj][m][1];
;                     if (ACT == 3) { const float pos = (float)((row0 + ai * HALF + m * 16) & 2047); float c3[4], s3[4];
; #pragma unroll
;                         for (int p = 0; p < 4; ++p) { float r = pos * rinv3[bj][p]; r -= floorf(r); s3[p] = rope3[bj] ? __builtin_amdgcn_sinf(r) : 0.f; c3[p] = rope3[bj] ? __builtin_amdgcn_cosf(r) : 1.f; }
;                         const f32x4 a = v0, b = v1;
;                         v0[0] = a[0] * c3[0] - a[1] * s3[0]; v0[1] = a[1] * c3[0] + a[0] * s3[0]; v0[2] = a[2] * c3[1] - a[3] * s3[1]; v0[3] = a[3] * c3[1] + a[2] * s3[1];
;                         v1[0] = b[0] * c3[2] - b[1] * s3[2]; v1[1] = b[1] * c3[2] + b[0] * s3[2]; v1[2] = b[2] * c3[3] - b[3] * s3[3]; v1[3] = b[3] * c3[3] + b[2] * s3[3]; }
;                     if (ACT == 2) { const f32x4 a = v0, b = v1;
;                         v0[0] = a[0] * rc[0][0] - a[1] * rs[0][0]; v0[1] = a[1] * rc[0][0] + a[0] * rs[0][0]; v0[2] = a[2] * rc[0][1] - a[3] * rs[0][1]; v0[3] = a[3] * rc[0][1] + a[2] * rs[0][1];
;                         v1[0] = b[0] * rc[1][0] - b[1] * rs[1][0]; v1[1] = b[1] * rc[1][0] + b[0] * rs[1][0]; v1[2] = b[2] * rc[1][1] - b[3] * rs[1][1]; v1[3] = b[3] * rc[1][1] + b[2] * rs[1][1]; }
;                     if (ACT == 1) {
; #pragma unroll
;                         for (int j = 0; j < 4; ++j) { const float a = __int_as_float(max(__float_as_int(v0[j]), 0)), b = __int_as_float(max(__float_as_int(v1[j]), 0)); v0[j] = a * a; v1[j] = b * b; } }
;                     u32x4 w; w.x = cvt_pk_bf16(v0[0], v0[1]); w.y = cvt_pk_bf16(v0[2], v0[3]); w.z = cvt_pk_bf16(v1[0], v1[1]); w.w = cvt_pk_bf16(v1[2], v1[3]);
;                     *(u32x4*)(rowp + (ACT == 1 ? bj * 2 * 2 * 8192 : bj * HALF)) = w; } }
	v_mul_f32_e32 v124, v160, v165
	v_floor_f32_e32 v124, v124
	v_mul_f32_e32 v120, v155, v165
	v_floor_f32_e32 v120, v120
	v_mul_f32_e32 v122, v157, v165
	v_fma_f32 v120, v155, v165, -v120
	v_floor_f32_e32 v122, v122
	v_sin_f32_e32 v121, v120
	v_cos_f32_e32 v120, v120
	v_fma_f32 v122, v157, v165, -v122
	v_mul_f32_e32 v126, v159, v165
	v_sin_f32_e32 v123, v122
	v_cos_f32_e32 v122, v122
	v_fma_f32 v124, v160, v165, -v124
	v_floor_f32_e32 v126, v126
	v_sin_f32_e32 v125, v124
	v_cos_f32_e32 v124, v124
	v_fma_f32 v126, v159, v165, -v126
	v_cmp_lt_i32_e64 s[4:5], s56, v164
	v_sin_f32_e32 v127, v126
	v_cos_f32_e32 v126, v126
	v_cndmask_b32_e64 v121, 0, v121, s[4:5]
	v_cndmask_b32_e64 v120, 1.0, v120, s[4:5]
	v_cndmask_b32_e64 v123, 0, v123, s[4:5]
	v_cndmask_b32_e64 v122, 1.0, v122, s[4:5]
	v_mul_f32_e32 v142, v117, v121
	v_mul_f32_e32 v117, v117, v120
	v_cndmask_b32_e64 v125, 0, v125, s[4:5]
	v_cndmask_b32_e64 v124, 1.0, v124, s[4:5]
	v_fma_f32 v142, v116, v120, -v142
	v_fmac_f32_e32 v117, v116, v121
	v_mul_f32_e32 v116, v119, v123
	v_mul_f32_e32 v119, v119, v122
	v_cndmask_b32_e64 v127, 0, v127, s[4:5]
	v_cndmask_b32_e64 v126, 1.0, v126, s[4:5]
	v_fma_f32 v116, v118, v122, -v116
	v_fmac_f32_e32 v119, v118, v123
	v_mul_f32_e32 v118, v113, v125
	v_mul_f32_e32 v120, v113, v124
	v_fma_f32 v118, v112, v124, -v118
	v_fmac_f32_e32 v120, v112, v125
	v_mul_f32_e32 v112, v115, v127
	v_mul_f32_e32 v115, v115, v126
	v_fma_f32 v121, v114, v126, -v112
	v_fmac_f32_e32 v115, v114, v127
	v_cvt_pk_bf16_f32 v112, v142, v117
	v_cvt_pk_bf16_f32 v113, v116, v119
	v_cvt_pk_bf16_f32 v114, v118, v120
	v_cvt_pk_bf16_f32 v115, v121, v115
	global_store_dwordx4 v[140:141], v[112:115], off offset:256
	s_nop 1
	v_bitop3_b32 v113, v162, s8, 16 bitop3:0xc8
	v_cvt_f32_u32_e32 v114, v113
	v_or_b32_e32 v112, 16, v162
	v_mad_i64_i32 v[112:113], s[44:45], v112, s57, v[144:145]
	v_mul_f32_e32 v115, v154, v114
	v_floor_f32_e32 v115, v115
	v_mul_f32_e32 v117, v156, v114
	v_fma_f32 v115, v154, v114, -v115
	v_floor_f32_e32 v117, v117
	v_mul_f32_e32 v119, v158, v114
	v_sin_f32_e32 v116, v115
	v_cos_f32_e32 v115, v115
	v_fma_f32 v117, v156, v114, -v117
	v_floor_f32_e32 v119, v119
	v_mul_f32_e32 v121, v161, v114
	v_sin_f32_e32 v118, v117
	v_cos_f32_e32 v117, v117
	v_fma_f32 v119, v158, v114, -v119
	v_floor_f32_e32 v121, v121
	v_sin_f32_e32 v120, v119
	v_cos_f32_e32 v119, v119
	v_fma_f32 v121, v161, v114, -v121
	v_sin_f32_e32 v122, v121
	v_cos_f32_e32 v121, v121
	v_cndmask_b32_e32 v116, 0, v116, vcc
	v_cndmask_b32_e32 v115, 1.0, v115, vcc
	v_cndmask_b32_e32 v118, 0, v118, vcc
	v_cndmask_b32_e32 v117, 1.0, v117, vcc
	v_mul_f32_e32 v123, v109, v116
	v_mul_f32_e32 v109, v109, v115
	v_cndmask_b32_e32 v120, 0, v120, vcc
	v_cndmask_b32_e32 v119, 1.0, v119, vcc
	v_fma_f32 v123, v108, v115, -v123
	v_fmac_f32_e32 v109, v108, v116
	v_mul_f32_e32 v108, v111, v118
	v_mul_f32_e32 v111, v111, v117
	v_cndmask_b32_e32 v122, 0, v122, vcc
	v_cndmask_b32_e32 v121, 1.0, v121, vcc
	v_fma_f32 v108, v110, v117, -v108
	v_fmac_f32_e32 v111, v110, v118
	v_mul_f32_e32 v110, v105, v120
	v_mul_f32_e32 v115, v105, v119
	v_fma_f32 v110, v104, v119, -v110
	v_fmac_f32_e32 v115, v104, v120
	v_mul_f32_e32 v104, v107, v122
	v_mul_f32_e32 v107, v107, v121
	v_lshl_add_u64 v[112:113], v[112:113], 0, v[146:147]
	v_fma_f32 v116, v106, v121, -v104
	v_fmac_f32_e32 v107, v106, v122
	v_cvt_pk_bf16_f32 v104, v123, v109
	v_cvt_pk_bf16_f32 v105, v108, v111
	v_cvt_pk_bf16_f32 v106, v110, v115
	v_cvt_pk_bf16_f32 v107, v116, v107
	global_store_dwordx4 v[112:113], v[104:107], off
	v_mul_f32_e32 v108, v160, v114
	v_floor_f32_e32 v108, v108
	v_mul_f32_e32 v104, v155, v114
	v_floor_f32_e32 v104, v104
	v_mul_f32_e32 v106, v157, v114
	v_fma_f32 v104, v155, v114, -v104
	v_floor_f32_e32 v106, v106
	v_sin_f32_e32 v105, v104
	v_cos_f32_e32 v104, v104
	v_fma_f32 v106, v157, v114, -v106
	v_mul_f32_e32 v110, v159, v114
	v_sin_f32_e32 v107, v106
	v_cos_f32_e32 v106, v106
	v_fma_f32 v108, v160, v114, -v108
	v_floor_f32_e32 v110, v110
	v_sin_f32_e32 v109, v108
	v_cos_f32_e32 v108, v108
	v_fma_f32 v110, v159, v114, -v110
	v_sin_f32_e32 v111, v110
	v_cos_f32_e32 v110, v110
	v_cndmask_b32_e64 v105, 0, v105, s[4:5]
	v_cndmask_b32_e64 v104, 1.0, v104, s[4:5]
	v_cndmask_b32_e64 v107, 0, v107, s[4:5]
	v_cndmask_b32_e64 v106, 1.0, v106, s[4:5]
	v_mul_f32_e32 v114, v101, v105
	v_mul_f32_e32 v101, v101, v104
	v_cndmask_b32_e64 v109, 0, v109, s[4:5]
	v_cndmask_b32_e64 v108, 1.0, v108, s[4:5]
	v_fma_f32 v114, v100, v104, -v114
	v_fmac_f32_e32 v101, v100, v105
	v_mul_f32_e32 v100, v103, v107
	v_mul_f32_e32 v103, v103, v106
	v_cndmask_b32_e64 v111, 0, v111, s[4:5]
	v_cndmask_b32_e64 v110, 1.0, v110, s[4:5]
	v_fma_f32 v100, v102, v106, -v100
	v_fmac_f32_e32 v103, v102, v107
	v_mul_f32_e32 v102, v97, v109
	v_mul_f32_e32 v104, v97, v108
	v_fma_f32 v102, v96, v108, -v102
	v_fmac_f32_e32 v104, v96, v109
	v_mul_f32_e32 v96, v99, v111
	v_mul_f32_e32 v99, v99, v110
	v_fma_f32 v105, v98, v110, -v96
	v_fmac_f32_e32 v99, v98, v111
	v_cvt_pk_bf16_f32 v96, v114, v101
	v_cvt_pk_bf16_f32 v97, v100, v103
	s_movk_i32 s8, 0x7ef
	v_cvt_pk_bf16_f32 v98, v102, v104
	v_cvt_pk_bf16_f32 v99, v105, v99
	global_store_dwordx4 v[112:113], v[96:99], off offset:256
	s_nop 1
	v_bitop3_b32 v97, v162, s8, 32 bitop3:0xc8
	v_cvt_f32_u32_e32 v98, v97
	v_or_b32_e32 v96, 32, v162
	v_mad_i64_i32 v[96:97], s[44:45], v96, s57, v[144:145]
	v_mul_f32_e32 v99, v154, v98
	v_floor_f32_e32 v99, v99
	v_mul_f32_e32 v101, v156, v98
	v_fma_f32 v99, v154, v98, -v99
	v_floor_f32_e32 v101, v101
	v_mul_f32_e32 v103, v158, v98
	v_sin_f32_e32 v100, v99
	v_cos_f32_e32 v99, v99
	v_fma_f32 v101, v156, v98, -v101
;     __device__ __forceinline__ void operator()(const f32x4 (&acc)[2][2][4][2], const Unit& u, int wr, int wc, int fr, int fq) const {
;     ...
;             for (int m = 0; m < 4; ++m) { bf16_t* rowp = O + (size_t)(row0 + ai * HALF + m * 16) * ldc + col0;
;                 if (ACT == 1) {
;                     const int ob = fr * 64 + 16 * fq, sw = ob ^ (((ob >> 9) & 1) << 5);
;                     rowp = O + ((size_t)(u.pm * (ldc / 64) + u.pn * 4 + (wc >> 1)) * 2 + ai) * 8192 + (((wr * 4 + m) * 2 + (wc & 1)) * 1024 + sw) / 2; }
;                 float rc[2][2], rs[2][2];
;                 if (ACT == 2) { const float pos = (float)((row0 + ai * HALF + m * 16) & 2047);
; #pragma unroll
;                     for (int n = 0; n < 2; ++n)
; #pragma unroll
;                         for (int e = 0; e < 2; ++e) { float r = pos * rinv[n][e]; r -= floorf(r); rs[n][e] = do_rope ? __builtin_amdgcn_sinf(r) : 0.f; rc[n][e] = do_rope ? __builtin_amdgcn_cosf(r) : 1.f; } }
; #pragma unroll
;                 for (int bj = 0; bj < 2; ++bj) { f32x4 v0 = acc[ai][bj][m][0], v1 = acc[ai][bj][m][1];
;                     if (ACT == 3) { const float pos = (float)((row0 + ai * HALF + m * 16) & 2047); float c3[4], s3[4];
; #pragma unroll
;                         for (int p = 0; p < 4; ++p) { float r = pos * rinv3[bj][p]; r -= floorf(r); s3[p] = rope3[bj] ? __builtin_amdgcn_sinf(r) : 0.f; c3[p] = rope3[bj] ? __builtin_amdgcn_cosf(r) : 1.f; }
;                         const f32x4 a = v0, b = v1;
;                         v0[0] = a[0] * c3[0] - a[1] * s3[0]; v0[1] = a[1] * c3[0] + a[0] * s3[0]; v0[2] = a[2] * c3[1] - a[3] * s3[1]; v0[3] = a[3] * c3[1] + a[2] * s3[1];
;                         v1[0] = b[0] * c3[2] - b[1] * s3[2]; v1[1] = b[1] * c3[2] + b[0] * s3[2]; v1[2] = b[2] * c3[3] - b[3] * s3[3]; v1[3] = b[3] * c3[3] + b[2] * s3[3]; }
;                     if (ACT == 2) { const f32x4 a = v0, b = v1;
;                         v0[0] = a[0] * rc[0][0] - a[1] * rs[0][0]; v0[1] = a[1] * rc[0][0] + a[0] * rs[0][0]; v0[2] = a[2] * rc[0][1] - a[3] * rs[0][1]; v0[3] = a[3] * rc[0][1] + a[2] * rs[0][1];
;                         v1[0] = b[0] * rc[1][0] - b[1] * rs[1][0]; v1[1] = b[1] * rc[1][0] + b[0] * rs[1][0]; v1[2] = b[2] * rc[1][1] - b[3] * rs[1][1]; v1[3] = b[3] * rc[1][1] + b[2] * rs[1][1]; }
;                     if (ACT == 1) {
; #pragma unroll
	v_floor_f32_e32 v103, v103
	v_mul_f32_e32 v105, v161, v98
	v_sin_f32_e32 v102, v101
	v_cos_f32_e32 v101, v101
	v_fma_f32 v103, v158, v98, -v103
	v_floor_f32_e32 v105, v105
	v_sin_f32_e32 v104, v103
	v_cos_f32_e32 v103, v103
	v_fma_f32 v105, v161, v98, -v105
	v_sin_f32_e32 v106, v105
	v_cos_f32_e32 v105, v105
	v_cndmask_b32_e32 v100, 0, v100, vcc
	v_cndmask_b32_e32 v99, 1.0, v99, vcc
	v_cndmask_b32_e32 v102, 0, v102, vcc
	v_cndmask_b32_e32 v101, 1.0, v101, vcc
	v_mul_f32_e32 v107, v93, v100
	v_mul_f32_e32 v93, v93, v99
	v_cndmask_b32_e32 v104, 0, v104, vcc
	v_cndmask_b32_e32 v103, 1.0, v103, vcc
	v_fma_f32 v107, v92, v99, -v107
	v_fmac_f32_e32 v93, v92, v100
	v_mul_f32_e32 v92, v95, v102
	v_mul_f32_e32 v95, v95, v101
	v_cndmask_b32_e32 v106, 0, v106, vcc
	v_cndmask_b32_e32 v105, 1.0, v105, vcc
	v_fma_f32 v92, v94, v101, -v92
	v_fmac_f32_e32 v95, v94, v102
	v_mul_f32_e32 v94, v89, v104
	v_mul_f32_e32 v99, v89, v103
	v_fma_f32 v94, v88, v103, -v94
	v_fmac_f32_e32 v99, v88, v104
	v_mul_f32_e32 v88, v91, v106
	v_mul_f32_e32 v91, v91, v105
	v_lshl_add_u64 v[96:97], v[96:97], 0, v[146:147]
	v_fma_f32 v100, v90, v105, -v88
	v_fmac_f32_e32 v91, v90, v106
	v_cvt_pk_bf16_f32 v88, v107, v93
	v_cvt_pk_bf16_f32 v89, v92, v95
	v_cvt_pk_bf16_f32 v90, v94, v99
	v_cvt_pk_bf16_f32 v91, v100, v91
	global_store_dwordx4 v[96:97], v[88:91], off
	v_mul_f32_e32 v92, v160, v98
	v_floor_f32_e32 v92, v92
	v_mul_f32_e32 v88, v155, v98
	v_floor_f32_e32 v88, v88
	v_mul_f32_e32 v90, v157, v98
	v_fma_f32 v88, v155, v98, -v88
	v_floor_f32_e32 v90, v90
	v_sin_f32_e32 v89, v88
	v_cos_f32_e32 v88, v88
	v_fma_f32 v90, v157, v98, -v90
	v_mul_f32_e32 v94, v159, v98
	v_sin_f32_e32 v91, v90
	v_cos_f32_e32 v90, v90
	v_fma_f32 v92, v160, v98, -v92
	v_floor_f32_e32 v94, v94
	v_sin_f32_e32 v93, v92
	v_cos_f32_e32 v92, v92
	v_fma_f32 v94, v159, v98, -v94
	v_sin_f32_e32 v95, v94
	v_cos_f32_e32 v94, v94
	v_cndmask_b32_e64 v89, 0, v89, s[4:5]
	v_cndmask_b32_e64 v88, 1.0, v88, s[4:5]
	v_cndmask_b32_e64 v91, 0, v91, s[4:5]
	v_cndmask_b32_e64 v90, 1.0, v90, s[4:5]
	v_mul_f32_e32 v98, v85, v89
	v_mul_f32_e32 v85, v85, v88
	v_cndmask_b32_e64 v93, 0, v93, s[4:5]
	v_cndmask_b32_e64 v92, 1.0, v92, s[4:5]
	v_fma_f32 v98, v84, v88, -v98
	v_fmac_f32_e32 v85, v84, v89
	v_mul_f32_e32 v84, v87, v91
	v_mul_f32_e32 v87, v87, v90
	v_cndmask_b32_e64 v95, 0, v95, s[4:5]
	v_cndmask_b32_e64 v94, 1.0, v94, s[4:5]
	v_fma_f32 v84, v86, v90, -v84
	v_fmac_f32_e32 v87, v86, v91
	v_mul_f32_e32 v86, v81, v93
	v_mul_f32_e32 v88, v81, v92
	v_fma_f32 v86, v80, v92, -v86
	v_fmac_f32_e32 v88, v80, v93
	v_mul_f32_e32 v80, v83, v95
	v_mul_f32_e32 v83, v83, v94
	v_fma_f32 v89, v82, v94, -v80
	v_fmac_f32_e32 v83, v82, v95
	v_cvt_pk_bf16_f32 v80, v98, v85
	v_cvt_pk_bf16_f32 v81, v84, v87
	s_movk_i32 s8, 0x7ff
	v_cvt_pk_bf16_f32 v82, v86, v88
	v_cvt_pk_bf16_f32 v83, v89, v83
	global_store_dwordx4 v[96:97], v[80:83], off offset:256
	s_nop 1
	v_bitop3_b32 v81, v162, s8, 48 bitop3:0xc8
	v_cvt_f32_u32_e32 v82, v81
	v_or_b32_e32 v80, 48, v162
	v_mad_i64_i32 v[80:81], s[44:45], v80, s57, v[144:145]
	v_mul_f32_e32 v83, v154, v82
	v_floor_f32_e32 v83, v83
	v_mul_f32_e32 v85, v156, v82
	v_fma_f32 v83, v154, v82, -v83
	v_floor_f32_e32 v85, v85
	v_mul_f32_e32 v87, v158, v82
	v_sin_f32_e32 v84, v83
	v_cos_f32_e32 v83, v83
	v_fma_f32 v85, v156, v82, -v85
	v_floor_f32_e32 v87, v87
	v_mul_f32_e32 v89, v161, v82
	v_sin_f32_e32 v86, v85
	v_cos_f32_e32 v85, v85
	v_fma_f32 v87, v158, v82, -v87
	v_floor_f32_e32 v89, v89
	v_sin_f32_e32 v88, v87
	v_cos_f32_e32 v87, v87
	v_fma_f32 v89, v161, v82, -v89
	v_sin_f32_e32 v90, v89
	v_cos_f32_e32 v89, v89
	v_cndmask_b32_e32 v84, 0, v84, vcc
	v_cndmask_b32_e32 v83, 1.0, v83, vcc
	v_cndmask_b32_e32 v86, 0, v86, vcc
	v_cndmask_b32_e32 v85, 1.0, v85, vcc
	v_mul_f32_e32 v91, v77, v84
	v_mul_f32_e32 v77, v77, v83
	v_cndmask_b32_e32 v88, 0, v88, vcc
	v_cndmask_b32_e32 v87, 1.0, v87, vcc
	v_fma_f32 v91, v76, v83, -v91
	v_fmac_f32_e32 v77, v76, v84
	v_mul_f32_e32 v76, v79, v86
	v_mul_f32_e32 v79, v79, v85
	v_cndmask_b32_e32 v90, 0, v90, vcc
	v_cndmask_b32_e32 v89, 1.0, v89, vcc
	v_fma_f32 v76, v78, v85, -v76
	v_fmac_f32_e32 v79, v78, v86
	v_mul_f32_e32 v78, v73, v88
	v_mul_f32_e32 v83, v73, v87
	v_fma_f32 v78, v72, v87, -v78
	v_fmac_f32_e32 v83, v72, v88
	v_mul_f32_e32 v72, v75, v90
	v_mul_f32_e32 v75, v75, v89
	v_lshl_add_u64 v[80:81], v[80:81], 0, v[146:147]
	v_fma_f32 v84, v74, v89, -v72
	v_fmac_f32_e32 v75, v74, v90
	v_cvt_pk_bf16_f32 v72, v91, v77
	v_cvt_pk_bf16_f32 v73, v76, v79
	v_cvt_pk_bf16_f32 v74, v78, v83
	v_cvt_pk_bf16_f32 v75, v84, v75
	global_store_dwordx4 v[80:81], v[72:75], off
	v_mul_f32_e32 v76, v160, v82
	v_floor_f32_e32 v76, v76
	v_mul_f32_e32 v72, v155, v82
	v_floor_f32_e32 v72, v72
	v_mul_f32_e32 v74, v157, v82
	v_fma_f32 v72, v155, v82, -v72
	v_floor_f32_e32 v74, v74
	v_sin_f32_e32 v73, v72
	v_cos_f32_e32 v72, v72
	v_fma_f32 v74, v157, v82, -v74
	v_mul_f32_e32 v78, v159, v82
	v_sin_f32_e32 v75, v74
	v_cos_f32_e32 v74, v74
	v_fma_f32 v76, v160, v82, -v76
	v_floor_f32_e32 v78, v78
	v_sin_f32_e32 v77, v76
	v_cos_f32_e32 v76, v76
	v_fma_f32 v78, v159, v82, -v78
	v_sin_f32_e32 v79, v78
	v_cos_f32_e32 v78, v78
	v_cndmask_b32_e64 v73, 0, v73, s[4:5]
	v_cndmask_b32_e64 v72, 1.0, v72, s[4:5]
	v_cndmask_b32_e64 v75, 0, v75, s[4:5]
	v_cndmask_b32_e64 v74, 1.0, v74, s[4:5]
	v_mul_f32_e32 v82, v69, v73
	v_mul_f32_e32 v69, v69, v72
	v_cndmask_b32_e64 v77, 0, v77, s[4:5]
	v_cndmask_b32_e64 v76, 1.0, v76, s[4:5]
	v_fma_f32 v82, v68, v72, -v82
	v_fmac_f32_e32 v69, v68, v73
	v_mul_f32_e32 v68, v71, v75
	v_mul_f32_e32 v71, v71, v74
	v_cndmask_b32_e64 v79, 0, v79, s[4:5]
	v_cndmask_b32_e64 v78, 1.0, v78, s[4:5]
;     __device__ __forceinline__ void operator()(const f32x4 (&acc)[2][2][4][2], const Unit& u, int wr, int wc, int fr, int fq) const {
;     ...
;             for (int m = 0; m < 4; ++m) { bf16_t* rowp = O + (size_t)(row0 + ai * HALF + m * 16) * ldc + col0;
;                 if (ACT == 1) {
;                     const int ob = fr * 64 + 16 * fq, sw = ob ^ (((ob >> 9) & 1) << 5);
;                     rowp = O + ((size_t)(u.pm * (ldc / 64) + u.pn * 4 + (wc >> 1)) * 2 + ai) * 8192 + (((wr * 4 + m) * 2 + (wc & 1)) * 1024 + sw) / 2; }
;                 float rc[2][2], rs[2][2];
;                 if (ACT == 2) { const float pos = (float)((row0 + ai * HALF + m * 16) & 2047);
; #pragma unroll
;                     for (int n = 0; n < 2; ++n)
; #pragma unroll
;                         for (int e = 0; e < 2; ++e) { float r = pos * rinv[n][e]; r -= floorf(r); rs[n][e] = do_rope ? __builtin_amdgcn_sinf(r) : 0.f; rc[n][e] = do_rope ? __builtin_amdgcn_cosf(r) : 1.f; } }
; #pragma unroll
;                 for (int bj = 0; bj < 2; ++bj) { f32x4 v0 = acc[ai][bj][m][0], v1 = acc[ai][bj][m][1];
;                     if (ACT == 3) { const float pos = (float)((row0 + ai * HALF + m * 16) & 2047); float c3[4], s3[4];
; #pragma unroll
;                         for (int p = 0; p < 4; ++p) { float r = pos * rinv3[bj][p]; r -= floorf(r); s3[p] = rope3[bj] ? __builtin_amdgcn_sinf(r) : 0.f; c3[p] = rope3[bj] ? __builtin_amdgcn_cosf(r) : 1.f; }
;                         const f32x4 a = v0, b = v1;
;                         v0[0] = a[0] * c3[0] - a[1] * s3[0]; v0[1] = a[1] * c3[0] + a[0] * s3[0]; v0[2] = a[2] * c3[1] - a[3] * s3[1]; v0[3] = a[3] * c3[1] + a[2] * s3[1];
;                         v1[0] = b[0] * c3[2] - b[1] * s3[2]; v1[1] = b[1] * c3[2] + b[0] * s3[2]; v1[2] = b[2] * c3[3] - b[3] * s3[3]; v1[3] = b[3] * c3[3] + b[2] * s3[3]; }
;                     if (ACT == 2) { const f32x4 a = v0, b = v1;
;                         v0[0] = a[0] * rc[0][0] - a[1] * rs[0][0]; v0[1] = a[1] * rc[0][0] + a[0] * rs[0][0]; v0[2] = a[2] * rc[0][1] - a[3] * rs[0][1]; v0[3] = a[3] * rc[0][1] + a[2] * rs[0][1];
;                         v1[0] = b[0] * rc[1][0] - b[1] * rs[1][0]; v1[1] = b[1] * rc[1][0] + b[0] * rs[1][0]; v1[2] = b[2] * rc[1][1] - b[3] * rs[1][1]; v1[3] = b[3] * rc[1][1] + b[2] * rs[1][1]; }
;                     if (ACT == 1) {
; #pragma unroll
	v_fma_f32 v68, v70, v74, -v68
	v_fmac_f32_e32 v71, v70, v75
	v_mul_f32_e32 v70, v65, v77
	v_mul_f32_e32 v72, v65, v76
	v_fma_f32 v70, v64, v76, -v70
	v_fmac_f32_e32 v72, v64, v77
	v_mul_f32_e32 v64, v67, v79
	v_mul_f32_e32 v67, v67, v78
	v_fma_f32 v73, v66, v78, -v64
	v_fmac_f32_e32 v67, v66, v79
	v_cvt_pk_bf16_f32 v64, v82, v69
	v_cvt_pk_bf16_f32 v65, v68, v71
	v_cvt_pk_bf16_f32 v66, v70, v72
	v_cvt_pk_bf16_f32 v67, v73, v67
	global_store_dwordx4 v[80:81], v[64:67], off offset:256
	s_nop 1
	v_add_u32_e32 v64, 0x80, v162
	v_and_b32_e32 v65, 0x7cf, v64
	v_cvt_f32_u32_e32 v66, v65
	v_mad_i64_i32 v[64:65], s[44:45], v64, s57, v[144:145]
	v_lshl_add_u64 v[64:65], v[64:65], 0, v[146:147]
	v_mul_f32_e32 v67, v154, v66
	v_floor_f32_e32 v67, v67
	v_mul_f32_e32 v69, v156, v66
	v_fma_f32 v67, v154, v66, -v67
	v_floor_f32_e32 v69, v69
	v_mul_f32_e32 v71, v158, v66
	v_sin_f32_e32 v68, v67
	v_cos_f32_e32 v67, v67
	v_fma_f32 v69, v156, v66, -v69
	v_floor_f32_e32 v71, v71
	v_mul_f32_e32 v73, v161, v66
	v_sin_f32_e32 v70, v69
	v_cos_f32_e32 v69, v69
	v_fma_f32 v71, v158, v66, -v71
	v_floor_f32_e32 v73, v73
	v_sin_f32_e32 v72, v71
	v_cos_f32_e32 v71, v71
	v_fma_f32 v73, v161, v66, -v73
	v_sin_f32_e32 v74, v73
	v_cos_f32_e32 v73, v73
	v_cndmask_b32_e32 v68, 0, v68, vcc
	v_cndmask_b32_e32 v67, 1.0, v67, vcc
	v_cndmask_b32_e32 v70, 0, v70, vcc
	v_cndmask_b32_e32 v69, 1.0, v69, vcc
	v_mul_f32_e32 v75, v61, v68
	v_mul_f32_e32 v61, v61, v67
	v_cndmask_b32_e32 v72, 0, v72, vcc
	v_cndmask_b32_e32 v71, 1.0, v71, vcc
	v_fma_f32 v75, v60, v67, -v75
	v_fmac_f32_e32 v61, v60, v68
	v_mul_f32_e32 v60, v63, v70
	v_mul_f32_e32 v63, v63, v69
	v_cndmask_b32_e32 v74, 0, v74, vcc
	v_cndmask_b32_e32 v73, 1.0, v73, vcc
	v_fma_f32 v60, v62, v69, -v60
	v_fmac_f32_e32 v63, v62, v70
	v_mul_f32_e32 v62, v57, v72
	v_mul_f32_e32 v67, v57, v71
	v_fma_f32 v62, v56, v71, -v62
	v_fmac_f32_e32 v67, v56, v72
	v_mul_f32_e32 v56, v59, v74
	v_mul_f32_e32 v59, v59, v73
	v_fma_f32 v68, v58, v73, -v56
	v_fmac_f32_e32 v59, v58, v74
	v_cvt_pk_bf16_f32 v56, v75, v61
	v_cvt_pk_bf16_f32 v57, v60, v63
	v_cvt_pk_bf16_f32 v58, v62, v67
	v_cvt_pk_bf16_f32 v59, v68, v59
	global_store_dwordx4 v[64:65], v[56:59], off
	v_mul_f32_e32 v60, v160, v66
	v_floor_f32_e32 v60, v60
	v_mul_f32_e32 v56, v155, v66
	v_floor_f32_e32 v56, v56
	v_mul_f32_e32 v58, v157, v66
	v_fma_f32 v56, v155, v66, -v56
	v_floor_f32_e32 v58, v58
	v_sin_f32_e32 v57, v56
	v_cos_f32_e32 v56, v56
	v_fma_f32 v58, v157, v66, -v58
	v_mul_f32_e32 v62, v159, v66
	v_sin_f32_e32 v59, v58
	v_cos_f32_e32 v58, v58
	v_fma_f32 v60, v160, v66, -v60
	v_floor_f32_e32 v62, v62
	v_sin_f32_e32 v61, v60
	v_cos_f32_e32 v60, v60
	v_fma_f32 v62, v159, v66, -v62
	v_sin_f32_e32 v63, v62
	v_cos_f32_e32 v62, v62
	v_cndmask_b32_e64 v57, 0, v57, s[4:5]
	v_cndmask_b32_e64 v56, 1.0, v56, s[4:5]
	v_cndmask_b32_e64 v59, 0, v59, s[4:5]
	v_cndmask_b32_e64 v58, 1.0, v58, s[4:5]
	v_mul_f32_e32 v66, v53, v57
	v_mul_f32_e32 v53, v53, v56
	v_cndmask_b32_e64 v61, 0, v61, s[4:5]
	v_cndmask_b32_e64 v60, 1.0, v60, s[4:5]
	v_fma_f32 v66, v52, v56, -v66
	v_fmac_f32_e32 v53, v52, v57
	v_mul_f32_e32 v52, v55, v59
	v_mul_f32_e32 v55, v55, v58
	v_cndmask_b32_e64 v63, 0, v63, s[4:5]
	v_cndmask_b32_e64 v62, 1.0, v62, s[4:5]
	v_fma_f32 v52, v54, v58, -v52
	v_fmac_f32_e32 v55, v54, v59
	v_mul_f32_e32 v54, v49, v61
	v_mul_f32_e32 v56, v49, v60
	v_fma_f32 v54, v48, v60, -v54
	v_fmac_f32_e32 v56, v48, v61
	v_mul_f32_e32 v48, v51, v63
	v_mul_f32_e32 v51, v51, v62
	v_fma_f32 v57, v50, v62, -v48
	v_fmac_f32_e32 v51, v50, v63
	v_cvt_pk_bf16_f32 v48, v66, v53
	v_cvt_pk_bf16_f32 v49, v52, v55
	v_cvt_pk_bf16_f32 v50, v54, v56
	v_cvt_pk_bf16_f32 v51, v57, v51
	global_store_dwordx4 v[64:65], v[48:51], off offset:256
	s_nop 1
	v_add_u32_e32 v48, 0x90, v162
	v_and_b32_e32 v49, 0x7df, v48
	v_cvt_f32_u32_e32 v50, v49
	v_mad_i64_i32 v[48:49], s[44:45], v48, s57, v[144:145]
	v_lshl_add_u64 v[48:49], v[48:49], 0, v[146:147]
	v_mul_f32_e32 v51, v154, v50
	v_floor_f32_e32 v51, v51
	v_mul_f32_e32 v53, v156, v50
	v_fma_f32 v51, v154, v50, -v51
	v_floor_f32_e32 v53, v53
	v_mul_f32_e32 v55, v158, v50
	v_sin_f32_e32 v52, v51
	v_cos_f32_e32 v51, v51
	v_fma_f32 v53, v156, v50, -v53
	v_floor_f32_e32 v55, v55
	v_mul_f32_e32 v57, v161, v50
	v_sin_f32_e32 v54, v53
	v_cos_f32_e32 v53, v53
	v_fma_f32 v55, v158, v50, -v55
	v_floor_f32_e32 v57, v57
	v_sin_f32_e32 v56, v55
	v_cos_f32_e32 v55, v55
	v_fma_f32 v57, v161, v50, -v57
	v_sin_f32_e32 v58, v57
	v_cos_f32_e32 v57, v57
	v_cndmask_b32_e32 v52, 0, v52, vcc
	v_cndmask_b32_e32 v51, 1.0, v51, vcc
	v_cndmask_b32_e32 v54, 0, v54, vcc
	v_cndmask_b32_e32 v53, 1.0, v53, vcc
	v_mul_f32_e32 v59, v45, v52
	v_mul_f32_e32 v45, v45, v51
	v_cndmask_b32_e32 v56, 0, v56, vcc
	v_cndmask_b32_e32 v55, 1.0, v55, vcc
	v_fma_f32 v59, v44, v51, -v59
	v_fmac_f32_e32 v45, v44, v52
	v_mul_f32_e32 v44, v47, v54
	v_mul_f32_e32 v47, v47, v53
	v_cndmask_b32_e32 v58, 0, v58, vcc
	v_cndmask_b32_e32 v57, 1.0, v57, vcc
	v_fma_f32 v44, v46, v53, -v44
	v_fmac_f32_e32 v47, v46, v54
	v_mul_f32_e32 v46, v41, v56
	v_mul_f32_e32 v51, v41, v55
	v_fma_f32 v46, v40, v55, -v46
	v_fmac_f32_e32 v51, v40, v56
	v_mul_f32_e32 v40, v43, v58
	v_mul_f32_e32 v43, v43, v57
	v_fma_f32 v52, v42, v57, -v40
	v_fmac_f32_e32 v43, v42, v58
	v_cvt_pk_bf16_f32 v40, v59, v45
	v_cvt_pk_bf16_f32 v41, v44, v47
	v_cvt_pk_bf16_f32 v42, v46, v51
	v_cvt_pk_bf16_f32 v43, v52, v43
	global_store_dwordx4 v[48:49], v[40:43], off
	v_mul_f32_e32 v44, v160, v50
	v_floor_f32_e32 v44, v44
	v_mul_f32_e32 v40, v155, v50
	v_floor_f32_e32 v40, v40
	v_mul_f32_e32 v42, v157, v50
	v_fma_f32 v40, v155, v50, -v40
	v_floor_f32_e32 v42, v42
	v_sin_f32_e32 v41, v40
;     __device__ __forceinline__ void operator()(const f32x4 (&acc)[2][2][4][2], const Unit& u, int wr, int wc, int fr, int fq) const {
;     ...
;             for (int m = 0; m < 4; ++m) { bf16_t* rowp = O + (size_t)(row0 + ai * HALF + m * 16) * ldc + col0;
;                 if (ACT == 1) {
;                     const int ob = fr * 64 + 16 * fq, sw = ob ^ (((ob >> 9) & 1) << 5);
;                     rowp = O + ((size_t)(u.pm * (ldc / 64) + u.pn * 4 + (wc >> 1)) * 2 + ai) * 8192 + (((wr * 4 + m) * 2 + (wc & 1)) * 1024 + sw) / 2; }
;                 float rc[2][2], rs[2][2];
;                 if (ACT == 2) { const float pos = (float)((row0 + ai * HALF + m * 16) & 2047);
; #pragma unroll
;                     for (int n = 0; n < 2; ++n)
; #pragma unroll
;                         for (int e = 0; e < 2; ++e) { float r = pos * rinv[n][e]; r -= floorf(r); rs[n][e] = do_rope ? __builtin_amdgcn_sinf(r) : 0.f; rc[n][e] = do_rope ? __builtin_amdgcn_cosf(r) : 1.f; } }
; #pragma unroll
;                 for (int bj = 0; bj < 2; ++bj) { f32x4 v0 = acc[ai][bj][m][0], v1 = acc[ai][bj][m][1];
;                     if (ACT == 3) { const float pos = (float)((row0 + ai * HALF + m * 16) & 2047); float c3[4], s3[4];
; #pragma unroll
;                         for (int p = 0; p < 4; ++p) { float r = pos * rinv3[bj][p]; r -= floorf(r); s3[p] = rope3[bj] ? __builtin_amdgcn_sinf(r) : 0.f; c3[p] = rope3[bj] ? __builtin_amdgcn_cosf(r) : 1.f; }
;                         const f32x4 a = v0, b = v1;
;                         v0[0] = a[0] * c3[0] - a[1] * s3[0]; v0[1] = a[1] * c3[0] + a[0] * s3[0]; v0[2] = a[2] * c3[1] - a[3] * s3[1]; v0[3] = a[3] * c3[1] + a[2] * s3[1];
;                         v1[0] = b[0] * c3[2] - b[1] * s3[2]; v1[1] = b[1] * c3[2] + b[0] * s3[2]; v1[2] = b[2] * c3[3] - b[3] * s3[3]; v1[3] = b[3] * c3[3] + b[2] * s3[3]; }
;                     if (ACT == 2) { const f32x4 a = v0, b = v1;
;                         v0[0] = a[0] * rc[0][0] - a[1] * rs[0][0]; v0[1] = a[1] * rc[0][0] + a[0] * rs[0][0]; v0[2] = a[2] * rc[0][1] - a[3] * rs[0][1]; v0[3] = a[3] * rc[0][1] + a[2] * rs[0][1];
;                         v1[0] = b[0] * rc[1][0] - b[1] * rs[1][0]; v1[1] = b[1] * rc[1][0] + b[0] * rs[1][0]; v1[2] = b[2] * rc[1][1] - b[3] * rs[1][1]; v1[3] = b[3] * rc[1][1] + b[2] * rs[1][1]; }
;                     if (ACT == 1) {
; #pragma unroll
	v_cos_f32_e32 v40, v40
	v_fma_f32 v42, v157, v50, -v42
	v_mul_f32_e32 v46, v159, v50
	v_sin_f32_e32 v43, v42
	v_cos_f32_e32 v42, v42
	v_fma_f32 v44, v160, v50, -v44
	v_floor_f32_e32 v46, v46
	v_sin_f32_e32 v45, v44
	v_cos_f32_e32 v44, v44
	v_fma_f32 v46, v159, v50, -v46
	v_sin_f32_e32 v47, v46
	v_cos_f32_e32 v46, v46
	v_cndmask_b32_e64 v41, 0, v41, s[4:5]
	v_cndmask_b32_e64 v40, 1.0, v40, s[4:5]
	v_cndmask_b32_e64 v43, 0, v43, s[4:5]
	v_cndmask_b32_e64 v42, 1.0, v42, s[4:5]
	v_mul_f32_e32 v50, v37, v41
	v_mul_f32_e32 v37, v37, v40
	v_cndmask_b32_e64 v45, 0, v45, s[4:5]
	v_cndmask_b32_e64 v44, 1.0, v44, s[4:5]
	v_fma_f32 v50, v36, v40, -v50
	v_fmac_f32_e32 v37, v36, v41
	v_mul_f32_e32 v36, v39, v43
	v_mul_f32_e32 v39, v39, v42
	v_cndmask_b32_e64 v47, 0, v47, s[4:5]
	v_cndmask_b32_e64 v46, 1.0, v46, s[4:5]
	v_fma_f32 v36, v38, v42, -v36
	v_fmac_f32_e32 v39, v38, v43
	v_mul_f32_e32 v38, v33, v45
	v_mul_f32_e32 v40, v33, v44
	v_fma_f32 v38, v32, v44, -v38
	v_fmac_f32_e32 v40, v32, v45
	v_mul_f32_e32 v32, v35, v47
	v_mul_f32_e32 v35, v35, v46
	v_fma_f32 v41, v34, v46, -v32
	v_fmac_f32_e32 v35, v34, v47
	v_cvt_pk_bf16_f32 v32, v50, v37
	v_cvt_pk_bf16_f32 v33, v36, v39
	v_cvt_pk_bf16_f32 v34, v38, v40
	v_cvt_pk_bf16_f32 v35, v41, v35
	global_store_dwordx4 v[48:49], v[32:35], off offset:256
	s_nop 1
	v_add_u32_e32 v32, 0xa0, v162
	v_and_b32_e32 v33, 0x7ef, v32
	v_cvt_f32_u32_e32 v34, v33
	v_mad_i64_i32 v[32:33], s[44:45], v32, s57, v[144:145]
	v_lshl_add_u64 v[32:33], v[32:33], 0, v[146:147]
	v_mul_f32_e32 v35, v154, v34
	v_floor_f32_e32 v35, v35
	v_mul_f32_e32 v37, v156, v34
	v_fma_f32 v35, v154, v34, -v35
	v_floor_f32_e32 v37, v37
	v_mul_f32_e32 v39, v158, v34
	v_sin_f32_e32 v36, v35
	v_cos_f32_e32 v35, v35
	v_fma_f32 v37, v156, v34, -v37
	v_floor_f32_e32 v39, v39
	v_mul_f32_e32 v41, v161, v34
	v_sin_f32_e32 v38, v37
	v_cos_f32_e32 v37, v37
	v_fma_f32 v39, v158, v34, -v39
	v_floor_f32_e32 v41, v41
	v_sin_f32_e32 v40, v39
	v_cos_f32_e32 v39, v39
	v_fma_f32 v41, v161, v34, -v41
	v_sin_f32_e32 v42, v41
	v_cos_f32_e32 v41, v41
	v_cndmask_b32_e32 v36, 0, v36, vcc
	v_cndmask_b32_e32 v35, 1.0, v35, vcc
	v_cndmask_b32_e32 v38, 0, v38, vcc
	v_cndmask_b32_e32 v37, 1.0, v37, vcc
	v_mul_f32_e32 v43, v29, v36
	v_mul_f32_e32 v29, v29, v35
	v_cndmask_b32_e32 v40, 0, v40, vcc
	v_cndmask_b32_e32 v39, 1.0, v39, vcc
	v_fma_f32 v43, v28, v35, -v43
	v_fmac_f32_e32 v29, v28, v36
	v_mul_f32_e32 v28, v31, v38
	v_mul_f32_e32 v31, v31, v37
	v_cndmask_b32_e32 v42, 0, v42, vcc
	v_cndmask_b32_e32 v41, 1.0, v41, vcc
	v_fma_f32 v28, v30, v37, -v28
	v_fmac_f32_e32 v31, v30, v38
	v_mul_f32_e32 v30, v25, v40
	v_mul_f32_e32 v35, v25, v39
	v_fma_f32 v30, v24, v39, -v30
	v_fmac_f32_e32 v35, v24, v40
	v_mul_f32_e32 v24, v27, v42
	v_mul_f32_e32 v27, v27, v41
	v_fma_f32 v36, v26, v41, -v24
	v_fmac_f32_e32 v27, v26, v42
	v_cvt_pk_bf16_f32 v24, v43, v29
	v_cvt_pk_bf16_f32 v25, v28, v31
	v_cvt_pk_bf16_f32 v26, v30, v35
	v_cvt_pk_bf16_f32 v27, v36, v27
	global_store_dwordx4 v[32:33], v[24:27], off
	v_mul_f32_e32 v28, v160, v34
	v_floor_f32_e32 v28, v28
	v_mul_f32_e32 v24, v155, v34
	v_floor_f32_e32 v24, v24
	v_mul_f32_e32 v26, v157, v34
	v_fma_f32 v24, v155, v34, -v24
	v_floor_f32_e32 v26, v26
	v_sin_f32_e32 v25, v24
	v_cos_f32_e32 v24, v24
	v_fma_f32 v26, v157, v34, -v26
	v_mul_f32_e32 v30, v159, v34
	v_sin_f32_e32 v27, v26
	v_cos_f32_e32 v26, v26
	v_fma_f32 v28, v160, v34, -v28
	v_floor_f32_e32 v30, v30
	v_sin_f32_e32 v29, v28
	v_cos_f32_e32 v28, v28
	v_fma_f32 v30, v159, v34, -v30
	v_sin_f32_e32 v31, v30
	v_cos_f32_e32 v30, v30
	v_cndmask_b32_e64 v25, 0, v25, s[4:5]
	v_cndmask_b32_e64 v24, 1.0, v24, s[4:5]
	v_cndmask_b32_e64 v27, 0, v27, s[4:5]
	v_cndmask_b32_e64 v26, 1.0, v26, s[4:5]
	v_mul_f32_e32 v34, v21, v25
	v_mul_f32_e32 v21, v21, v24
	v_cndmask_b32_e64 v29, 0, v29, s[4:5]
	v_cndmask_b32_e64 v28, 1.0, v28, s[4:5]
	v_fma_f32 v34, v20, v24, -v34
	v_fmac_f32_e32 v21, v20, v25
	v_mul_f32_e32 v20, v23, v27
; #define PG8_BAR __builtin_amdgcn_s_barrier()
;     __device__ __forceinline__ void operator()(const f32x4 (&acc)[2][2][4][2], const Unit& u, int wr, int wc, int fr, int fq) const {
;     ...
;                 for (int bj = 0; bj < 2; ++bj) { f32x4 v0 = acc[ai][bj][m][0], v1 = acc[ai][bj][m][1];
;                     if (ACT == 3) { const float pos = (float)((row0 + ai * HALF + m * 16) & 2047); float c3[4], s3[4];
; #pragma unroll
;                         for (int p = 0; p < 4; ++p) { float r = pos * rinv3[bj][p]; r -= floorf(r); s3[p] = rope3[bj] ? __builtin_amdgcn_sinf(r) : 0.f; c3[p] = rope3[bj] ? __builtin_amdgcn_cosf(r) : 1.f; }
;                         const f32x4 a = v0, b = v1;
;                         v0[0] = a[0] * c3[0] - a[1] * s3[0]; v0[1] = a[1] * c3[0] + a[0] * s3[0]; v0[2] = a[2] * c3[1] - a[3] * s3[1]; v0[3] = a[3] * c3[1] + a[2] * s3[1];
;                         v1[0] = b[0] * c3[2] - b[1] * s3[2]; v1[1] = b[1] * c3[2] + b[0] * s3[2]; v1[2] = b[2] * c3[3] - b[3] * s3[3]; v1[3] = b[3] * c3[3] + b[2] * s3[3]; }
;                     if (ACT == 2) { const f32x4 a = v0, b = v1;
;                         v0[0] = a[0] * rc[0][0] - a[1] * rs[0][0]; v0[1] = a[1] * rc[0][0] + a[0] * rs[0][0]; v0[2] = a[2] * rc[0][1] - a[3] * rs[0][1]; v0[3] = a[3] * rc[0][1] + a[2] * rs[0][1];
;                         v1[0] = b[0] * rc[1][0] - b[1] * rs[1][0]; v1[1] = b[1] * rc[1][0] + b[0] * rs[1][0]; v1[2] = b[2] * rc[1][1] - b[3] * rs[1][1]; v1[3] = b[3] * rc[1][1] + b[2] * rs[1][1]; }
;                     if (ACT == 1) {
; #pragma unroll
;                         for (int j = 0; j < 4; ++j) { const float a = __int_as_float(max(__float_as_int(v0[j]), 0)), b = __int_as_float(max(__float_as_int(v1[j]), 0)); v0[j] = a * a; v1[j] = b * b; } }
;                     u32x4 w; w.x = cvt_pk_bf16(v0[0], v0[1]); w.y = cvt_pk_bf16(v0[2], v0[3]); w.z = cvt_pk_bf16(v1[0], v1[1]); w.w = cvt_pk_bf16(v1[2], v1[3]);
;                     *(u32x4*)(rowp + (ACT == 1 ? bj * 2 * 2 * 8192 : bj * HALF)) = w; } }
; template <class Epi, class Sched, bool ALIGN_EPI = false, bool SP2 = false, bool A_TILED = false>
; __device__ __forceinline__ void gemm_phase(PG8_LAS unsigned char* lds, const Gemm g, const Sched& S, const Epi& E, const int wave_s) {
;     ...
;         if (!has_next) break;
;         cur = nxt; cA = nA; cB = nB; ++ui;
;         if constexpr (ALIGN_EPI) { if (wr == 1) PG8_BAR; }
	v_mul_f32_e32 v23, v23, v26
	v_cndmask_b32_e64 v31, 0, v31, s[4:5]
	v_cndmask_b32_e64 v30, 1.0, v30, s[4:5]
	v_fma_f32 v20, v22, v26, -v20
	v_fmac_f32_e32 v23, v22, v27
	v_mul_f32_e32 v22, v17, v29
	v_mul_f32_e32 v24, v17, v28
	v_fma_f32 v22, v16, v28, -v22
	v_fmac_f32_e32 v24, v16, v29
	v_mul_f32_e32 v16, v19, v31
	v_mul_f32_e32 v19, v19, v30
	v_fma_f32 v25, v18, v30, -v16
	v_fmac_f32_e32 v19, v18, v31
	v_cvt_pk_bf16_f32 v16, v34, v21
	v_cvt_pk_bf16_f32 v17, v20, v23
	v_cvt_pk_bf16_f32 v18, v22, v24
	v_cvt_pk_bf16_f32 v19, v25, v19
	global_store_dwordx4 v[32:33], v[16:19], off offset:256
	s_nop 1
	v_add_u32_e32 v16, 0xb0, v162
	v_and_b32_e32 v17, 0x7ff, v16
	v_cvt_f32_u32_e32 v18, v17
	v_mad_i64_i32 v[16:17], s[44:45], v16, s57, v[144:145]
	v_lshl_add_u64 v[16:17], v[16:17], 0, v[146:147]
	v_mul_f32_e32 v19, v154, v18
	v_floor_f32_e32 v19, v19
	v_mul_f32_e32 v21, v156, v18
	v_fma_f32 v19, v154, v18, -v19
	v_floor_f32_e32 v21, v21
	v_mul_f32_e32 v23, v158, v18
	v_sin_f32_e32 v20, v19
	v_cos_f32_e32 v19, v19
	v_fma_f32 v21, v156, v18, -v21
	v_floor_f32_e32 v23, v23
	v_mul_f32_e32 v25, v161, v18
	v_sin_f32_e32 v22, v21
	v_cos_f32_e32 v21, v21
	v_fma_f32 v23, v158, v18, -v23
	v_floor_f32_e32 v25, v25
	v_sin_f32_e32 v24, v23
	v_cos_f32_e32 v23, v23
	v_fma_f32 v25, v161, v18, -v25
	v_sin_f32_e32 v26, v25
	v_cos_f32_e32 v25, v25
	v_cndmask_b32_e32 v20, 0, v20, vcc
	v_cndmask_b32_e32 v19, 1.0, v19, vcc
	v_cndmask_b32_e32 v22, 0, v22, vcc
	v_cndmask_b32_e32 v21, 1.0, v21, vcc
	v_mul_f32_e32 v27, v13, v20
	v_mul_f32_e32 v13, v13, v19
	v_cndmask_b32_e32 v24, 0, v24, vcc
	v_cndmask_b32_e32 v23, 1.0, v23, vcc
	v_fma_f32 v27, v12, v19, -v27
	v_fmac_f32_e32 v13, v12, v20
	v_mul_f32_e32 v12, v15, v22
	v_mul_f32_e32 v15, v15, v21
	v_cndmask_b32_e32 v26, 0, v26, vcc
	v_cndmask_b32_e32 v25, 1.0, v25, vcc
	v_fma_f32 v12, v14, v21, -v12
	v_fmac_f32_e32 v15, v14, v22
	v_mul_f32_e32 v14, v9, v24
	v_mul_f32_e32 v19, v9, v23
	v_fma_f32 v14, v8, v23, -v14
	v_fmac_f32_e32 v19, v8, v24
	v_mul_f32_e32 v8, v11, v26
	v_mul_f32_e32 v11, v11, v25
	v_fma_f32 v20, v10, v25, -v8
	v_fmac_f32_e32 v11, v10, v26
	v_cvt_pk_bf16_f32 v8, v27, v13
	v_cvt_pk_bf16_f32 v9, v12, v15
	v_cvt_pk_bf16_f32 v10, v14, v19
	v_cvt_pk_bf16_f32 v11, v20, v11
	global_store_dwordx4 v[16:17], v[8:11], off
	v_mul_f32_e32 v12, v160, v18
	v_floor_f32_e32 v12, v12
	v_mul_f32_e32 v8, v155, v18
	v_floor_f32_e32 v8, v8
	v_mul_f32_e32 v10, v157, v18
	v_fma_f32 v8, v155, v18, -v8
	v_floor_f32_e32 v10, v10
	v_sin_f32_e32 v9, v8
	v_cos_f32_e32 v8, v8
	v_fma_f32 v10, v157, v18, -v10
	v_mul_f32_e32 v14, v159, v18
	v_sin_f32_e32 v11, v10
	v_cos_f32_e32 v10, v10
	v_fma_f32 v12, v160, v18, -v12
	v_floor_f32_e32 v14, v14
	v_sin_f32_e32 v13, v12
	v_cos_f32_e32 v12, v12
	v_fma_f32 v14, v159, v18, -v14
	v_sin_f32_e32 v15, v14
	v_cos_f32_e32 v14, v14
	v_cndmask_b32_e64 v9, 0, v9, s[4:5]
	v_cndmask_b32_e64 v8, 1.0, v8, s[4:5]
	v_cndmask_b32_e64 v11, 0, v11, s[4:5]
	v_cndmask_b32_e64 v10, 1.0, v10, s[4:5]
	v_mul_f32_e32 v18, v5, v9
	v_mul_f32_e32 v5, v5, v8
	v_cndmask_b32_e64 v13, 0, v13, s[4:5]
	v_cndmask_b32_e64 v12, 1.0, v12, s[4:5]
	v_fma_f32 v18, v4, v8, -v18
	v_fmac_f32_e32 v5, v4, v9
	v_mul_f32_e32 v4, v7, v11
	v_mul_f32_e32 v7, v7, v10
	v_cndmask_b32_e64 v15, 0, v15, s[4:5]
	v_cndmask_b32_e64 v14, 1.0, v14, s[4:5]
	v_fma_f32 v4, v6, v10, -v4
	v_fmac_f32_e32 v7, v6, v11
	v_mul_f32_e32 v6, v1, v13
	v_mul_f32_e32 v8, v1, v12
	v_fma_f32 v6, v0, v12, -v6
	v_fmac_f32_e32 v8, v0, v13
	v_mul_f32_e32 v0, v3, v15
	v_mul_f32_e32 v3, v3, v14
	v_fmac_f32_e32 v3, v2, v15
	s_andn2_b64 vcc, exec, s[2:3]
	s_mov_b64 s[2:3], -1
	v_fma_f32 v9, v2, v14, -v0
	v_cvt_pk_bf16_f32 v0, v18, v5
	v_cvt_pk_bf16_f32 v1, v4, v7
	v_cvt_pk_bf16_f32 v2, v6, v8
	v_cvt_pk_bf16_f32 v3, v9, v3
	global_store_dwordx4 v[16:17], v[0:3], off offset:256
	s_mov_b32 s98, 1
	s_cbranch_vccnz .LBB0_2542
	s_andn2_b64 vcc, exec, s[46:47]
	s_cbranch_vccnz .LBB0_2541
	s_barrier
	s_branch .LBB0_2541

; #define PG8_STAGE(bufoff, gbase, voff) do { _Pragma("unroll") for (int _i = 0; _i < 2; ++_i) \
;         __builtin_amdgcn_global_load_lds((const unsigned*)((const char*)(gbase) + (voff)[_i]), (PG8_LAS unsigned*)(lds + (bufoff) + ldsw + _i * 8192), 16, 0, 0); } while (0)
; #define PG8_WAIT_V(n) asm volatile("s_waitcnt vmcnt(" #n ")" ::: "memory")
; #define PG8_BAR __builtin_amdgcn_s_barrier()
; template <class Epi, class Sched, bool ALIGN_EPI = false, bool SP2 = false, bool A_TILED = false>
; __device__ __forceinline__ void gemm_phase(PG8_LAS unsigned char* lds, const Gemm g, const Sched& S, const Epi& E, const int wave_s) {
;     ...
;     const int aoff = lds_byte(wr * 64 + fr, fq * 8), boff = lds_byte(wc * 32 + fr, fq * 8);
;     ...
;     Unit cur, nxt; int ui = 0;
;     if (!S.next(0, cur)) return;
;     f32x4 acc[2][2][4][2];
;     bf16x8 At[4][2], B0[2][2], B1[2][2];
;     const char* cA = (const char*)g.A + (size_t)cur.pm * tstepA; const char* cB = (const char*)g.Bt + (size_t)cur.pn * tstep;
;     S.a_ready(cur);
;     if constexpr (SP2) {
;         PG8_STAGE(PG8_SB(0, 0), cB, voffB); PG8_STAGE(PG8_SB(0, 1), cB + hstep, voffB); PG8_STAGE(PG8_SA(0, 0), cA, voffA); PG8_STAGE(PG8_SA(0, 1), cA + hstepA, voffA);
;         if (wr == 1) PG8_BAR;
;         PG8_WAIT_V(2); PG8_BAR;
;         PG8_STAGE(PG8_SB(1, 0), cB + kstep, voffB); PG8_STAGE(PG8_SA(1, 0), cA + kstepA, voffA); PG8_STAGE(PG8_SB(1, 1), cB + hstep + kstep, voffB);
;         PG8_WAIT_V(6); PG8_BAR;
.LBB0_2556:
	s_mul_i32 s40, s96, 0x7000000
	s_add_u32 s12, s12, s40
	s_addc_u32 s13, s13, 0
	s_add_u32 s12, s12, 0x25e00000
	s_addc_u32 s13, s13, 0
	s_lshl_b32 s41, s41, 5
	s_mov_b64 s[44:45], 0x80
	s_and_b32 s41, s41, 0x60
	s_add_i32 m0, s0, 0x18000
	v_lshl_add_u64 v[6:7], v[6:7], 0, s[44:45]
	s_lshl_b32 s40, s42, 6
	s_lshl_b32 s48, s42, 13
	s_lshl_b32 s49, s41, 7
	s_waitcnt vmcnt(2)
	s_barrier
	global_load_lds_dwordx4 v[6:7], off
	v_lshl_add_u64 v[4:5], v[4:5], 0, s[44:45]
	s_add_i32 m0, s0, 0x1a000
	s_add_i32 s42, s0, 0x8000
	s_add_i32 s43, s0, 0xa000
	global_load_lds_dwordx4 v[4:5], off
	v_lshl_add_u64 v[0:1], v[0:1], 0, s[44:45]
	s_mov_b32 m0, s42
	s_add_u32 s46, s74, 0x20080
	global_load_lds_dwordx4 v[0:1], off
	v_lshl_add_u64 v[0:1], v[2:3], 0, s[44:45]
	s_mov_b32 m0, s43
	s_addc_u32 s47, s75, 0
	global_load_lds_dwordx4 v[0:1], off
	s_add_i32 m0, s0, 0x1c000
	v_lshl_add_u64 v[0:1], s[46:47], 0, v[128:129]
	global_load_lds_dwordx4 v128, s[46:47]
	v_lshl_add_u64 v[0:1], s[46:47], 0, v[130:131]
	s_add_i32 m0, s0, 0x1e000
	s_sext_i32_i8 s50, s2
	global_load_lds_dwordx4 v130, s[46:47]
	v_and_b32_e32 v0, 48, v10
	v_lshlrev_b32_e32 v1, 6, v10
	s_movk_i32 s2, 0x3c0
	v_and_or_b32 v0, v1, s2, v0
	v_lshlrev_b32_e32 v1, 2, v10
	v_and_b32_e32 v1, 32, v1
	v_bitop3_b32 v2, v0, s48, v1 bitop3:0xde
	v_bitop3_b32 v146, s49, v0, v1 bitop3:0xf6
	v_lshlrev_b32_e32 v0, 13, v8
	v_and_b32_e32 v0, 0xffffc000, v0
	v_lshl_add_u32 v0, v9, 10, v0
	v_and_b32_e32 v1, 1, v8
	v_lshl_or_b32 v0, v1, 6, v0
	v_lshl_add_u32 v136, v11, 1, v0
	v_lshlrev_b32_e32 v0, 13, v13
	v_and_b32_e32 v0, 0xffffc000, v0
	s_waitcnt vmcnt(6)
	s_mov_b32 s98, 0
	s_cmpk_lt_u32 s3, 0x100
	v_lshl_add_u32 v0, v12, 10, v0
	v_and_b32_e32 v1, 1, v13
	s_cselect_b64 s[46:47], -1, 0
	v_mov_b32_e32 v137, 0
	v_lshl_or_b32 v0, v1, 6, v0
	s_add_i32 s48, 0, 0x10000
	s_add_i32 s49, 0, 0x14000
	v_lshl_add_u32 v138, v14, 1, v0
	v_mov_b32_e32 v139, v137
	s_mov_b64 s[60:61], 0x100
	v_add_u32_e32 v147, s48, v146
	v_add_u32_e32 v148, s49, v146
	v_add_u32_e32 v149, 0, v2
	s_mov_b64 s[62:63], 0x180
	s_barrier
	s_branch .LBB0_2559

.LBB0_2565:
	s_ashr_i32 s67, s66, 31
	ds_read_b128 v[0:3], v147
	ds_read_b128 v[4:7], v147 offset:1024
	ds_read_b128 v[8:11], v147 offset:2048
	ds_read_b128 v[12:15], v147 offset:3072
	ds_read_b128 v[16:19], v148
	ds_read_b128 v[20:23], v148 offset:1024
	ds_read_b128 v[24:27], v148 offset:2048
	ds_read_b128 v[28:31], v148 offset:3072
	s_lshl_b64 s[52:53], s[66:67], 18
	s_add_u32 s68, s8, s52
	s_addc_u32 s69, s14, s53
	s_and_b64 s[52:53], s[2:3], exec
	s_cselect_b32 s51, s69, s77
	s_cselect_b32 s52, s68, s76
	s_ashr_i32 s65, s64, 31
	s_lshl_b64 s[54:55], s[64:65], 18
	s_add_u32 s72, s15, s54
	s_addc_u32 s73, s23, s55
	s_and_b64 s[54:55], s[2:3], exec
	s_cselect_b32 s53, s73, s75
	s_cselect_b32 s54, s72, s74
	s_add_u32 s56, s76, 0x20080
	s_addc_u32 s57, s77, 0
	s_add_i32 s55, s0, 0xc000
	v_lshl_add_u64 v[64:65], s[56:57], 0, v[134:135]
	s_mov_b32 m0, s55
	ds_read_b128 v[32:35], v149
	ds_read_b128 v[36:39], v149 offset:1024
	ds_read_b128 v[40:43], v149 offset:2048
	ds_read_b128 v[44:47], v149 offset:3072
	ds_read_b128 v[48:51], v149 offset:4096
	ds_read_b128 v[52:55], v149 offset:5120
	ds_read_b128 v[56:59], v149 offset:6144
	ds_read_b128 v[60:63], v149 offset:7168
	global_load_lds_dwordx4 v134, s[56:57]
	v_lshl_add_u64 v[64:65], s[56:57], 0, v[132:133]
	s_add_i32 s56, s0, 0xe000
	s_mov_b32 m0, s56
	s_nop 0
	global_load_lds_dwordx4 v[64:65], off
	s_waitcnt vmcnt(24) lgkmcnt(0)
	s_cmp_lg_u32 s98, 0
	s_cbranch_scc1 .Lpw_13
	s_waitcnt vmcnt(8)
.Lpw_13:
	s_setprio 1
	s_barrier
	v_mfma_f32_16x16x32_bf16 v[88:91], v[0:3], v[56:59], 0
	v_mfma_f32_16x16x32_bf16 v[64:67], v[0:3], v[32:35], 0
	v_mfma_f32_16x16x32_bf16 v[68:71], v[8:11], v[32:35], 0
	v_mfma_f32_16x16x32_bf16 v[72:75], v[0:3], v[40:43], 0
	v_mfma_f32_16x16x32_bf16 v[76:79], v[8:11], v[40:43], 0
	v_mfma_f32_16x16x32_bf16 v[80:83], v[0:3], v[48:51], 0
	v_mfma_f32_16x16x32_bf16 v[84:87], v[8:11], v[48:51], 0
	v_mfma_f32_16x16x32_bf16 v[92:95], v[4:7], v[60:63], v[88:91]
	v_mfma_f32_16x16x32_bf16 v[88:91], v[8:11], v[56:59], 0
	v_mfma_f32_16x16x32_bf16 v[64:67], v[4:7], v[36:39], v[64:67]
	v_mfma_f32_16x16x32_bf16 v[68:71], v[12:15], v[36:39], v[68:71]
	v_mfma_f32_16x16x32_bf16 v[72:75], v[4:7], v[44:47], v[72:75]
	v_mfma_f32_16x16x32_bf16 v[76:79], v[12:15], v[44:47], v[76:79]
	v_mfma_f32_16x16x32_bf16 v[80:83], v[4:7], v[52:55], v[80:83]
	v_mfma_f32_16x16x32_bf16 v[84:87], v[12:15], v[52:55], v[84:87]
	v_mfma_f32_16x16x32_bf16 v[100:103], v[12:15], v[60:63], v[88:91]
	s_setprio 0
	s_setprio 1
	v_mfma_f32_16x16x32_bf16 v[88:91], v[16:19], v[32:35], 0
	v_mfma_f32_16x16x32_bf16 v[32:35], v[24:27], v[32:35], 0
	v_mfma_f32_16x16x32_bf16 v[108:111], v[20:23], v[36:39], v[88:91]
	v_mfma_f32_16x16x32_bf16 v[32:35], v[28:31], v[36:39], v[32:35]
	v_mfma_f32_16x16x32_bf16 v[36:39], v[16:19], v[40:43], 0
	v_mfma_f32_16x16x32_bf16 v[40:43], v[24:27], v[40:43], 0
	v_mfma_f32_16x16x32_bf16 v[36:39], v[20:23], v[44:47], v[36:39]
	v_mfma_f32_16x16x32_bf16 v[40:43], v[28:31], v[44:47], v[40:43]
	v_mfma_f32_16x16x32_bf16 v[44:47], v[16:19], v[48:51], 0
	v_mfma_f32_16x16x32_bf16 v[48:51], v[24:27], v[48:51], 0
	v_mfma_f32_16x16x32_bf16 v[44:47], v[20:23], v[52:55], v[44:47]
	v_mfma_f32_16x16x32_bf16 v[52:55], v[28:31], v[52:55], v[48:51]
	v_mfma_f32_16x16x32_bf16 v[48:51], v[16:19], v[56:59], 0
	v_mfma_f32_16x16x32_bf16 v[150:153], v[20:23], v[60:63], v[48:51]
	v_mfma_f32_16x16x32_bf16 v[48:51], v[24:27], v[56:59], 0
	v_mfma_f32_16x16x32_bf16 v[154:157], v[28:31], v[60:63], v[48:51]
	s_barrier
	s_setprio 0
	s_add_i32 s57, s48, s36
	v_lshl_add_u64 v[250:251], s[74:75], 0, v[128:129]
	s_add_i32 s58, s57, 0x2000
	v_lshl_add_u64 v[120:121], v[250:251], 0, s[60:61]
	s_mov_b32 m0, s57
	v_lshl_add_u64 v[252:253], s[74:75], 0, v[130:131]
	s_add_u32 s78, s74, 0x20100
	ds_read_b128 v[48:51], v149 offset:16384
	ds_read_b128 v[56:59], v149 offset:17408
	ds_read_b128 v[60:63], v149 offset:18432
	ds_read_b128 v[88:91], v149 offset:19456
	ds_read_b128 v[96:99], v149 offset:20480
	ds_read_b128 v[104:107], v149 offset:21504
	ds_read_b128 v[112:115], v149 offset:22528
	ds_read_b128 v[116:119], v149 offset:23552
	global_load_lds_dwordx4 v[120:121], off
	v_lshl_add_u64 v[120:121], v[252:253], 0, s[60:61]
	s_mov_b32 m0, s58
	s_addc_u32 s79, s75, 0
	s_add_i32 s59, s49, s36
	global_load_lds_dwordx4 v[120:121], off
	v_lshl_add_u64 v[120:121], s[78:79], 0, v[128:129]
	s_mov_b32 m0, s59
	s_add_i32 s65, s59, 0x2000
	global_load_lds_dwordx4 v128, s[78:79]
	v_lshl_add_u64 v[120:121], s[78:79], 0, v[130:131]
	s_mov_b32 m0, s65
	v_lshl_add_u64 v[140:141], s[76:77], 0, v[134:135]
	global_load_lds_dwordx4 v130, s[78:79]
	v_lshl_add_u64 v[120:121], v[140:141], 0, s[60:61]
	s_mov_b32 m0, s0
	v_lshl_add_u64 v[142:143], s[76:77], 0, v[132:133]
	global_load_lds_dwordx4 v[120:121], off
	v_lshl_add_u64 v[120:121], v[142:143], 0, s[60:61]
	s_mov_b32 m0, s1
	s_nop 0
	global_load_lds_dwordx4 v[120:121], off
	s_waitcnt vmcnt(24) lgkmcnt(0)
	s_cmp_lg_u32 s98, 0
	s_cbranch_scc1 .Lpw_14
	s_waitcnt vmcnt(8)
.Lpw_14:
	s_setprio 1
	s_barrier
	v_mfma_f32_16x16x32_bf16 v[120:123], v[0:3], v[48:51], 0
	v_mfma_f32_16x16x32_bf16 v[158:161], v[4:7], v[56:59], v[120:123]
	v_mfma_f32_16x16x32_bf16 v[120:123], v[8:11], v[48:51], 0
	v_mfma_f32_16x16x32_bf16 v[162:165], v[12:15], v[56:59], v[120:123]
	v_mfma_f32_16x16x32_bf16 v[120:123], v[0:3], v[60:63], 0
	v_mfma_f32_16x16x32_bf16 v[166:169], v[4:7], v[88:91], v[120:123]
	v_mfma_f32_16x16x32_bf16 v[120:123], v[8:11], v[60:63], 0
	v_mfma_f32_16x16x32_bf16 v[170:173], v[12:15], v[88:91], v[120:123]
	v_mfma_f32_16x16x32_bf16 v[120:123], v[0:3], v[96:99], 0
	v_mfma_f32_16x16x32_bf16 v[0:3], v[0:3], v[112:115], 0
	v_mfma_f32_16x16x32_bf16 v[174:177], v[4:7], v[104:107], v[120:123]
	v_mfma_f32_16x16x32_bf16 v[0:3], v[4:7], v[116:119], v[0:3]
	v_mfma_f32_16x16x32_bf16 v[4:7], v[8:11], v[112:115], 0
	v_mfma_f32_16x16x32_bf16 v[120:123], v[8:11], v[96:99], 0
	v_mfma_f32_16x16x32_bf16 v[4:7], v[12:15], v[116:119], v[4:7]
	v_mfma_f32_16x16x32_bf16 v[178:181], v[12:15], v[104:107], v[120:123]
	s_setprio 0
	s_setprio 1
	v_mfma_f32_16x16x32_bf16 v[8:11], v[16:19], v[48:51], 0
	v_mfma_f32_16x16x32_bf16 v[182:185], v[20:23], v[56:59], v[8:11]
	v_mfma_f32_16x16x32_bf16 v[8:11], v[24:27], v[48:51], 0
	v_mfma_f32_16x16x32_bf16 v[186:189], v[28:31], v[56:59], v[8:11]
	v_mfma_f32_16x16x32_bf16 v[8:11], v[16:19], v[60:63], 0
	v_mfma_f32_16x16x32_bf16 v[190:193], v[20:23], v[88:91], v[8:11]
	v_mfma_f32_16x16x32_bf16 v[8:11], v[24:27], v[60:63], 0
	v_mfma_f32_16x16x32_bf16 v[194:197], v[28:31], v[88:91], v[8:11]
	v_mfma_f32_16x16x32_bf16 v[8:11], v[16:19], v[96:99], 0
	v_mfma_f32_16x16x32_bf16 v[198:201], v[20:23], v[104:107], v[8:11]
	v_mfma_f32_16x16x32_bf16 v[8:11], v[24:27], v[96:99], 0
	v_mfma_f32_16x16x32_bf16 v[202:205], v[28:31], v[104:107], v[8:11]
	v_mfma_f32_16x16x32_bf16 v[8:11], v[16:19], v[112:115], 0
	v_mfma_f32_16x16x32_bf16 v[206:209], v[20:23], v[116:119], v[8:11]
	v_mfma_f32_16x16x32_bf16 v[8:11], v[24:27], v[112:115], 0
	v_mfma_f32_16x16x32_bf16 v[210:213], v[28:31], v[116:119], v[8:11]
	s_barrier
	s_setprio 0
	s_add_i32 s67, 0, 0x18000
	s_add_i32 s80, 0, 0x1c000
	v_add_u32_e32 v144, s67, v146
	v_add_u32_e32 v145, s80, v146
	s_nop 0
	ds_read_b128 v[8:11], v144
	ds_read_b128 v[12:15], v144 offset:1024
	ds_read_b128 v[16:19], v144 offset:2048
	ds_read_b128 v[20:23], v144 offset:3072
	ds_read_b128 v[214:217], v145
	ds_read_b128 v[218:221], v145 offset:1024
	ds_read_b128 v[222:225], v145 offset:2048
	ds_read_b128 v[226:229], v145 offset:3072
	s_add_u32 s78, s76, 0x20100
	s_addc_u32 s79, s77, 0
	s_mov_b32 m0, s37
	v_lshl_add_u64 v[48:49], s[78:79], 0, v[134:135]
	ds_read_b128 v[24:27], v149 offset:32768
	ds_read_b128 v[28:31], v149 offset:33792
	ds_read_b128 v[60:63], v149 offset:34816
	ds_read_b128 v[230:233], v149 offset:35840
	ds_read_b128 v[234:237], v149 offset:36864
	ds_read_b128 v[238:241], v149 offset:37888
	ds_read_b128 v[242:245], v149 offset:38912
	ds_read_b128 v[246:249], v149 offset:39936
	global_load_lds_dwordx4 v134, s[78:79]
	v_lshl_add_u64 v[48:49], s[78:79], 0, v[132:133]
	s_mov_b32 m0, s38
	s_nop 0
	global_load_lds_dwordx4 v132, s[78:79]
	s_waitcnt vmcnt(8) lgkmcnt(0)
	s_setprio 1
	s_barrier
	v_mfma_f32_16x16x32_bf16 v[48:51], v[8:11], v[24:27], v[64:67]
	v_mfma_f32_16x16x32_bf16 v[120:123], v[12:15], v[28:31], v[48:51]
	v_mfma_f32_16x16x32_bf16 v[48:51], v[16:19], v[24:27], v[68:71]
	v_mfma_f32_16x16x32_bf16 v[112:115], v[20:23], v[28:31], v[48:51]
	v_mfma_f32_16x16x32_bf16 v[48:51], v[8:11], v[60:63], v[72:75]
	v_mfma_f32_16x16x32_bf16 v[104:107], v[12:15], v[230:233], v[48:51]
	v_mfma_f32_16x16x32_bf16 v[48:51], v[16:19], v[60:63], v[76:79]
	v_mfma_f32_16x16x32_bf16 v[96:99], v[20:23], v[230:233], v[48:51]
	v_mfma_f32_16x16x32_bf16 v[48:51], v[8:11], v[234:237], v[80:83]
	v_mfma_f32_16x16x32_bf16 v[88:91], v[12:15], v[238:241], v[48:51]
	v_mfma_f32_16x16x32_bf16 v[48:51], v[16:19], v[234:237], v[84:87]
	v_mfma_f32_16x16x32_bf16 v[80:83], v[20:23], v[238:241], v[48:51]
	v_mfma_f32_16x16x32_bf16 v[48:51], v[8:11], v[242:245], v[92:95]
	v_mfma_f32_16x16x32_bf16 v[56:59], v[12:15], v[246:249], v[48:51]
	v_mfma_f32_16x16x32_bf16 v[48:51], v[16:19], v[242:245], v[100:103]
	v_mfma_f32_16x16x32_bf16 v[48:51], v[20:23], v[246:249], v[48:51]
	s_setprio 0
	s_setprio 1
	v_mfma_f32_16x16x32_bf16 v[64:67], v[214:217], v[24:27], v[108:111]
	v_mfma_f32_16x16x32_bf16 v[24:27], v[222:225], v[24:27], v[32:35]
	v_mfma_f32_16x16x32_bf16 v[116:119], v[226:229], v[28:31], v[24:27]
	v_mfma_f32_16x16x32_bf16 v[24:27], v[214:217], v[60:63], v[36:39]
	v_mfma_f32_16x16x32_bf16 v[108:111], v[218:221], v[230:233], v[24:27]
	v_mfma_f32_16x16x32_bf16 v[24:27], v[222:225], v[60:63], v[40:43]
	v_mfma_f32_16x16x32_bf16 v[100:103], v[226:229], v[230:233], v[24:27]
	v_mfma_f32_16x16x32_bf16 v[24:27], v[214:217], v[234:237], v[44:47]
	v_mfma_f32_16x16x32_bf16 v[92:95], v[218:221], v[238:241], v[24:27]
	v_mfma_f32_16x16x32_bf16 v[24:27], v[222:225], v[234:237], v[52:55]
	v_mfma_f32_16x16x32_bf16 v[84:87], v[226:229], v[238:241], v[24:27]
	v_mfma_f32_16x16x32_bf16 v[24:27], v[214:217], v[242:245], v[150:153]
	v_mfma_f32_16x16x32_bf16 v[60:63], v[218:221], v[246:249], v[24:27]
	v_mfma_f32_16x16x32_bf16 v[24:27], v[222:225], v[242:245], v[154:157]
	v_mfma_f32_16x16x32_bf16 v[124:127], v[218:221], v[28:31], v[64:67]
	v_mfma_f32_16x16x32_bf16 v[52:55], v[226:229], v[246:249], v[24:27]
	s_barrier
	s_setprio 0
	s_add_i32 s67, s67, s36
	s_add_i32 s71, s67, 0x2000
	s_nop 1
	v_lshl_add_u64 v[24:25], v[250:251], 0, s[62:63]
	s_mov_b32 m0, s67
	s_add_u32 s78, s74, 0x20180
	ds_read_b128 v[32:35], v149 offset:49152
	ds_read_b128 v[36:39], v149 offset:50176
	ds_read_b128 v[150:153], v149 offset:51200
	ds_read_b128 v[154:157], v149 offset:52224
	ds_read_b128 v[230:233], v149 offset:53248
	ds_read_b128 v[234:237], v149 offset:54272
	ds_read_b128 v[238:241], v149 offset:55296
	ds_read_b128 v[242:245], v149 offset:56320
	global_load_lds_dwordx4 v[24:25], off
	v_lshl_add_u64 v[24:25], v[252:253], 0, s[62:63]
	s_mov_b32 m0, s71
	s_addc_u32 s79, s75, 0
	s_add_i32 s80, s80, s36
	global_load_lds_dwordx4 v[24:25], off
	v_lshl_add_u64 v[24:25], s[78:79], 0, v[128:129]
	s_mov_b32 m0, s80
	s_add_i32 s81, s80, 0x2000
	global_load_lds_dwordx4 v128, s[78:79]
	v_lshl_add_u64 v[24:25], s[78:79], 0, v[130:131]
	s_mov_b32 m0, s81
	s_nop 0
	global_load_lds_dwordx4 v130, s[78:79]
	v_lshl_add_u64 v[24:25], v[140:141], 0, s[62:63]
	s_mov_b32 m0, s42
	s_nop 0
	global_load_lds_dwordx4 v[24:25], off
	v_lshl_add_u64 v[24:25], v[142:143], 0, s[62:63]
	s_mov_b32 m0, s43
	s_nop 0
	global_load_lds_dwordx4 v[24:25], off
	s_waitcnt vmcnt(8) lgkmcnt(0)
	s_setprio 1
	s_barrier
	v_mfma_f32_16x16x32_bf16 v[24:27], v[8:11], v[32:35], v[158:161]
	v_mfma_f32_16x16x32_bf16 v[76:79], v[12:15], v[36:39], v[24:27]
	v_mfma_f32_16x16x32_bf16 v[24:27], v[16:19], v[32:35], v[162:165]
	v_mfma_f32_16x16x32_bf16 v[72:75], v[20:23], v[36:39], v[24:27]
	v_mfma_f32_16x16x32_bf16 v[24:27], v[8:11], v[150:153], v[166:169]
	v_mfma_f32_16x16x32_bf16 v[44:47], v[12:15], v[154:157], v[24:27]
	v_mfma_f32_16x16x32_bf16 v[24:27], v[16:19], v[150:153], v[170:173]
	v_mfma_f32_16x16x32_bf16 v[40:43], v[20:23], v[154:157], v[24:27]
	v_mfma_f32_16x16x32_bf16 v[24:27], v[8:11], v[230:233], v[174:177]
	v_mfma_f32_16x16x32_bf16 v[0:3], v[8:11], v[238:241], v[0:3]
	v_mfma_f32_16x16x32_bf16 v[28:31], v[12:15], v[234:237], v[24:27]
	v_mfma_f32_16x16x32_bf16 v[24:27], v[16:19], v[230:233], v[178:181]
	v_mfma_f32_16x16x32_bf16 v[12:15], v[12:15], v[242:245], v[0:3]
	v_mfma_f32_16x16x32_bf16 v[0:3], v[16:19], v[238:241], v[4:7]
	v_mfma_f32_16x16x32_bf16 v[24:27], v[20:23], v[234:237], v[24:27]
	v_mfma_f32_16x16x32_bf16 v[8:11], v[20:23], v[242:245], v[0:3]
	s_setprio 0
	s_setprio 1
	v_mfma_f32_16x16x32_bf16 v[0:3], v[214:217], v[32:35], v[182:185]
	v_mfma_f32_16x16x32_bf16 v[68:71], v[218:221], v[36:39], v[0:3]
	v_mfma_f32_16x16x32_bf16 v[0:3], v[222:225], v[32:35], v[186:189]
	v_mfma_f32_16x16x32_bf16 v[64:67], v[226:229], v[36:39], v[0:3]
	v_mfma_f32_16x16x32_bf16 v[0:3], v[214:217], v[150:153], v[190:193]
	v_mfma_f32_16x16x32_bf16 v[36:39], v[218:221], v[154:157], v[0:3]
	v_mfma_f32_16x16x32_bf16 v[0:3], v[222:225], v[150:153], v[194:197]
	v_mfma_f32_16x16x32_bf16 v[32:35], v[226:229], v[154:157], v[0:3]
	v_mfma_f32_16x16x32_bf16 v[0:3], v[214:217], v[230:233], v[198:201]
	v_mfma_f32_16x16x32_bf16 v[20:23], v[218:221], v[234:237], v[0:3]
	v_mfma_f32_16x16x32_bf16 v[0:3], v[222:225], v[230:233], v[202:205]
	v_mfma_f32_16x16x32_bf16 v[16:19], v[226:229], v[234:237], v[0:3]
	v_mfma_f32_16x16x32_bf16 v[0:3], v[214:217], v[238:241], v[206:209]
	v_mfma_f32_16x16x32_bf16 v[4:7], v[218:221], v[242:245], v[0:3]
	v_mfma_f32_16x16x32_bf16 v[0:3], v[222:225], v[238:241], v[210:213]
	v_mfma_f32_16x16x32_bf16 v[0:3], v[226:229], v[242:245], v[0:3]
	s_barrier
	s_setprio 0
	s_add_u32 s82, s74, 0x200
	s_addc_u32 s83, s75, 0
	s_add_u32 s74, s76, 0x20180
	s_addc_u32 s75, s77, 0
	s_mov_b32 s85, 0

;     __device__ __forceinline__ void operator()(const f32x4 (&acc)[2][2][4][2], const Unit& u, int wr, int wc, int fr, int fq) const {
;         const int row0 = u.pm * BM + wr * 64 + fr; const int col0 = u.pn * BM + wc * 32 + 8 * fq;
;         const bool do_rope = (ACT == 2) && (((u.pn * BM) % 6144) < 4096);
;         float rinv[2][2];
;         if (ACT == 2) {
; #pragma unroll
;             for (int n = 0; n < 2; ++n)
; #pragma unroll
;                 for (int e = 0; e < 2; ++e) rinv[n][e] = exp2f(-(float)(16 * wc + 4 * fq + 2 * n + e) * (13.287712379549449f / 64.0f)) * 0.15915494309189535f;
;         }
;         float rinv3[2][4]; bool rope3[2];
;         if (ACT == 3) {
; #pragma unroll
;             for (int bj = 0; bj < 2; ++bj) { const int jj = (col0 + bj * HALF) % 192; rope3[bj] = jj >= 128; const int i0 = (jj - 128) >> 1;
; #pragma unroll
;                 for (int p = 0; p < 4; ++p) rinv3[bj][p] = exp2f(-(float)(i0 + p) * (13.287712379549449f / 32.0f)) * 0.15915494309189535f; }
;         }
; #pragma unroll
;         for (int ai = 0; ai < 2; ++ai)
; #pragma unroll
;             for (int m = 0; m < 4; ++m) { bf16_t* rowp = O + (size_t)(row0 + ai * HALF + m * 16) * ldc + col0;
;                 if (ACT == 1) {
;                     const int ob = fr * 64 + 16 * fq, sw = ob ^ (((ob >> 9) & 1) << 5);
;                     rowp = O + ((size_t)(u.pm * (ldc / 64) + u.pn * 4 + (wc >> 1)) * 2 + ai) * 8192 + (((wr * 4 + m) * 2 + (wc & 1)) * 1024 + sw) / 2; }
;                 float rc[2][2], rs[2][2];
;                 if (ACT == 2) { const float pos = (float)((row0 + ai * HALF + m * 16) & 2047);
; #pragma unroll
;                     for (int n = 0; n < 2; ++n)
; #pragma unroll
;                         for (int e = 0; e < 2; ++e) { float r = pos * rinv[n][e]; r -= floorf(r); rs[n][e] = do_rope ? __builtin_amdgcn_sinf(r) : 0.f; rc[n][e] = do_rope ? __builtin_amdgcn_cosf(r) : 1.f; } }
; #pragma unroll
;                 for (int bj = 0; bj < 2; ++bj) { f32x4 v0 = acc[ai][bj][m][0], v1 = acc[ai][bj][m][1];
;                     if (ACT == 3) { const float pos = (float)((row0 + ai * HALF + m * 16) & 2047); float c3[4], s3[4];
; #pragma unroll
;                         for (int p = 0; p < 4; ++p) { float r = pos * rinv3[bj][p]; r -= floorf(r); s3[p] = rope3[bj] ? __builtin_amdgcn_sinf(r) : 0.f; c3[p] = rope3[bj] ? __builtin_amdgcn_cosf(r) : 1.f; }
.LBB0_2569:
	v_mov_b32_e32 v140, 0
	s_lshl_b32 s51, s70, 8
	v_mbcnt_lo_u32_b32 v140, -1, v140
	v_mbcnt_hi_u32_b32 v140, -1, v140
	v_or_b32_e32 v141, s33, v140
	s_add_i32 s51, s51, s40
	v_and_or_b32 v140, v141, 15, s51
	s_lshl_b32 s50, s50, 8
	v_lshrrev_b32_e32 v141, 1, v141
	v_and_or_b32 v141, v141, 24, s50
	v_or_b32_e32 v142, s41, v141
	v_ashrrev_i32_e32 v141, 31, v140
	v_ashrrev_i32_e32 v143, 31, v142
	v_lshlrev_b64 v[144:145], 13, v[140:141]
	v_lshl_add_u64 v[144:145], s[12:13], 0, v[144:145]
	v_lshlrev_b64 v[142:143], 1, v[142:143]
	v_lshl_add_u64 v[144:145], v[144:145], 0, v[142:143]
	v_cvt_pk_bf16_f32 v120, v120, v121
	v_cvt_pk_bf16_f32 v121, v122, v123
	v_cvt_pk_bf16_f32 v122, v112, v113
	v_cvt_pk_bf16_f32 v123, v114, v115
	global_store_dwordx4 v[144:145], v[120:123], off
	v_cvt_pk_bf16_f32 v112, v124, v125
	v_cvt_pk_bf16_f32 v113, v126, v127
	v_cvt_pk_bf16_f32 v114, v116, v117
	v_cvt_pk_bf16_f32 v115, v118, v119
	global_store_dwordx4 v[144:145], v[112:115], off offset:256
	v_cvt_pk_bf16_f32 v104, v104, v105
	v_cvt_pk_bf16_f32 v105, v106, v107
	v_cvt_pk_bf16_f32 v106, v96, v97
	v_cvt_pk_bf16_f32 v107, v98, v99
	s_mov_b64 s[50:51], 0x100000
	s_nop 0
	v_or_b32_e32 v112, 16, v140
	v_ashrrev_i32_e32 v113, 31, v112
	v_lshlrev_b64 v[112:113], 13, v[112:113]
	v_lshl_add_u64 v[112:113], s[12:13], 0, v[112:113]
	v_lshl_add_u64 v[112:113], v[112:113], 0, v[142:143]
	global_store_dwordx4 v[112:113], v[104:107], off
	v_cvt_pk_bf16_f32 v96, v108, v109
	v_cvt_pk_bf16_f32 v97, v110, v111
	v_cvt_pk_bf16_f32 v98, v100, v101
	v_cvt_pk_bf16_f32 v99, v102, v103
	global_store_dwordx4 v[112:113], v[96:99], off offset:256
	v_cvt_pk_bf16_f32 v88, v88, v89
	v_cvt_pk_bf16_f32 v89, v90, v91
	v_cvt_pk_bf16_f32 v90, v80, v81
	v_cvt_pk_bf16_f32 v91, v82, v83
	s_nop 1
	v_or_b32_e32 v96, 32, v140
	v_ashrrev_i32_e32 v97, 31, v96
	v_lshlrev_b64 v[96:97], 13, v[96:97]
	v_lshl_add_u64 v[96:97], s[12:13], 0, v[96:97]
	v_lshl_add_u64 v[96:97], v[96:97], 0, v[142:143]
	global_store_dwordx4 v[96:97], v[88:91], off
	v_cvt_pk_bf16_f32 v80, v92, v93
	v_cvt_pk_bf16_f32 v81, v94, v95
	v_cvt_pk_bf16_f32 v82, v84, v85
	v_cvt_pk_bf16_f32 v83, v86, v87
	global_store_dwordx4 v[96:97], v[80:83], off offset:256
	v_cvt_pk_bf16_f32 v56, v56, v57
	v_cvt_pk_bf16_f32 v57, v58, v59
	v_cvt_pk_bf16_f32 v58, v48, v49
	v_cvt_pk_bf16_f32 v59, v50, v51
	s_nop 1
	v_or_b32_e32 v80, 48, v140
	v_ashrrev_i32_e32 v81, 31, v80
	v_lshlrev_b64 v[80:81], 13, v[80:81]
	v_lshl_add_u64 v[80:81], s[12:13], 0, v[80:81]
	v_lshl_add_u64 v[80:81], v[80:81], 0, v[142:143]
	global_store_dwordx4 v[80:81], v[56:59], off
	v_cvt_pk_bf16_f32 v48, v60, v61
	v_cvt_pk_bf16_f32 v49, v62, v63
	v_cvt_pk_bf16_f32 v50, v52, v53
	v_lshl_add_u64 v[52:53], v[144:145], 0, s[50:51]
	s_mov_b32 s50, 0x100000
	v_cvt_pk_bf16_f32 v51, v54, v55
	v_add_co_u32_e32 v54, vcc, s50, v144
	global_store_dwordx4 v[80:81], v[48:51], off offset:256
	s_nop 0
	v_addc_co_u32_e32 v55, vcc, 0, v145, vcc
	v_cvt_pk_bf16_f32 v48, v76, v77
	v_cvt_pk_bf16_f32 v49, v78, v79
	v_cvt_pk_bf16_f32 v50, v72, v73
	v_cvt_pk_bf16_f32 v51, v74, v75
	global_store_dwordx4 v[54:55], v[48:51], off
	s_mov_b64 s[50:51], 0x120000
	s_nop 0
	v_cvt_pk_bf16_f32 v48, v68, v69
	v_cvt_pk_bf16_f32 v49, v70, v71
	v_cvt_pk_bf16_f32 v50, v64, v65
	v_cvt_pk_bf16_f32 v51, v66, v67
	global_store_dwordx4 v[52:53], v[48:51], off offset:256
	v_cvt_pk_bf16_f32 v44, v44, v45
	v_cvt_pk_bf16_f32 v45, v46, v47
	v_cvt_pk_bf16_f32 v46, v40, v41
	v_cvt_pk_bf16_f32 v47, v42, v43
	s_nop 1
	v_lshl_add_u64 v[48:49], v[144:145], 0, s[50:51]
	s_mov_b32 s50, 0x120000
	v_add_co_u32_e32 v40, vcc, s50, v144
	s_mov_b64 s[50:51], 0x140000
	s_nop 0
	v_addc_co_u32_e32 v41, vcc, 0, v145, vcc
	global_store_dwordx4 v[40:41], v[44:47], off
	v_cvt_pk_bf16_f32 v36, v36, v37
	v_cvt_pk_bf16_f32 v37, v38, v39
	v_cvt_pk_bf16_f32 v38, v32, v33
	v_lshl_add_u64 v[32:33], v[144:145], 0, s[50:51]
	s_mov_b32 s50, 0x140000
	v_cvt_pk_bf16_f32 v39, v34, v35
	global_store_dwordx4 v[48:49], v[36:39], off offset:256
	v_cvt_pk_bf16_f32 v28, v28, v29
	v_cvt_pk_bf16_f32 v29, v30, v31
	v_cvt_pk_bf16_f32 v30, v24, v25
	v_add_co_u32_e32 v24, vcc, s50, v144
	s_mov_b64 s[50:51], 0x160000
	s_nop 0
	v_addc_co_u32_e32 v25, vcc, 0, v145, vcc
	v_cvt_pk_bf16_f32 v31, v26, v27
	global_store_dwordx4 v[24:25], v[28:31], off
	v_cvt_pk_bf16_f32 v20, v20, v21
	v_cvt_pk_bf16_f32 v21, v22, v23
	v_cvt_pk_bf16_f32 v22, v16, v17
	v_lshl_add_u64 v[16:17], v[144:145], 0, s[50:51]
	s_mov_b32 s50, 0x160000
	v_cvt_pk_bf16_f32 v23, v18, v19
	global_store_dwordx4 v[32:33], v[20:23], off offset:256
	v_cvt_pk_bf16_f32 v12, v12, v13
	v_cvt_pk_bf16_f32 v13, v14, v15
	v_cvt_pk_bf16_f32 v14, v8, v9
	v_add_co_u32_e32 v8, vcc, s50, v144
	v_cvt_pk_bf16_f32 v15, v10, v11
	s_nop 1
	v_addc_co_u32_e32 v9, vcc, 0, v145, vcc
	s_andn2_b64 vcc, exec, s[2:3]
	s_mov_b64 s[2:3], -1
	global_store_dwordx4 v[8:9], v[12:15], off
	v_cvt_pk_bf16_f32 v4, v4, v5
	v_cvt_pk_bf16_f32 v5, v6, v7
	v_cvt_pk_bf16_f32 v6, v0, v1
	v_cvt_pk_bf16_f32 v7, v2, v3
	global_store_dwordx4 v[16:17], v[4:7], off offset:256
	s_mov_b32 s98, 1
	s_cbranch_vccnz .LBB0_2558
	s_andn2_b64 vcc, exec, s[4:5]
	s_cbranch_vccnz .LBB0_2557
	s_barrier
	s_branch .LBB0_2557

; #define PG8_STAGE(bufoff, gbase, voff) do { _Pragma("unroll") for (int _i = 0; _i < 2; ++_i) \
;         __builtin_amdgcn_global_load_lds((const unsigned*)((const char*)(gbase) + (voff)[_i]), (PG8_LAS unsigned*)(lds + (bufoff) + ldsw + _i * 8192), 16, 0, 0); } while (0)
; #define PG8_WAIT_V(n) asm volatile("s_waitcnt vmcnt(" #n ")" ::: "memory")
; #define PG8_BAR __builtin_amdgcn_s_barrier()
; template <class Epi, class Sched, bool ALIGN_EPI = false, bool SP2 = false, bool A_TILED = false>
; __device__ __forceinline__ void gemm_phase(PG8_LAS unsigned char* lds, const Gemm g, const Sched& S, const Epi& E, const int wave_s) {
;     ...
;     const int aoff = lds_byte(wr * 64 + fr, fq * 8), boff = lds_byte(wc * 32 + fr, fq * 8);
;     ...
;     Unit cur, nxt; int ui = 0;
;     if (!S.next(0, cur)) return;
;     f32x4 acc[2][2][4][2];
;     bf16x8 At[4][2], B0[2][2], B1[2][2];
;     const char* cA = (const char*)g.A + (size_t)cur.pm * tstepA; const char* cB = (const char*)g.Bt + (size_t)cur.pn * tstep;
;     S.a_ready(cur);
;     if constexpr (SP2) {
;         PG8_STAGE(PG8_SB(0, 0), cB, voffB); PG8_STAGE(PG8_SB(0, 1), cB + hstep, voffB); PG8_STAGE(PG8_SA(0, 0), cA, voffA); PG8_STAGE(PG8_SA(0, 1), cA + hstepA, voffA);
;         if (wr == 1) PG8_BAR;
;         PG8_WAIT_V(2); PG8_BAR;
;         PG8_STAGE(PG8_SB(1, 0), cB + kstep, voffB); PG8_STAGE(PG8_SA(1, 0), cA + kstepA, voffA); PG8_STAGE(PG8_SB(1, 1), cB + hstep + kstep, voffB);
;         PG8_WAIT_V(6); PG8_BAR;
.LBB0_2831:
	s_ashr_i32 s40, s86, 31
	s_add_u32 s41, s2, 0x34600000
	s_addc_u32 s42, s3, 0
	s_lshl_b32 s47, s12, 13
	s_mov_b64 s[12:13], 0x80
	s_and_b32 s2, s46, 3
	s_add_i32 m0, s22, 0x18000
	v_lshl_add_u64 v[6:7], v[6:7], 0, s[12:13]
	s_lshl_b32 s49, s2, 12
	s_waitcnt vmcnt(2)
	s_barrier
	global_load_lds_dwordx4 v[6:7], off
	v_lshl_add_u64 v[4:5], v[4:5], 0, s[12:13]
	s_add_i32 m0, s22, 0x1a000
	s_add_i32 s43, s22, 0x8000
	s_add_i32 s48, s22, 0xa000
	global_load_lds_dwordx4 v[4:5], off
	v_lshl_add_u64 v[0:1], v[0:1], 0, s[12:13]
	s_mov_b32 m0, s43
	s_add_u32 s2, s72, 0x80080
	global_load_lds_dwordx4 v[0:1], off
	v_lshl_add_u64 v[0:1], v[2:3], 0, s[12:13]
	s_mov_b32 m0, s48
	s_addc_u32 s3, s73, 0
	global_load_lds_dwordx4 v[0:1], off
	s_add_i32 m0, s22, 0x1c000
	v_lshl_add_u64 v[0:1], s[2:3], 0, v[128:129]
	global_load_lds_dwordx4 v128, s[2:3]
	v_lshl_add_u64 v[0:1], s[2:3], 0, v[130:131]
	s_add_i32 m0, s22, 0x1e000
	s_cmpk_lt_u32 s45, 0x100
	global_load_lds_dwordx4 v130, s[2:3]
	v_and_b32_e32 v0, 15, v8
	v_and_b32_e32 v1, 48, v8
	v_lshl_or_b32 v0, v0, 6, v1
	v_lshlrev_b32_e32 v1, 2, v8
	v_and_b32_e32 v1, 32, v1
	v_bitop3_b32 v2, v0, s47, v1 bitop3:0xde
	v_bitop3_b32 v144, v0, s49, v1 bitop3:0xde
	v_lshlrev_b32_e32 v0, 15, v9
	v_and_b32_e32 v0, 0xffff0000, v0
	v_lshl_add_u32 v0, v10, 12, v0
	v_and_b32_e32 v1, 1, v9
	v_lshl_or_b32 v0, v1, 6, v0
	v_lshl_add_u32 v136, v11, 1, v0
	v_lshlrev_b32_e32 v0, 15, v13
	v_and_b32_e32 v0, 0xffff0000, v0
	s_waitcnt vmcnt(6)
	s_mov_b32 s98, 0
	v_lshl_add_u32 v0, v12, 12, v0
	v_and_b32_e32 v1, 1, v13
	s_sext_i32_i16 s53, s44
	s_cselect_b64 s[44:45], -1, 0
	s_and_b32 s2, s15, 0x400
	v_mov_b32_e32 v137, 0
	v_lshl_or_b32 v0, v1, 6, v0
	s_add_i32 s51, 0, 0x10000
	s_add_i32 s52, 0, 0x14000
	s_bfe_u32 s49, s46, 0x10001
	s_or_b32 s50, s2, s47
	v_lshl_add_u32 v138, v14, 1, v0
	v_mov_b32_e32 v139, v137
	v_mov_b64_e32 v[140:141], 0x200
	v_mov_b64_e32 v[142:143], 0x1ff
	v_add_u32_e32 v145, s51, v144
	v_add_u32_e32 v146, s52, v144
	v_add_u32_e32 v147, 0, v2
	s_mov_b64 s[46:47], 0x100
	s_mov_b64 s[60:61], 0x180
	s_barrier
	s_branch .LBB0_2834

.LBB0_2840:
	s_ashr_i32 s65, s64, 31
	s_lshl_b64 s[54:55], s[64:65], 20
	s_add_u32 s66, s1, s54
	ds_read_b128 v[0:3], v145
	ds_read_b128 v[4:7], v145 offset:1024
	ds_read_b128 v[8:11], v145 offset:2048
	ds_read_b128 v[12:15], v145 offset:3072
	ds_read_b128 v[16:19], v146
	ds_read_b128 v[20:23], v146 offset:1024
	ds_read_b128 v[24:27], v146 offset:2048
	ds_read_b128 v[28:31], v146 offset:3072
	s_addc_u32 s67, s8, s55
	s_ashr_i32 s63, s62, 31
	s_lshl_b64 s[54:55], s[62:63], 20
	s_add_u32 s68, s9, s54
	s_addc_u32 s69, s14, s55
	s_and_b64 s[54:55], s[2:3], exec
	s_cselect_b32 s54, s67, s75
	s_cselect_b32 s55, s66, s74
	s_cselect_b32 s56, s69, s73
	s_cselect_b32 s57, s68, s72
	s_add_u32 s76, s74, 0x80080
	s_addc_u32 s77, s75, 0
	s_add_i32 s58, s22, 0xc000
	v_lshl_add_u64 v[64:65], s[76:77], 0, v[134:135]
	s_mov_b32 m0, s58
	s_add_i32 s59, s22, 0xe000
	ds_read_b128 v[32:35], v147
	ds_read_b128 v[36:39], v147 offset:1024
	ds_read_b128 v[40:43], v147 offset:2048
	ds_read_b128 v[44:47], v147 offset:3072
	ds_read_b128 v[48:51], v147 offset:4096
	ds_read_b128 v[52:55], v147 offset:5120
	ds_read_b128 v[56:59], v147 offset:6144
	ds_read_b128 v[60:63], v147 offset:7168
	global_load_lds_dwordx4 v134, s[76:77]
	v_lshl_add_u64 v[64:65], s[76:77], 0, v[132:133]
	s_mov_b32 m0, s59
	s_nop 0
	global_load_lds_dwordx4 v132, s[76:77]
	s_waitcnt vmcnt(24) lgkmcnt(0)
	s_cmp_lg_u32 s98, 0
	s_cbranch_scc1 .Lpw_15
	s_waitcnt vmcnt(8)
.Lpw_15:
	s_setprio 1
	s_barrier
	v_mfma_f32_16x16x32_bf16 v[88:91], v[0:3], v[56:59], 0
	v_mfma_f32_16x16x32_bf16 v[64:67], v[0:3], v[32:35], 0
	v_mfma_f32_16x16x32_bf16 v[68:71], v[8:11], v[32:35], 0
	v_mfma_f32_16x16x32_bf16 v[72:75], v[0:3], v[40:43], 0
	v_mfma_f32_16x16x32_bf16 v[76:79], v[8:11], v[40:43], 0
	v_mfma_f32_16x16x32_bf16 v[80:83], v[0:3], v[48:51], 0
	v_mfma_f32_16x16x32_bf16 v[84:87], v[8:11], v[48:51], 0
	v_mfma_f32_16x16x32_bf16 v[96:99], v[4:7], v[60:63], v[88:91]
	v_mfma_f32_16x16x32_bf16 v[88:91], v[8:11], v[56:59], 0
	v_mfma_f32_16x16x32_bf16 v[64:67], v[4:7], v[36:39], v[64:67]
	v_mfma_f32_16x16x32_bf16 v[68:71], v[12:15], v[36:39], v[68:71]
	v_mfma_f32_16x16x32_bf16 v[72:75], v[4:7], v[44:47], v[72:75]
	v_mfma_f32_16x16x32_bf16 v[76:79], v[12:15], v[44:47], v[76:79]
	v_mfma_f32_16x16x32_bf16 v[80:83], v[4:7], v[52:55], v[80:83]
	v_mfma_f32_16x16x32_bf16 v[84:87], v[12:15], v[52:55], v[84:87]
	v_mfma_f32_16x16x32_bf16 v[100:103], v[12:15], v[60:63], v[88:91]
	s_setprio 0
	s_setprio 1
	v_mfma_f32_16x16x32_bf16 v[88:91], v[16:19], v[32:35], 0
	v_mfma_f32_16x16x32_bf16 v[32:35], v[24:27], v[32:35], 0
	v_mfma_f32_16x16x32_bf16 v[112:115], v[20:23], v[36:39], v[88:91]
	v_mfma_f32_16x16x32_bf16 v[32:35], v[28:31], v[36:39], v[32:35]
	v_mfma_f32_16x16x32_bf16 v[36:39], v[16:19], v[40:43], 0
	v_mfma_f32_16x16x32_bf16 v[40:43], v[24:27], v[40:43], 0
	v_mfma_f32_16x16x32_bf16 v[36:39], v[20:23], v[44:47], v[36:39]
	v_mfma_f32_16x16x32_bf16 v[40:43], v[28:31], v[44:47], v[40:43]
	v_mfma_f32_16x16x32_bf16 v[44:47], v[16:19], v[48:51], 0
	v_mfma_f32_16x16x32_bf16 v[48:51], v[24:27], v[48:51], 0
	v_mfma_f32_16x16x32_bf16 v[44:47], v[20:23], v[52:55], v[44:47]
	v_mfma_f32_16x16x32_bf16 v[48:51], v[28:31], v[52:55], v[48:51]
	v_mfma_f32_16x16x32_bf16 v[52:55], v[16:19], v[56:59], 0
	v_mfma_f32_16x16x32_bf16 v[56:59], v[24:27], v[56:59], 0
	v_mfma_f32_16x16x32_bf16 v[52:55], v[20:23], v[60:63], v[52:55]
	v_mfma_f32_16x16x32_bf16 v[56:59], v[28:31], v[60:63], v[56:59]
	s_barrier
	s_setprio 0
	s_add_i32 s63, s51, s15
	v_lshl_add_u64 v[242:243], s[72:73], 0, v[128:129]
	s_add_i32 s65, s63, 0x2000
	v_lshl_add_u64 v[148:149], v[242:243], 0, s[46:47]
	s_mov_b32 m0, s63
	v_lshl_add_u64 v[244:245], s[72:73], 0, v[130:131]
	s_add_u32 s76, s72, 0x80100
	ds_read_b128 v[60:63], v147 offset:16384
	ds_read_b128 v[88:91], v147 offset:17408
	ds_read_b128 v[92:95], v147 offset:18432
	ds_read_b128 v[104:107], v147 offset:19456
	ds_read_b128 v[108:111], v147 offset:20480
	ds_read_b128 v[116:119], v147 offset:21504
	ds_read_b128 v[120:123], v147 offset:22528
	ds_read_b128 v[124:127], v147 offset:23552
	global_load_lds_dwordx4 v[148:149], off
	v_lshl_add_u64 v[148:149], v[244:245], 0, s[46:47]
	s_mov_b32 m0, s65
	s_addc_u32 s77, s73, 0
	s_add_i32 s71, s52, s15
	global_load_lds_dwordx4 v[148:149], off
	v_lshl_add_u64 v[148:149], s[76:77], 0, v[128:129]
	s_mov_b32 m0, s71
	s_add_i32 s78, s71, 0x2000
	global_load_lds_dwordx4 v128, s[76:77]
	v_lshl_add_u64 v[148:149], s[76:77], 0, v[130:131]
	s_mov_b32 m0, s78
	v_lshl_add_u64 v[246:247], s[74:75], 0, v[134:135]
	global_load_lds_dwordx4 v130, s[76:77]
	v_lshl_add_u64 v[148:149], v[246:247], 0, s[46:47]
	s_mov_b32 m0, s22
	v_lshl_add_u64 v[248:249], s[74:75], 0, v[132:133]
	global_load_lds_dwordx4 v[148:149], off
	v_lshl_add_u64 v[148:149], v[248:249], 0, s[46:47]
	s_mov_b32 m0, s23
	s_nop 0
	global_load_lds_dwordx4 v[148:149], off
	s_waitcnt vmcnt(24) lgkmcnt(0)
	s_cmp_lg_u32 s98, 0
	s_cbranch_scc1 .Lpw_16
	s_waitcnt vmcnt(8)
.Lpw_16:
	s_setprio 1
	s_barrier
	v_mfma_f32_16x16x32_bf16 v[148:151], v[0:3], v[60:63], 0
	v_mfma_f32_16x16x32_bf16 v[158:161], v[0:3], v[92:95], 0
	v_mfma_f32_16x16x32_bf16 v[166:169], v[0:3], v[108:111], 0
	v_mfma_f32_16x16x32_bf16 v[0:3], v[0:3], v[120:123], 0
	v_mfma_f32_16x16x32_bf16 v[150:153], v[4:7], v[88:91], v[148:151]
	v_mfma_f32_16x16x32_bf16 v[158:161], v[4:7], v[104:107], v[158:161]
	v_mfma_f32_16x16x32_bf16 v[166:169], v[4:7], v[116:119], v[166:169]
	v_mfma_f32_16x16x32_bf16 v[0:3], v[4:7], v[124:127], v[0:3]
	v_mfma_f32_16x16x32_bf16 v[4:7], v[8:11], v[120:123], 0
	v_mfma_f32_16x16x32_bf16 v[154:157], v[8:11], v[60:63], 0
	v_mfma_f32_16x16x32_bf16 v[162:165], v[8:11], v[92:95], 0
	v_mfma_f32_16x16x32_bf16 v[170:173], v[8:11], v[108:111], 0
	v_mfma_f32_16x16x32_bf16 v[4:7], v[12:15], v[124:127], v[4:7]
	v_mfma_f32_16x16x32_bf16 v[154:157], v[12:15], v[88:91], v[154:157]
	v_mfma_f32_16x16x32_bf16 v[162:165], v[12:15], v[104:107], v[162:165]
	v_mfma_f32_16x16x32_bf16 v[170:173], v[12:15], v[116:119], v[170:173]
	s_setprio 0
	s_setprio 1
	v_mfma_f32_16x16x32_bf16 v[8:11], v[16:19], v[60:63], 0
	v_mfma_f32_16x16x32_bf16 v[174:177], v[20:23], v[88:91], v[8:11]
	v_mfma_f32_16x16x32_bf16 v[8:11], v[24:27], v[60:63], 0
	v_mfma_f32_16x16x32_bf16 v[60:63], v[28:31], v[88:91], v[8:11]
	v_mfma_f32_16x16x32_bf16 v[8:11], v[16:19], v[92:95], 0
	v_mfma_f32_16x16x32_bf16 v[178:181], v[20:23], v[104:107], v[8:11]
	v_mfma_f32_16x16x32_bf16 v[8:11], v[24:27], v[92:95], 0
	v_mfma_f32_16x16x32_bf16 v[182:185], v[28:31], v[104:107], v[8:11]
	v_mfma_f32_16x16x32_bf16 v[8:11], v[16:19], v[108:111], 0
	v_mfma_f32_16x16x32_bf16 v[186:189], v[20:23], v[116:119], v[8:11]
	v_mfma_f32_16x16x32_bf16 v[8:11], v[24:27], v[108:111], 0
	v_mfma_f32_16x16x32_bf16 v[190:193], v[28:31], v[116:119], v[8:11]
	v_mfma_f32_16x16x32_bf16 v[8:11], v[16:19], v[120:123], 0
	v_mfma_f32_16x16x32_bf16 v[194:197], v[20:23], v[124:127], v[8:11]
	v_mfma_f32_16x16x32_bf16 v[8:11], v[24:27], v[120:123], 0
	v_mfma_f32_16x16x32_bf16 v[198:201], v[28:31], v[124:127], v[8:11]
	s_barrier
	s_setprio 0
	s_add_i32 s79, 0, 0x18000
	s_add_i32 s81, 0, 0x1c000
	v_add_u32_e32 v148, s79, v144
	v_add_u32_e32 v149, s81, v144
	s_nop 0
	ds_read_b128 v[8:11], v148
	ds_read_b128 v[12:15], v148 offset:1024
	ds_read_b128 v[16:19], v148 offset:2048
	ds_read_b128 v[20:23], v148 offset:3072
	ds_read_b128 v[202:205], v149
	ds_read_b128 v[206:209], v149 offset:1024
	ds_read_b128 v[210:213], v149 offset:2048
	ds_read_b128 v[214:217], v149 offset:3072
	s_add_u32 s76, s74, 0x80100
	s_addc_u32 s77, s75, 0
	s_mov_b32 m0, s36
	v_lshl_add_u64 v[88:89], s[76:77], 0, v[134:135]
	ds_read_b128 v[24:27], v147 offset:32768
	ds_read_b128 v[28:31], v147 offset:33792
	ds_read_b128 v[218:221], v147 offset:34816
	ds_read_b128 v[222:225], v147 offset:35840
	ds_read_b128 v[226:229], v147 offset:36864
	ds_read_b128 v[230:233], v147 offset:37888
	ds_read_b128 v[234:237], v147 offset:38912
	ds_read_b128 v[238:241], v147 offset:39936
	global_load_lds_dwordx4 v134, s[76:77]
	v_lshl_add_u64 v[88:89], s[76:77], 0, v[132:133]
	s_mov_b32 m0, s37
	s_nop 0
	global_load_lds_dwordx4 v132, s[76:77]
	s_waitcnt vmcnt(8) lgkmcnt(0)
	s_setprio 1
	s_barrier
	v_mfma_f32_16x16x32_bf16 v[64:67], v[8:11], v[24:27], v[64:67]
	v_mfma_f32_16x16x32_bf16 v[120:123], v[12:15], v[28:31], v[64:67]
	v_mfma_f32_16x16x32_bf16 v[64:67], v[16:19], v[24:27], v[68:71]
	v_mfma_f32_16x16x32_bf16 v[124:127], v[20:23], v[28:31], v[64:67]
	v_mfma_f32_16x16x32_bf16 v[64:67], v[8:11], v[218:221], v[72:75]
	v_mfma_f32_16x16x32_bf16 v[104:107], v[12:15], v[222:225], v[64:67]
	v_mfma_f32_16x16x32_bf16 v[64:67], v[16:19], v[218:221], v[76:79]
	v_mfma_f32_16x16x32_bf16 v[108:111], v[20:23], v[222:225], v[64:67]
	v_mfma_f32_16x16x32_bf16 v[64:67], v[8:11], v[226:229], v[80:83]
	v_mfma_f32_16x16x32_bf16 v[88:91], v[12:15], v[230:233], v[64:67]
	v_mfma_f32_16x16x32_bf16 v[64:67], v[16:19], v[226:229], v[84:87]
	v_mfma_f32_16x16x32_bf16 v[92:95], v[20:23], v[230:233], v[64:67]
	v_mfma_f32_16x16x32_bf16 v[64:67], v[8:11], v[234:237], v[96:99]
	v_mfma_f32_16x16x32_bf16 v[68:71], v[16:19], v[234:237], v[100:103]
	v_mfma_f32_16x16x32_bf16 v[64:67], v[12:15], v[238:241], v[64:67]
	v_mfma_f32_16x16x32_bf16 v[68:71], v[20:23], v[238:241], v[68:71]
	s_setprio 0
	s_setprio 1
	v_mfma_f32_16x16x32_bf16 v[72:75], v[202:205], v[24:27], v[112:115]
	v_mfma_f32_16x16x32_bf16 v[24:27], v[210:213], v[24:27], v[32:35]
	v_mfma_f32_16x16x32_bf16 v[116:119], v[214:217], v[28:31], v[24:27]
	v_mfma_f32_16x16x32_bf16 v[24:27], v[202:205], v[218:221], v[36:39]
	v_mfma_f32_16x16x32_bf16 v[96:99], v[206:209], v[222:225], v[24:27]
	v_mfma_f32_16x16x32_bf16 v[24:27], v[210:213], v[218:221], v[40:43]
	v_mfma_f32_16x16x32_bf16 v[100:103], v[214:217], v[222:225], v[24:27]
	v_mfma_f32_16x16x32_bf16 v[24:27], v[202:205], v[226:229], v[44:47]
	v_mfma_f32_16x16x32_bf16 v[80:83], v[206:209], v[230:233], v[24:27]
	v_mfma_f32_16x16x32_bf16 v[24:27], v[210:213], v[226:229], v[48:51]
	v_mfma_f32_16x16x32_bf16 v[84:87], v[214:217], v[230:233], v[24:27]
	v_mfma_f32_16x16x32_bf16 v[24:27], v[202:205], v[234:237], v[52:55]
	v_mfma_f32_16x16x32_bf16 v[48:51], v[206:209], v[238:241], v[24:27]
	v_mfma_f32_16x16x32_bf16 v[24:27], v[210:213], v[234:237], v[56:59]
	v_mfma_f32_16x16x32_bf16 v[112:115], v[206:209], v[28:31], v[72:75]
	v_mfma_f32_16x16x32_bf16 v[52:55], v[214:217], v[238:241], v[24:27]
	s_barrier
	s_setprio 0
	s_add_i32 s79, s79, s15
	s_add_i32 s80, s79, 0x2000
	s_nop 1
	v_lshl_add_u64 v[24:25], v[242:243], 0, s[60:61]
	s_mov_b32 m0, s79
	s_add_u32 s76, s72, 0x80180
	ds_read_b128 v[32:35], v147 offset:49152
	ds_read_b128 v[36:39], v147 offset:50176
	ds_read_b128 v[218:221], v147 offset:51200
	ds_read_b128 v[222:225], v147 offset:52224
	ds_read_b128 v[226:229], v147 offset:53248
	ds_read_b128 v[230:233], v147 offset:54272
	ds_read_b128 v[234:237], v147 offset:55296
	ds_read_b128 v[238:241], v147 offset:56320
	global_load_lds_dwordx4 v[24:25], off
	v_lshl_add_u64 v[24:25], v[244:245], 0, s[60:61]
	s_mov_b32 m0, s80
	s_addc_u32 s77, s73, 0
	s_add_i32 s81, s81, s15
	global_load_lds_dwordx4 v[24:25], off
	v_lshl_add_u64 v[24:25], s[76:77], 0, v[128:129]
	s_mov_b32 m0, s81
	s_add_i32 s82, s81, 0x2000
	global_load_lds_dwordx4 v128, s[76:77]
	v_lshl_add_u64 v[24:25], s[76:77], 0, v[130:131]
	s_mov_b32 m0, s82
	s_nop 0
	global_load_lds_dwordx4 v130, s[76:77]
	v_lshl_add_u64 v[24:25], v[246:247], 0, s[60:61]
	s_mov_b32 m0, s43
	s_nop 0
	global_load_lds_dwordx4 v[24:25], off
	v_lshl_add_u64 v[24:25], v[248:249], 0, s[60:61]
	s_mov_b32 m0, s48
	s_nop 0
	global_load_lds_dwordx4 v[24:25], off
	s_waitcnt vmcnt(8) lgkmcnt(0)
	s_setprio 1
	s_barrier
	v_mfma_f32_16x16x32_bf16 v[24:27], v[8:11], v[32:35], v[150:153]
	v_mfma_f32_16x16x32_bf16 v[72:75], v[12:15], v[36:39], v[24:27]
	v_mfma_f32_16x16x32_bf16 v[24:27], v[16:19], v[32:35], v[154:157]
	v_mfma_f32_16x16x32_bf16 v[76:79], v[20:23], v[36:39], v[24:27]
	v_mfma_f32_16x16x32_bf16 v[24:27], v[8:11], v[218:221], v[158:161]
	v_mfma_f32_16x16x32_bf16 v[40:43], v[12:15], v[222:225], v[24:27]
	v_mfma_f32_16x16x32_bf16 v[24:27], v[16:19], v[218:221], v[162:165]
	v_mfma_f32_16x16x32_bf16 v[0:3], v[8:11], v[234:237], v[0:3]
	v_mfma_f32_16x16x32_bf16 v[44:47], v[20:23], v[222:225], v[24:27]
	v_mfma_f32_16x16x32_bf16 v[24:27], v[8:11], v[226:229], v[166:169]
	v_mfma_f32_16x16x32_bf16 v[28:31], v[16:19], v[226:229], v[170:173]
	v_mfma_f32_16x16x32_bf16 v[8:11], v[12:15], v[238:241], v[0:3]
	v_mfma_f32_16x16x32_bf16 v[0:3], v[16:19], v[234:237], v[4:7]
	v_mfma_f32_16x16x32_bf16 v[24:27], v[12:15], v[230:233], v[24:27]
	v_mfma_f32_16x16x32_bf16 v[28:31], v[20:23], v[230:233], v[28:31]
	v_mfma_f32_16x16x32_bf16 v[12:15], v[20:23], v[238:241], v[0:3]
	s_setprio 0
	s_setprio 1
	v_mfma_f32_16x16x32_bf16 v[0:3], v[202:205], v[32:35], v[174:177]
	v_mfma_f32_16x16x32_bf16 v[56:59], v[206:209], v[36:39], v[0:3]
	v_mfma_f32_16x16x32_bf16 v[0:3], v[210:213], v[32:35], v[60:63]
	v_mfma_f32_16x16x32_bf16 v[60:63], v[214:217], v[36:39], v[0:3]
	v_mfma_f32_16x16x32_bf16 v[0:3], v[202:205], v[218:221], v[178:181]
	v_mfma_f32_16x16x32_bf16 v[32:35], v[206:209], v[222:225], v[0:3]
	v_mfma_f32_16x16x32_bf16 v[0:3], v[210:213], v[218:221], v[182:185]
	v_mfma_f32_16x16x32_bf16 v[36:39], v[214:217], v[222:225], v[0:3]
	v_mfma_f32_16x16x32_bf16 v[0:3], v[202:205], v[226:229], v[186:189]
	v_mfma_f32_16x16x32_bf16 v[16:19], v[206:209], v[230:233], v[0:3]
	v_mfma_f32_16x16x32_bf16 v[0:3], v[210:213], v[226:229], v[190:193]
	v_mfma_f32_16x16x32_bf16 v[20:23], v[214:217], v[230:233], v[0:3]
	v_mfma_f32_16x16x32_bf16 v[0:3], v[202:205], v[234:237], v[194:197]
	v_mfma_f32_16x16x32_bf16 v[4:7], v[210:213], v[234:237], v[198:201]
	v_mfma_f32_16x16x32_bf16 v[0:3], v[206:209], v[238:241], v[0:3]
	v_mfma_f32_16x16x32_bf16 v[4:7], v[214:217], v[238:241], v[4:7]
	s_barrier
	s_setprio 0
	s_add_u32 s83, s72, 0x200
	s_addc_u32 s85, s73, 0
	s_add_u32 s72, s74, 0x80180
	s_addc_u32 s73, s75, 0
	s_mov_b32 s88, 0

;     __device__ __forceinline__ void operator()(const f32x4 (&acc)[2][2][4][2], const Unit& u, int wr, int wc, int fr, int fq) const {
;     ...
; #pragma unroll
;         for (int ai = 0; ai < 2; ++ai)
; #pragma unroll
;             for (int m = 0; m < 4; ++m) { bf16_t* rowp = O + (size_t)(row0 + ai * HALF + m * 16) * ldc + col0;
;                 if (ACT == 1) {
;                     const int ob = fr * 64 + 16 * fq, sw = ob ^ (((ob >> 9) & 1) << 5);
;                     rowp = O + ((size_t)(u.pm * (ldc / 64) + u.pn * 4 + (wc >> 1)) * 2 + ai) * 8192 + (((wr * 4 + m) * 2 + (wc & 1)) * 1024 + sw) / 2; }
;                 float rc[2][2], rs[2][2];
;                 if (ACT == 2) { const float pos = (float)((row0 + ai * HALF + m * 16) & 2047);
; #pragma unroll
;                     for (int n = 0; n < 2; ++n)
; #pragma unroll
;                         for (int e = 0; e < 2; ++e) { float r = pos * rinv[n][e]; r -= floorf(r); rs[n][e] = do_rope ? __builtin_amdgcn_sinf(r) : 0.f; rc[n][e] = do_rope ? __builtin_amdgcn_cosf(r) : 1.f; } }
; #pragma unroll
;                 for (int bj = 0; bj < 2; ++bj) { f32x4 v0 = acc[ai][bj][m][0], v1 = acc[ai][bj][m][1];
;                     if (ACT == 3) { const float pos = (float)((row0 + ai * HALF + m * 16) & 2047); float c3[4], s3[4];
; #pragma unroll
;                         for (int p = 0; p < 4; ++p) { float r = pos * rinv3[bj][p]; r -= floorf(r); s3[p] = rope3[bj] ? __builtin_amdgcn_sinf(r) : 0.f; c3[p] = rope3[bj] ? __builtin_amdgcn_cosf(r) : 1.f; }
;                         const f32x4 a = v0, b = v1;
;                         v0[0] = a[0] * c3[0] - a[1] * s3[0]; v0[1] = a[1] * c3[0] + a[0] * s3[0]; v0[2] = a[2] * c3[1] - a[3] * s3[1]; v0[3] = a[3] * c3[1] + a[2] * s3[1];
;                         v1[0] = b[0] * c3[2] - b[1] * s3[2]; v1[1] = b[1] * c3[2] + b[0] * s3[2]; v1[2] = b[2] * c3[3] - b[3] * s3[3]; v1[3] = b[3] * c3[3] + b[2] * s3[3]; }
;                     if (ACT == 2) { const f32x4 a = v0, b = v1;
;                         v0[0] = a[0] * rc[0][0] - a[1] * rs[0][0]; v0[1] = a[1] * rc[0][0] + a[0] * rs[0][0]; v0[2] = a[2] * rc[0][1] - a[3] * rs[0][1]; v0[3] = a[3] * rc[0][1] + a[2] * rs[0][1];
;                         v1[0] = b[0] * rc[1][0] - b[1] * rs[1][0]; v1[1] = b[1] * rc[1][0] + b[0] * rs[1][0]; v1[2] = b[2] * rc[1][1] - b[3] * rs[1][1]; v1[3] = b[3] * rc[1][1] + b[2] * rs[1][1]; }
.LBB0_2844:
	v_mov_b32_e32 v148, 0
	s_lshl_b32 s53, s53, 2
	v_mbcnt_lo_u32_b32 v148, -1, v148
	v_mbcnt_hi_u32_b32 v148, -1, v148
	v_or_b32_e32 v148, s33, v148
	s_or_b32 s53, s53, s49
	v_and_b32_e32 v149, 15, v148
	v_and_b32_e32 v150, 48, v148
	v_lshlrev_b32_e32 v148, 2, v148
	s_lshl_b32 s54, s70, 7
	v_lshl_or_b32 v149, v149, 6, v150
	v_and_b32_e32 v148, 32, v148
	s_add_i32 s54, s53, s54
	s_ashr_i32 s55, s54, 31
	v_bitop3_b32 v148, v149, s50, v148 bitop3:0xde
	s_lshl_b64 s[54:55], s[54:55], 15
	v_ashrrev_i32_e32 v148, 1, v148
	s_add_u32 s70, s41, s54
	v_ashrrev_i32_e32 v149, 31, v148
	s_addc_u32 s71, s42, s55
	v_lshlrev_b64 v[150:151], 1, v[148:149]
	v_max_i32_e32 v120, 0, v120
	v_max_i32_e32 v121, 0, v121
	v_max_i32_e32 v122, 0, v122
	v_max_i32_e32 v123, 0, v123
	v_max_i32_e32 v112, 0, v112
	v_max_i32_e32 v116, 0, v116
	v_max_i32_e32 v113, 0, v113
	v_max_i32_e32 v114, 0, v114
	v_lshl_add_u64 v[152:153], s[70:71], 0, v[150:151]
	v_max_i32_e32 v124, 0, v124
	v_mul_f32_e32 v120, v120, v120
	v_max_i32_e32 v125, 0, v125
	v_mul_f32_e32 v121, v121, v121
	v_max_i32_e32 v126, 0, v126
	v_mul_f32_e32 v122, v122, v122
	v_max_i32_e32 v127, 0, v127
	v_mul_f32_e32 v123, v123, v123
	v_mul_f32_e32 v112, v112, v112
	v_mul_f32_e32 v116, v116, v116
	v_max_i32_e32 v117, 0, v117
	v_mul_f32_e32 v113, v113, v113
	v_mul_f32_e32 v114, v114, v114
	v_max_i32_e32 v115, 0, v115
	v_mul_f32_e32 v124, v124, v124
	v_mul_f32_e32 v125, v125, v125
	v_mul_f32_e32 v126, v126, v126
	v_mul_f32_e32 v127, v127, v127
	v_cvt_pk_bf16_f32 v120, v120, v121
	v_cvt_pk_bf16_f32 v121, v122, v123
	v_cvt_pk_bf16_f32 v122, v124, v125
	v_cvt_pk_bf16_f32 v123, v126, v127
	global_store_dwordx4 v[152:153], v[120:123], off
	v_mul_f32_e32 v117, v117, v117
	v_mul_f32_e32 v115, v115, v115
	v_cvt_pk_bf16_f32 v112, v112, v113
	v_cvt_pk_bf16_f32 v113, v114, v115
	v_cvt_pk_bf16_f32 v114, v116, v117
	v_add_co_u32_e32 v116, vcc, s39, v152
	v_max_i32_e32 v104, 0, v104
	v_max_i32_e32 v105, 0, v105
	v_max_i32_e32 v106, 0, v106
	v_max_i32_e32 v107, 0, v107
	v_max_i32_e32 v96, 0, v96
	v_max_i32_e32 v118, 0, v118
	v_max_i32_e32 v119, 0, v119
	v_addc_co_u32_e32 v117, vcc, 0, v153, vcc
	v_max_i32_e32 v108, 0, v108
	v_mul_f32_e32 v104, v104, v104
	v_max_i32_e32 v109, 0, v109
	v_mul_f32_e32 v105, v105, v105
	v_max_i32_e32 v110, 0, v110
	v_mul_f32_e32 v106, v106, v106
	v_max_i32_e32 v111, 0, v111
	v_mul_f32_e32 v107, v107, v107
	v_mul_f32_e32 v96, v96, v96
	v_max_i32_e32 v97, 0, v97
	v_max_i32_e32 v98, 0, v98
	v_max_i32_e32 v99, 0, v99
	v_mul_f32_e32 v118, v118, v118
	v_mul_f32_e32 v119, v119, v119
	v_cvt_pk_bf16_f32 v115, v118, v119
	global_store_dwordx4 v[116:117], v[112:115], off
	v_mul_f32_e32 v108, v108, v108
	v_mul_f32_e32 v109, v109, v109
	v_mul_f32_e32 v110, v110, v110
	v_mul_f32_e32 v111, v111, v111
	v_cvt_pk_bf16_f32 v104, v104, v105
	v_cvt_pk_bf16_f32 v105, v106, v107
	v_cvt_pk_bf16_f32 v106, v108, v109
	v_cvt_pk_bf16_f32 v107, v110, v111
	global_store_dwordx4 v[152:153], v[104:107], off offset:2048
	v_max_i32_e32 v100, 0, v100
	v_max_i32_e32 v101, 0, v101
	v_mul_f32_e32 v97, v97, v97
	v_max_i32_e32 v102, 0, v102
	v_mul_f32_e32 v98, v98, v98
	v_max_i32_e32 v103, 0, v103
	v_mul_f32_e32 v99, v99, v99
	v_cvt_pk_bf16_f32 v96, v96, v97
	v_mul_f32_e32 v100, v100, v100
	v_mul_f32_e32 v101, v101, v101
	v_mul_f32_e32 v102, v102, v102
	v_mul_f32_e32 v103, v103, v103
	v_cvt_pk_bf16_f32 v97, v98, v99
	v_cvt_pk_bf16_f32 v98, v100, v101
	v_cvt_pk_bf16_f32 v99, v102, v103
	global_store_dwordx4 v[116:117], v[96:99], off offset:2048
	v_max_i32_e32 v88, 0, v88
	v_max_i32_e32 v89, 0, v89
	v_or_b32_e32 v96, 0x800, v148
	v_ashrrev_i32_e32 v97, 31, v96
	v_lshlrev_b64 v[96:97], 1, v[96:97]
	v_max_i32_e32 v90, 0, v90
	v_max_i32_e32 v91, 0, v91
	v_max_i32_e32 v80, 0, v80
	v_max_i32_e32 v84, 0, v84
	v_max_i32_e32 v81, 0, v81
	v_max_i32_e32 v82, 0, v82
	v_lshl_add_u64 v[98:99], s[70:71], 0, v[96:97]
	v_max_i32_e32 v92, 0, v92
	v_mul_f32_e32 v88, v88, v88
	v_max_i32_e32 v93, 0, v93
	v_mul_f32_e32 v89, v89, v89
	v_max_i32_e32 v94, 0, v94
	v_mul_f32_e32 v90, v90, v90
	v_max_i32_e32 v95, 0, v95
	v_mul_f32_e32 v91, v91, v91
	v_mul_f32_e32 v80, v80, v80
	v_mul_f32_e32 v84, v84, v84
	v_max_i32_e32 v85, 0, v85
	v_mul_f32_e32 v81, v81, v81
	v_mul_f32_e32 v82, v82, v82
	v_max_i32_e32 v83, 0, v83
	v_mul_f32_e32 v92, v92, v92
	v_mul_f32_e32 v93, v93, v93
	v_mul_f32_e32 v94, v94, v94
	v_mul_f32_e32 v95, v95, v95
	v_cvt_pk_bf16_f32 v88, v88, v89
	v_cvt_pk_bf16_f32 v89, v90, v91
	v_cvt_pk_bf16_f32 v90, v92, v93
	v_cvt_pk_bf16_f32 v91, v94, v95
	global_store_dwordx4 v[98:99], v[88:91], off
	v_mul_f32_e32 v85, v85, v85
	v_mul_f32_e32 v83, v83, v83
	v_cvt_pk_bf16_f32 v80, v80, v81
	v_cvt_pk_bf16_f32 v81, v82, v83
	v_cvt_pk_bf16_f32 v82, v84, v85
	v_add_co_u32_e32 v84, vcc, s39, v98
	v_max_i32_e32 v86, 0, v86
	v_max_i32_e32 v87, 0, v87
	v_addc_co_u32_e32 v85, vcc, 0, v99, vcc
	v_mul_f32_e32 v86, v86, v86
	v_mul_f32_e32 v87, v87, v87
	v_cvt_pk_bf16_f32 v83, v86, v87
	global_store_dwordx4 v[84:85], v[80:83], off
	v_max_i32_e32 v64, 0, v64
	v_max_i32_e32 v65, 0, v65
	v_or_b32_e32 v80, 0xc00, v148
	v_ashrrev_i32_e32 v81, 31, v80
	v_lshlrev_b64 v[80:81], 1, v[80:81]
	v_max_i32_e32 v66, 0, v66
	v_max_i32_e32 v67, 0, v67
	v_max_i32_e32 v48, 0, v48
	v_max_i32_e32 v52, 0, v52
	v_max_i32_e32 v49, 0, v49
	v_max_i32_e32 v50, 0, v50
	v_lshl_add_u64 v[82:83], s[70:71], 0, v[80:81]
	v_max_i32_e32 v68, 0, v68
	v_mul_f32_e32 v64, v64, v64
	v_max_i32_e32 v69, 0, v69
	v_mul_f32_e32 v65, v65, v65
	v_max_i32_e32 v70, 0, v70
	v_mul_f32_e32 v66, v66, v66
	v_max_i32_e32 v71, 0, v71
	v_mul_f32_e32 v67, v67, v67
	v_mul_f32_e32 v48, v48, v48
	v_mul_f32_e32 v52, v52, v52
;     __device__ __forceinline__ void operator()(const f32x4 (&acc)[2][2][4][2], const Unit& u, int wr, int wc, int fr, int fq) const {
;     ...
; #pragma unroll
;         for (int ai = 0; ai < 2; ++ai)
; #pragma unroll
;             for (int m = 0; m < 4; ++m) { bf16_t* rowp = O + (size_t)(row0 + ai * HALF + m * 16) * ldc + col0;
;                 if (ACT == 1) {
;                     const int ob = fr * 64 + 16 * fq, sw = ob ^ (((ob >> 9) & 1) << 5);
;                     rowp = O + ((size_t)(u.pm * (ldc / 64) + u.pn * 4 + (wc >> 1)) * 2 + ai) * 8192 + (((wr * 4 + m) * 2 + (wc & 1)) * 1024 + sw) / 2; }
;                 float rc[2][2], rs[2][2];
;                 if (ACT == 2) { const float pos = (float)((row0 + ai * HALF + m * 16) & 2047);
; #pragma unroll
;                     for (int n = 0; n < 2; ++n)
; #pragma unroll
;                         for (int e = 0; e < 2; ++e) { float r = pos * rinv[n][e]; r -= floorf(r); rs[n][e] = do_rope ? __builtin_amdgcn_sinf(r) : 0.f; rc[n][e] = do_rope ? __builtin_amdgcn_cosf(r) : 1.f; } }
; #pragma unroll
;                 for (int bj = 0; bj < 2; ++bj) { f32x4 v0 = acc[ai][bj][m][0], v1 = acc[ai][bj][m][1];
;                     if (ACT == 3) { const float pos = (float)((row0 + ai * HALF + m * 16) & 2047); float c3[4], s3[4];
; #pragma unroll
;                         for (int p = 0; p < 4; ++p) { float r = pos * rinv3[bj][p]; r -= floorf(r); s3[p] = rope3[bj] ? __builtin_amdgcn_sinf(r) : 0.f; c3[p] = rope3[bj] ? __builtin_amdgcn_cosf(r) : 1.f; }
;                         const f32x4 a = v0, b = v1;
;                         v0[0] = a[0] * c3[0] - a[1] * s3[0]; v0[1] = a[1] * c3[0] + a[0] * s3[0]; v0[2] = a[2] * c3[1] - a[3] * s3[1]; v0[3] = a[3] * c3[1] + a[2] * s3[1];
;                         v1[0] = b[0] * c3[2] - b[1] * s3[2]; v1[1] = b[1] * c3[2] + b[0] * s3[2]; v1[2] = b[2] * c3[3] - b[3] * s3[3]; v1[3] = b[3] * c3[3] + b[2] * s3[3]; }
;                     if (ACT == 2) { const f32x4 a = v0, b = v1;
;                         v0[0] = a[0] * rc[0][0] - a[1] * rs[0][0]; v0[1] = a[1] * rc[0][0] + a[0] * rs[0][0]; v0[2] = a[2] * rc[0][1] - a[3] * rs[0][1]; v0[3] = a[3] * rc[0][1] + a[2] * rs[0][1];
;                         v1[0] = b[0] * rc[1][0] - b[1] * rs[1][0]; v1[1] = b[1] * rc[1][0] + b[0] * rs[1][0]; v1[2] = b[2] * rc[1][1] - b[3] * rs[1][1]; v1[3] = b[3] * rc[1][1] + b[2] * rs[1][1]; }
	v_max_i32_e32 v53, 0, v53
	v_mul_f32_e32 v49, v49, v49
	v_mul_f32_e32 v50, v50, v50
	v_max_i32_e32 v51, 0, v51
	v_mul_f32_e32 v68, v68, v68
	v_mul_f32_e32 v69, v69, v69
	v_mul_f32_e32 v70, v70, v70
	v_mul_f32_e32 v71, v71, v71
	v_cvt_pk_bf16_f32 v64, v64, v65
	v_cvt_pk_bf16_f32 v65, v66, v67
	v_cvt_pk_bf16_f32 v66, v68, v69
	v_cvt_pk_bf16_f32 v67, v70, v71
	global_store_dwordx4 v[82:83], v[64:67], off
	v_mul_f32_e32 v53, v53, v53
	v_mul_f32_e32 v51, v51, v51
	v_cvt_pk_bf16_f32 v48, v48, v49
	v_cvt_pk_bf16_f32 v49, v50, v51
	v_cvt_pk_bf16_f32 v50, v52, v53
	v_add_co_u32_e32 v52, vcc, s39, v82
	v_max_i32_e32 v54, 0, v54
	v_max_i32_e32 v55, 0, v55
	v_addc_co_u32_e32 v53, vcc, 0, v83, vcc
	v_mul_f32_e32 v54, v54, v54
	v_mul_f32_e32 v55, v55, v55
	v_cvt_pk_bf16_f32 v51, v54, v55
	global_store_dwordx4 v[52:53], v[48:51], off
	s_add_u32 s70, s70, 0x4000
	s_addc_u32 s71, s71, 0
	v_max_i32_e32 v49, 0, v76
	v_max_i32_e32 v48, 0, v72
	v_mul_f32_e32 v50, v49, v49
	v_max_i32_e32 v49, 0, v73
	v_mul_f32_e32 v48, v48, v48
	v_max_i32_e32 v51, 0, v77
	v_mul_f32_e32 v49, v49, v49
	v_max_i32_e32 v54, 0, v74
	v_max_i32_e32 v64, 0, v75
	v_lshl_add_u64 v[52:53], s[70:71], 0, v[150:151]
	v_mul_f32_e32 v51, v51, v51
	v_max_i32_e32 v55, 0, v78
	v_mul_f32_e32 v54, v54, v54
	v_max_i32_e32 v65, 0, v79
	v_mul_f32_e32 v64, v64, v64
	v_cvt_pk_bf16_f32 v48, v48, v49
	v_cvt_pk_bf16_f32 v49, v54, v64
	v_mul_f32_e32 v55, v55, v55
	v_mul_f32_e32 v65, v65, v65
	v_cvt_pk_bf16_f32 v50, v50, v51
	v_cvt_pk_bf16_f32 v51, v55, v65
	global_store_dwordx4 v[52:53], v[48:51], off
	v_or_b32_e32 v112, 0x400, v148
	v_max_i32_e32 v54, 0, v58
	v_max_i32_e32 v49, 0, v60
	v_max_i32_e32 v48, 0, v56
	v_mul_f32_e32 v50, v49, v49
	v_max_i32_e32 v49, 0, v57
	v_mul_f32_e32 v48, v48, v48
	v_max_i32_e32 v51, 0, v61
	v_mul_f32_e32 v49, v49, v49
	v_max_i32_e32 v56, 0, v59
	v_add_co_u32_e32 v52, vcc, s39, v52
	v_ashrrev_i32_e32 v113, 31, v112
	v_mul_f32_e32 v51, v51, v51
	v_max_i32_e32 v55, 0, v62
	v_mul_f32_e32 v54, v54, v54
	v_max_i32_e32 v57, 0, v63
	v_mul_f32_e32 v56, v56, v56
	v_cvt_pk_bf16_f32 v48, v48, v49
	v_cvt_pk_bf16_f32 v49, v54, v56
	v_addc_co_u32_e32 v53, vcc, 0, v53, vcc
	v_max_i32_e32 v40, 0, v40
	v_max_i32_e32 v41, 0, v41
	v_max_i32_e32 v42, 0, v42
	v_max_i32_e32 v43, 0, v43
	v_max_i32_e32 v32, 0, v32
	v_max_i32_e32 v36, 0, v36
	v_max_i32_e32 v33, 0, v33
	v_max_i32_e32 v34, 0, v34
	v_mul_f32_e32 v55, v55, v55
	v_mul_f32_e32 v57, v57, v57
	v_cvt_pk_bf16_f32 v50, v50, v51
	v_cvt_pk_bf16_f32 v51, v55, v57
	global_store_dwordx4 v[52:53], v[48:51], off
	v_max_i32_e32 v44, 0, v44
	v_mul_f32_e32 v40, v40, v40
	v_lshl_add_u64 v[48:49], v[112:113], 1, s[70:71]
	v_max_i32_e32 v45, 0, v45
	v_mul_f32_e32 v41, v41, v41
	v_max_i32_e32 v46, 0, v46
	v_mul_f32_e32 v42, v42, v42
	v_max_i32_e32 v47, 0, v47
	v_mul_f32_e32 v43, v43, v43
	v_mul_f32_e32 v32, v32, v32
	v_mul_f32_e32 v36, v36, v36
	v_max_i32_e32 v37, 0, v37
	v_mul_f32_e32 v33, v33, v33
	v_mul_f32_e32 v34, v34, v34
	v_max_i32_e32 v35, 0, v35
	v_mul_f32_e32 v44, v44, v44
	v_mul_f32_e32 v45, v45, v45
	v_mul_f32_e32 v46, v46, v46
	v_mul_f32_e32 v47, v47, v47
	v_cvt_pk_bf16_f32 v40, v40, v41
	v_cvt_pk_bf16_f32 v41, v42, v43
	v_cvt_pk_bf16_f32 v42, v44, v45
	v_cvt_pk_bf16_f32 v43, v46, v47
	global_store_dwordx4 v[48:49], v[40:43], off
	v_mul_f32_e32 v37, v37, v37
	v_mul_f32_e32 v35, v35, v35
	v_cvt_pk_bf16_f32 v32, v32, v33
	v_cvt_pk_bf16_f32 v33, v34, v35
	v_cvt_pk_bf16_f32 v34, v36, v37
	v_add_co_u32_e32 v36, vcc, s39, v48
	v_max_i32_e32 v38, 0, v38
	v_max_i32_e32 v39, 0, v39
	v_addc_co_u32_e32 v37, vcc, 0, v49, vcc
	v_max_i32_e32 v24, 0, v24
	v_max_i32_e32 v25, 0, v25
	v_max_i32_e32 v26, 0, v26
	v_max_i32_e32 v27, 0, v27
	v_max_i32_e32 v16, 0, v16
	v_max_i32_e32 v20, 0, v20
	v_max_i32_e32 v17, 0, v17
	v_max_i32_e32 v18, 0, v18
	v_mul_f32_e32 v38, v38, v38
	v_mul_f32_e32 v39, v39, v39
	v_cvt_pk_bf16_f32 v35, v38, v39
	global_store_dwordx4 v[36:37], v[32:35], off
	v_max_i32_e32 v28, 0, v28
	v_mul_f32_e32 v24, v24, v24
	v_lshl_add_u64 v[32:33], s[70:71], 0, v[96:97]
	v_max_i32_e32 v29, 0, v29
	v_mul_f32_e32 v25, v25, v25
	v_max_i32_e32 v30, 0, v30
	v_mul_f32_e32 v26, v26, v26
	v_max_i32_e32 v31, 0, v31
	v_mul_f32_e32 v27, v27, v27
	v_mul_f32_e32 v16, v16, v16
	v_mul_f32_e32 v20, v20, v20
	v_max_i32_e32 v21, 0, v21
	v_mul_f32_e32 v17, v17, v17
	v_mul_f32_e32 v18, v18, v18
	v_max_i32_e32 v19, 0, v19
	v_mul_f32_e32 v28, v28, v28
	v_mul_f32_e32 v29, v29, v29
	v_mul_f32_e32 v30, v30, v30
	v_mul_f32_e32 v31, v31, v31
	v_cvt_pk_bf16_f32 v24, v24, v25
	v_cvt_pk_bf16_f32 v25, v26, v27
	v_cvt_pk_bf16_f32 v26, v28, v29
	v_cvt_pk_bf16_f32 v27, v30, v31
	global_store_dwordx4 v[32:33], v[24:27], off
	v_mul_f32_e32 v21, v21, v21
	v_mul_f32_e32 v19, v19, v19
	v_cvt_pk_bf16_f32 v16, v16, v17
	v_cvt_pk_bf16_f32 v17, v18, v19
	v_cvt_pk_bf16_f32 v18, v20, v21
	v_add_co_u32_e32 v20, vcc, s39, v32
	v_max_i32_e32 v22, 0, v22
	v_max_i32_e32 v23, 0, v23
	v_addc_co_u32_e32 v21, vcc, 0, v33, vcc
	v_max_i32_e32 v8, 0, v8
	v_max_i32_e32 v9, 0, v9
	v_max_i32_e32 v10, 0, v10
	v_max_i32_e32 v11, 0, v11
	v_max_i32_e32 v0, 0, v0
	v_max_i32_e32 v4, 0, v4
	v_max_i32_e32 v1, 0, v1
	v_max_i32_e32 v2, 0, v2
	v_mul_f32_e32 v22, v22, v22
	v_mul_f32_e32 v23, v23, v23
	v_cvt_pk_bf16_f32 v19, v22, v23
	global_store_dwordx4 v[20:21], v[16:19], off
	v_max_i32_e32 v12, 0, v12
	v_mul_f32_e32 v8, v8, v8
	v_lshl_add_u64 v[16:17], s[70:71], 0, v[80:81]
	v_max_i32_e32 v13, 0, v13
	v_mul_f32_e32 v9, v9, v9
	v_max_i32_e32 v14, 0, v14
	v_mul_f32_e32 v10, v10, v10
	v_max_i32_e32 v15, 0, v15
	v_mul_f32_e32 v11, v11, v11
	v_mul_f32_e32 v0, v0, v0
	v_mul_f32_e32 v4, v4, v4
	v_max_i32_e32 v5, 0, v5
	v_mul_f32_e32 v1, v1, v1
	v_mul_f32_e32 v2, v2, v2
	v_max_i32_e32 v3, 0, v3
	v_mul_f32_e32 v12, v12, v12
	v_mul_f32_e32 v13, v13, v13
	v_mul_f32_e32 v14, v14, v14
	v_mul_f32_e32 v15, v15, v15
	v_cvt_pk_bf16_f32 v8, v8, v9
	v_cvt_pk_bf16_f32 v9, v10, v11
	v_cvt_pk_bf16_f32 v10, v12, v13
	v_cvt_pk_bf16_f32 v11, v14, v15
	global_store_dwordx4 v[16:17], v[8:11], off
	v_mul_f32_e32 v5, v5, v5
	v_mul_f32_e32 v3, v3, v3
	v_cvt_pk_bf16_f32 v0, v0, v1
	v_cvt_pk_bf16_f32 v1, v2, v3
	v_cvt_pk_bf16_f32 v2, v4, v5
	v_add_co_u32_e32 v4, vcc, 0x10000, v16
	v_max_i32_e32 v6, 0, v6
	s_nop 0
	v_addc_co_u32_e32 v5, vcc, 0, v17, vcc
	v_max_i32_e32 v7, 0, v7
	s_andn2_b64 vcc, exec, s[2:3]
	s_mov_b64 s[2:3], -1
	v_mul_f32_e32 v6, v6, v6
	v_mul_f32_e32 v7, v7, v7
	v_cvt_pk_bf16_f32 v3, v6, v7
	global_store_dwordx4 v[4:5], v[0:3], off
	s_mov_b32 s98, 1
	s_cbranch_vccnz .LBB0_2833
	s_andn2_b64 vcc, exec, s[6:7]
	s_cbranch_vccnz .LBB0_2832
	s_barrier
	s_branch .LBB0_2832

; #define PG8_STAGE(bufoff, gbase, voff) do { _Pragma("unroll") for (int _i = 0; _i < 2; ++_i) \
;         __builtin_amdgcn_global_load_lds((const unsigned*)((const char*)(gbase) + (voff)[_i]), (PG8_LAS unsigned*)(lds + (bufoff) + ldsw + _i * 8192), 16, 0, 0); } while (0)
; #define PG8_WAIT_V(n) asm volatile("s_waitcnt vmcnt(" #n ")" ::: "memory")
; #define PG8_BAR __builtin_amdgcn_s_barrier()
; template <class Epi, class Sched, bool ALIGN_EPI = false, bool SP2 = false, bool A_TILED = false>
; __device__ __forceinline__ void gemm_phase(PG8_LAS unsigned char* lds, const Gemm g, const Sched& S, const Epi& E, const int wave_s) {
;     ...
;     const int aoff = lds_byte(wr * 64 + fr, fq * 8), boff = lds_byte(wc * 32 + fr, fq * 8);
;     ...
;     Unit cur, nxt; int ui = 0;
;     if (!S.next(0, cur)) return;
;     f32x4 acc[2][2][4][2];
;     bf16x8 At[4][2], B0[2][2], B1[2][2];
;     const char* cA = (const char*)g.A + (size_t)cur.pm * tstepA; const char* cB = (const char*)g.Bt + (size_t)cur.pn * tstep;
;     S.a_ready(cur);
;     if constexpr (SP2) {
;         PG8_STAGE(PG8_SB(0, 0), cB, voffB); PG8_STAGE(PG8_SB(0, 1), cB + hstep, voffB); PG8_STAGE(PG8_SA(0, 0), cA, voffA); PG8_STAGE(PG8_SA(0, 1), cA + hstepA, voffA);
;         if (wr == 1) PG8_BAR;
;         PG8_WAIT_V(2); PG8_BAR;
;         PG8_STAGE(PG8_SB(1, 0), cB + kstep, voffB); PG8_STAGE(PG8_SA(1, 0), cA + kstepA, voffA); PG8_STAGE(PG8_SB(1, 1), cB + hstep + kstep, voffB);
;         PG8_WAIT_V(6); PG8_BAR;
.LBB0_3336:
	s_ashr_i32 s56, s86, 31
	s_add_u32 s0, s0, s29
	s_addc_u32 s1, s1, 0
	s_add_u32 s6, s0, 0x22600000
	s_addc_u32 s7, s1, 0
	s_lshl_b32 s57, s13, 6
	s_lshl_b32 s16, s13, 13
	s_lshl_b32 s0, s12, 5
	s_mov_b64 s[12:13], 0x80
	s_and_b32 s58, s0, 0x60
	s_add_i32 m0, s41, 0x18000
	v_lshl_add_u64 v[6:7], v[6:7], 0, s[12:13]
	s_lshl_b32 s17, s58, 7
	s_waitcnt vmcnt(2)
	s_barrier
	global_load_lds_dwordx4 v[6:7], off
	v_lshl_add_u64 v[4:5], v[4:5], 0, s[12:13]
	s_add_i32 m0, s41, 0x1a000
	s_add_i32 s59, s41, 0x8000
	s_add_i32 s60, s41, 0xa000
	global_load_lds_dwordx4 v[4:5], off
	v_lshl_add_u64 v[0:1], v[0:1], 0, s[12:13]
	s_mov_b32 m0, s59
	s_add_u32 s0, s42, 0x80080
	global_load_lds_dwordx4 v[0:1], off
	v_lshl_add_u64 v[0:1], v[2:3], 0, s[12:13]
	s_mov_b32 m0, s60
	s_addc_u32 s1, s43, 0
	global_load_lds_dwordx4 v[0:1], off
	s_add_i32 m0, s41, 0x1c000
	v_lshl_add_u64 v[0:1], s[0:1], 0, v[128:129]
	global_load_lds_dwordx4 v128, s[0:1]
	v_lshl_add_u64 v[0:1], s[0:1], 0, v[130:131]
	s_add_i32 m0, s41, 0x1e000
	s_movk_i32 s0, 0x3c0
	global_load_lds_dwordx4 v[0:1], off
	v_and_b32_e32 v0, 48, v8
	v_lshlrev_b32_e32 v1, 6, v8
	v_and_or_b32 v0, v1, s0, v0
	v_lshlrev_b32_e32 v1, 2, v8
	v_and_b32_e32 v1, 32, v1
	v_bitop3_b32 v2, v0, s16, v1 bitop3:0xde
	v_bitop3_b32 v148, s17, v0, v1 bitop3:0xf6
	v_lshlrev_b32_e32 v0, 15, v9
	v_and_b32_e32 v0, 0xffff0000, v0
	v_lshl_add_u32 v0, v10, 12, v0
	v_and_b32_e32 v1, 1, v9
	v_lshl_or_b32 v0, v1, 6, v0
	v_lshl_add_u32 v136, v11, 1, v0
	v_lshlrev_b32_e32 v0, 15, v13
	v_and_b32_e32 v0, 0xffff0000, v0
	s_waitcnt vmcnt(6)
	s_mov_b32 s98, 0
	s_cmpk_lt_u32 s15, 0x100
	v_lshl_add_u32 v0, v12, 12, v0
	v_and_b32_e32 v1, 1, v13
	s_sext_i32_i16 s66, s14
	s_cselect_b64 s[14:15], -1, 0
	v_mov_b32_e32 v137, 0
	v_lshl_or_b32 v0, v1, 6, v0
	s_add_i32 s61, 0, 0x10000
	s_add_i32 s62, 0, 0x14000
	v_lshl_add_u32 v138, v14, 1, v0
	v_mov_b32_e32 v139, v137
	s_mov_b64 s[16:17], 0x180
	v_add_u32_e32 v149, s61, v148
	v_add_u32_e32 v150, s62, v148
	v_add_u32_e32 v151, 0, v2
	s_mov_b64 s[20:21], 0x100
	s_movk_i32 s63, 0x3000
	s_add_i32 s64, s41, 0xc000
	s_add_i32 s65, s41, 0xe000
	s_barrier
	s_branch .LBB0_3339

.LBB0_3341:
	s_ashr_i32 s25, s24, 31
	ds_read_b128 v[0:3], v149
	ds_read_b128 v[4:7], v149 offset:1024
	ds_read_b128 v[8:11], v149 offset:2048
	ds_read_b128 v[12:15], v149 offset:3072
	ds_read_b128 v[16:19], v150
	ds_read_b128 v[20:23], v150 offset:1024
	ds_read_b128 v[24:27], v150 offset:2048
	ds_read_b128 v[28:31], v150 offset:3072
	s_lshl_b64 s[26:27], s[24:25], 20
	s_add_u32 s26, s9, s26
	s_addc_u32 s27, s36, s27
	s_and_b64 s[38:39], s[0:1], exec
	s_cselect_b32 s25, s27, s45
	s_cselect_b32 s67, s26, s44
	s_ashr_i32 s23, s22, 31
	s_lshl_b64 s[38:39], s[22:23], 20
	s_add_u32 s38, s37, s38
	s_addc_u32 s39, s48, s39
	s_and_b64 s[46:47], s[0:1], exec
	s_cselect_b32 s23, s39, s43
	s_cselect_b32 s68, s38, s42
	s_add_u32 s46, s44, 0x80080
	s_addc_u32 s47, s45, 0
	s_mov_b32 m0, s64
	v_lshl_add_u64 v[64:65], s[46:47], 0, v[134:135]
	ds_read_b128 v[32:35], v151
	ds_read_b128 v[36:39], v151 offset:1024
	ds_read_b128 v[40:43], v151 offset:2048
	ds_read_b128 v[44:47], v151 offset:3072
	ds_read_b128 v[48:51], v151 offset:4096
	ds_read_b128 v[52:55], v151 offset:5120
	ds_read_b128 v[56:59], v151 offset:6144
	ds_read_b128 v[60:63], v151 offset:7168
	global_load_lds_dwordx4 v134, s[46:47]
	v_lshl_add_u64 v[64:65], s[46:47], 0, v[132:133]
	s_mov_b32 m0, s65
	s_nop 0
	global_load_lds_dwordx4 v132, s[46:47]
	s_waitcnt vmcnt(24) lgkmcnt(0)
	s_cmp_lg_u32 s98, 0
	s_cbranch_scc1 .Lpw_17
	s_waitcnt vmcnt(8)
.Lpw_17:
	s_setprio 1
	s_barrier
	v_mfma_f32_16x16x32_bf16 v[88:91], v[0:3], v[56:59], 0
	v_mfma_f32_16x16x32_bf16 v[64:67], v[0:3], v[32:35], 0
	v_mfma_f32_16x16x32_bf16 v[68:71], v[8:11], v[32:35], 0
	v_mfma_f32_16x16x32_bf16 v[72:75], v[0:3], v[40:43], 0
	v_mfma_f32_16x16x32_bf16 v[76:79], v[8:11], v[40:43], 0
	v_mfma_f32_16x16x32_bf16 v[80:83], v[0:3], v[48:51], 0
	v_mfma_f32_16x16x32_bf16 v[84:87], v[8:11], v[48:51], 0
	v_mfma_f32_16x16x32_bf16 v[92:95], v[4:7], v[60:63], v[88:91]
	v_mfma_f32_16x16x32_bf16 v[88:91], v[8:11], v[56:59], 0
	v_mfma_f32_16x16x32_bf16 v[64:67], v[4:7], v[36:39], v[64:67]
	v_mfma_f32_16x16x32_bf16 v[68:71], v[12:15], v[36:39], v[68:71]
	v_mfma_f32_16x16x32_bf16 v[72:75], v[4:7], v[44:47], v[72:75]
	v_mfma_f32_16x16x32_bf16 v[76:79], v[12:15], v[44:47], v[76:79]
	v_mfma_f32_16x16x32_bf16 v[80:83], v[4:7], v[52:55], v[80:83]
	v_mfma_f32_16x16x32_bf16 v[84:87], v[12:15], v[52:55], v[84:87]
	v_mfma_f32_16x16x32_bf16 v[100:103], v[12:15], v[60:63], v[88:91]
	s_setprio 0
	s_setprio 1
	v_mfma_f32_16x16x32_bf16 v[88:91], v[16:19], v[32:35], 0
	v_mfma_f32_16x16x32_bf16 v[32:35], v[24:27], v[32:35], 0
	v_mfma_f32_16x16x32_bf16 v[108:111], v[20:23], v[36:39], v[88:91]
	v_mfma_f32_16x16x32_bf16 v[32:35], v[28:31], v[36:39], v[32:35]
	v_mfma_f32_16x16x32_bf16 v[36:39], v[16:19], v[40:43], 0
	v_mfma_f32_16x16x32_bf16 v[40:43], v[24:27], v[40:43], 0
	v_mfma_f32_16x16x32_bf16 v[36:39], v[20:23], v[44:47], v[36:39]
	v_mfma_f32_16x16x32_bf16 v[40:43], v[28:31], v[44:47], v[40:43]
	v_mfma_f32_16x16x32_bf16 v[44:47], v[16:19], v[48:51], 0
	v_mfma_f32_16x16x32_bf16 v[48:51], v[24:27], v[48:51], 0
	v_mfma_f32_16x16x32_bf16 v[44:47], v[20:23], v[52:55], v[44:47]
	v_mfma_f32_16x16x32_bf16 v[52:55], v[28:31], v[52:55], v[48:51]
	v_mfma_f32_16x16x32_bf16 v[48:51], v[16:19], v[56:59], 0
	v_mfma_f32_16x16x32_bf16 v[152:155], v[20:23], v[60:63], v[48:51]
	v_mfma_f32_16x16x32_bf16 v[48:51], v[24:27], v[56:59], 0
	v_mfma_f32_16x16x32_bf16 v[156:159], v[28:31], v[60:63], v[48:51]
	s_barrier
	s_setprio 0
	s_add_i32 s69, s61, s49
	v_lshl_add_u64 v[146:147], s[42:43], 0, v[128:129]
	s_add_i32 s70, s69, 0x2000
	v_lshl_add_u64 v[120:121], v[146:147], 0, s[20:21]
	s_mov_b32 m0, s69
	v_lshl_add_u64 v[252:253], s[42:43], 0, v[130:131]
	s_add_u32 s46, s42, 0x80100
	ds_read_b128 v[48:51], v151 offset:16384
	ds_read_b128 v[56:59], v151 offset:17408
	ds_read_b128 v[60:63], v151 offset:18432
	ds_read_b128 v[88:91], v151 offset:19456
	ds_read_b128 v[96:99], v151 offset:20480
	ds_read_b128 v[104:107], v151 offset:21504
	ds_read_b128 v[112:115], v151 offset:22528
	ds_read_b128 v[116:119], v151 offset:23552
	global_load_lds_dwordx4 v[120:121], off
	v_lshl_add_u64 v[120:121], v[252:253], 0, s[20:21]
	s_mov_b32 m0, s70
	s_addc_u32 s47, s43, 0
	s_add_i32 s71, s62, s49
	global_load_lds_dwordx4 v[120:121], off
	v_lshl_add_u64 v[120:121], s[46:47], 0, v[128:129]
	s_mov_b32 m0, s71
	s_add_i32 s72, s71, 0x2000
	global_load_lds_dwordx4 v128, s[46:47]
	v_lshl_add_u64 v[120:121], s[46:47], 0, v[130:131]
	s_mov_b32 m0, s72
	v_lshl_add_u64 v[140:141], s[44:45], 0, v[134:135]
	global_load_lds_dwordx4 v130, s[46:47]
	v_lshl_add_u64 v[120:121], v[140:141], 0, s[20:21]
	s_mov_b32 m0, s41
	v_lshl_add_u64 v[142:143], s[44:45], 0, v[132:133]
	global_load_lds_dwordx4 v[120:121], off
	v_lshl_add_u64 v[120:121], v[142:143], 0, s[20:21]
	s_mov_b32 m0, s52
	s_nop 0
	global_load_lds_dwordx4 v[120:121], off
	s_waitcnt vmcnt(24) lgkmcnt(0)
	s_cmp_lg_u32 s98, 0
	s_cbranch_scc1 .Lpw_18
	s_waitcnt vmcnt(8)
.Lpw_18:
	s_setprio 1
	s_barrier
	v_mfma_f32_16x16x32_bf16 v[120:123], v[0:3], v[48:51], 0
	v_mfma_f32_16x16x32_bf16 v[160:163], v[4:7], v[56:59], v[120:123]
	v_mfma_f32_16x16x32_bf16 v[120:123], v[8:11], v[48:51], 0
	v_mfma_f32_16x16x32_bf16 v[164:167], v[12:15], v[56:59], v[120:123]
	v_mfma_f32_16x16x32_bf16 v[120:123], v[0:3], v[60:63], 0
	v_mfma_f32_16x16x32_bf16 v[168:171], v[4:7], v[88:91], v[120:123]
	v_mfma_f32_16x16x32_bf16 v[120:123], v[8:11], v[60:63], 0
	v_mfma_f32_16x16x32_bf16 v[172:175], v[12:15], v[88:91], v[120:123]
	v_mfma_f32_16x16x32_bf16 v[120:123], v[0:3], v[96:99], 0
	v_mfma_f32_16x16x32_bf16 v[0:3], v[0:3], v[112:115], 0
	v_mfma_f32_16x16x32_bf16 v[176:179], v[4:7], v[104:107], v[120:123]
	v_mfma_f32_16x16x32_bf16 v[0:3], v[4:7], v[116:119], v[0:3]
	v_mfma_f32_16x16x32_bf16 v[4:7], v[8:11], v[112:115], 0
	v_mfma_f32_16x16x32_bf16 v[120:123], v[8:11], v[96:99], 0
	v_mfma_f32_16x16x32_bf16 v[4:7], v[12:15], v[116:119], v[4:7]
	v_mfma_f32_16x16x32_bf16 v[180:183], v[12:15], v[104:107], v[120:123]
	s_setprio 0
	s_setprio 1
	v_mfma_f32_16x16x32_bf16 v[8:11], v[16:19], v[48:51], 0
	v_mfma_f32_16x16x32_bf16 v[12:15], v[20:23], v[56:59], v[8:11]
	v_mfma_f32_16x16x32_bf16 v[8:11], v[24:27], v[48:51], 0
	v_mfma_f32_16x16x32_bf16 v[184:187], v[28:31], v[56:59], v[8:11]
	v_mfma_f32_16x16x32_bf16 v[8:11], v[16:19], v[60:63], 0
	v_mfma_f32_16x16x32_bf16 v[188:191], v[20:23], v[88:91], v[8:11]
	v_mfma_f32_16x16x32_bf16 v[8:11], v[24:27], v[60:63], 0
	v_mfma_f32_16x16x32_bf16 v[192:195], v[28:31], v[88:91], v[8:11]
	v_mfma_f32_16x16x32_bf16 v[8:11], v[16:19], v[96:99], 0
	v_mfma_f32_16x16x32_bf16 v[196:199], v[20:23], v[104:107], v[8:11]
	v_mfma_f32_16x16x32_bf16 v[8:11], v[24:27], v[96:99], 0
	v_mfma_f32_16x16x32_bf16 v[200:203], v[28:31], v[104:107], v[8:11]
	v_mfma_f32_16x16x32_bf16 v[8:11], v[16:19], v[112:115], 0
	v_mfma_f32_16x16x32_bf16 v[204:207], v[20:23], v[116:119], v[8:11]
	v_mfma_f32_16x16x32_bf16 v[8:11], v[24:27], v[112:115], 0
	v_mfma_f32_16x16x32_bf16 v[208:211], v[28:31], v[116:119], v[8:11]
	s_barrier
	s_setprio 0
	s_add_i32 s73, 0, 0x18000
	s_add_i32 s75, 0, 0x1c000
	v_add_u32_e32 v144, s73, v148
	v_add_u32_e32 v145, s75, v148
	s_nop 0
	ds_read_b128 v[8:11], v144
	ds_read_b128 v[20:23], v144 offset:1024
	ds_read_b128 v[28:31], v144 offset:2048
	ds_read_b128 v[212:215], v144 offset:3072
	ds_read_b128 v[216:219], v145
	ds_read_b128 v[220:223], v145 offset:1024
	ds_read_b128 v[224:227], v145 offset:2048
	ds_read_b128 v[228:231], v145 offset:3072
	s_add_u32 s46, s44, 0x80100
	s_addc_u32 s47, s45, 0
	s_mov_b32 m0, s53
	v_lshl_add_u64 v[48:49], s[46:47], 0, v[134:135]
	ds_read_b128 v[16:19], v151 offset:32768
	ds_read_b128 v[24:27], v151 offset:33792
	ds_read_b128 v[60:63], v151 offset:34816
	ds_read_b128 v[232:235], v151 offset:35840
	ds_read_b128 v[236:239], v151 offset:36864
	ds_read_b128 v[240:243], v151 offset:37888
	ds_read_b128 v[244:247], v151 offset:38912
	ds_read_b128 v[248:251], v151 offset:39936
	global_load_lds_dwordx4 v134, s[46:47]
	v_lshl_add_u64 v[48:49], s[46:47], 0, v[132:133]
	s_mov_b32 m0, s54
	s_nop 0
	global_load_lds_dwordx4 v132, s[46:47]
	s_waitcnt vmcnt(8) lgkmcnt(0)
	s_setprio 1
	s_barrier
	v_mfma_f32_16x16x32_bf16 v[48:51], v[8:11], v[16:19], v[64:67]
	v_mfma_f32_16x16x32_bf16 v[120:123], v[20:23], v[24:27], v[48:51]
	v_mfma_f32_16x16x32_bf16 v[48:51], v[28:31], v[16:19], v[68:71]
	v_mfma_f32_16x16x32_bf16 v[112:115], v[212:215], v[24:27], v[48:51]
	v_mfma_f32_16x16x32_bf16 v[48:51], v[8:11], v[60:63], v[72:75]
	v_mfma_f32_16x16x32_bf16 v[104:107], v[20:23], v[232:235], v[48:51]
	v_mfma_f32_16x16x32_bf16 v[48:51], v[28:31], v[60:63], v[76:79]
	v_mfma_f32_16x16x32_bf16 v[96:99], v[212:215], v[232:235], v[48:51]
	v_mfma_f32_16x16x32_bf16 v[48:51], v[8:11], v[236:239], v[80:83]
	v_mfma_f32_16x16x32_bf16 v[88:91], v[20:23], v[240:243], v[48:51]
	v_mfma_f32_16x16x32_bf16 v[48:51], v[28:31], v[236:239], v[84:87]
	v_mfma_f32_16x16x32_bf16 v[80:83], v[212:215], v[240:243], v[48:51]
	v_mfma_f32_16x16x32_bf16 v[48:51], v[8:11], v[244:247], v[92:95]
	v_mfma_f32_16x16x32_bf16 v[56:59], v[20:23], v[248:251], v[48:51]
	v_mfma_f32_16x16x32_bf16 v[48:51], v[28:31], v[244:247], v[100:103]
	v_mfma_f32_16x16x32_bf16 v[48:51], v[212:215], v[248:251], v[48:51]
	s_setprio 0
	s_setprio 1
	v_mfma_f32_16x16x32_bf16 v[64:67], v[216:219], v[16:19], v[108:111]
	v_mfma_f32_16x16x32_bf16 v[16:19], v[224:227], v[16:19], v[32:35]
	v_mfma_f32_16x16x32_bf16 v[116:119], v[228:231], v[24:27], v[16:19]
	v_mfma_f32_16x16x32_bf16 v[16:19], v[216:219], v[60:63], v[36:39]
	v_mfma_f32_16x16x32_bf16 v[108:111], v[220:223], v[232:235], v[16:19]
	v_mfma_f32_16x16x32_bf16 v[16:19], v[224:227], v[60:63], v[40:43]
	v_mfma_f32_16x16x32_bf16 v[100:103], v[228:231], v[232:235], v[16:19]
	v_mfma_f32_16x16x32_bf16 v[16:19], v[216:219], v[236:239], v[44:47]
	v_mfma_f32_16x16x32_bf16 v[92:95], v[220:223], v[240:243], v[16:19]
	v_mfma_f32_16x16x32_bf16 v[16:19], v[224:227], v[236:239], v[52:55]
	v_mfma_f32_16x16x32_bf16 v[84:87], v[228:231], v[240:243], v[16:19]
	v_mfma_f32_16x16x32_bf16 v[16:19], v[216:219], v[244:247], v[152:155]
	v_mfma_f32_16x16x32_bf16 v[60:63], v[220:223], v[248:251], v[16:19]
	v_mfma_f32_16x16x32_bf16 v[16:19], v[224:227], v[244:247], v[156:159]
	v_mfma_f32_16x16x32_bf16 v[124:127], v[220:223], v[24:27], v[64:67]
	v_mfma_f32_16x16x32_bf16 v[52:55], v[228:231], v[248:251], v[16:19]
	s_barrier
	s_setprio 0
	s_add_i32 s73, s73, s49
	s_add_i32 s74, s73, 0x2000
	s_nop 1
	v_lshl_add_u64 v[16:17], v[146:147], 0, s[16:17]
	s_mov_b32 m0, s73
	s_add_u32 s46, s42, 0x80180
	ds_read_b128 v[36:39], v151 offset:49152
	ds_read_b128 v[44:47], v151 offset:50176
	ds_read_b128 v[152:155], v151 offset:51200
	ds_read_b128 v[156:159], v151 offset:52224
	ds_read_b128 v[232:235], v151 offset:53248
	ds_read_b128 v[236:239], v151 offset:54272
	ds_read_b128 v[240:243], v151 offset:55296
	ds_read_b128 v[244:247], v151 offset:56320
	global_load_lds_dwordx4 v[16:17], off
	v_lshl_add_u64 v[16:17], v[252:253], 0, s[16:17]
	s_mov_b32 m0, s74
	s_addc_u32 s47, s43, 0
	s_add_i32 s75, s75, s49
	global_load_lds_dwordx4 v[16:17], off
	v_lshl_add_u64 v[16:17], s[46:47], 0, v[128:129]
	s_mov_b32 m0, s75
	s_add_i32 s76, s75, 0x2000
	global_load_lds_dwordx4 v128, s[46:47]
	v_lshl_add_u64 v[16:17], s[46:47], 0, v[130:131]
	s_mov_b32 m0, s76
	s_nop 0
	global_load_lds_dwordx4 v130, s[46:47]
	v_lshl_add_u64 v[16:17], v[140:141], 0, s[16:17]
	s_mov_b32 m0, s59
	s_nop 0
	global_load_lds_dwordx4 v[16:17], off
	v_lshl_add_u64 v[16:17], v[142:143], 0, s[16:17]
	s_mov_b32 m0, s60
	s_nop 0
	global_load_lds_dwordx4 v[16:17], off
	s_waitcnt vmcnt(8) lgkmcnt(0)
	s_setprio 1
	s_barrier
	v_mfma_f32_16x16x32_bf16 v[16:19], v[8:11], v[36:39], v[160:163]
	v_mfma_f32_16x16x32_bf16 v[72:75], v[20:23], v[44:47], v[16:19]
	v_mfma_f32_16x16x32_bf16 v[16:19], v[28:31], v[36:39], v[164:167]
	v_mfma_f32_16x16x32_bf16 v[64:67], v[212:215], v[44:47], v[16:19]
	v_mfma_f32_16x16x32_bf16 v[16:19], v[8:11], v[152:155], v[168:171]
	v_mfma_f32_16x16x32_bf16 v[40:43], v[20:23], v[156:159], v[16:19]
	v_mfma_f32_16x16x32_bf16 v[16:19], v[28:31], v[152:155], v[172:175]
	v_mfma_f32_16x16x32_bf16 v[32:35], v[212:215], v[156:159], v[16:19]
	v_mfma_f32_16x16x32_bf16 v[16:19], v[8:11], v[232:235], v[176:179]
	v_mfma_f32_16x16x32_bf16 v[0:3], v[8:11], v[240:243], v[0:3]
	v_mfma_f32_16x16x32_bf16 v[24:27], v[20:23], v[236:239], v[16:19]
	v_mfma_f32_16x16x32_bf16 v[16:19], v[28:31], v[232:235], v[180:183]
	v_mfma_f32_16x16x32_bf16 v[8:11], v[20:23], v[244:247], v[0:3]
	v_mfma_f32_16x16x32_bf16 v[0:3], v[28:31], v[240:243], v[4:7]
	v_mfma_f32_16x16x32_bf16 v[16:19], v[212:215], v[236:239], v[16:19]
	v_mfma_f32_16x16x32_bf16 v[0:3], v[212:215], v[244:247], v[0:3]
	s_setprio 0
	s_setprio 1
	v_mfma_f32_16x16x32_bf16 v[4:7], v[216:219], v[36:39], v[12:15]
	v_mfma_f32_16x16x32_bf16 v[76:79], v[220:223], v[44:47], v[4:7]
	v_mfma_f32_16x16x32_bf16 v[4:7], v[224:227], v[36:39], v[184:187]
	v_mfma_f32_16x16x32_bf16 v[68:71], v[228:231], v[44:47], v[4:7]
	v_mfma_f32_16x16x32_bf16 v[4:7], v[216:219], v[152:155], v[188:191]
	v_mfma_f32_16x16x32_bf16 v[44:47], v[220:223], v[156:159], v[4:7]
	v_mfma_f32_16x16x32_bf16 v[4:7], v[224:227], v[152:155], v[192:195]
	v_mfma_f32_16x16x32_bf16 v[36:39], v[228:231], v[156:159], v[4:7]
	v_mfma_f32_16x16x32_bf16 v[4:7], v[216:219], v[232:235], v[196:199]
	v_mfma_f32_16x16x32_bf16 v[28:31], v[220:223], v[236:239], v[4:7]
	v_mfma_f32_16x16x32_bf16 v[4:7], v[224:227], v[232:235], v[200:203]
	v_mfma_f32_16x16x32_bf16 v[20:23], v[228:231], v[236:239], v[4:7]
	v_mfma_f32_16x16x32_bf16 v[4:7], v[216:219], v[240:243], v[204:207]
	v_mfma_f32_16x16x32_bf16 v[12:15], v[220:223], v[244:247], v[4:7]
	v_mfma_f32_16x16x32_bf16 v[4:7], v[224:227], v[240:243], v[208:211]
	v_mfma_f32_16x16x32_bf16 v[4:7], v[228:231], v[244:247], v[4:7]
	s_barrier
	s_setprio 0
	s_add_u32 s77, s42, 0x200
	s_addc_u32 s78, s43, 0
	s_add_u32 s42, s44, 0x80180
	s_addc_u32 s43, s45, 0
	s_mov_b32 s79, 0

;     __device__ __forceinline__ void operator()(const f32x4 (&acc)[2][2][4][2], const Unit& u, int wr, int wc, int fr, int fq) const {
;         const int row0 = u.pm * BM + wr * 64 + fr; const int col0 = u.pn * BM + wc * 32 + 8 * fq;
;         const bool do_rope = (ACT == 2) && (((u.pn * BM) % 6144) < 4096);
;         float rinv[2][2];
;         if (ACT == 2) {
; #pragma unroll
;             for (int n = 0; n < 2; ++n)
; #pragma unroll
;                 for (int e = 0; e < 2; ++e) rinv[n][e] = exp2f(-(float)(16 * wc + 4 * fq + 2 * n + e) * (13.287712379549449f / 64.0f)) * 0.15915494309189535f;
;         }
;         float rinv3[2][4]; bool rope3[2];
;         if (ACT == 3) {
; #pragma unroll
;             for (int bj = 0; bj < 2; ++bj) { const int jj = (col0 + bj * HALF) % 192; rope3[bj] = jj >= 128; const int i0 = (jj - 128) >> 1;
; #pragma unroll
;                 for (int p = 0; p < 4; ++p) rinv3[bj][p] = exp2f(-(float)(i0 + p) * (13.287712379549449f / 32.0f)) * 0.15915494309189535f; }
;         }
; #pragma unroll
;         for (int ai = 0; ai < 2; ++ai)
; #pragma unroll
;             for (int m = 0; m < 4; ++m) { bf16_t* rowp = O + (size_t)(row0 + ai * HALF + m * 16) * ldc + col0;
;                 if (ACT == 1) {
;                     const int ob = fr * 64 + 16 * fq, sw = ob ^ (((ob >> 9) & 1) << 5);
;                     rowp = O + ((size_t)(u.pm * (ldc / 64) + u.pn * 4 + (wc >> 1)) * 2 + ai) * 8192 + (((wr * 4 + m) * 2 + (wc & 1)) * 1024 + sw) / 2; }
;                 float rc[2][2], rs[2][2];
;                 if (ACT == 2) { const float pos = (float)((row0 + ai * HALF + m * 16) & 2047);
; #pragma unroll
;                     for (int n = 0; n < 2; ++n)
; #pragma unroll
;                         for (int e = 0; e < 2; ++e) { float r = pos * rinv[n][e]; r -= floorf(r); rs[n][e] = do_rope ? __builtin_amdgcn_sinf(r) : 0.f; rc[n][e] = do_rope ? __builtin_amdgcn_cosf(r) : 1.f; } }
; #pragma unroll
;                 for (int bj = 0; bj < 2; ++bj) { f32x4 v0 = acc[ai][bj][m][0], v1 = acc[ai][bj][m][1];
;                     if (ACT == 3) { const float pos = (float)((row0 + ai * HALF + m * 16) & 2047); float c3[4], s3[4];
; #pragma unroll
;                         for (int p = 0; p < 4; ++p) { float r = pos * rinv3[bj][p]; r -= floorf(r); s3[p] = rope3[bj] ? __builtin_amdgcn_sinf(r) : 0.f; c3[p] = rope3[bj] ? __builtin_amdgcn_cosf(r) : 1.f; }
.LBB0_3345:
	v_mov_b32_e32 v140, 0
	s_lshl_b32 s23, s40, 8
	v_mbcnt_lo_u32_b32 v140, -1, v140
	v_mbcnt_hi_u32_b32 v140, -1, v140
	v_or_b32_e32 v140, s33, v140
	s_add_i32 s23, s23, s57
	v_and_or_b32 v152, v140, 15, s23
	s_lshl_b32 s23, s66, 8
	v_lshrrev_b32_e32 v140, 1, v140
	v_and_or_b32 v140, v140, 24, s23
	v_or_b32_e32 v140, s58, v140
	v_ashrrev_i32_e32 v141, 31, v140
	v_mov_b64_e32 v[144:145], s[6:7]
	v_mad_i64_i32 v[142:143], s[42:43], v152, s63, v[144:145]
	v_lshlrev_b64 v[146:147], 1, v[140:141]
	v_lshl_add_u64 v[140:141], v[142:143], 0, v[146:147]
	v_cvt_pk_bf16_f32 v120, v120, v121
	v_cvt_pk_bf16_f32 v121, v122, v123
	v_cvt_pk_bf16_f32 v122, v112, v113
	v_cvt_pk_bf16_f32 v123, v114, v115
	global_store_dwordx4 v[140:141], v[120:123], off
	v_cvt_pk_bf16_f32 v112, v124, v125
	v_cvt_pk_bf16_f32 v113, v126, v127
	v_cvt_pk_bf16_f32 v114, v116, v117
	v_cvt_pk_bf16_f32 v115, v118, v119
	global_store_dwordx4 v[140:141], v[112:115], off offset:256
	v_cvt_pk_bf16_f32 v104, v104, v105
	v_cvt_pk_bf16_f32 v105, v106, v107
	v_cvt_pk_bf16_f32 v106, v96, v97
	v_cvt_pk_bf16_f32 v107, v98, v99
	s_andn2_b64 vcc, exec, s[0:1]
	s_nop 0
	v_or_b32_e32 v112, 16, v152
	v_mad_i64_i32 v[112:113], s[42:43], v112, s63, v[144:145]
	v_lshl_add_u64 v[112:113], v[112:113], 0, v[146:147]
	global_store_dwordx4 v[112:113], v[104:107], off
	v_cvt_pk_bf16_f32 v96, v108, v109
	v_cvt_pk_bf16_f32 v97, v110, v111
	v_cvt_pk_bf16_f32 v98, v100, v101
	v_cvt_pk_bf16_f32 v99, v102, v103
	global_store_dwordx4 v[112:113], v[96:99], off offset:256
	v_cvt_pk_bf16_f32 v88, v88, v89
	v_cvt_pk_bf16_f32 v89, v90, v91
	v_cvt_pk_bf16_f32 v90, v80, v81
	v_cvt_pk_bf16_f32 v91, v82, v83
	s_mov_b64 s[0:1], -1
	s_nop 0
	v_or_b32_e32 v96, 32, v152
	v_mad_i64_i32 v[96:97], s[42:43], v96, s63, v[144:145]
	v_lshl_add_u64 v[96:97], v[96:97], 0, v[146:147]
	global_store_dwordx4 v[96:97], v[88:91], off
	v_cvt_pk_bf16_f32 v80, v92, v93
	v_cvt_pk_bf16_f32 v81, v94, v95
	v_cvt_pk_bf16_f32 v82, v84, v85
	v_cvt_pk_bf16_f32 v83, v86, v87
	global_store_dwordx4 v[96:97], v[80:83], off offset:256
	v_cvt_pk_bf16_f32 v56, v56, v57
	v_cvt_pk_bf16_f32 v57, v58, v59
	v_cvt_pk_bf16_f32 v58, v48, v49
	v_cvt_pk_bf16_f32 v59, v50, v51
	s_nop 1
	v_or_b32_e32 v80, 48, v152
	v_mad_i64_i32 v[80:81], s[42:43], v80, s63, v[144:145]
	v_lshl_add_u64 v[80:81], v[80:81], 0, v[146:147]
	global_store_dwordx4 v[80:81], v[56:59], off
	v_cvt_pk_bf16_f32 v48, v60, v61
	v_cvt_pk_bf16_f32 v49, v62, v63
	v_cvt_pk_bf16_f32 v50, v52, v53
	v_cvt_pk_bf16_f32 v51, v54, v55
	global_store_dwordx4 v[80:81], v[48:51], off offset:256
	s_nop 1
	v_add_u32_e32 v48, 0x80, v152
	v_mad_i64_i32 v[48:49], s[42:43], v48, s63, v[144:145]
	v_lshl_add_u64 v[52:53], v[48:49], 0, v[146:147]
	v_cvt_pk_bf16_f32 v48, v72, v73
	v_cvt_pk_bf16_f32 v49, v74, v75
	v_cvt_pk_bf16_f32 v50, v64, v65
	v_cvt_pk_bf16_f32 v51, v66, v67
	global_store_dwordx4 v[52:53], v[48:51], off
	s_nop 1
	v_cvt_pk_bf16_f32 v48, v76, v77
	v_cvt_pk_bf16_f32 v49, v78, v79
	v_cvt_pk_bf16_f32 v50, v68, v69
	v_cvt_pk_bf16_f32 v51, v70, v71
	global_store_dwordx4 v[52:53], v[48:51], off offset:256
	v_cvt_pk_bf16_f32 v40, v40, v41
	v_cvt_pk_bf16_f32 v41, v42, v43
	v_cvt_pk_bf16_f32 v42, v32, v33
	v_cvt_pk_bf16_f32 v43, v34, v35
	s_nop 1
	v_add_u32_e32 v48, 0x90, v152
	v_mad_i64_i32 v[48:49], s[42:43], v48, s63, v[144:145]
	v_lshl_add_u64 v[48:49], v[48:49], 0, v[146:147]
	global_store_dwordx4 v[48:49], v[40:43], off
	v_cvt_pk_bf16_f32 v32, v44, v45
	v_cvt_pk_bf16_f32 v33, v46, v47
	v_cvt_pk_bf16_f32 v34, v36, v37
	v_cvt_pk_bf16_f32 v35, v38, v39
	global_store_dwordx4 v[48:49], v[32:35], off offset:256
	v_cvt_pk_bf16_f32 v24, v24, v25
	v_cvt_pk_bf16_f32 v25, v26, v27
	v_cvt_pk_bf16_f32 v26, v16, v17
	v_cvt_pk_bf16_f32 v27, v18, v19
	s_nop 1
	v_add_u32_e32 v32, 0xa0, v152
	v_mad_i64_i32 v[32:33], s[42:43], v32, s63, v[144:145]
	v_lshl_add_u64 v[32:33], v[32:33], 0, v[146:147]
	global_store_dwordx4 v[32:33], v[24:27], off
	v_cvt_pk_bf16_f32 v16, v28, v29
	v_cvt_pk_bf16_f32 v17, v30, v31
	v_cvt_pk_bf16_f32 v18, v20, v21
	v_cvt_pk_bf16_f32 v19, v22, v23
	global_store_dwordx4 v[32:33], v[16:19], off offset:256
	v_cvt_pk_bf16_f32 v8, v8, v9
	v_cvt_pk_bf16_f32 v9, v10, v11
	v_cvt_pk_bf16_f32 v10, v0, v1
	v_cvt_pk_bf16_f32 v11, v2, v3
	s_nop 1
	v_add_u32_e32 v16, 0xb0, v152
	v_mad_i64_i32 v[16:17], s[42:43], v16, s63, v[144:145]
	v_lshl_add_u64 v[16:17], v[16:17], 0, v[146:147]
	global_store_dwordx4 v[16:17], v[8:11], off
	v_cvt_pk_bf16_f32 v0, v12, v13
	v_cvt_pk_bf16_f32 v1, v14, v15
	v_cvt_pk_bf16_f32 v2, v4, v5
	v_cvt_pk_bf16_f32 v3, v6, v7
	global_store_dwordx4 v[16:17], v[0:3], off offset:256
	s_mov_b32 s98, 1
	s_cbranch_vccnz .LBB0_3338
	s_andn2_b64 vcc, exec, s[4:5]
	s_cbranch_vccnz .LBB0_3337
	s_barrier
	s_branch .LBB0_3337

; #define PG8_STAGE(bufoff, gbase, voff) do { _Pragma("unroll") for (int _i = 0; _i < 2; ++_i) \
;         __builtin_amdgcn_global_load_lds((const unsigned*)((const char*)(gbase) + (voff)[_i]), (PG8_LAS unsigned*)(lds + (bufoff) + ldsw + _i * 8192), 16, 0, 0); } while (0)
; #define PG8_WAIT_V(n) asm volatile("s_waitcnt vmcnt(" #n ")" ::: "memory")
; #define PG8_BAR __builtin_amdgcn_s_barrier()
; template <class Epi, class Sched, bool ALIGN_EPI = false, bool SP2 = false, bool A_TILED = false>
; __device__ __forceinline__ void gemm_phase(PG8_LAS unsigned char* lds, const Gemm g, const Sched& S, const Epi& E, const int wave_s) {
;     ...
;     const int aoff = lds_byte(wr * 64 + fr, fq * 8), boff = lds_byte(wc * 32 + fr, fq * 8);
;     ...
;     Unit cur, nxt; int ui = 0;
;     if (!S.next(0, cur)) return;
;     f32x4 acc[2][2][4][2];
;     bf16x8 At[4][2], B0[2][2], B1[2][2];
;     const char* cA = (const char*)g.A + (size_t)cur.pm * tstepA; const char* cB = (const char*)g.Bt + (size_t)cur.pn * tstep;
;     S.a_ready(cur);
;     if constexpr (SP2) {
;         PG8_STAGE(PG8_SB(0, 0), cB, voffB); PG8_STAGE(PG8_SB(0, 1), cB + hstep, voffB); PG8_STAGE(PG8_SA(0, 0), cA, voffA); PG8_STAGE(PG8_SA(0, 1), cA + hstepA, voffA);
;         if (wr == 1) PG8_BAR;
;         PG8_WAIT_V(2); PG8_BAR;
;         PG8_STAGE(PG8_SB(1, 0), cB + kstep, voffB); PG8_STAGE(PG8_SA(1, 0), cA + kstepA, voffA); PG8_STAGE(PG8_SB(1, 1), cB + hstep + kstep, voffB);
;         PG8_WAIT_V(6); PG8_BAR;
.LBB0_3710:
	s_ashr_i32 s53, s86, 31
	s_add_u32 s54, s0, 0x34600000
	s_addc_u32 s55, s1, 0
	s_lshl_b32 s13, s6, 13
	s_mov_b64 s[6:7], 0x80
	s_and_b32 s0, s12, 3
	s_add_i32 m0, s47, 0x18000
	v_lshl_add_u64 v[6:7], v[6:7], 0, s[6:7]
	s_lshl_b32 s14, s0, 12
	s_waitcnt vmcnt(2)
	s_barrier
	global_load_lds_dwordx4 v[6:7], off
	v_lshl_add_u64 v[4:5], v[4:5], 0, s[6:7]
	s_add_i32 m0, s47, 0x1a000
	s_add_i32 s56, s47, 0x8000
	s_add_i32 s57, s47, 0xa000
	global_load_lds_dwordx4 v[4:5], off
	v_lshl_add_u64 v[0:1], v[0:1], 0, s[6:7]
	s_mov_b32 m0, s56
	s_add_u32 s0, s26, 0x80080
	global_load_lds_dwordx4 v[0:1], off
	v_lshl_add_u64 v[0:1], v[2:3], 0, s[6:7]
	s_mov_b32 m0, s57
	s_addc_u32 s1, s27, 0
	global_load_lds_dwordx4 v[0:1], off
	s_add_i32 m0, s47, 0x1c000
	v_lshl_add_u64 v[0:1], s[0:1], 0, v[128:129]
	global_load_lds_dwordx4 v128, s[0:1]
	v_lshl_add_u64 v[0:1], s[0:1], 0, v[130:131]
	s_add_i32 m0, s47, 0x1e000
	s_cmpk_lt_u32 s9, 0x100
	global_load_lds_dwordx4 v130, s[0:1]
	v_and_b32_e32 v0, 15, v8
	v_and_b32_e32 v1, 48, v8
	v_lshl_or_b32 v0, v0, 6, v1
	v_lshlrev_b32_e32 v1, 2, v8
	v_and_b32_e32 v1, 32, v1
	v_bitop3_b32 v2, v0, s13, v1 bitop3:0xde
	v_bitop3_b32 v144, v0, s14, v1 bitop3:0xde
	v_lshlrev_b32_e32 v0, 15, v9
	v_and_b32_e32 v0, 0xffff0000, v0
	v_lshl_add_u32 v0, v10, 12, v0
	v_and_b32_e32 v1, 1, v9
	v_lshl_or_b32 v0, v1, 6, v0
	v_lshl_add_u32 v136, v11, 1, v0
	v_lshlrev_b32_e32 v0, 15, v13
	v_and_b32_e32 v0, 0xffff0000, v0
	s_waitcnt vmcnt(6)
	s_mov_b32 s98, 0
	v_lshl_add_u32 v0, v12, 12, v0
	v_and_b32_e32 v1, 1, v13
	s_sext_i32_i16 s25, s8
	s_cselect_b64 s[8:9], -1, 0
	s_and_b32 s0, s45, 0x400
	v_mov_b32_e32 v137, 0
	v_lshl_or_b32 v0, v1, 6, v0
	s_add_i32 s60, 0, 0x10000
	s_add_i32 s61, 0, 0x14000
	s_bfe_u32 s58, s12, 0x10001
	s_or_b32 s59, s0, s13
	v_lshl_add_u32 v138, v14, 1, v0
	v_mov_b32_e32 v139, v137
	v_mov_b64_e32 v[140:141], 0x200
	v_mov_b64_e32 v[142:143], 0x1ff
	v_add_u32_e32 v145, s60, v144
	v_add_u32_e32 v146, s61, v144
	v_add_u32_e32 v147, 0, v2
	s_mov_b64 s[12:13], 0x100
	s_mov_b64 s[14:15], 0x180
	s_barrier
	s_branch .LBB0_3713

.LBB0_3719:
	s_ashr_i32 s19, s18, 31
	s_lshl_b64 s[20:21], s[18:19], 20
	s_add_u32 s20, s41, s20
	ds_read_b128 v[0:3], v145
	ds_read_b128 v[4:7], v145 offset:1024
	ds_read_b128 v[8:11], v145 offset:2048
	ds_read_b128 v[12:15], v145 offset:3072
	ds_read_b128 v[16:19], v146
	ds_read_b128 v[20:23], v146 offset:1024
	ds_read_b128 v[24:27], v146 offset:2048
	ds_read_b128 v[28:31], v146 offset:3072
	s_addc_u32 s21, s42, s21
	s_ashr_i32 s17, s16, 31
	s_lshl_b64 s[22:23], s[16:17], 20
	s_add_u32 s22, s43, s22
	s_addc_u32 s23, s44, s23
	s_and_b64 s[38:39], s[0:1], exec
	s_cselect_b32 s17, s21, s37
	s_cselect_b32 s19, s20, s36
	s_cselect_b32 s62, s23, s27
	s_cselect_b32 s63, s22, s26
	s_add_u32 s38, s36, 0x80080
	s_addc_u32 s39, s37, 0
	s_add_i32 s64, s47, 0xc000
	v_lshl_add_u64 v[64:65], s[38:39], 0, v[134:135]
	s_mov_b32 m0, s64
	s_add_i32 s65, s47, 0xe000
	ds_read_b128 v[32:35], v147
	ds_read_b128 v[36:39], v147 offset:1024
	ds_read_b128 v[40:43], v147 offset:2048
	ds_read_b128 v[44:47], v147 offset:3072
	ds_read_b128 v[48:51], v147 offset:4096
	ds_read_b128 v[52:55], v147 offset:5120
	ds_read_b128 v[56:59], v147 offset:6144
	ds_read_b128 v[60:63], v147 offset:7168
	global_load_lds_dwordx4 v134, s[38:39]
	v_lshl_add_u64 v[64:65], s[38:39], 0, v[132:133]
	s_mov_b32 m0, s65
	s_nop 0
	global_load_lds_dwordx4 v132, s[38:39]
	s_waitcnt vmcnt(24) lgkmcnt(0)
	s_cmp_lg_u32 s98, 0
	s_cbranch_scc1 .Lpw_19
	s_waitcnt vmcnt(8)
.Lpw_19:
	s_setprio 1
	s_barrier
	v_mfma_f32_16x16x32_bf16 v[88:91], v[0:3], v[56:59], 0
	v_mfma_f32_16x16x32_bf16 v[64:67], v[0:3], v[32:35], 0
	v_mfma_f32_16x16x32_bf16 v[68:71], v[8:11], v[32:35], 0
	v_mfma_f32_16x16x32_bf16 v[72:75], v[0:3], v[40:43], 0
	v_mfma_f32_16x16x32_bf16 v[76:79], v[8:11], v[40:43], 0
	v_mfma_f32_16x16x32_bf16 v[80:83], v[0:3], v[48:51], 0
	v_mfma_f32_16x16x32_bf16 v[84:87], v[8:11], v[48:51], 0
	v_mfma_f32_16x16x32_bf16 v[96:99], v[4:7], v[60:63], v[88:91]
	v_mfma_f32_16x16x32_bf16 v[88:91], v[8:11], v[56:59], 0
	v_mfma_f32_16x16x32_bf16 v[64:67], v[4:7], v[36:39], v[64:67]
	v_mfma_f32_16x16x32_bf16 v[68:71], v[12:15], v[36:39], v[68:71]
	v_mfma_f32_16x16x32_bf16 v[72:75], v[4:7], v[44:47], v[72:75]
	v_mfma_f32_16x16x32_bf16 v[76:79], v[12:15], v[44:47], v[76:79]
	v_mfma_f32_16x16x32_bf16 v[80:83], v[4:7], v[52:55], v[80:83]
	v_mfma_f32_16x16x32_bf16 v[84:87], v[12:15], v[52:55], v[84:87]
	v_mfma_f32_16x16x32_bf16 v[100:103], v[12:15], v[60:63], v[88:91]
	s_setprio 0
	s_setprio 1
	v_mfma_f32_16x16x32_bf16 v[88:91], v[16:19], v[32:35], 0
	v_mfma_f32_16x16x32_bf16 v[32:35], v[24:27], v[32:35], 0
	v_mfma_f32_16x16x32_bf16 v[112:115], v[20:23], v[36:39], v[88:91]
	v_mfma_f32_16x16x32_bf16 v[32:35], v[28:31], v[36:39], v[32:35]
	v_mfma_f32_16x16x32_bf16 v[36:39], v[16:19], v[40:43], 0
	v_mfma_f32_16x16x32_bf16 v[40:43], v[24:27], v[40:43], 0
	v_mfma_f32_16x16x32_bf16 v[36:39], v[20:23], v[44:47], v[36:39]
	v_mfma_f32_16x16x32_bf16 v[40:43], v[28:31], v[44:47], v[40:43]
	v_mfma_f32_16x16x32_bf16 v[44:47], v[16:19], v[48:51], 0
	v_mfma_f32_16x16x32_bf16 v[48:51], v[24:27], v[48:51], 0
	v_mfma_f32_16x16x32_bf16 v[44:47], v[20:23], v[52:55], v[44:47]
	v_mfma_f32_16x16x32_bf16 v[48:51], v[28:31], v[52:55], v[48:51]
	v_mfma_f32_16x16x32_bf16 v[52:55], v[16:19], v[56:59], 0
	v_mfma_f32_16x16x32_bf16 v[56:59], v[24:27], v[56:59], 0
	v_mfma_f32_16x16x32_bf16 v[52:55], v[20:23], v[60:63], v[52:55]
	v_mfma_f32_16x16x32_bf16 v[56:59], v[28:31], v[60:63], v[56:59]
	s_barrier
	s_setprio 0
	s_add_i32 s66, s60, s45
	v_lshl_add_u64 v[242:243], s[26:27], 0, v[128:129]
	s_add_i32 s67, s66, 0x2000
	v_lshl_add_u64 v[148:149], v[242:243], 0, s[12:13]
	s_mov_b32 m0, s66
	v_lshl_add_u64 v[244:245], s[26:27], 0, v[130:131]
	s_add_u32 s38, s26, 0x80100
	ds_read_b128 v[60:63], v147 offset:16384
	ds_read_b128 v[88:91], v147 offset:17408
	ds_read_b128 v[92:95], v147 offset:18432
	ds_read_b128 v[104:107], v147 offset:19456
	ds_read_b128 v[108:111], v147 offset:20480
	ds_read_b128 v[116:119], v147 offset:21504
	ds_read_b128 v[120:123], v147 offset:22528
	ds_read_b128 v[124:127], v147 offset:23552
	global_load_lds_dwordx4 v[148:149], off
	v_lshl_add_u64 v[148:149], v[244:245], 0, s[12:13]
	s_mov_b32 m0, s67
	s_addc_u32 s39, s27, 0
	s_add_i32 s68, s61, s45
	global_load_lds_dwordx4 v[148:149], off
	v_lshl_add_u64 v[148:149], s[38:39], 0, v[128:129]
	s_mov_b32 m0, s68
	s_add_i32 s69, s68, 0x2000
	global_load_lds_dwordx4 v128, s[38:39]
	v_lshl_add_u64 v[148:149], s[38:39], 0, v[130:131]
	s_mov_b32 m0, s69
	v_lshl_add_u64 v[246:247], s[36:37], 0, v[134:135]
	global_load_lds_dwordx4 v130, s[38:39]
	v_lshl_add_u64 v[148:149], v[246:247], 0, s[12:13]
	s_mov_b32 m0, s47
	v_lshl_add_u64 v[248:249], s[36:37], 0, v[132:133]
	global_load_lds_dwordx4 v[148:149], off
	v_lshl_add_u64 v[148:149], v[248:249], 0, s[12:13]
	s_mov_b32 m0, s48
	s_nop 0
	global_load_lds_dwordx4 v[148:149], off
	s_waitcnt vmcnt(24) lgkmcnt(0)
	s_cmp_lg_u32 s98, 0
	s_cbranch_scc1 .Lpw_20
	s_waitcnt vmcnt(8)
.Lpw_20:
	s_setprio 1
	s_barrier
	v_mfma_f32_16x16x32_bf16 v[148:151], v[0:3], v[60:63], 0
	v_mfma_f32_16x16x32_bf16 v[158:161], v[0:3], v[92:95], 0
	v_mfma_f32_16x16x32_bf16 v[166:169], v[0:3], v[108:111], 0
	v_mfma_f32_16x16x32_bf16 v[0:3], v[0:3], v[120:123], 0
	v_mfma_f32_16x16x32_bf16 v[150:153], v[4:7], v[88:91], v[148:151]
	v_mfma_f32_16x16x32_bf16 v[158:161], v[4:7], v[104:107], v[158:161]
	v_mfma_f32_16x16x32_bf16 v[166:169], v[4:7], v[116:119], v[166:169]
	v_mfma_f32_16x16x32_bf16 v[0:3], v[4:7], v[124:127], v[0:3]
	v_mfma_f32_16x16x32_bf16 v[4:7], v[8:11], v[120:123], 0
	v_mfma_f32_16x16x32_bf16 v[154:157], v[8:11], v[60:63], 0
	v_mfma_f32_16x16x32_bf16 v[162:165], v[8:11], v[92:95], 0
	v_mfma_f32_16x16x32_bf16 v[170:173], v[8:11], v[108:111], 0
	v_mfma_f32_16x16x32_bf16 v[4:7], v[12:15], v[124:127], v[4:7]
	v_mfma_f32_16x16x32_bf16 v[154:157], v[12:15], v[88:91], v[154:157]
	v_mfma_f32_16x16x32_bf16 v[162:165], v[12:15], v[104:107], v[162:165]
	v_mfma_f32_16x16x32_bf16 v[170:173], v[12:15], v[116:119], v[170:173]
	s_setprio 0
	s_setprio 1
	v_mfma_f32_16x16x32_bf16 v[8:11], v[16:19], v[60:63], 0
	v_mfma_f32_16x16x32_bf16 v[174:177], v[20:23], v[88:91], v[8:11]
	v_mfma_f32_16x16x32_bf16 v[8:11], v[24:27], v[60:63], 0
	v_mfma_f32_16x16x32_bf16 v[60:63], v[28:31], v[88:91], v[8:11]
	v_mfma_f32_16x16x32_bf16 v[8:11], v[16:19], v[92:95], 0
	v_mfma_f32_16x16x32_bf16 v[178:181], v[20:23], v[104:107], v[8:11]
	v_mfma_f32_16x16x32_bf16 v[8:11], v[24:27], v[92:95], 0
	v_mfma_f32_16x16x32_bf16 v[182:185], v[28:31], v[104:107], v[8:11]
	v_mfma_f32_16x16x32_bf16 v[8:11], v[16:19], v[108:111], 0
	v_mfma_f32_16x16x32_bf16 v[186:189], v[20:23], v[116:119], v[8:11]
	v_mfma_f32_16x16x32_bf16 v[8:11], v[24:27], v[108:111], 0
	v_mfma_f32_16x16x32_bf16 v[190:193], v[28:31], v[116:119], v[8:11]
	v_mfma_f32_16x16x32_bf16 v[8:11], v[16:19], v[120:123], 0
	v_mfma_f32_16x16x32_bf16 v[194:197], v[20:23], v[124:127], v[8:11]
	v_mfma_f32_16x16x32_bf16 v[8:11], v[24:27], v[120:123], 0
	v_mfma_f32_16x16x32_bf16 v[198:201], v[28:31], v[124:127], v[8:11]
	s_barrier
	s_setprio 0
	s_add_i32 s70, 0, 0x18000
	s_add_i32 s72, 0, 0x1c000
	v_add_u32_e32 v148, s70, v144
	v_add_u32_e32 v149, s72, v144
	s_nop 0
	ds_read_b128 v[8:11], v148
	ds_read_b128 v[12:15], v148 offset:1024
	ds_read_b128 v[16:19], v148 offset:2048
	ds_read_b128 v[20:23], v148 offset:3072
	ds_read_b128 v[202:205], v149
	ds_read_b128 v[206:209], v149 offset:1024
	ds_read_b128 v[210:213], v149 offset:2048
	ds_read_b128 v[214:217], v149 offset:3072
	s_add_u32 s38, s36, 0x80100
	s_addc_u32 s39, s37, 0
	s_mov_b32 m0, s49
	v_lshl_add_u64 v[88:89], s[38:39], 0, v[134:135]
	ds_read_b128 v[24:27], v147 offset:32768
	ds_read_b128 v[28:31], v147 offset:33792
	ds_read_b128 v[218:221], v147 offset:34816
	ds_read_b128 v[222:225], v147 offset:35840
	ds_read_b128 v[226:229], v147 offset:36864
	ds_read_b128 v[230:233], v147 offset:37888
	ds_read_b128 v[234:237], v147 offset:38912
	ds_read_b128 v[238:241], v147 offset:39936
	global_load_lds_dwordx4 v134, s[38:39]
	v_lshl_add_u64 v[88:89], s[38:39], 0, v[132:133]
	s_mov_b32 m0, s50
	s_nop 0
	global_load_lds_dwordx4 v132, s[38:39]
	s_waitcnt vmcnt(8) lgkmcnt(0)
	s_setprio 1
	s_barrier
	v_mfma_f32_16x16x32_bf16 v[64:67], v[8:11], v[24:27], v[64:67]
	v_mfma_f32_16x16x32_bf16 v[120:123], v[12:15], v[28:31], v[64:67]
	v_mfma_f32_16x16x32_bf16 v[64:67], v[16:19], v[24:27], v[68:71]
	v_mfma_f32_16x16x32_bf16 v[124:127], v[20:23], v[28:31], v[64:67]
	v_mfma_f32_16x16x32_bf16 v[64:67], v[8:11], v[218:221], v[72:75]
	v_mfma_f32_16x16x32_bf16 v[104:107], v[12:15], v[222:225], v[64:67]
	v_mfma_f32_16x16x32_bf16 v[64:67], v[16:19], v[218:221], v[76:79]
	v_mfma_f32_16x16x32_bf16 v[108:111], v[20:23], v[222:225], v[64:67]
	v_mfma_f32_16x16x32_bf16 v[64:67], v[8:11], v[226:229], v[80:83]
	v_mfma_f32_16x16x32_bf16 v[88:91], v[12:15], v[230:233], v[64:67]
	v_mfma_f32_16x16x32_bf16 v[64:67], v[16:19], v[226:229], v[84:87]
	v_mfma_f32_16x16x32_bf16 v[92:95], v[20:23], v[230:233], v[64:67]
	v_mfma_f32_16x16x32_bf16 v[64:67], v[8:11], v[234:237], v[96:99]
	v_mfma_f32_16x16x32_bf16 v[68:71], v[16:19], v[234:237], v[100:103]
	v_mfma_f32_16x16x32_bf16 v[64:67], v[12:15], v[238:241], v[64:67]
	v_mfma_f32_16x16x32_bf16 v[68:71], v[20:23], v[238:241], v[68:71]
	s_setprio 0
	s_setprio 1
	v_mfma_f32_16x16x32_bf16 v[72:75], v[202:205], v[24:27], v[112:115]
	v_mfma_f32_16x16x32_bf16 v[24:27], v[210:213], v[24:27], v[32:35]
	v_mfma_f32_16x16x32_bf16 v[116:119], v[214:217], v[28:31], v[24:27]
	v_mfma_f32_16x16x32_bf16 v[24:27], v[202:205], v[218:221], v[36:39]
	v_mfma_f32_16x16x32_bf16 v[96:99], v[206:209], v[222:225], v[24:27]
	v_mfma_f32_16x16x32_bf16 v[24:27], v[210:213], v[218:221], v[40:43]
	v_mfma_f32_16x16x32_bf16 v[100:103], v[214:217], v[222:225], v[24:27]
	v_mfma_f32_16x16x32_bf16 v[24:27], v[202:205], v[226:229], v[44:47]
	v_mfma_f32_16x16x32_bf16 v[80:83], v[206:209], v[230:233], v[24:27]
	v_mfma_f32_16x16x32_bf16 v[24:27], v[210:213], v[226:229], v[48:51]
	v_mfma_f32_16x16x32_bf16 v[84:87], v[214:217], v[230:233], v[24:27]
	v_mfma_f32_16x16x32_bf16 v[24:27], v[202:205], v[234:237], v[52:55]
	v_mfma_f32_16x16x32_bf16 v[48:51], v[206:209], v[238:241], v[24:27]
	v_mfma_f32_16x16x32_bf16 v[24:27], v[210:213], v[234:237], v[56:59]
	v_mfma_f32_16x16x32_bf16 v[112:115], v[206:209], v[28:31], v[72:75]
	v_mfma_f32_16x16x32_bf16 v[52:55], v[214:217], v[238:241], v[24:27]
	s_barrier
	s_setprio 0
	s_add_i32 s70, s70, s45
	s_add_i32 s71, s70, 0x2000
	s_nop 1
	v_lshl_add_u64 v[24:25], v[242:243], 0, s[14:15]
	s_mov_b32 m0, s70
	s_add_u32 s38, s26, 0x80180
	ds_read_b128 v[32:35], v147 offset:49152
	ds_read_b128 v[36:39], v147 offset:50176
	ds_read_b128 v[218:221], v147 offset:51200
	ds_read_b128 v[222:225], v147 offset:52224
	ds_read_b128 v[226:229], v147 offset:53248
	ds_read_b128 v[230:233], v147 offset:54272
	ds_read_b128 v[234:237], v147 offset:55296
	ds_read_b128 v[238:241], v147 offset:56320
	global_load_lds_dwordx4 v[24:25], off
	v_lshl_add_u64 v[24:25], v[244:245], 0, s[14:15]
	s_mov_b32 m0, s71
	s_addc_u32 s39, s27, 0
	s_add_i32 s72, s72, s45
	global_load_lds_dwordx4 v[24:25], off
	v_lshl_add_u64 v[24:25], s[38:39], 0, v[128:129]
	s_mov_b32 m0, s72
	s_add_i32 s73, s72, 0x2000
	global_load_lds_dwordx4 v128, s[38:39]
	v_lshl_add_u64 v[24:25], s[38:39], 0, v[130:131]
	s_mov_b32 m0, s73
	s_nop 0
	global_load_lds_dwordx4 v130, s[38:39]
	v_lshl_add_u64 v[24:25], v[246:247], 0, s[14:15]
	s_mov_b32 m0, s56
	s_nop 0
	global_load_lds_dwordx4 v[24:25], off
	v_lshl_add_u64 v[24:25], v[248:249], 0, s[14:15]
	s_mov_b32 m0, s57
	s_nop 0
	global_load_lds_dwordx4 v[24:25], off
	s_waitcnt vmcnt(8) lgkmcnt(0)
	s_setprio 1
	s_barrier
	v_mfma_f32_16x16x32_bf16 v[24:27], v[8:11], v[32:35], v[150:153]
	v_mfma_f32_16x16x32_bf16 v[72:75], v[12:15], v[36:39], v[24:27]
	v_mfma_f32_16x16x32_bf16 v[24:27], v[16:19], v[32:35], v[154:157]
	v_mfma_f32_16x16x32_bf16 v[76:79], v[20:23], v[36:39], v[24:27]
	v_mfma_f32_16x16x32_bf16 v[24:27], v[8:11], v[218:221], v[158:161]
	v_mfma_f32_16x16x32_bf16 v[40:43], v[12:15], v[222:225], v[24:27]
	v_mfma_f32_16x16x32_bf16 v[24:27], v[16:19], v[218:221], v[162:165]
	v_mfma_f32_16x16x32_bf16 v[0:3], v[8:11], v[234:237], v[0:3]
	v_mfma_f32_16x16x32_bf16 v[44:47], v[20:23], v[222:225], v[24:27]
	v_mfma_f32_16x16x32_bf16 v[24:27], v[8:11], v[226:229], v[166:169]
	v_mfma_f32_16x16x32_bf16 v[28:31], v[16:19], v[226:229], v[170:173]
	v_mfma_f32_16x16x32_bf16 v[8:11], v[12:15], v[238:241], v[0:3]
	v_mfma_f32_16x16x32_bf16 v[0:3], v[16:19], v[234:237], v[4:7]
	v_mfma_f32_16x16x32_bf16 v[24:27], v[12:15], v[230:233], v[24:27]
	v_mfma_f32_16x16x32_bf16 v[28:31], v[20:23], v[230:233], v[28:31]
	v_mfma_f32_16x16x32_bf16 v[12:15], v[20:23], v[238:241], v[0:3]
	s_setprio 0
	s_setprio 1
	v_mfma_f32_16x16x32_bf16 v[0:3], v[202:205], v[32:35], v[174:177]
	v_mfma_f32_16x16x32_bf16 v[56:59], v[206:209], v[36:39], v[0:3]
	v_mfma_f32_16x16x32_bf16 v[0:3], v[210:213], v[32:35], v[60:63]
	v_mfma_f32_16x16x32_bf16 v[60:63], v[214:217], v[36:39], v[0:3]
	v_mfma_f32_16x16x32_bf16 v[0:3], v[202:205], v[218:221], v[178:181]
	v_mfma_f32_16x16x32_bf16 v[32:35], v[206:209], v[222:225], v[0:3]
	v_mfma_f32_16x16x32_bf16 v[0:3], v[210:213], v[218:221], v[182:185]
	v_mfma_f32_16x16x32_bf16 v[36:39], v[214:217], v[222:225], v[0:3]
	v_mfma_f32_16x16x32_bf16 v[0:3], v[202:205], v[226:229], v[186:189]
	v_mfma_f32_16x16x32_bf16 v[16:19], v[206:209], v[230:233], v[0:3]
	v_mfma_f32_16x16x32_bf16 v[0:3], v[210:213], v[226:229], v[190:193]
	v_mfma_f32_16x16x32_bf16 v[20:23], v[214:217], v[230:233], v[0:3]
	v_mfma_f32_16x16x32_bf16 v[0:3], v[202:205], v[234:237], v[194:197]
	v_mfma_f32_16x16x32_bf16 v[4:7], v[210:213], v[234:237], v[198:201]
	v_mfma_f32_16x16x32_bf16 v[0:3], v[206:209], v[238:241], v[0:3]
	v_mfma_f32_16x16x32_bf16 v[4:7], v[214:217], v[238:241], v[4:7]
	s_barrier
	s_setprio 0
	s_add_u32 s74, s26, 0x200
	s_addc_u32 s75, s27, 0
	s_add_u32 s26, s36, 0x80180
	s_addc_u32 s27, s37, 0
	s_mov_b32 s76, 0

;     __device__ __forceinline__ void operator()(const f32x4 (&acc)[2][2][4][2], const Unit& u, int wr, int wc, int fr, int fq) const {
;     ...
; #pragma unroll
;         for (int ai = 0; ai < 2; ++ai)
; #pragma unroll
;             for (int m = 0; m < 4; ++m) { bf16_t* rowp = O + (size_t)(row0 + ai * HALF + m * 16) * ldc + col0;
;                 if (ACT == 1) {
;                     const int ob = fr * 64 + 16 * fq, sw = ob ^ (((ob >> 9) & 1) << 5);
;                     rowp = O + ((size_t)(u.pm * (ldc / 64) + u.pn * 4 + (wc >> 1)) * 2 + ai) * 8192 + (((wr * 4 + m) * 2 + (wc & 1)) * 1024 + sw) / 2; }
;                 float rc[2][2], rs[2][2];
;                 if (ACT == 2) { const float pos = (float)((row0 + ai * HALF + m * 16) & 2047);
; #pragma unroll
;                     for (int n = 0; n < 2; ++n)
; #pragma unroll
;                         for (int e = 0; e < 2; ++e) { float r = pos * rinv[n][e]; r -= floorf(r); rs[n][e] = do_rope ? __builtin_amdgcn_sinf(r) : 0.f; rc[n][e] = do_rope ? __builtin_amdgcn_cosf(r) : 1.f; } }
; #pragma unroll
;                 for (int bj = 0; bj < 2; ++bj) { f32x4 v0 = acc[ai][bj][m][0], v1 = acc[ai][bj][m][1];
;                     if (ACT == 3) { const float pos = (float)((row0 + ai * HALF + m * 16) & 2047); float c3[4], s3[4];
; #pragma unroll
;                         for (int p = 0; p < 4; ++p) { float r = pos * rinv3[bj][p]; r -= floorf(r); s3[p] = rope3[bj] ? __builtin_amdgcn_sinf(r) : 0.f; c3[p] = rope3[bj] ? __builtin_amdgcn_cosf(r) : 1.f; }
;                         const f32x4 a = v0, b = v1;
;                         v0[0] = a[0] * c3[0] - a[1] * s3[0]; v0[1] = a[1] * c3[0] + a[0] * s3[0]; v0[2] = a[2] * c3[1] - a[3] * s3[1]; v0[3] = a[3] * c3[1] + a[2] * s3[1];
;                         v1[0] = b[0] * c3[2] - b[1] * s3[2]; v1[1] = b[1] * c3[2] + b[0] * s3[2]; v1[2] = b[2] * c3[3] - b[3] * s3[3]; v1[3] = b[3] * c3[3] + b[2] * s3[3]; }
;                     if (ACT == 2) { const f32x4 a = v0, b = v1;
;                         v0[0] = a[0] * rc[0][0] - a[1] * rs[0][0]; v0[1] = a[1] * rc[0][0] + a[0] * rs[0][0]; v0[2] = a[2] * rc[0][1] - a[3] * rs[0][1]; v0[3] = a[3] * rc[0][1] + a[2] * rs[0][1];
;                         v1[0] = b[0] * rc[1][0] - b[1] * rs[1][0]; v1[1] = b[1] * rc[1][0] + b[0] * rs[1][0]; v1[2] = b[2] * rc[1][1] - b[3] * rs[1][1]; v1[3] = b[3] * rc[1][1] + b[2] * rs[1][1]; }
.LBB0_3723:
	v_mov_b32_e32 v148, 0
	s_lshl_b32 s17, s25, 2
	v_mbcnt_lo_u32_b32 v148, -1, v148
	v_mbcnt_hi_u32_b32 v148, -1, v148
	v_or_b32_e32 v148, s33, v148
	s_or_b32 s17, s17, s58
	v_and_b32_e32 v149, 15, v148
	v_and_b32_e32 v150, 48, v148
	v_lshlrev_b32_e32 v148, 2, v148
	s_lshl_b32 s19, s24, 7
	v_lshl_or_b32 v149, v149, 6, v150
	v_and_b32_e32 v148, 32, v148
	s_add_i32 s24, s17, s19
	s_ashr_i32 s25, s24, 31
	v_bitop3_b32 v148, v149, s59, v148 bitop3:0xde
	s_lshl_b64 s[24:25], s[24:25], 15
	v_ashrrev_i32_e32 v148, 1, v148
	s_add_u32 s24, s54, s24
	v_ashrrev_i32_e32 v149, 31, v148
	s_addc_u32 s25, s55, s25
	v_lshlrev_b64 v[150:151], 1, v[148:149]
	v_max_i32_e32 v120, 0, v120
	v_max_i32_e32 v121, 0, v121
	v_max_i32_e32 v122, 0, v122
	v_max_i32_e32 v123, 0, v123
	v_max_i32_e32 v112, 0, v112
	v_max_i32_e32 v116, 0, v116
	v_max_i32_e32 v113, 0, v113
	v_max_i32_e32 v114, 0, v114
	v_lshl_add_u64 v[152:153], s[24:25], 0, v[150:151]
	v_max_i32_e32 v124, 0, v124
	v_mul_f32_e32 v120, v120, v120
	v_max_i32_e32 v125, 0, v125
	v_mul_f32_e32 v121, v121, v121
	v_max_i32_e32 v126, 0, v126
	v_mul_f32_e32 v122, v122, v122
	v_max_i32_e32 v127, 0, v127
	v_mul_f32_e32 v123, v123, v123
	v_mul_f32_e32 v112, v112, v112
	v_mul_f32_e32 v116, v116, v116
	v_max_i32_e32 v117, 0, v117
	v_mul_f32_e32 v113, v113, v113
	v_mul_f32_e32 v114, v114, v114
	v_max_i32_e32 v115, 0, v115
	v_mul_f32_e32 v124, v124, v124
	v_mul_f32_e32 v125, v125, v125
	v_mul_f32_e32 v126, v126, v126
	v_mul_f32_e32 v127, v127, v127
	v_cvt_pk_bf16_f32 v120, v120, v121
	v_cvt_pk_bf16_f32 v121, v122, v123
	v_cvt_pk_bf16_f32 v122, v124, v125
	v_cvt_pk_bf16_f32 v123, v126, v127
	global_store_dwordx4 v[152:153], v[120:123], off
	v_mul_f32_e32 v117, v117, v117
	v_mul_f32_e32 v115, v115, v115
	v_cvt_pk_bf16_f32 v112, v112, v113
	v_cvt_pk_bf16_f32 v113, v114, v115
	v_cvt_pk_bf16_f32 v114, v116, v117
	v_add_co_u32_e32 v116, vcc, s52, v152
	v_max_i32_e32 v104, 0, v104
	v_max_i32_e32 v105, 0, v105
	v_max_i32_e32 v106, 0, v106
	v_max_i32_e32 v107, 0, v107
	v_max_i32_e32 v96, 0, v96
	v_max_i32_e32 v118, 0, v118
	v_max_i32_e32 v119, 0, v119
	v_addc_co_u32_e32 v117, vcc, 0, v153, vcc
	v_max_i32_e32 v108, 0, v108
	v_mul_f32_e32 v104, v104, v104
	v_max_i32_e32 v109, 0, v109
	v_mul_f32_e32 v105, v105, v105
	v_max_i32_e32 v110, 0, v110
	v_mul_f32_e32 v106, v106, v106
	v_max_i32_e32 v111, 0, v111
	v_mul_f32_e32 v107, v107, v107
	v_mul_f32_e32 v96, v96, v96
	v_max_i32_e32 v97, 0, v97
	v_max_i32_e32 v98, 0, v98
	v_max_i32_e32 v99, 0, v99
	v_mul_f32_e32 v118, v118, v118
	v_mul_f32_e32 v119, v119, v119
	v_cvt_pk_bf16_f32 v115, v118, v119
	global_store_dwordx4 v[116:117], v[112:115], off
	v_mul_f32_e32 v108, v108, v108
	v_mul_f32_e32 v109, v109, v109
	v_mul_f32_e32 v110, v110, v110
	v_mul_f32_e32 v111, v111, v111
	v_cvt_pk_bf16_f32 v104, v104, v105
	v_cvt_pk_bf16_f32 v105, v106, v107
	v_cvt_pk_bf16_f32 v106, v108, v109
	v_cvt_pk_bf16_f32 v107, v110, v111
	global_store_dwordx4 v[152:153], v[104:107], off offset:2048
	v_max_i32_e32 v100, 0, v100
	v_max_i32_e32 v101, 0, v101
	v_mul_f32_e32 v97, v97, v97
	v_max_i32_e32 v102, 0, v102
	v_mul_f32_e32 v98, v98, v98
	v_max_i32_e32 v103, 0, v103
	v_mul_f32_e32 v99, v99, v99
	v_cvt_pk_bf16_f32 v96, v96, v97
	v_mul_f32_e32 v100, v100, v100
	v_mul_f32_e32 v101, v101, v101
	v_mul_f32_e32 v102, v102, v102
	v_mul_f32_e32 v103, v103, v103
	v_cvt_pk_bf16_f32 v97, v98, v99
	v_cvt_pk_bf16_f32 v98, v100, v101
	v_cvt_pk_bf16_f32 v99, v102, v103
	global_store_dwordx4 v[116:117], v[96:99], off offset:2048
	v_max_i32_e32 v88, 0, v88
	v_max_i32_e32 v89, 0, v89
	v_or_b32_e32 v96, 0x800, v148
	v_ashrrev_i32_e32 v97, 31, v96
	v_lshlrev_b64 v[96:97], 1, v[96:97]
	v_max_i32_e32 v90, 0, v90
	v_max_i32_e32 v91, 0, v91
	v_max_i32_e32 v80, 0, v80
	v_max_i32_e32 v84, 0, v84
	v_max_i32_e32 v81, 0, v81
	v_max_i32_e32 v82, 0, v82
	v_lshl_add_u64 v[98:99], s[24:25], 0, v[96:97]
	v_max_i32_e32 v92, 0, v92
	v_mul_f32_e32 v88, v88, v88
	v_max_i32_e32 v93, 0, v93
	v_mul_f32_e32 v89, v89, v89
	v_max_i32_e32 v94, 0, v94
	v_mul_f32_e32 v90, v90, v90
	v_max_i32_e32 v95, 0, v95
	v_mul_f32_e32 v91, v91, v91
	v_mul_f32_e32 v80, v80, v80
	v_mul_f32_e32 v84, v84, v84
	v_max_i32_e32 v85, 0, v85
	v_mul_f32_e32 v81, v81, v81
	v_mul_f32_e32 v82, v82, v82
	v_max_i32_e32 v83, 0, v83
	v_mul_f32_e32 v92, v92, v92
	v_mul_f32_e32 v93, v93, v93
	v_mul_f32_e32 v94, v94, v94
	v_mul_f32_e32 v95, v95, v95
	v_cvt_pk_bf16_f32 v88, v88, v89
	v_cvt_pk_bf16_f32 v89, v90, v91
	v_cvt_pk_bf16_f32 v90, v92, v93
	v_cvt_pk_bf16_f32 v91, v94, v95
	global_store_dwordx4 v[98:99], v[88:91], off
	v_mul_f32_e32 v85, v85, v85
	v_mul_f32_e32 v83, v83, v83
	v_cvt_pk_bf16_f32 v80, v80, v81
	v_cvt_pk_bf16_f32 v81, v82, v83
	v_cvt_pk_bf16_f32 v82, v84, v85
	v_add_co_u32_e32 v84, vcc, s52, v98
	v_max_i32_e32 v86, 0, v86
	v_max_i32_e32 v87, 0, v87
	v_addc_co_u32_e32 v85, vcc, 0, v99, vcc
	v_mul_f32_e32 v86, v86, v86
	v_mul_f32_e32 v87, v87, v87
	v_cvt_pk_bf16_f32 v83, v86, v87
	global_store_dwordx4 v[84:85], v[80:83], off
	v_max_i32_e32 v64, 0, v64
	v_max_i32_e32 v65, 0, v65
	v_or_b32_e32 v80, 0xc00, v148
	v_ashrrev_i32_e32 v81, 31, v80
	v_lshlrev_b64 v[80:81], 1, v[80:81]
	v_max_i32_e32 v66, 0, v66
	v_max_i32_e32 v67, 0, v67
	v_max_i32_e32 v48, 0, v48
	v_max_i32_e32 v52, 0, v52
	v_max_i32_e32 v49, 0, v49
	v_max_i32_e32 v50, 0, v50
	v_lshl_add_u64 v[82:83], s[24:25], 0, v[80:81]
	v_max_i32_e32 v68, 0, v68
	v_mul_f32_e32 v64, v64, v64
	v_max_i32_e32 v69, 0, v69
	v_mul_f32_e32 v65, v65, v65
	v_max_i32_e32 v70, 0, v70
	v_mul_f32_e32 v66, v66, v66
	v_max_i32_e32 v71, 0, v71
	v_mul_f32_e32 v67, v67, v67
	v_mul_f32_e32 v48, v48, v48
	v_mul_f32_e32 v52, v52, v52
;     __device__ __forceinline__ void operator()(const f32x4 (&acc)[2][2][4][2], const Unit& u, int wr, int wc, int fr, int fq) const {
;     ...
; #pragma unroll
;         for (int ai = 0; ai < 2; ++ai)
; #pragma unroll
;             for (int m = 0; m < 4; ++m) { bf16_t* rowp = O + (size_t)(row0 + ai * HALF + m * 16) * ldc + col0;
;                 if (ACT == 1) {
;                     const int ob = fr * 64 + 16 * fq, sw = ob ^ (((ob >> 9) & 1) << 5);
;                     rowp = O + ((size_t)(u.pm * (ldc / 64) + u.pn * 4 + (wc >> 1)) * 2 + ai) * 8192 + (((wr * 4 + m) * 2 + (wc & 1)) * 1024 + sw) / 2; }
;                 float rc[2][2], rs[2][2];
;                 if (ACT == 2) { const float pos = (float)((row0 + ai * HALF + m * 16) & 2047);
; #pragma unroll
;                     for (int n = 0; n < 2; ++n)
; #pragma unroll
;                         for (int e = 0; e < 2; ++e) { float r = pos * rinv[n][e]; r -= floorf(r); rs[n][e] = do_rope ? __builtin_amdgcn_sinf(r) : 0.f; rc[n][e] = do_rope ? __builtin_amdgcn_cosf(r) : 1.f; } }
; #pragma unroll
;                 for (int bj = 0; bj < 2; ++bj) { f32x4 v0 = acc[ai][bj][m][0], v1 = acc[ai][bj][m][1];
;                     if (ACT == 3) { const float pos = (float)((row0 + ai * HALF + m * 16) & 2047); float c3[4], s3[4];
; #pragma unroll
;                         for (int p = 0; p < 4; ++p) { float r = pos * rinv3[bj][p]; r -= floorf(r); s3[p] = rope3[bj] ? __builtin_amdgcn_sinf(r) : 0.f; c3[p] = rope3[bj] ? __builtin_amdgcn_cosf(r) : 1.f; }
;                         const f32x4 a = v0, b = v1;
;                         v0[0] = a[0] * c3[0] - a[1] * s3[0]; v0[1] = a[1] * c3[0] + a[0] * s3[0]; v0[2] = a[2] * c3[1] - a[3] * s3[1]; v0[3] = a[3] * c3[1] + a[2] * s3[1];
;                         v1[0] = b[0] * c3[2] - b[1] * s3[2]; v1[1] = b[1] * c3[2] + b[0] * s3[2]; v1[2] = b[2] * c3[3] - b[3] * s3[3]; v1[3] = b[3] * c3[3] + b[2] * s3[3]; }
;                     if (ACT == 2) { const f32x4 a = v0, b = v1;
;                         v0[0] = a[0] * rc[0][0] - a[1] * rs[0][0]; v0[1] = a[1] * rc[0][0] + a[0] * rs[0][0]; v0[2] = a[2] * rc[0][1] - a[3] * rs[0][1]; v0[3] = a[3] * rc[0][1] + a[2] * rs[0][1];
;                         v1[0] = b[0] * rc[1][0] - b[1] * rs[1][0]; v1[1] = b[1] * rc[1][0] + b[0] * rs[1][0]; v1[2] = b[2] * rc[1][1] - b[3] * rs[1][1]; v1[3] = b[3] * rc[1][1] + b[2] * rs[1][1]; }
	v_max_i32_e32 v53, 0, v53
	v_mul_f32_e32 v49, v49, v49
	v_mul_f32_e32 v50, v50, v50
	v_max_i32_e32 v51, 0, v51
	v_mul_f32_e32 v68, v68, v68
	v_mul_f32_e32 v69, v69, v69
	v_mul_f32_e32 v70, v70, v70
	v_mul_f32_e32 v71, v71, v71
	v_cvt_pk_bf16_f32 v64, v64, v65
	v_cvt_pk_bf16_f32 v65, v66, v67
	v_cvt_pk_bf16_f32 v66, v68, v69
	v_cvt_pk_bf16_f32 v67, v70, v71
	global_store_dwordx4 v[82:83], v[64:67], off
	v_mul_f32_e32 v53, v53, v53
	v_mul_f32_e32 v51, v51, v51
	v_cvt_pk_bf16_f32 v48, v48, v49
	v_cvt_pk_bf16_f32 v49, v50, v51
	v_cvt_pk_bf16_f32 v50, v52, v53
	v_add_co_u32_e32 v52, vcc, s52, v82
	v_max_i32_e32 v54, 0, v54
	v_max_i32_e32 v55, 0, v55
	v_addc_co_u32_e32 v53, vcc, 0, v83, vcc
	v_mul_f32_e32 v54, v54, v54
	v_mul_f32_e32 v55, v55, v55
	v_cvt_pk_bf16_f32 v51, v54, v55
	global_store_dwordx4 v[52:53], v[48:51], off
	s_add_u32 s24, s24, 0x4000
	s_addc_u32 s25, s25, 0
	v_max_i32_e32 v49, 0, v76
	v_max_i32_e32 v48, 0, v72
	v_mul_f32_e32 v50, v49, v49
	v_max_i32_e32 v49, 0, v73
	v_mul_f32_e32 v48, v48, v48
	v_max_i32_e32 v51, 0, v77
	v_mul_f32_e32 v49, v49, v49
	v_max_i32_e32 v54, 0, v74
	v_max_i32_e32 v64, 0, v75
	v_lshl_add_u64 v[52:53], s[24:25], 0, v[150:151]
	v_mul_f32_e32 v51, v51, v51
	v_max_i32_e32 v55, 0, v78
	v_mul_f32_e32 v54, v54, v54
	v_max_i32_e32 v65, 0, v79
	v_mul_f32_e32 v64, v64, v64
	v_cvt_pk_bf16_f32 v48, v48, v49
	v_cvt_pk_bf16_f32 v49, v54, v64
	v_mul_f32_e32 v55, v55, v55
	v_mul_f32_e32 v65, v65, v65
	v_cvt_pk_bf16_f32 v50, v50, v51
	v_cvt_pk_bf16_f32 v51, v55, v65
	global_store_dwordx4 v[52:53], v[48:51], off
	v_or_b32_e32 v112, 0x400, v148
	v_max_i32_e32 v54, 0, v58
	v_max_i32_e32 v49, 0, v60
	v_max_i32_e32 v48, 0, v56
	v_mul_f32_e32 v50, v49, v49
	v_max_i32_e32 v49, 0, v57
	v_mul_f32_e32 v48, v48, v48
	v_max_i32_e32 v51, 0, v61
	v_mul_f32_e32 v49, v49, v49
	v_max_i32_e32 v56, 0, v59
	v_add_co_u32_e32 v52, vcc, s52, v52
	v_ashrrev_i32_e32 v113, 31, v112
	v_mul_f32_e32 v51, v51, v51
	v_max_i32_e32 v55, 0, v62
	v_mul_f32_e32 v54, v54, v54
	v_max_i32_e32 v57, 0, v63
	v_mul_f32_e32 v56, v56, v56
	v_cvt_pk_bf16_f32 v48, v48, v49
	v_cvt_pk_bf16_f32 v49, v54, v56
	v_addc_co_u32_e32 v53, vcc, 0, v53, vcc
	v_max_i32_e32 v40, 0, v40
	v_max_i32_e32 v41, 0, v41
	v_max_i32_e32 v42, 0, v42
	v_max_i32_e32 v43, 0, v43
	v_max_i32_e32 v32, 0, v32
	v_max_i32_e32 v36, 0, v36
	v_max_i32_e32 v33, 0, v33
	v_max_i32_e32 v34, 0, v34
	v_mul_f32_e32 v55, v55, v55
	v_mul_f32_e32 v57, v57, v57
	v_cvt_pk_bf16_f32 v50, v50, v51
	v_cvt_pk_bf16_f32 v51, v55, v57
	global_store_dwordx4 v[52:53], v[48:51], off
	v_max_i32_e32 v44, 0, v44
	v_mul_f32_e32 v40, v40, v40
	v_lshl_add_u64 v[48:49], v[112:113], 1, s[24:25]
	v_max_i32_e32 v45, 0, v45
	v_mul_f32_e32 v41, v41, v41
	v_max_i32_e32 v46, 0, v46
	v_mul_f32_e32 v42, v42, v42
	v_max_i32_e32 v47, 0, v47
	v_mul_f32_e32 v43, v43, v43
	v_mul_f32_e32 v32, v32, v32
	v_mul_f32_e32 v36, v36, v36
	v_max_i32_e32 v37, 0, v37
	v_mul_f32_e32 v33, v33, v33
	v_mul_f32_e32 v34, v34, v34
	v_max_i32_e32 v35, 0, v35
	v_mul_f32_e32 v44, v44, v44
	v_mul_f32_e32 v45, v45, v45
	v_mul_f32_e32 v46, v46, v46
	v_mul_f32_e32 v47, v47, v47
	v_cvt_pk_bf16_f32 v40, v40, v41
	v_cvt_pk_bf16_f32 v41, v42, v43
	v_cvt_pk_bf16_f32 v42, v44, v45
	v_cvt_pk_bf16_f32 v43, v46, v47
	global_store_dwordx4 v[48:49], v[40:43], off
	v_mul_f32_e32 v37, v37, v37
	v_mul_f32_e32 v35, v35, v35
	v_cvt_pk_bf16_f32 v32, v32, v33
	v_cvt_pk_bf16_f32 v33, v34, v35
	v_cvt_pk_bf16_f32 v34, v36, v37
	v_add_co_u32_e32 v36, vcc, s52, v48
	v_max_i32_e32 v38, 0, v38
	v_max_i32_e32 v39, 0, v39
	v_addc_co_u32_e32 v37, vcc, 0, v49, vcc
	v_max_i32_e32 v24, 0, v24
	v_max_i32_e32 v25, 0, v25
	v_max_i32_e32 v26, 0, v26
	v_max_i32_e32 v27, 0, v27
	v_max_i32_e32 v16, 0, v16
	v_max_i32_e32 v20, 0, v20
	v_max_i32_e32 v17, 0, v17
	v_max_i32_e32 v18, 0, v18
	v_mul_f32_e32 v38, v38, v38
	v_mul_f32_e32 v39, v39, v39
	v_cvt_pk_bf16_f32 v35, v38, v39
	global_store_dwordx4 v[36:37], v[32:35], off
	v_max_i32_e32 v28, 0, v28
	v_mul_f32_e32 v24, v24, v24
	v_lshl_add_u64 v[32:33], s[24:25], 0, v[96:97]
	v_max_i32_e32 v29, 0, v29
	v_mul_f32_e32 v25, v25, v25
	v_max_i32_e32 v30, 0, v30
	v_mul_f32_e32 v26, v26, v26
	v_max_i32_e32 v31, 0, v31
	v_mul_f32_e32 v27, v27, v27
	v_mul_f32_e32 v16, v16, v16
	v_mul_f32_e32 v20, v20, v20
	v_max_i32_e32 v21, 0, v21
	v_mul_f32_e32 v17, v17, v17
	v_mul_f32_e32 v18, v18, v18
	v_max_i32_e32 v19, 0, v19
	v_mul_f32_e32 v28, v28, v28
	v_mul_f32_e32 v29, v29, v29
	v_mul_f32_e32 v30, v30, v30
	v_mul_f32_e32 v31, v31, v31
	v_cvt_pk_bf16_f32 v24, v24, v25
	v_cvt_pk_bf16_f32 v25, v26, v27
	v_cvt_pk_bf16_f32 v26, v28, v29
	v_cvt_pk_bf16_f32 v27, v30, v31
	global_store_dwordx4 v[32:33], v[24:27], off
	v_mul_f32_e32 v21, v21, v21
	v_mul_f32_e32 v19, v19, v19
	v_cvt_pk_bf16_f32 v16, v16, v17
	v_cvt_pk_bf16_f32 v17, v18, v19
	v_cvt_pk_bf16_f32 v18, v20, v21
	v_add_co_u32_e32 v20, vcc, s52, v32
	v_max_i32_e32 v22, 0, v22
	v_max_i32_e32 v23, 0, v23
	v_addc_co_u32_e32 v21, vcc, 0, v33, vcc
	v_max_i32_e32 v8, 0, v8
	v_max_i32_e32 v9, 0, v9
	v_max_i32_e32 v10, 0, v10
	v_max_i32_e32 v11, 0, v11
	v_max_i32_e32 v0, 0, v0
	v_max_i32_e32 v4, 0, v4
	v_max_i32_e32 v1, 0, v1
	v_max_i32_e32 v2, 0, v2
	v_mul_f32_e32 v22, v22, v22
	v_mul_f32_e32 v23, v23, v23
	v_cvt_pk_bf16_f32 v19, v22, v23
	global_store_dwordx4 v[20:21], v[16:19], off
	v_max_i32_e32 v12, 0, v12
	v_mul_f32_e32 v8, v8, v8
	v_lshl_add_u64 v[16:17], s[24:25], 0, v[80:81]
	v_max_i32_e32 v13, 0, v13
	v_mul_f32_e32 v9, v9, v9
	v_max_i32_e32 v14, 0, v14
	v_mul_f32_e32 v10, v10, v10
	v_max_i32_e32 v15, 0, v15
	v_mul_f32_e32 v11, v11, v11
	v_mul_f32_e32 v0, v0, v0
	v_mul_f32_e32 v4, v4, v4
	v_max_i32_e32 v5, 0, v5
	v_mul_f32_e32 v1, v1, v1
	v_mul_f32_e32 v2, v2, v2
	v_max_i32_e32 v3, 0, v3
	v_mul_f32_e32 v12, v12, v12
	v_mul_f32_e32 v13, v13, v13
	v_mul_f32_e32 v14, v14, v14
	v_mul_f32_e32 v15, v15, v15
	v_cvt_pk_bf16_f32 v8, v8, v9
	v_cvt_pk_bf16_f32 v9, v10, v11
	v_cvt_pk_bf16_f32 v10, v12, v13
	v_cvt_pk_bf16_f32 v11, v14, v15
	global_store_dwordx4 v[16:17], v[8:11], off
	v_mul_f32_e32 v5, v5, v5
	v_mul_f32_e32 v3, v3, v3
	v_cvt_pk_bf16_f32 v0, v0, v1
	v_cvt_pk_bf16_f32 v1, v2, v3
	v_cvt_pk_bf16_f32 v2, v4, v5
	v_add_co_u32_e32 v4, vcc, 0x10000, v16
	v_max_i32_e32 v6, 0, v6
	s_nop 0
	v_addc_co_u32_e32 v5, vcc, 0, v17, vcc
	v_max_i32_e32 v7, 0, v7
	s_andn2_b64 vcc, exec, s[0:1]
	s_mov_b64 s[0:1], -1
	v_mul_f32_e32 v6, v6, v6
	v_mul_f32_e32 v7, v7, v7
	v_cvt_pk_bf16_f32 v3, v6, v7
	global_store_dwordx4 v[4:5], v[0:3], off
	s_mov_b32 s98, 1
	s_cbranch_vccnz .LBB0_3712
	s_andn2_b64 vcc, exec, s[4:5]
	s_cbranch_vccnz .LBB0_3711
	s_barrier
	s_branch .LBB0_3711
